# phase 5 forward substitution: the even-j/odd-j partial sums become the two halves of v_pk_fma_f32 (same arithmetic, half the VALU instructions)
# baseline (speedup 1.0000x reference)
; #define LAS __attribute__((address_space(3)))
; __device__ __forceinline__ float bf2f(unsigned short x) { return __uint_as_float(((unsigned)x) << 16); }
; __device__ __forceinline__ void chunk_prep_phase(const Params& p, int bid, int nblk, LAS unsigned char* lds0) {
;     ...
;             { const float br = betg[2]; ab0 = (f32x2){bf2f(*(const LAS bf16_t*)(lg + P5_VS + 544 + c * 2)) * br, bf2f(*(const LAS bf16_t*)(lg + P5_KS + 544 + c * 2)) * br * __expf(decg[2])}; ab1 = (f32x2){0.f, 0.f}; } ab0 -= mq[1][0] * xy[0]; ab1 -= mq[1][1] * xy[1]; xy[2] = ab0 + ab1; up[256] = xy[2][0]; wp[256] = f2bf(-xy[2][1]); mq[1] = *(const LAS f32x4*)(Mg + 388);
.Ls4_n1:
	s_waitcnt lgkmcnt(1)
	v_lshlrev_b32_e32 v228, 16, v228
	v_mul_f32_e32 v232, v228, v218
	v_mul_f32_e32 v230, v232, v2
	v_mov_b32_e32 v231, 0
	ds_read_u16 v229, v7 offset:816
	v_pk_fma_f32 v[230:231], v[196:197], v[84:85], v[230:231] neg_lo:[1,0,0] neg_hi:[1,0,0]
	ds_read_b128 v[196:199], v8 offset:1552
	v_add_f32_e32 v86, v230, v231
	s_cbranch_vccz .Ls4_u2
	v_cvt_pk_bf16_f32 v233, -v86, v86
	global_store_short v6, v233, s[8:9] offset:512
	s_branch .Ls4_n2

; #define LAS __attribute__((address_space(3)))
; __device__ __forceinline__ float bf2f(unsigned short x) { return __uint_as_float(((unsigned)x) << 16); }
; __device__ __forceinline__ void chunk_prep_phase(const Params& p, int bid, int nblk, LAS unsigned char* lds0) {
;     ...
;             { const float br = betg[3]; ab0 = (f32x2){bf2f(*(const LAS bf16_t*)(lg + P5_VS + 816 + c * 2)) * br, bf2f(*(const LAS bf16_t*)(lg + P5_KS + 816 + c * 2)) * br * __expf(decg[3])}; ab1 = (f32x2){0.f, 0.f}; } ab0 -= mq[2][0] * xy[0]; ab1 -= mq[2][1] * xy[1]; ab0 -= mq[2][2] * xy[2]; xy[3] = ab0 + ab1; up[384] = xy[3][0]; wp[384] = f2bf(-xy[3][1]); mq[2] = *(const LAS f32x4*)(Mg + 448);
.Ls4_n2:
	s_waitcnt lgkmcnt(1)
	v_lshlrev_b32_e32 v229, 16, v229
	v_mul_f32_e32 v232, v229, v219
	v_mul_f32_e32 v230, v232, v3
	v_mov_b32_e32 v231, 0
	ds_read_u16 v228, v7 offset:1088
	ds_read_b128 v[216:219], v8 offset:16672
	ds_read_b128 v[0:3], v8 offset:16416
	v_pk_fma_f32 v[230:231], v[200:201], v[84:85], v[230:231] neg_lo:[1,0,0] neg_hi:[1,0,0]
	v_fma_f32 v230, -v202, v86, v230
	ds_read_b128 v[200:203], v8 offset:1792
	v_add_f32_e32 v87, v230, v231
	s_cbranch_vccz .Ls4_u3
	v_cvt_pk_bf16_f32 v233, -v87, v87
	global_store_short v6, v233, s[8:9] offset:768
	s_branch .Ls4_n3

; #define LAS __attribute__((address_space(3)))
; __device__ __forceinline__ float bf2f(unsigned short x) { return __uint_as_float(((unsigned)x) << 16); }
; __device__ __forceinline__ void chunk_prep_phase(const Params& p, int bid, int nblk, LAS unsigned char* lds0) {
;     ...
;             { const float br = betg[4]; ab0 = (f32x2){bf2f(*(const LAS bf16_t*)(lg + P5_VS + 1088 + c * 2)) * br, bf2f(*(const LAS bf16_t*)(lg + P5_KS + 1088 + c * 2)) * br * __expf(decg[4])}; ab1 = (f32x2){0.f, 0.f}; } ab0 -= mq[3][0] * xy[0]; ab1 -= mq[3][1] * xy[1]; ab0 -= mq[3][2] * xy[2]; ab1 -= mq[3][3] * xy[3]; xy[4] = ab0 + ab1; up[512] = xy[4][0]; wp[512] = f2bf(-xy[4][1]); mq[3] = *(const LAS f32x4*)(Mg + 452);
.Ls4_n3:
	v_mul_f32_e32 v224, s16, v224
	v_mul_f32_e32 v225, s16, v225
	v_mul_f32_e32 v226, s16, v226
	v_mul_f32_e32 v227, s16, v227
	v_exp_f32_e32 v224, v224
	v_exp_f32_e32 v225, v225
	v_exp_f32_e32 v226, v226
	v_exp_f32_e32 v227, v227
	s_nop 0
	s_waitcnt lgkmcnt(3)
	v_lshlrev_b32_e32 v228, 16, v228
	v_mul_f32_e32 v232, v228, v220
	v_mul_f32_e32 v230, v232, v224
	v_mov_b32_e32 v231, 0
	ds_read_u16 v229, v7 offset:1360
	v_pk_fma_f32 v[230:231], v[204:205], v[84:85], v[230:231] neg_lo:[1,0,0] neg_hi:[1,0,0]
	v_pk_fma_f32 v[230:231], v[206:207], v[86:87], v[230:231] neg_lo:[1,0,0] neg_hi:[1,0,0]
	ds_read_b128 v[204:207], v8 offset:1808
	v_add_f32_e32 v88, v230, v231
	s_cbranch_vccz .Ls4_u4
	v_cvt_pk_bf16_f32 v233, -v88, v88
	global_store_short v6, v233, s[8:9] offset:1024
	s_branch .Ls4_n4

; #define LAS __attribute__((address_space(3)))
; __device__ __forceinline__ float bf2f(unsigned short x) { return __uint_as_float(((unsigned)x) << 16); }
; __device__ __forceinline__ void chunk_prep_phase(const Params& p, int bid, int nblk, LAS unsigned char* lds0) {
;     ...
;             { const float br = betg[5]; ab0 = (f32x2){bf2f(*(const LAS bf16_t*)(lg + P5_VS + 1360 + c * 2)) * br, bf2f(*(const LAS bf16_t*)(lg + P5_KS + 1360 + c * 2)) * br * __expf(decg[5])}; ab1 = (f32x2){0.f, 0.f}; } ab0 -= mq[4][0] * xy[0]; ab1 -= mq[4][1] * xy[1]; ab0 -= mq[4][2] * xy[2]; ab1 -= mq[4][3] * xy[3]; mq[4] = *(const LAS f32x4*)(Mg + 512);
;             ab0 -= mq[5][0] * xy[4]; xy[5] = ab0 + ab1; up[640] = xy[5][0]; wp[640] = f2bf(-xy[5][1]); mq[5] = *(const LAS f32x4*)(Mg + 516);
.Ls4_n4:
	s_waitcnt lgkmcnt(1)
	v_lshlrev_b32_e32 v229, 16, v229
	v_mul_f32_e32 v232, v229, v221
	v_mul_f32_e32 v230, v232, v225
	v_mov_b32_e32 v231, 0
	ds_read_u16 v228, v7 offset:1632
	v_pk_fma_f32 v[230:231], v[208:209], v[84:85], v[230:231] neg_lo:[1,0,0] neg_hi:[1,0,0]
	v_pk_fma_f32 v[230:231], v[210:211], v[86:87], v[230:231] neg_lo:[1,0,0] neg_hi:[1,0,0]
	ds_read_b128 v[208:211], v8 offset:2048
	v_fma_f32 v230, -v212, v88, v230
	ds_read_b128 v[212:215], v8 offset:2064
	v_add_f32_e32 v89, v230, v231
	s_cbranch_vccz .Ls4_u5
	v_cvt_pk_bf16_f32 v233, -v89, v89
	global_store_short v6, v233, s[8:9] offset:1280
	s_branch .Ls4_n5

; #define LAS __attribute__((address_space(3)))
; __device__ __forceinline__ float bf2f(unsigned short x) { return __uint_as_float(((unsigned)x) << 16); }
; __device__ __forceinline__ void chunk_prep_phase(const Params& p, int bid, int nblk, LAS unsigned char* lds0) {
;     ...
;             { const float br = betg[6]; ab0 = (f32x2){bf2f(*(const LAS bf16_t*)(lg + P5_VS + 1632 + c * 2)) * br, bf2f(*(const LAS bf16_t*)(lg + P5_KS + 1632 + c * 2)) * br * __expf(decg[6])}; ab1 = (f32x2){0.f, 0.f}; } ab0 -= mq[0][0] * xy[0]; ab1 -= mq[0][1] * xy[1]; ab0 -= mq[0][2] * xy[2]; ab1 -= mq[0][3] * xy[3]; mq[0] = *(const LAS f32x4*)(Mg + 576);
;             ab0 -= mq[1][0] * xy[4]; ab1 -= mq[1][1] * xy[5]; xy[6] = ab0 + ab1; up[768] = xy[6][0]; wp[768] = f2bf(-xy[6][1]); mq[1] = *(const LAS f32x4*)(Mg + 580);
.Ls4_n5:
	s_waitcnt lgkmcnt(2)
	v_lshlrev_b32_e32 v228, 16, v228
	v_mul_f32_e32 v232, v228, v222
	v_mul_f32_e32 v230, v232, v226
	v_mov_b32_e32 v231, 0
	ds_read_u16 v229, v7 offset:1904
	v_pk_fma_f32 v[230:231], v[192:193], v[84:85], v[230:231] neg_lo:[1,0,0] neg_hi:[1,0,0]
	v_pk_fma_f32 v[230:231], v[194:195], v[86:87], v[230:231] neg_lo:[1,0,0] neg_hi:[1,0,0]
	ds_read_b128 v[192:195], v8 offset:2304
	v_pk_fma_f32 v[230:231], v[196:197], v[88:89], v[230:231] neg_lo:[1,0,0] neg_hi:[1,0,0]
	ds_read_b128 v[196:199], v8 offset:2320
	v_add_f32_e32 v90, v230, v231
	s_cbranch_vccz .Ls4_u6
	v_cvt_pk_bf16_f32 v233, -v90, v90
	global_store_short v6, v233, s[8:9] offset:1536
	s_branch .Ls4_n6

; #define LAS __attribute__((address_space(3)))
; __device__ __forceinline__ float bf2f(unsigned short x) { return __uint_as_float(((unsigned)x) << 16); }
; __device__ __forceinline__ void chunk_prep_phase(const Params& p, int bid, int nblk, LAS unsigned char* lds0) {
;     ...
;             { const float br = betg[7]; ab0 = (f32x2){bf2f(*(const LAS bf16_t*)(lg + P5_VS + 1904 + c * 2)) * br, bf2f(*(const LAS bf16_t*)(lg + P5_KS + 1904 + c * 2)) * br * __expf(decg[7])}; ab1 = (f32x2){0.f, 0.f}; } ab0 -= mq[2][0] * xy[0]; ab1 -= mq[2][1] * xy[1]; ab0 -= mq[2][2] * xy[2]; ab1 -= mq[2][3] * xy[3]; mq[2] = *(const LAS f32x4*)(Mg + 584);
;             ab0 -= mq[3][0] * xy[4]; ab1 -= mq[3][1] * xy[5]; ab0 -= mq[3][2] * xy[6]; xy[7] = ab0 + ab1; up[896] = xy[7][0]; wp[896] = f2bf(-xy[7][1]); mq[3] = *(const LAS f32x4*)(Mg + 640);
.Ls4_n6:
	s_waitcnt lgkmcnt(2)
	v_lshlrev_b32_e32 v229, 16, v229
	v_mul_f32_e32 v232, v229, v223
	v_mul_f32_e32 v230, v232, v227
	v_mov_b32_e32 v231, 0
	ds_read_u16 v228, v7 offset:2176
	ds_read_b128 v[220:223], v8 offset:16688
	ds_read_b128 v[224:227], v8 offset:16432
	v_pk_fma_f32 v[230:231], v[200:201], v[84:85], v[230:231] neg_lo:[1,0,0] neg_hi:[1,0,0]
	v_pk_fma_f32 v[230:231], v[202:203], v[86:87], v[230:231] neg_lo:[1,0,0] neg_hi:[1,0,0]
	ds_read_b128 v[200:203], v8 offset:2336
	v_pk_fma_f32 v[230:231], v[204:205], v[88:89], v[230:231] neg_lo:[1,0,0] neg_hi:[1,0,0]
	v_fma_f32 v230, -v206, v90, v230
	ds_read_b128 v[204:207], v8 offset:2560
	v_add_f32_e32 v91, v230, v231
	s_cbranch_vccz .Ls4_u7
	v_cvt_pk_bf16_f32 v233, -v91, v91
	global_store_short v6, v233, s[8:9] offset:1792
	s_branch .Ls4_n7

; #define LAS __attribute__((address_space(3)))
; __device__ __forceinline__ float bf2f(unsigned short x) { return __uint_as_float(((unsigned)x) << 16); }
; __device__ __forceinline__ void chunk_prep_phase(const Params& p, int bid, int nblk, LAS unsigned char* lds0) {
;     ...
;             { const float br = betg[8]; ab0 = (f32x2){bf2f(*(const LAS bf16_t*)(lg + P5_VS + 2176 + c * 2)) * br, bf2f(*(const LAS bf16_t*)(lg + P5_KS + 2176 + c * 2)) * br * __expf(decg[8])}; ab1 = (f32x2){0.f, 0.f}; } ab0 -= mq[4][0] * xy[0]; ab1 -= mq[4][1] * xy[1]; ab0 -= mq[4][2] * xy[2]; ab1 -= mq[4][3] * xy[3]; mq[4] = *(const LAS f32x4*)(Mg + 644);
;             ab0 -= mq[5][0] * xy[4]; ab1 -= mq[5][1] * xy[5]; ab0 -= mq[5][2] * xy[6]; ab1 -= mq[5][3] * xy[7]; xy[8] = ab0 + ab1; up[1024] = xy[8][0]; wp[1024] = f2bf(-xy[8][1]); mq[5] = *(const LAS f32x4*)(Mg + 648);
.Ls4_n7:
	v_mul_f32_e32 v0, s16, v0
	v_mul_f32_e32 v1, s16, v1
	v_mul_f32_e32 v2, s16, v2
	v_mul_f32_e32 v3, s16, v3
	v_exp_f32_e32 v0, v0
	v_exp_f32_e32 v1, v1
	v_exp_f32_e32 v2, v2
	v_exp_f32_e32 v3, v3
	s_nop 0
	s_waitcnt lgkmcnt(4)
	v_lshlrev_b32_e32 v228, 16, v228
	v_mul_f32_e32 v232, v228, v216
	v_mul_f32_e32 v230, v232, v0
	v_mov_b32_e32 v231, 0
	ds_read_u16 v229, v7 offset:2448
	v_pk_fma_f32 v[230:231], v[208:209], v[84:85], v[230:231] neg_lo:[1,0,0] neg_hi:[1,0,0]
	v_pk_fma_f32 v[230:231], v[210:211], v[86:87], v[230:231] neg_lo:[1,0,0] neg_hi:[1,0,0]
	ds_read_b128 v[208:211], v8 offset:2576
	v_pk_fma_f32 v[230:231], v[212:213], v[88:89], v[230:231] neg_lo:[1,0,0] neg_hi:[1,0,0]
	v_pk_fma_f32 v[230:231], v[214:215], v[90:91], v[230:231] neg_lo:[1,0,0] neg_hi:[1,0,0]
	ds_read_b128 v[212:215], v8 offset:2592
	v_add_f32_e32 v92, v230, v231
	s_cbranch_vccz .Ls4_u8
	v_cvt_pk_bf16_f32 v233, -v92, v92
	global_store_short v6, v233, s[8:9] offset:2048
	s_branch .Ls4_n8

; #define LAS __attribute__((address_space(3)))
; __device__ __forceinline__ float bf2f(unsigned short x) { return __uint_as_float(((unsigned)x) << 16); }
; __device__ __forceinline__ void chunk_prep_phase(const Params& p, int bid, int nblk, LAS unsigned char* lds0) {
;     ...
;             { const float br = betg[9]; ab0 = (f32x2){bf2f(*(const LAS bf16_t*)(lg + P5_VS + 2448 + c * 2)) * br, bf2f(*(const LAS bf16_t*)(lg + P5_KS + 2448 + c * 2)) * br * __expf(decg[9])}; ab1 = (f32x2){0.f, 0.f}; } ab0 -= mq[0][0] * xy[0]; ab1 -= mq[0][1] * xy[1]; ab0 -= mq[0][2] * xy[2]; ab1 -= mq[0][3] * xy[3]; mq[0] = *(const LAS f32x4*)(Mg + 704);
;             ab0 -= mq[1][0] * xy[4]; ab1 -= mq[1][1] * xy[5]; ab0 -= mq[1][2] * xy[6]; ab1 -= mq[1][3] * xy[7]; mq[1] = *(const LAS f32x4*)(Mg + 708);
;             ab0 -= mq[2][0] * xy[8]; xy[9] = ab0 + ab1; up[1152] = xy[9][0]; wp[1152] = f2bf(-xy[9][1]); mq[2] = *(const LAS f32x4*)(Mg + 712);
.Ls4_n8:
	s_waitcnt lgkmcnt(2)
	v_lshlrev_b32_e32 v229, 16, v229
	v_mul_f32_e32 v232, v229, v217
	v_mul_f32_e32 v230, v232, v1
	v_mov_b32_e32 v231, 0
	ds_read_u16 v228, v7 offset:2720
	v_pk_fma_f32 v[230:231], v[192:193], v[84:85], v[230:231] neg_lo:[1,0,0] neg_hi:[1,0,0]
	v_pk_fma_f32 v[230:231], v[194:195], v[86:87], v[230:231] neg_lo:[1,0,0] neg_hi:[1,0,0]
	ds_read_b128 v[192:195], v8 offset:2816
	v_pk_fma_f32 v[230:231], v[196:197], v[88:89], v[230:231] neg_lo:[1,0,0] neg_hi:[1,0,0]
	v_pk_fma_f32 v[230:231], v[198:199], v[90:91], v[230:231] neg_lo:[1,0,0] neg_hi:[1,0,0]
	ds_read_b128 v[196:199], v8 offset:2832
	v_fma_f32 v230, -v200, v92, v230
	ds_read_b128 v[200:203], v8 offset:2848
	v_add_f32_e32 v93, v230, v231
	s_cbranch_vccz .Ls4_u9
	v_cvt_pk_bf16_f32 v233, -v93, v93
	global_store_short v6, v233, s[8:9] offset:2304
	s_branch .Ls4_n9

; #define LAS __attribute__((address_space(3)))
; __device__ __forceinline__ float bf2f(unsigned short x) { return __uint_as_float(((unsigned)x) << 16); }
; __device__ __forceinline__ void chunk_prep_phase(const Params& p, int bid, int nblk, LAS unsigned char* lds0) {
;     ...
;             { const float br = betg[10]; ab0 = (f32x2){bf2f(*(const LAS bf16_t*)(lg + P5_VS + 2720 + c * 2)) * br, bf2f(*(const LAS bf16_t*)(lg + P5_KS + 2720 + c * 2)) * br * __expf(decg[10])}; ab1 = (f32x2){0.f, 0.f}; } ab0 -= mq[3][0] * xy[0]; ab1 -= mq[3][1] * xy[1]; ab0 -= mq[3][2] * xy[2]; ab1 -= mq[3][3] * xy[3]; mq[3] = *(const LAS f32x4*)(Mg + 768);
;             ab0 -= mq[4][0] * xy[4]; ab1 -= mq[4][1] * xy[5]; ab0 -= mq[4][2] * xy[6]; ab1 -= mq[4][3] * xy[7]; mq[4] = *(const LAS f32x4*)(Mg + 772);
;             ab0 -= mq[5][0] * xy[8]; ab1 -= mq[5][1] * xy[9]; xy[10] = ab0 + ab1; up[1280] = xy[10][0]; wp[1280] = f2bf(-xy[10][1]); mq[5] = *(const LAS f32x4*)(Mg + 776);
.Ls4_n9:
	s_waitcnt lgkmcnt(3)
	v_lshlrev_b32_e32 v228, 16, v228
	v_mul_f32_e32 v232, v228, v218
	v_mul_f32_e32 v230, v232, v2
	v_mov_b32_e32 v231, 0
	ds_read_u16 v229, v7 offset:2992
	v_pk_fma_f32 v[230:231], v[204:205], v[84:85], v[230:231] neg_lo:[1,0,0] neg_hi:[1,0,0]
	v_pk_fma_f32 v[230:231], v[206:207], v[86:87], v[230:231] neg_lo:[1,0,0] neg_hi:[1,0,0]
	ds_read_b128 v[204:207], v8 offset:3072
	v_pk_fma_f32 v[230:231], v[208:209], v[88:89], v[230:231] neg_lo:[1,0,0] neg_hi:[1,0,0]
	v_pk_fma_f32 v[230:231], v[210:211], v[90:91], v[230:231] neg_lo:[1,0,0] neg_hi:[1,0,0]
	ds_read_b128 v[208:211], v8 offset:3088
	v_pk_fma_f32 v[230:231], v[212:213], v[92:93], v[230:231] neg_lo:[1,0,0] neg_hi:[1,0,0]
	ds_read_b128 v[212:215], v8 offset:3104
	v_add_f32_e32 v94, v230, v231
	s_cbranch_vccz .Ls4_u10
	v_cvt_pk_bf16_f32 v233, -v94, v94
	global_store_short v6, v233, s[8:9] offset:2560
	s_branch .Ls4_n10

; #define LAS __attribute__((address_space(3)))
; __device__ __forceinline__ float bf2f(unsigned short x) { return __uint_as_float(((unsigned)x) << 16); }
; __device__ __forceinline__ void chunk_prep_phase(const Params& p, int bid, int nblk, LAS unsigned char* lds0) {
;     ...
;             { const float br = betg[11]; ab0 = (f32x2){bf2f(*(const LAS bf16_t*)(lg + P5_VS + 2992 + c * 2)) * br, bf2f(*(const LAS bf16_t*)(lg + P5_KS + 2992 + c * 2)) * br * __expf(decg[11])}; ab1 = (f32x2){0.f, 0.f}; } ab0 -= mq[0][0] * xy[0]; ab1 -= mq[0][1] * xy[1]; ab0 -= mq[0][2] * xy[2]; ab1 -= mq[0][3] * xy[3]; mq[0] = *(const LAS f32x4*)(Mg + 832);
;             ab0 -= mq[1][0] * xy[4]; ab1 -= mq[1][1] * xy[5]; ab0 -= mq[1][2] * xy[6]; ab1 -= mq[1][3] * xy[7]; mq[1] = *(const LAS f32x4*)(Mg + 836);
;             ab0 -= mq[2][0] * xy[8]; ab1 -= mq[2][1] * xy[9]; ab0 -= mq[2][2] * xy[10]; xy[11] = ab0 + ab1; up[1408] = xy[11][0]; wp[1408] = f2bf(-xy[11][1]); mq[2] = *(const LAS f32x4*)(Mg + 840);
.Ls4_n10:
	s_waitcnt lgkmcnt(3)
	v_lshlrev_b32_e32 v229, 16, v229
	v_mul_f32_e32 v232, v229, v219
	v_mul_f32_e32 v230, v232, v3
	v_mov_b32_e32 v231, 0
	ds_read_u16 v228, v7 offset:3264
	ds_read_b128 v[216:219], v8 offset:16704
	ds_read_b128 v[0:3], v8 offset:16448
	v_pk_fma_f32 v[230:231], v[192:193], v[84:85], v[230:231] neg_lo:[1,0,0] neg_hi:[1,0,0]
	v_pk_fma_f32 v[230:231], v[194:195], v[86:87], v[230:231] neg_lo:[1,0,0] neg_hi:[1,0,0]
	ds_read_b128 v[192:195], v8 offset:3328
	v_pk_fma_f32 v[230:231], v[196:197], v[88:89], v[230:231] neg_lo:[1,0,0] neg_hi:[1,0,0]
	v_pk_fma_f32 v[230:231], v[198:199], v[90:91], v[230:231] neg_lo:[1,0,0] neg_hi:[1,0,0]
	ds_read_b128 v[196:199], v8 offset:3344
	v_pk_fma_f32 v[230:231], v[200:201], v[92:93], v[230:231] neg_lo:[1,0,0] neg_hi:[1,0,0]
	v_fma_f32 v230, -v202, v94, v230
	ds_read_b128 v[200:203], v8 offset:3360
	v_add_f32_e32 v95, v230, v231
	s_cbranch_vccz .Ls4_u11
	v_cvt_pk_bf16_f32 v233, -v95, v95
	global_store_short v6, v233, s[8:9] offset:2816
	s_branch .Ls4_n11

; #define LAS __attribute__((address_space(3)))
; __device__ __forceinline__ float bf2f(unsigned short x) { return __uint_as_float(((unsigned)x) << 16); }
; __device__ __forceinline__ void chunk_prep_phase(const Params& p, int bid, int nblk, LAS unsigned char* lds0) {
;     ...
;             { const float br = betg[12]; ab0 = (f32x2){bf2f(*(const LAS bf16_t*)(lg + P5_VS + 3264 + c * 2)) * br, bf2f(*(const LAS bf16_t*)(lg + P5_KS + 3264 + c * 2)) * br * __expf(decg[12])}; ab1 = (f32x2){0.f, 0.f}; } ab0 -= mq[3][0] * xy[0]; ab1 -= mq[3][1] * xy[1]; ab0 -= mq[3][2] * xy[2]; ab1 -= mq[3][3] * xy[3]; mq[3] = *(const LAS f32x4*)(Mg + 844);
;             ab0 -= mq[4][0] * xy[4]; ab1 -= mq[4][1] * xy[5]; ab0 -= mq[4][2] * xy[6]; ab1 -= mq[4][3] * xy[7]; mq[4] = *(const LAS f32x4*)(Mg + 896);
;             ab0 -= mq[5][0] * xy[8]; ab1 -= mq[5][1] * xy[9]; ab0 -= mq[5][2] * xy[10]; ab1 -= mq[5][3] * xy[11]; xy[12] = ab0 + ab1; up[1536] = xy[12][0]; wp[1536] = f2bf(-xy[12][1]); mq[5] = *(const LAS f32x4*)(Mg + 900);
.Ls4_n11:
	v_mul_f32_e32 v224, s16, v224
	v_mul_f32_e32 v225, s16, v225
	v_mul_f32_e32 v226, s16, v226
	v_mul_f32_e32 v227, s16, v227
	v_exp_f32_e32 v224, v224
	v_exp_f32_e32 v225, v225
	v_exp_f32_e32 v226, v226
	v_exp_f32_e32 v227, v227
	s_nop 0
	s_waitcnt lgkmcnt(5)
	v_lshlrev_b32_e32 v228, 16, v228
	v_mul_f32_e32 v232, v228, v220
	v_mul_f32_e32 v230, v232, v224
	v_mov_b32_e32 v231, 0
	ds_read_u16 v229, v7 offset:3536
	v_pk_fma_f32 v[230:231], v[204:205], v[84:85], v[230:231] neg_lo:[1,0,0] neg_hi:[1,0,0]
	v_pk_fma_f32 v[230:231], v[206:207], v[86:87], v[230:231] neg_lo:[1,0,0] neg_hi:[1,0,0]
	ds_read_b128 v[204:207], v8 offset:3376
	v_pk_fma_f32 v[230:231], v[208:209], v[88:89], v[230:231] neg_lo:[1,0,0] neg_hi:[1,0,0]
	v_pk_fma_f32 v[230:231], v[210:211], v[90:91], v[230:231] neg_lo:[1,0,0] neg_hi:[1,0,0]
	ds_read_b128 v[208:211], v8 offset:3584
	v_pk_fma_f32 v[230:231], v[212:213], v[92:93], v[230:231] neg_lo:[1,0,0] neg_hi:[1,0,0]
	v_pk_fma_f32 v[230:231], v[214:215], v[94:95], v[230:231] neg_lo:[1,0,0] neg_hi:[1,0,0]
	ds_read_b128 v[212:215], v8 offset:3600
	v_add_f32_e32 v96, v230, v231
	s_cbranch_vccz .Ls4_u12
	v_cvt_pk_bf16_f32 v233, -v96, v96
	global_store_short v6, v233, s[8:9] offset:3072
	s_branch .Ls4_n12

; #define LAS __attribute__((address_space(3)))
; __device__ __forceinline__ float bf2f(unsigned short x) { return __uint_as_float(((unsigned)x) << 16); }
; __device__ __forceinline__ void chunk_prep_phase(const Params& p, int bid, int nblk, LAS unsigned char* lds0) {
;     ...
;             { const float br = betg[13]; ab0 = (f32x2){bf2f(*(const LAS bf16_t*)(lg + P5_VS + 3536 + c * 2)) * br, bf2f(*(const LAS bf16_t*)(lg + P5_KS + 3536 + c * 2)) * br * __expf(decg[13])}; ab1 = (f32x2){0.f, 0.f}; } ab0 -= mq[0][0] * xy[0]; ab1 -= mq[0][1] * xy[1]; ab0 -= mq[0][2] * xy[2]; ab1 -= mq[0][3] * xy[3]; mq[0] = *(const LAS f32x4*)(Mg + 904);
;             ab0 -= mq[1][0] * xy[4]; ab1 -= mq[1][1] * xy[5]; ab0 -= mq[1][2] * xy[6]; ab1 -= mq[1][3] * xy[7]; mq[1] = *(const LAS f32x4*)(Mg + 908);
;             ab0 -= mq[2][0] * xy[8]; ab1 -= mq[2][1] * xy[9]; ab0 -= mq[2][2] * xy[10]; ab1 -= mq[2][3] * xy[11]; mq[2] = *(const LAS f32x4*)(Mg + 960);
;             ab0 -= mq[3][0] * xy[12]; xy[13] = ab0 + ab1; up[1664] = xy[13][0]; wp[1664] = f2bf(-xy[13][1]); mq[3] = *(const LAS f32x4*)(Mg + 964);
.Ls4_n12:
	s_waitcnt lgkmcnt(3)
	v_lshlrev_b32_e32 v229, 16, v229
	v_mul_f32_e32 v232, v229, v221
	v_mul_f32_e32 v230, v232, v225
	v_mov_b32_e32 v231, 0
	ds_read_u16 v228, v7 offset:3808
	v_pk_fma_f32 v[230:231], v[192:193], v[84:85], v[230:231] neg_lo:[1,0,0] neg_hi:[1,0,0]
	v_pk_fma_f32 v[230:231], v[194:195], v[86:87], v[230:231] neg_lo:[1,0,0] neg_hi:[1,0,0]
	ds_read_b128 v[192:195], v8 offset:3616
	v_pk_fma_f32 v[230:231], v[196:197], v[88:89], v[230:231] neg_lo:[1,0,0] neg_hi:[1,0,0]
	v_pk_fma_f32 v[230:231], v[198:199], v[90:91], v[230:231] neg_lo:[1,0,0] neg_hi:[1,0,0]
	ds_read_b128 v[196:199], v8 offset:3632
	v_pk_fma_f32 v[230:231], v[200:201], v[92:93], v[230:231] neg_lo:[1,0,0] neg_hi:[1,0,0]
	v_pk_fma_f32 v[230:231], v[202:203], v[94:95], v[230:231] neg_lo:[1,0,0] neg_hi:[1,0,0]
	ds_read_b128 v[200:203], v8 offset:3840
	s_waitcnt lgkmcnt(6)
	v_fma_f32 v230, -v204, v96, v230
	ds_read_b128 v[204:207], v8 offset:3856
	v_add_f32_e32 v97, v230, v231
	s_cbranch_vccz .Ls4_u13
	v_cvt_pk_bf16_f32 v233, -v97, v97
	global_store_short v6, v233, s[8:9] offset:3328
	s_branch .Ls4_n13

; #define LAS __attribute__((address_space(3)))
; __device__ __forceinline__ float bf2f(unsigned short x) { return __uint_as_float(((unsigned)x) << 16); }
; __device__ __forceinline__ void chunk_prep_phase(const Params& p, int bid, int nblk, LAS unsigned char* lds0) {
;     ...
;             { const float br = betg[14]; ab0 = (f32x2){bf2f(*(const LAS bf16_t*)(lg + P5_VS + 3808 + c * 2)) * br, bf2f(*(const LAS bf16_t*)(lg + P5_KS + 3808 + c * 2)) * br * __expf(decg[14])}; ab1 = (f32x2){0.f, 0.f}; } ab0 -= mq[4][0] * xy[0]; ab1 -= mq[4][1] * xy[1]; ab0 -= mq[4][2] * xy[2]; ab1 -= mq[4][3] * xy[3]; mq[4] = *(const LAS f32x4*)(Mg + 968);
;             ab0 -= mq[5][0] * xy[4]; ab1 -= mq[5][1] * xy[5]; ab0 -= mq[5][2] * xy[6]; ab1 -= mq[5][3] * xy[7]; mq[5] = *(const LAS f32x4*)(Mg + 972);
;             ab0 -= mq[0][0] * xy[8]; ab1 -= mq[0][1] * xy[9]; ab0 -= mq[0][2] * xy[10]; ab1 -= mq[0][3] * xy[11]; mq[0] = *(const LAS f32x4*)(Mg + 1024);
;             ab0 -= mq[1][0] * xy[12]; ab1 -= mq[1][1] * xy[13]; xy[14] = ab0 + ab1; up[1792] = xy[14][0]; wp[1792] = f2bf(-xy[14][1]); mq[1] = *(const LAS f32x4*)(Mg + 1028);
.Ls4_n13:
	s_waitcnt lgkmcnt(4)
	v_lshlrev_b32_e32 v228, 16, v228
	v_mul_f32_e32 v232, v228, v222
	v_mul_f32_e32 v230, v232, v226
	v_mov_b32_e32 v231, 0
	ds_read_u16 v229, v7 offset:4080
	v_pk_fma_f32 v[230:231], v[208:209], v[84:85], v[230:231] neg_lo:[1,0,0] neg_hi:[1,0,0]
	v_pk_fma_f32 v[230:231], v[210:211], v[86:87], v[230:231] neg_lo:[1,0,0] neg_hi:[1,0,0]
	ds_read_b128 v[208:211], v8 offset:3872
	v_pk_fma_f32 v[230:231], v[212:213], v[88:89], v[230:231] neg_lo:[1,0,0] neg_hi:[1,0,0]
	v_pk_fma_f32 v[230:231], v[214:215], v[90:91], v[230:231] neg_lo:[1,0,0] neg_hi:[1,0,0]
	ds_read_b128 v[212:215], v8 offset:3888
	s_waitcnt lgkmcnt(6)
	v_pk_fma_f32 v[230:231], v[192:193], v[92:93], v[230:231] neg_lo:[1,0,0] neg_hi:[1,0,0]
	v_pk_fma_f32 v[230:231], v[194:195], v[94:95], v[230:231] neg_lo:[1,0,0] neg_hi:[1,0,0]
	ds_read_b128 v[192:195], v8 offset:4096
	s_waitcnt lgkmcnt(6)
	v_pk_fma_f32 v[230:231], v[196:197], v[96:97], v[230:231] neg_lo:[1,0,0] neg_hi:[1,0,0]
	ds_read_b128 v[196:199], v8 offset:4112
	v_add_f32_e32 v98, v230, v231
	s_cbranch_vccz .Ls4_u14
	v_cvt_pk_bf16_f32 v233, -v98, v98
	global_store_short v6, v233, s[8:9] offset:3584
	s_branch .Ls4_n14

; #define LAS __attribute__((address_space(3)))
; __device__ __forceinline__ float bf2f(unsigned short x) { return __uint_as_float(((unsigned)x) << 16); }
; __device__ __forceinline__ void chunk_prep_phase(const Params& p, int bid, int nblk, LAS unsigned char* lds0) {
;     ...
;             { const float br = betg[15]; ab0 = (f32x2){bf2f(*(const LAS bf16_t*)(lg + P5_VS + 4080 + c * 2)) * br, bf2f(*(const LAS bf16_t*)(lg + P5_KS + 4080 + c * 2)) * br * __expf(decg[15])}; ab1 = (f32x2){0.f, 0.f}; } ab0 -= mq[2][0] * xy[0]; ab1 -= mq[2][1] * xy[1]; ab0 -= mq[2][2] * xy[2]; ab1 -= mq[2][3] * xy[3]; mq[2] = *(const LAS f32x4*)(Mg + 1032);
;             ab0 -= mq[3][0] * xy[4]; ab1 -= mq[3][1] * xy[5]; ab0 -= mq[3][2] * xy[6]; ab1 -= mq[3][3] * xy[7]; mq[3] = *(const LAS f32x4*)(Mg + 1036);
;             ab0 -= mq[4][0] * xy[8]; ab1 -= mq[4][1] * xy[9]; ab0 -= mq[4][2] * xy[10]; ab1 -= mq[4][3] * xy[11]; mq[4] = *(const LAS f32x4*)(Mg + 1088);
;             ab0 -= mq[5][0] * xy[12]; ab1 -= mq[5][1] * xy[13]; ab0 -= mq[5][2] * xy[14]; xy[15] = ab0 + ab1; up[1920] = xy[15][0]; wp[1920] = f2bf(-xy[15][1]); mq[5] = *(const LAS f32x4*)(Mg + 1092);
.Ls4_n14:
	s_waitcnt lgkmcnt(4)
	v_lshlrev_b32_e32 v229, 16, v229
	v_mul_f32_e32 v232, v229, v223
	v_mul_f32_e32 v230, v232, v227
	v_mov_b32_e32 v231, 0
	ds_read_u16 v228, v7 offset:4352
	ds_read_b128 v[220:223], v8 offset:16720
	ds_read_b128 v[224:227], v8 offset:16464
	v_pk_fma_f32 v[230:231], v[200:201], v[84:85], v[230:231] neg_lo:[1,0,0] neg_hi:[1,0,0]
	v_pk_fma_f32 v[230:231], v[202:203], v[86:87], v[230:231] neg_lo:[1,0,0] neg_hi:[1,0,0]
	ds_read_b128 v[200:203], v8 offset:4128
	v_pk_fma_f32 v[230:231], v[204:205], v[88:89], v[230:231] neg_lo:[1,0,0] neg_hi:[1,0,0]
	v_pk_fma_f32 v[230:231], v[206:207], v[90:91], v[230:231] neg_lo:[1,0,0] neg_hi:[1,0,0]
	ds_read_b128 v[204:207], v8 offset:4144
	s_waitcnt lgkmcnt(8)
	v_pk_fma_f32 v[230:231], v[208:209], v[92:93], v[230:231] neg_lo:[1,0,0] neg_hi:[1,0,0]
	v_pk_fma_f32 v[230:231], v[210:211], v[94:95], v[230:231] neg_lo:[1,0,0] neg_hi:[1,0,0]
	ds_read_b128 v[208:211], v8 offset:4352
	s_waitcnt lgkmcnt(8)
	v_pk_fma_f32 v[230:231], v[212:213], v[96:97], v[230:231] neg_lo:[1,0,0] neg_hi:[1,0,0]
	v_fma_f32 v230, -v214, v98, v230
	ds_read_b128 v[212:215], v8 offset:4368
	v_add_f32_e32 v99, v230, v231
	s_cbranch_vccz .Ls4_u15
	v_cvt_pk_bf16_f32 v233, -v99, v99
	global_store_short v6, v233, s[8:9] offset:3840
	s_branch .Ls4_n15

; #define LAS __attribute__((address_space(3)))
; __device__ __forceinline__ float bf2f(unsigned short x) { return __uint_as_float(((unsigned)x) << 16); }
; __device__ __forceinline__ void chunk_prep_phase(const Params& p, int bid, int nblk, LAS unsigned char* lds0) {
;     ...
;             { const float br = betg[16]; ab0 = (f32x2){bf2f(*(const LAS bf16_t*)(lg + P5_VS + 4352 + c * 2)) * br, bf2f(*(const LAS bf16_t*)(lg + P5_KS + 4352 + c * 2)) * br * __expf(decg[16])}; ab1 = (f32x2){0.f, 0.f}; } ab0 -= mq[0][0] * xy[0]; ab1 -= mq[0][1] * xy[1]; ab0 -= mq[0][2] * xy[2]; ab1 -= mq[0][3] * xy[3]; mq[0] = *(const LAS f32x4*)(Mg + 1096);
;             ab0 -= mq[1][0] * xy[4]; ab1 -= mq[1][1] * xy[5]; ab0 -= mq[1][2] * xy[6]; ab1 -= mq[1][3] * xy[7]; mq[1] = *(const LAS f32x4*)(Mg + 1100);
;             ab0 -= mq[2][0] * xy[8]; ab1 -= mq[2][1] * xy[9]; ab0 -= mq[2][2] * xy[10]; ab1 -= mq[2][3] * xy[11]; mq[2] = *(const LAS f32x4*)(Mg + 1104);
;             ab0 -= mq[3][0] * xy[12]; ab1 -= mq[3][1] * xy[13]; ab0 -= mq[3][2] * xy[14]; ab1 -= mq[3][3] * xy[15]; xy[16] = ab0 + ab1; up[2048] = xy[16][0]; wp[2048] = f2bf(-xy[16][1]); mq[3] = *(const LAS f32x4*)(Mg + 1152);
.Ls4_n15:
	v_mul_f32_e32 v0, s16, v0
	v_mul_f32_e32 v1, s16, v1
	v_mul_f32_e32 v2, s16, v2
	v_mul_f32_e32 v3, s16, v3
	v_exp_f32_e32 v0, v0
	v_exp_f32_e32 v1, v1
	v_exp_f32_e32 v2, v2
	v_exp_f32_e32 v3, v3
	s_nop 0
	s_waitcnt lgkmcnt(6)
	v_lshlrev_b32_e32 v228, 16, v228
	v_mul_f32_e32 v232, v228, v216
	v_mul_f32_e32 v230, v232, v0
	v_mov_b32_e32 v231, 0
	ds_read_u16 v229, v7 offset:4624
	v_pk_fma_f32 v[230:231], v[192:193], v[84:85], v[230:231] neg_lo:[1,0,0] neg_hi:[1,0,0]
	v_pk_fma_f32 v[230:231], v[194:195], v[86:87], v[230:231] neg_lo:[1,0,0] neg_hi:[1,0,0]
	ds_read_b128 v[192:195], v8 offset:4384
	v_pk_fma_f32 v[230:231], v[196:197], v[88:89], v[230:231] neg_lo:[1,0,0] neg_hi:[1,0,0]
	v_pk_fma_f32 v[230:231], v[198:199], v[90:91], v[230:231] neg_lo:[1,0,0] neg_hi:[1,0,0]
	ds_read_b128 v[196:199], v8 offset:4400
	s_waitcnt lgkmcnt(6)
	v_pk_fma_f32 v[230:231], v[200:201], v[92:93], v[230:231] neg_lo:[1,0,0] neg_hi:[1,0,0]
	v_pk_fma_f32 v[230:231], v[202:203], v[94:95], v[230:231] neg_lo:[1,0,0] neg_hi:[1,0,0]
	ds_read_b128 v[200:203], v8 offset:4416
	s_waitcnt lgkmcnt(6)
	v_pk_fma_f32 v[230:231], v[204:205], v[96:97], v[230:231] neg_lo:[1,0,0] neg_hi:[1,0,0]
	v_pk_fma_f32 v[230:231], v[206:207], v[98:99], v[230:231] neg_lo:[1,0,0] neg_hi:[1,0,0]
	ds_read_b128 v[204:207], v8 offset:4608
	v_add_f32_e32 v100, v230, v231
	s_cbranch_vccz .Ls4_u16
	s_add_u32 s8, s8, 0x1000
	s_addc_u32 s9, s9, 0
	v_cvt_pk_bf16_f32 v233, -v100, v100
	global_store_short v6, v233, s[8:9] offset:0
	s_branch .Ls4_n16

; #define LAS __attribute__((address_space(3)))
; __device__ __forceinline__ float bf2f(unsigned short x) { return __uint_as_float(((unsigned)x) << 16); }
; __device__ __forceinline__ void chunk_prep_phase(const Params& p, int bid, int nblk, LAS unsigned char* lds0) {
;     ...
;             { const float br = betg[17]; ab0 = (f32x2){bf2f(*(const LAS bf16_t*)(lg + P5_VS + 4624 + c * 2)) * br, bf2f(*(const LAS bf16_t*)(lg + P5_KS + 4624 + c * 2)) * br * __expf(decg[17])}; ab1 = (f32x2){0.f, 0.f}; } ab0 -= mq[4][0] * xy[0]; ab1 -= mq[4][1] * xy[1]; ab0 -= mq[4][2] * xy[2]; ab1 -= mq[4][3] * xy[3]; mq[4] = *(const LAS f32x4*)(Mg + 1156);
;             ab0 -= mq[5][0] * xy[4]; ab1 -= mq[5][1] * xy[5]; ab0 -= mq[5][2] * xy[6]; ab1 -= mq[5][3] * xy[7]; mq[5] = *(const LAS f32x4*)(Mg + 1160);
;             ab0 -= mq[0][0] * xy[8]; ab1 -= mq[0][1] * xy[9]; ab0 -= mq[0][2] * xy[10]; ab1 -= mq[0][3] * xy[11]; mq[0] = *(const LAS f32x4*)(Mg + 1164);
;             ab0 -= mq[1][0] * xy[12]; ab1 -= mq[1][1] * xy[13]; ab0 -= mq[1][2] * xy[14]; ab1 -= mq[1][3] * xy[15]; mq[1] = *(const LAS f32x4*)(Mg + 1168);
;             ab0 -= mq[2][0] * xy[16]; xy[17] = ab0 + ab1; up[2176] = xy[17][0]; wp[2176] = f2bf(-xy[17][1]); mq[2] = *(const LAS f32x4*)(Mg + 1216);
.Ls4_n16:
	s_waitcnt lgkmcnt(4)
	v_lshlrev_b32_e32 v229, 16, v229
	v_mul_f32_e32 v232, v229, v217
	v_mul_f32_e32 v230, v232, v1
	v_mov_b32_e32 v231, 0
	ds_read_u16 v228, v7 offset:4896
	v_pk_fma_f32 v[230:231], v[208:209], v[84:85], v[230:231] neg_lo:[1,0,0] neg_hi:[1,0,0]
	v_pk_fma_f32 v[230:231], v[210:211], v[86:87], v[230:231] neg_lo:[1,0,0] neg_hi:[1,0,0]
	ds_read_b128 v[208:211], v8 offset:4624
	v_pk_fma_f32 v[230:231], v[212:213], v[88:89], v[230:231] neg_lo:[1,0,0] neg_hi:[1,0,0]
	v_pk_fma_f32 v[230:231], v[214:215], v[90:91], v[230:231] neg_lo:[1,0,0] neg_hi:[1,0,0]
	ds_read_b128 v[212:215], v8 offset:4640
	s_waitcnt lgkmcnt(6)
	v_pk_fma_f32 v[230:231], v[192:193], v[92:93], v[230:231] neg_lo:[1,0,0] neg_hi:[1,0,0]
	v_pk_fma_f32 v[230:231], v[194:195], v[94:95], v[230:231] neg_lo:[1,0,0] neg_hi:[1,0,0]
	ds_read_b128 v[192:195], v8 offset:4656
	s_waitcnt lgkmcnt(6)
	v_pk_fma_f32 v[230:231], v[196:197], v[96:97], v[230:231] neg_lo:[1,0,0] neg_hi:[1,0,0]
	v_pk_fma_f32 v[230:231], v[198:199], v[98:99], v[230:231] neg_lo:[1,0,0] neg_hi:[1,0,0]
	ds_read_b128 v[196:199], v8 offset:4672
	s_waitcnt lgkmcnt(6)
	v_fma_f32 v230, -v200, v100, v230
	ds_read_b128 v[200:203], v8 offset:4864
	v_add_f32_e32 v101, v230, v231
	s_cbranch_vccz .Ls4_u17
	v_cvt_pk_bf16_f32 v233, -v101, v101
	global_store_short v6, v233, s[8:9] offset:256
	s_branch .Ls4_n17

; #define LAS __attribute__((address_space(3)))
; __device__ __forceinline__ float bf2f(unsigned short x) { return __uint_as_float(((unsigned)x) << 16); }
; __device__ __forceinline__ void chunk_prep_phase(const Params& p, int bid, int nblk, LAS unsigned char* lds0) {
;     ...
;             { const float br = betg[18]; ab0 = (f32x2){bf2f(*(const LAS bf16_t*)(lg + P5_VS + 4896 + c * 2)) * br, bf2f(*(const LAS bf16_t*)(lg + P5_KS + 4896 + c * 2)) * br * __expf(decg[18])}; ab1 = (f32x2){0.f, 0.f}; } ab0 -= mq[3][0] * xy[0]; ab1 -= mq[3][1] * xy[1]; ab0 -= mq[3][2] * xy[2]; ab1 -= mq[3][3] * xy[3]; mq[3] = *(const LAS f32x4*)(Mg + 1220);
;             ab0 -= mq[4][0] * xy[4]; ab1 -= mq[4][1] * xy[5]; ab0 -= mq[4][2] * xy[6]; ab1 -= mq[4][3] * xy[7]; mq[4] = *(const LAS f32x4*)(Mg + 1224);
;             ab0 -= mq[5][0] * xy[8]; ab1 -= mq[5][1] * xy[9]; ab0 -= mq[5][2] * xy[10]; ab1 -= mq[5][3] * xy[11]; mq[5] = *(const LAS f32x4*)(Mg + 1228);
;             ab0 -= mq[0][0] * xy[12]; ab1 -= mq[0][1] * xy[13]; ab0 -= mq[0][2] * xy[14]; ab1 -= mq[0][3] * xy[15]; mq[0] = *(const LAS f32x4*)(Mg + 1232);
;             ab0 -= mq[1][0] * xy[16]; ab1 -= mq[1][1] * xy[17]; xy[18] = ab0 + ab1; up[2304] = xy[18][0]; wp[2304] = f2bf(-xy[18][1]); mq[1] = *(const LAS f32x4*)(Mg + 1280);
.Ls4_n17:
	s_waitcnt lgkmcnt(5)
	v_lshlrev_b32_e32 v228, 16, v228
	v_mul_f32_e32 v232, v228, v218
	v_mul_f32_e32 v230, v232, v2
	v_mov_b32_e32 v231, 0
	ds_read_u16 v229, v7 offset:5168
	v_pk_fma_f32 v[230:231], v[204:205], v[84:85], v[230:231] neg_lo:[1,0,0] neg_hi:[1,0,0]
	v_pk_fma_f32 v[230:231], v[206:207], v[86:87], v[230:231] neg_lo:[1,0,0] neg_hi:[1,0,0]
	ds_read_b128 v[204:207], v8 offset:4880
	s_waitcnt lgkmcnt(6)
	v_pk_fma_f32 v[230:231], v[208:209], v[88:89], v[230:231] neg_lo:[1,0,0] neg_hi:[1,0,0]
	v_pk_fma_f32 v[230:231], v[210:211], v[90:91], v[230:231] neg_lo:[1,0,0] neg_hi:[1,0,0]
	ds_read_b128 v[208:211], v8 offset:4896
	s_waitcnt lgkmcnt(6)
	v_pk_fma_f32 v[230:231], v[212:213], v[92:93], v[230:231] neg_lo:[1,0,0] neg_hi:[1,0,0]
	v_pk_fma_f32 v[230:231], v[214:215], v[94:95], v[230:231] neg_lo:[1,0,0] neg_hi:[1,0,0]
	ds_read_b128 v[212:215], v8 offset:4912
	s_waitcnt lgkmcnt(6)
	v_pk_fma_f32 v[230:231], v[192:193], v[96:97], v[230:231] neg_lo:[1,0,0] neg_hi:[1,0,0]
	v_pk_fma_f32 v[230:231], v[194:195], v[98:99], v[230:231] neg_lo:[1,0,0] neg_hi:[1,0,0]
	ds_read_b128 v[192:195], v8 offset:4928
	s_waitcnt lgkmcnt(6)
	v_pk_fma_f32 v[230:231], v[196:197], v[100:101], v[230:231] neg_lo:[1,0,0] neg_hi:[1,0,0]
	ds_read_b128 v[196:199], v8 offset:5120
	v_add_f32_e32 v102, v230, v231
	s_cbranch_vccz .Ls4_u18
	v_cvt_pk_bf16_f32 v233, -v102, v102
	global_store_short v6, v233, s[8:9] offset:512
	s_branch .Ls4_n18

; #define LAS __attribute__((address_space(3)))
; __device__ __forceinline__ float bf2f(unsigned short x) { return __uint_as_float(((unsigned)x) << 16); }
; __device__ __forceinline__ void chunk_prep_phase(const Params& p, int bid, int nblk, LAS unsigned char* lds0) {
;     ...
;             { const float br = betg[19]; ab0 = (f32x2){bf2f(*(const LAS bf16_t*)(lg + P5_VS + 5168 + c * 2)) * br, bf2f(*(const LAS bf16_t*)(lg + P5_KS + 5168 + c * 2)) * br * __expf(decg[19])}; ab1 = (f32x2){0.f, 0.f}; } ab0 -= mq[2][0] * xy[0]; ab1 -= mq[2][1] * xy[1]; ab0 -= mq[2][2] * xy[2]; ab1 -= mq[2][3] * xy[3]; mq[2] = *(const LAS f32x4*)(Mg + 1284);
;             ab0 -= mq[3][0] * xy[4]; ab1 -= mq[3][1] * xy[5]; ab0 -= mq[3][2] * xy[6]; ab1 -= mq[3][3] * xy[7]; mq[3] = *(const LAS f32x4*)(Mg + 1288);
;             ab0 -= mq[4][0] * xy[8]; ab1 -= mq[4][1] * xy[9]; ab0 -= mq[4][2] * xy[10]; ab1 -= mq[4][3] * xy[11]; mq[4] = *(const LAS f32x4*)(Mg + 1292);
;             ab0 -= mq[5][0] * xy[12]; ab1 -= mq[5][1] * xy[13]; ab0 -= mq[5][2] * xy[14]; ab1 -= mq[5][3] * xy[15]; mq[5] = *(const LAS f32x4*)(Mg + 1296);
;             ab0 -= mq[0][0] * xy[16]; ab1 -= mq[0][1] * xy[17]; ab0 -= mq[0][2] * xy[18]; xy[19] = ab0 + ab1; up[2432] = xy[19][0]; wp[2432] = f2bf(-xy[19][1]); mq[0] = *(const LAS f32x4*)(Mg + 1344);
.Ls4_n18:
	s_waitcnt lgkmcnt(5)
	v_lshlrev_b32_e32 v229, 16, v229
	v_mul_f32_e32 v232, v229, v219
	v_mul_f32_e32 v230, v232, v3
	v_mov_b32_e32 v231, 0
	ds_read_u16 v228, v7 offset:5440
	ds_read_b128 v[216:219], v8 offset:16736
	ds_read_b128 v[0:3], v8 offset:16480
	v_pk_fma_f32 v[230:231], v[200:201], v[84:85], v[230:231] neg_lo:[1,0,0] neg_hi:[1,0,0]
	v_pk_fma_f32 v[230:231], v[202:203], v[86:87], v[230:231] neg_lo:[1,0,0] neg_hi:[1,0,0]
	ds_read_b128 v[200:203], v8 offset:5136
	s_waitcnt lgkmcnt(8)
	v_pk_fma_f32 v[230:231], v[204:205], v[88:89], v[230:231] neg_lo:[1,0,0] neg_hi:[1,0,0]
	v_pk_fma_f32 v[230:231], v[206:207], v[90:91], v[230:231] neg_lo:[1,0,0] neg_hi:[1,0,0]
	ds_read_b128 v[204:207], v8 offset:5152
	s_waitcnt lgkmcnt(8)
	v_pk_fma_f32 v[230:231], v[208:209], v[92:93], v[230:231] neg_lo:[1,0,0] neg_hi:[1,0,0]
	v_pk_fma_f32 v[230:231], v[210:211], v[94:95], v[230:231] neg_lo:[1,0,0] neg_hi:[1,0,0]
	ds_read_b128 v[208:211], v8 offset:5168
	s_waitcnt lgkmcnt(8)
	v_pk_fma_f32 v[230:231], v[212:213], v[96:97], v[230:231] neg_lo:[1,0,0] neg_hi:[1,0,0]
	v_pk_fma_f32 v[230:231], v[214:215], v[98:99], v[230:231] neg_lo:[1,0,0] neg_hi:[1,0,0]
	ds_read_b128 v[212:215], v8 offset:5184
	s_waitcnt lgkmcnt(8)
	v_pk_fma_f32 v[230:231], v[192:193], v[100:101], v[230:231] neg_lo:[1,0,0] neg_hi:[1,0,0]
	v_fma_f32 v230, -v194, v102, v230
	ds_read_b128 v[192:195], v8 offset:5376
	v_add_f32_e32 v103, v230, v231
	s_cbranch_vccz .Ls4_u19
	v_cvt_pk_bf16_f32 v233, -v103, v103
	global_store_short v6, v233, s[8:9] offset:768
	s_branch .Ls4_n19

; #define LAS __attribute__((address_space(3)))
; __device__ __forceinline__ float bf2f(unsigned short x) { return __uint_as_float(((unsigned)x) << 16); }
; __device__ __forceinline__ void chunk_prep_phase(const Params& p, int bid, int nblk, LAS unsigned char* lds0) {
;     ...
;             { const float br = betg[20]; ab0 = (f32x2){bf2f(*(const LAS bf16_t*)(lg + P5_VS + 5440 + c * 2)) * br, bf2f(*(const LAS bf16_t*)(lg + P5_KS + 5440 + c * 2)) * br * __expf(decg[20])}; ab1 = (f32x2){0.f, 0.f}; } ab0 -= mq[1][0] * xy[0]; ab1 -= mq[1][1] * xy[1]; ab0 -= mq[1][2] * xy[2]; ab1 -= mq[1][3] * xy[3]; mq[1] = *(const LAS f32x4*)(Mg + 1348);
;             ab0 -= mq[2][0] * xy[4]; ab1 -= mq[2][1] * xy[5]; ab0 -= mq[2][2] * xy[6]; ab1 -= mq[2][3] * xy[7]; mq[2] = *(const LAS f32x4*)(Mg + 1352);
;             ab0 -= mq[3][0] * xy[8]; ab1 -= mq[3][1] * xy[9]; ab0 -= mq[3][2] * xy[10]; ab1 -= mq[3][3] * xy[11]; mq[3] = *(const LAS f32x4*)(Mg + 1356);
;             ab0 -= mq[4][0] * xy[12]; ab1 -= mq[4][1] * xy[13]; ab0 -= mq[4][2] * xy[14]; ab1 -= mq[4][3] * xy[15]; mq[4] = *(const LAS f32x4*)(Mg + 1360);
;             ab0 -= mq[5][0] * xy[16]; ab1 -= mq[5][1] * xy[17]; ab0 -= mq[5][2] * xy[18]; ab1 -= mq[5][3] * xy[19]; xy[20] = ab0 + ab1; up[2560] = xy[20][0]; wp[2560] = f2bf(-xy[20][1]); mq[5] = *(const LAS f32x4*)(Mg + 1364);
.Ls4_n19:
	v_mul_f32_e32 v224, s16, v224
	v_mul_f32_e32 v225, s16, v225
	v_mul_f32_e32 v226, s16, v226
	v_mul_f32_e32 v227, s16, v227
	v_exp_f32_e32 v224, v224
	v_exp_f32_e32 v225, v225
	v_exp_f32_e32 v226, v226
	v_exp_f32_e32 v227, v227
	s_nop 0
	s_waitcnt lgkmcnt(7)
	v_lshlrev_b32_e32 v228, 16, v228
	v_mul_f32_e32 v232, v228, v220
	v_mul_f32_e32 v230, v232, v224
	v_mov_b32_e32 v231, 0
	ds_read_u16 v229, v7 offset:5712
	v_pk_fma_f32 v[230:231], v[196:197], v[84:85], v[230:231] neg_lo:[1,0,0] neg_hi:[1,0,0]
	v_pk_fma_f32 v[230:231], v[198:199], v[86:87], v[230:231] neg_lo:[1,0,0] neg_hi:[1,0,0]
	ds_read_b128 v[196:199], v8 offset:5392
	s_waitcnt lgkmcnt(6)
	v_pk_fma_f32 v[230:231], v[200:201], v[88:89], v[230:231] neg_lo:[1,0,0] neg_hi:[1,0,0]
	v_pk_fma_f32 v[230:231], v[202:203], v[90:91], v[230:231] neg_lo:[1,0,0] neg_hi:[1,0,0]
	ds_read_b128 v[200:203], v8 offset:5408
	s_waitcnt lgkmcnt(6)
	v_pk_fma_f32 v[230:231], v[204:205], v[92:93], v[230:231] neg_lo:[1,0,0] neg_hi:[1,0,0]
	v_pk_fma_f32 v[230:231], v[206:207], v[94:95], v[230:231] neg_lo:[1,0,0] neg_hi:[1,0,0]
	ds_read_b128 v[204:207], v8 offset:5424
	s_waitcnt lgkmcnt(6)
	v_pk_fma_f32 v[230:231], v[208:209], v[96:97], v[230:231] neg_lo:[1,0,0] neg_hi:[1,0,0]
	v_pk_fma_f32 v[230:231], v[210:211], v[98:99], v[230:231] neg_lo:[1,0,0] neg_hi:[1,0,0]
	ds_read_b128 v[208:211], v8 offset:5440
	s_waitcnt lgkmcnt(6)
	v_pk_fma_f32 v[230:231], v[212:213], v[100:101], v[230:231] neg_lo:[1,0,0] neg_hi:[1,0,0]
	v_pk_fma_f32 v[230:231], v[214:215], v[102:103], v[230:231] neg_lo:[1,0,0] neg_hi:[1,0,0]
	ds_read_b128 v[212:215], v8 offset:5456
	v_add_f32_e32 v104, v230, v231
	s_cbranch_vccz .Ls4_u20
	v_cvt_pk_bf16_f32 v233, -v104, v104
	global_store_short v6, v233, s[8:9] offset:1024
	s_branch .Ls4_n20

; #define LAS __attribute__((address_space(3)))
; __device__ __forceinline__ float bf2f(unsigned short x) { return __uint_as_float(((unsigned)x) << 16); }
; __device__ __forceinline__ void chunk_prep_phase(const Params& p, int bid, int nblk, LAS unsigned char* lds0) {
;     ...
;             { const float br = betg[21]; ab0 = (f32x2){bf2f(*(const LAS bf16_t*)(lg + P5_VS + 5712 + c * 2)) * br, bf2f(*(const LAS bf16_t*)(lg + P5_KS + 5712 + c * 2)) * br * __expf(decg[21])}; ab1 = (f32x2){0.f, 0.f}; } ab0 -= mq[0][0] * xy[0]; ab1 -= mq[0][1] * xy[1]; ab0 -= mq[0][2] * xy[2]; ab1 -= mq[0][3] * xy[3]; mq[0] = *(const LAS f32x4*)(Mg + 1408);
;             ab0 -= mq[1][0] * xy[4]; ab1 -= mq[1][1] * xy[5]; ab0 -= mq[1][2] * xy[6]; ab1 -= mq[1][3] * xy[7]; mq[1] = *(const LAS f32x4*)(Mg + 1412);
;             ab0 -= mq[2][0] * xy[8]; ab1 -= mq[2][1] * xy[9]; ab0 -= mq[2][2] * xy[10]; ab1 -= mq[2][3] * xy[11]; mq[2] = *(const LAS f32x4*)(Mg + 1416);
;             ab0 -= mq[3][0] * xy[12]; ab1 -= mq[3][1] * xy[13]; ab0 -= mq[3][2] * xy[14]; ab1 -= mq[3][3] * xy[15]; mq[3] = *(const LAS f32x4*)(Mg + 1420);
;             ab0 -= mq[4][0] * xy[16]; ab1 -= mq[4][1] * xy[17]; ab0 -= mq[4][2] * xy[18]; ab1 -= mq[4][3] * xy[19]; mq[4] = *(const LAS f32x4*)(Mg + 1424);
;             ab0 -= mq[5][0] * xy[20]; xy[21] = ab0 + ab1; up[2688] = xy[21][0]; wp[2688] = f2bf(-xy[21][1]); mq[5] = *(const LAS f32x4*)(Mg + 1428);
.Ls4_n20:
	s_waitcnt lgkmcnt(5)
	v_lshlrev_b32_e32 v229, 16, v229
	v_mul_f32_e32 v232, v229, v221
	v_mul_f32_e32 v230, v232, v225
	v_mov_b32_e32 v231, 0
	ds_read_u16 v228, v7 offset:5984
	v_pk_fma_f32 v[230:231], v[192:193], v[84:85], v[230:231] neg_lo:[1,0,0] neg_hi:[1,0,0]
	v_pk_fma_f32 v[230:231], v[194:195], v[86:87], v[230:231] neg_lo:[1,0,0] neg_hi:[1,0,0]
	ds_read_b128 v[192:195], v8 offset:5632
	s_waitcnt lgkmcnt(6)
	v_pk_fma_f32 v[230:231], v[196:197], v[88:89], v[230:231] neg_lo:[1,0,0] neg_hi:[1,0,0]
	v_pk_fma_f32 v[230:231], v[198:199], v[90:91], v[230:231] neg_lo:[1,0,0] neg_hi:[1,0,0]
	ds_read_b128 v[196:199], v8 offset:5648
	s_waitcnt lgkmcnt(6)
	v_pk_fma_f32 v[230:231], v[200:201], v[92:93], v[230:231] neg_lo:[1,0,0] neg_hi:[1,0,0]
	v_pk_fma_f32 v[230:231], v[202:203], v[94:95], v[230:231] neg_lo:[1,0,0] neg_hi:[1,0,0]
	ds_read_b128 v[200:203], v8 offset:5664
	s_waitcnt lgkmcnt(6)
	v_pk_fma_f32 v[230:231], v[204:205], v[96:97], v[230:231] neg_lo:[1,0,0] neg_hi:[1,0,0]
	v_pk_fma_f32 v[230:231], v[206:207], v[98:99], v[230:231] neg_lo:[1,0,0] neg_hi:[1,0,0]
	ds_read_b128 v[204:207], v8 offset:5680
	s_waitcnt lgkmcnt(6)
	v_pk_fma_f32 v[230:231], v[208:209], v[100:101], v[230:231] neg_lo:[1,0,0] neg_hi:[1,0,0]
	v_pk_fma_f32 v[230:231], v[210:211], v[102:103], v[230:231] neg_lo:[1,0,0] neg_hi:[1,0,0]
	ds_read_b128 v[208:211], v8 offset:5696
	s_waitcnt lgkmcnt(6)
	v_fma_f32 v230, -v212, v104, v230
	ds_read_b128 v[212:215], v8 offset:5712
	v_add_f32_e32 v105, v230, v231
	s_cbranch_vccz .Ls4_u21
	v_cvt_pk_bf16_f32 v233, -v105, v105
	global_store_short v6, v233, s[8:9] offset:1280
	s_branch .Ls4_n21

; #define LAS __attribute__((address_space(3)))
; __device__ __forceinline__ float bf2f(unsigned short x) { return __uint_as_float(((unsigned)x) << 16); }
; __device__ __forceinline__ void chunk_prep_phase(const Params& p, int bid, int nblk, LAS unsigned char* lds0) {
;     ...
;             { const float br = betg[22]; ab0 = (f32x2){bf2f(*(const LAS bf16_t*)(lg + P5_VS + 5984 + c * 2)) * br, bf2f(*(const LAS bf16_t*)(lg + P5_KS + 5984 + c * 2)) * br * __expf(decg[22])}; ab1 = (f32x2){0.f, 0.f}; } ab0 -= mq[0][0] * xy[0]; ab1 -= mq[0][1] * xy[1]; ab0 -= mq[0][2] * xy[2]; ab1 -= mq[0][3] * xy[3]; mq[0] = *(const LAS f32x4*)(Mg + 1472);
;             ab0 -= mq[1][0] * xy[4]; ab1 -= mq[1][1] * xy[5]; ab0 -= mq[1][2] * xy[6]; ab1 -= mq[1][3] * xy[7]; mq[1] = *(const LAS f32x4*)(Mg + 1476);
;             ab0 -= mq[2][0] * xy[8]; ab1 -= mq[2][1] * xy[9]; ab0 -= mq[2][2] * xy[10]; ab1 -= mq[2][3] * xy[11]; mq[2] = *(const LAS f32x4*)(Mg + 1480);
;             ab0 -= mq[3][0] * xy[12]; ab1 -= mq[3][1] * xy[13]; ab0 -= mq[3][2] * xy[14]; ab1 -= mq[3][3] * xy[15]; mq[3] = *(const LAS f32x4*)(Mg + 1484);
;             ab0 -= mq[4][0] * xy[16]; ab1 -= mq[4][1] * xy[17]; ab0 -= mq[4][2] * xy[18]; ab1 -= mq[4][3] * xy[19]; mq[4] = *(const LAS f32x4*)(Mg + 1488);
;             ab0 -= mq[5][0] * xy[20]; ab1 -= mq[5][1] * xy[21]; xy[22] = ab0 + ab1; up[2816] = xy[22][0]; wp[2816] = f2bf(-xy[22][1]); mq[5] = *(const LAS f32x4*)(Mg + 1492);
.Ls4_n21:
	s_waitcnt lgkmcnt(6)
	v_lshlrev_b32_e32 v228, 16, v228
	v_mul_f32_e32 v232, v228, v222
	v_mul_f32_e32 v230, v232, v226
	v_mov_b32_e32 v231, 0
	ds_read_u16 v229, v7 offset:6256
	s_waitcnt lgkmcnt(6)
	v_pk_fma_f32 v[230:231], v[192:193], v[84:85], v[230:231] neg_lo:[1,0,0] neg_hi:[1,0,0]
	v_pk_fma_f32 v[230:231], v[194:195], v[86:87], v[230:231] neg_lo:[1,0,0] neg_hi:[1,0,0]
	ds_read_b128 v[192:195], v8 offset:5888
	s_waitcnt lgkmcnt(6)
	v_pk_fma_f32 v[230:231], v[196:197], v[88:89], v[230:231] neg_lo:[1,0,0] neg_hi:[1,0,0]
	v_pk_fma_f32 v[230:231], v[198:199], v[90:91], v[230:231] neg_lo:[1,0,0] neg_hi:[1,0,0]
	ds_read_b128 v[196:199], v8 offset:5904
	s_waitcnt lgkmcnt(6)
	v_pk_fma_f32 v[230:231], v[200:201], v[92:93], v[230:231] neg_lo:[1,0,0] neg_hi:[1,0,0]
	v_pk_fma_f32 v[230:231], v[202:203], v[94:95], v[230:231] neg_lo:[1,0,0] neg_hi:[1,0,0]
	ds_read_b128 v[200:203], v8 offset:5920
	s_waitcnt lgkmcnt(6)
	v_pk_fma_f32 v[230:231], v[204:205], v[96:97], v[230:231] neg_lo:[1,0,0] neg_hi:[1,0,0]
	v_pk_fma_f32 v[230:231], v[206:207], v[98:99], v[230:231] neg_lo:[1,0,0] neg_hi:[1,0,0]
	ds_read_b128 v[204:207], v8 offset:5936
	s_waitcnt lgkmcnt(6)
	v_pk_fma_f32 v[230:231], v[208:209], v[100:101], v[230:231] neg_lo:[1,0,0] neg_hi:[1,0,0]
	v_pk_fma_f32 v[230:231], v[210:211], v[102:103], v[230:231] neg_lo:[1,0,0] neg_hi:[1,0,0]
	ds_read_b128 v[208:211], v8 offset:5952
	s_waitcnt lgkmcnt(6)
	v_pk_fma_f32 v[230:231], v[212:213], v[104:105], v[230:231] neg_lo:[1,0,0] neg_hi:[1,0,0]
	ds_read_b128 v[212:215], v8 offset:5968
	v_add_f32_e32 v106, v230, v231
	s_cbranch_vccz .Ls4_u22
	v_cvt_pk_bf16_f32 v233, -v106, v106
	global_store_short v6, v233, s[8:9] offset:1536
	s_branch .Ls4_n22

; #define LAS __attribute__((address_space(3)))
; __device__ __forceinline__ float bf2f(unsigned short x) { return __uint_as_float(((unsigned)x) << 16); }
; __device__ __forceinline__ void chunk_prep_phase(const Params& p, int bid, int nblk, LAS unsigned char* lds0) {
;     ...
;             { const float br = betg[23]; ab0 = (f32x2){bf2f(*(const LAS bf16_t*)(lg + P5_VS + 6256 + c * 2)) * br, bf2f(*(const LAS bf16_t*)(lg + P5_KS + 6256 + c * 2)) * br * __expf(decg[23])}; ab1 = (f32x2){0.f, 0.f}; } ab0 -= mq[0][0] * xy[0]; ab1 -= mq[0][1] * xy[1]; ab0 -= mq[0][2] * xy[2]; ab1 -= mq[0][3] * xy[3]; mq[0] = *(const LAS f32x4*)(Mg + 1536);
;             ab0 -= mq[1][0] * xy[4]; ab1 -= mq[1][1] * xy[5]; ab0 -= mq[1][2] * xy[6]; ab1 -= mq[1][3] * xy[7]; mq[1] = *(const LAS f32x4*)(Mg + 1540);
;             ab0 -= mq[2][0] * xy[8]; ab1 -= mq[2][1] * xy[9]; ab0 -= mq[2][2] * xy[10]; ab1 -= mq[2][3] * xy[11]; mq[2] = *(const LAS f32x4*)(Mg + 1544);
;             ab0 -= mq[3][0] * xy[12]; ab1 -= mq[3][1] * xy[13]; ab0 -= mq[3][2] * xy[14]; ab1 -= mq[3][3] * xy[15]; mq[3] = *(const LAS f32x4*)(Mg + 1548);
;             ab0 -= mq[4][0] * xy[16]; ab1 -= mq[4][1] * xy[17]; ab0 -= mq[4][2] * xy[18]; ab1 -= mq[4][3] * xy[19]; mq[4] = *(const LAS f32x4*)(Mg + 1552);
;             ab0 -= mq[5][0] * xy[20]; ab1 -= mq[5][1] * xy[21]; ab0 -= mq[5][2] * xy[22]; xy[23] = ab0 + ab1; up[2944] = xy[23][0]; wp[2944] = f2bf(-xy[23][1]); mq[5] = *(const LAS f32x4*)(Mg + 1556);
.Ls4_n22:
	s_waitcnt lgkmcnt(6)
	v_lshlrev_b32_e32 v229, 16, v229
	v_mul_f32_e32 v232, v229, v223
	v_mul_f32_e32 v230, v232, v227
	v_mov_b32_e32 v231, 0
	ds_read_u16 v228, v7 offset:6528
	ds_read_b128 v[220:223], v8 offset:16752
	ds_read_b128 v[224:227], v8 offset:16496
	s_waitcnt lgkmcnt(8)
	v_pk_fma_f32 v[230:231], v[192:193], v[84:85], v[230:231] neg_lo:[1,0,0] neg_hi:[1,0,0]
	v_pk_fma_f32 v[230:231], v[194:195], v[86:87], v[230:231] neg_lo:[1,0,0] neg_hi:[1,0,0]
	ds_read_b128 v[192:195], v8 offset:6144
	s_waitcnt lgkmcnt(8)
	v_pk_fma_f32 v[230:231], v[196:197], v[88:89], v[230:231] neg_lo:[1,0,0] neg_hi:[1,0,0]
	v_pk_fma_f32 v[230:231], v[198:199], v[90:91], v[230:231] neg_lo:[1,0,0] neg_hi:[1,0,0]
	ds_read_b128 v[196:199], v8 offset:6160
	s_waitcnt lgkmcnt(8)
	v_pk_fma_f32 v[230:231], v[200:201], v[92:93], v[230:231] neg_lo:[1,0,0] neg_hi:[1,0,0]
	v_pk_fma_f32 v[230:231], v[202:203], v[94:95], v[230:231] neg_lo:[1,0,0] neg_hi:[1,0,0]
	ds_read_b128 v[200:203], v8 offset:6176
	s_waitcnt lgkmcnt(8)
	v_pk_fma_f32 v[230:231], v[204:205], v[96:97], v[230:231] neg_lo:[1,0,0] neg_hi:[1,0,0]
	v_pk_fma_f32 v[230:231], v[206:207], v[98:99], v[230:231] neg_lo:[1,0,0] neg_hi:[1,0,0]
	ds_read_b128 v[204:207], v8 offset:6192
	s_waitcnt lgkmcnt(8)
	v_pk_fma_f32 v[230:231], v[208:209], v[100:101], v[230:231] neg_lo:[1,0,0] neg_hi:[1,0,0]
	v_pk_fma_f32 v[230:231], v[210:211], v[102:103], v[230:231] neg_lo:[1,0,0] neg_hi:[1,0,0]
	ds_read_b128 v[208:211], v8 offset:6208
	s_waitcnt lgkmcnt(8)
	v_pk_fma_f32 v[230:231], v[212:213], v[104:105], v[230:231] neg_lo:[1,0,0] neg_hi:[1,0,0]
	v_fma_f32 v230, -v214, v106, v230
	ds_read_b128 v[212:215], v8 offset:6224
	v_add_f32_e32 v107, v230, v231
	s_cbranch_vccz .Ls4_u23
	v_cvt_pk_bf16_f32 v233, -v107, v107
	global_store_short v6, v233, s[8:9] offset:1792
	s_branch .Ls4_n23

; #define LAS __attribute__((address_space(3)))
; __device__ __forceinline__ float bf2f(unsigned short x) { return __uint_as_float(((unsigned)x) << 16); }
; __device__ __forceinline__ void chunk_prep_phase(const Params& p, int bid, int nblk, LAS unsigned char* lds0) {
;     ...
;             { const float br = betg[24]; ab0 = (f32x2){bf2f(*(const LAS bf16_t*)(lg + P5_VS + 6528 + c * 2)) * br, bf2f(*(const LAS bf16_t*)(lg + P5_KS + 6528 + c * 2)) * br * __expf(decg[24])}; ab1 = (f32x2){0.f, 0.f}; } ab0 -= mq[0][0] * xy[0]; ab1 -= mq[0][1] * xy[1]; ab0 -= mq[0][2] * xy[2]; ab1 -= mq[0][3] * xy[3]; mq[0] = *(const LAS f32x4*)(Mg + 1600);
;             ab0 -= mq[1][0] * xy[4]; ab1 -= mq[1][1] * xy[5]; ab0 -= mq[1][2] * xy[6]; ab1 -= mq[1][3] * xy[7]; mq[1] = *(const LAS f32x4*)(Mg + 1604);
;             ab0 -= mq[2][0] * xy[8]; ab1 -= mq[2][1] * xy[9]; ab0 -= mq[2][2] * xy[10]; ab1 -= mq[2][3] * xy[11]; mq[2] = *(const LAS f32x4*)(Mg + 1608);
;             ab0 -= mq[3][0] * xy[12]; ab1 -= mq[3][1] * xy[13]; ab0 -= mq[3][2] * xy[14]; ab1 -= mq[3][3] * xy[15]; mq[3] = *(const LAS f32x4*)(Mg + 1612);
;             ab0 -= mq[4][0] * xy[16]; ab1 -= mq[4][1] * xy[17]; ab0 -= mq[4][2] * xy[18]; ab1 -= mq[4][3] * xy[19]; mq[4] = *(const LAS f32x4*)(Mg + 1616);
;             ab0 -= mq[5][0] * xy[20]; ab1 -= mq[5][1] * xy[21]; ab0 -= mq[5][2] * xy[22]; ab1 -= mq[5][3] * xy[23]; xy[24] = ab0 + ab1; up[3072] = xy[24][0]; wp[3072] = f2bf(-xy[24][1]); mq[5] = *(const LAS f32x4*)(Mg + 1620);
.Ls4_n23:
	v_mul_f32_e32 v0, s16, v0
	v_mul_f32_e32 v1, s16, v1
	v_mul_f32_e32 v2, s16, v2
	v_mul_f32_e32 v3, s16, v3
	v_exp_f32_e32 v0, v0
	v_exp_f32_e32 v1, v1
	v_exp_f32_e32 v2, v2
	v_exp_f32_e32 v3, v3
	s_nop 0
	s_waitcnt lgkmcnt(8)
	v_lshlrev_b32_e32 v228, 16, v228
	v_mul_f32_e32 v232, v228, v216
	v_mul_f32_e32 v230, v232, v0
	v_mov_b32_e32 v231, 0
	ds_read_u16 v229, v7 offset:6800
	s_waitcnt lgkmcnt(6)
	v_pk_fma_f32 v[230:231], v[192:193], v[84:85], v[230:231] neg_lo:[1,0,0] neg_hi:[1,0,0]
	v_pk_fma_f32 v[230:231], v[194:195], v[86:87], v[230:231] neg_lo:[1,0,0] neg_hi:[1,0,0]
	ds_read_b128 v[192:195], v8 offset:6400
	s_waitcnt lgkmcnt(6)
	v_pk_fma_f32 v[230:231], v[196:197], v[88:89], v[230:231] neg_lo:[1,0,0] neg_hi:[1,0,0]
	v_pk_fma_f32 v[230:231], v[198:199], v[90:91], v[230:231] neg_lo:[1,0,0] neg_hi:[1,0,0]
	ds_read_b128 v[196:199], v8 offset:6416
	s_waitcnt lgkmcnt(6)
	v_pk_fma_f32 v[230:231], v[200:201], v[92:93], v[230:231] neg_lo:[1,0,0] neg_hi:[1,0,0]
	v_pk_fma_f32 v[230:231], v[202:203], v[94:95], v[230:231] neg_lo:[1,0,0] neg_hi:[1,0,0]
	ds_read_b128 v[200:203], v8 offset:6432
	s_waitcnt lgkmcnt(6)
	v_pk_fma_f32 v[230:231], v[204:205], v[96:97], v[230:231] neg_lo:[1,0,0] neg_hi:[1,0,0]
	v_pk_fma_f32 v[230:231], v[206:207], v[98:99], v[230:231] neg_lo:[1,0,0] neg_hi:[1,0,0]
	ds_read_b128 v[204:207], v8 offset:6448
	s_waitcnt lgkmcnt(6)
	v_pk_fma_f32 v[230:231], v[208:209], v[100:101], v[230:231] neg_lo:[1,0,0] neg_hi:[1,0,0]
	v_pk_fma_f32 v[230:231], v[210:211], v[102:103], v[230:231] neg_lo:[1,0,0] neg_hi:[1,0,0]
	ds_read_b128 v[208:211], v8 offset:6464
	s_waitcnt lgkmcnt(6)
	v_pk_fma_f32 v[230:231], v[212:213], v[104:105], v[230:231] neg_lo:[1,0,0] neg_hi:[1,0,0]
	v_pk_fma_f32 v[230:231], v[214:215], v[106:107], v[230:231] neg_lo:[1,0,0] neg_hi:[1,0,0]
	ds_read_b128 v[212:215], v8 offset:6480
	v_add_f32_e32 v108, v230, v231
	s_cbranch_vccz .Ls4_u24
	v_cvt_pk_bf16_f32 v233, -v108, v108
	global_store_short v6, v233, s[8:9] offset:2048
	s_branch .Ls4_n24

; #define LAS __attribute__((address_space(3)))
; __device__ __forceinline__ float bf2f(unsigned short x) { return __uint_as_float(((unsigned)x) << 16); }
; __device__ __forceinline__ void chunk_prep_phase(const Params& p, int bid, int nblk, LAS unsigned char* lds0) {
;     ...
;             { const float br = betg[25]; ab0 = (f32x2){bf2f(*(const LAS bf16_t*)(lg + P5_VS + 6800 + c * 2)) * br, bf2f(*(const LAS bf16_t*)(lg + P5_KS + 6800 + c * 2)) * br * __expf(decg[25])}; ab1 = (f32x2){0.f, 0.f}; } ab0 -= mq[0][0] * xy[0]; ab1 -= mq[0][1] * xy[1]; ab0 -= mq[0][2] * xy[2]; ab1 -= mq[0][3] * xy[3]; mq[0] = *(const LAS f32x4*)(Mg + 1624);
;             ab0 -= mq[1][0] * xy[4]; ab1 -= mq[1][1] * xy[5]; ab0 -= mq[1][2] * xy[6]; ab1 -= mq[1][3] * xy[7]; mq[1] = *(const LAS f32x4*)(Mg + 1664);
;             ab0 -= mq[2][0] * xy[8]; ab1 -= mq[2][1] * xy[9]; ab0 -= mq[2][2] * xy[10]; ab1 -= mq[2][3] * xy[11]; mq[2] = *(const LAS f32x4*)(Mg + 1668);
;             ab0 -= mq[3][0] * xy[12]; ab1 -= mq[3][1] * xy[13]; ab0 -= mq[3][2] * xy[14]; ab1 -= mq[3][3] * xy[15]; mq[3] = *(const LAS f32x4*)(Mg + 1672);
;             ab0 -= mq[4][0] * xy[16]; ab1 -= mq[4][1] * xy[17]; ab0 -= mq[4][2] * xy[18]; ab1 -= mq[4][3] * xy[19]; mq[4] = *(const LAS f32x4*)(Mg + 1676);
;             ab0 -= mq[5][0] * xy[20]; ab1 -= mq[5][1] * xy[21]; ab0 -= mq[5][2] * xy[22]; ab1 -= mq[5][3] * xy[23]; mq[5] = *(const LAS f32x4*)(Mg + 1680);
;             ab0 -= mq[0][0] * xy[24]; xy[25] = ab0 + ab1; up[3200] = xy[25][0]; wp[3200] = f2bf(-xy[25][1]); mq[0] = *(const LAS f32x4*)(Mg + 1684);
.Ls4_n24:
	s_waitcnt lgkmcnt(6)
	v_lshlrev_b32_e32 v229, 16, v229
	v_mul_f32_e32 v232, v229, v217
	v_mul_f32_e32 v230, v232, v1
	v_mov_b32_e32 v231, 0
	ds_read_u16 v228, v7 offset:7072
	s_waitcnt lgkmcnt(6)
	v_pk_fma_f32 v[230:231], v[192:193], v[84:85], v[230:231] neg_lo:[1,0,0] neg_hi:[1,0,0]
	v_pk_fma_f32 v[230:231], v[194:195], v[86:87], v[230:231] neg_lo:[1,0,0] neg_hi:[1,0,0]
	ds_read_b128 v[192:195], v8 offset:6496
	s_waitcnt lgkmcnt(6)
	v_pk_fma_f32 v[230:231], v[196:197], v[88:89], v[230:231] neg_lo:[1,0,0] neg_hi:[1,0,0]
	v_pk_fma_f32 v[230:231], v[198:199], v[90:91], v[230:231] neg_lo:[1,0,0] neg_hi:[1,0,0]
	ds_read_b128 v[196:199], v8 offset:6656
	s_waitcnt lgkmcnt(6)
	v_pk_fma_f32 v[230:231], v[200:201], v[92:93], v[230:231] neg_lo:[1,0,0] neg_hi:[1,0,0]
	v_pk_fma_f32 v[230:231], v[202:203], v[94:95], v[230:231] neg_lo:[1,0,0] neg_hi:[1,0,0]
	ds_read_b128 v[200:203], v8 offset:6672
	s_waitcnt lgkmcnt(6)
	v_pk_fma_f32 v[230:231], v[204:205], v[96:97], v[230:231] neg_lo:[1,0,0] neg_hi:[1,0,0]
	v_pk_fma_f32 v[230:231], v[206:207], v[98:99], v[230:231] neg_lo:[1,0,0] neg_hi:[1,0,0]
	ds_read_b128 v[204:207], v8 offset:6688
	s_waitcnt lgkmcnt(6)
	v_pk_fma_f32 v[230:231], v[208:209], v[100:101], v[230:231] neg_lo:[1,0,0] neg_hi:[1,0,0]
	v_pk_fma_f32 v[230:231], v[210:211], v[102:103], v[230:231] neg_lo:[1,0,0] neg_hi:[1,0,0]
	ds_read_b128 v[208:211], v8 offset:6704
	s_waitcnt lgkmcnt(6)
	v_pk_fma_f32 v[230:231], v[212:213], v[104:105], v[230:231] neg_lo:[1,0,0] neg_hi:[1,0,0]
	v_pk_fma_f32 v[230:231], v[214:215], v[106:107], v[230:231] neg_lo:[1,0,0] neg_hi:[1,0,0]
	ds_read_b128 v[212:215], v8 offset:6720
	s_waitcnt lgkmcnt(5)
	v_fma_f32 v230, -v192, v108, v230
	ds_read_b128 v[192:195], v8 offset:6736
	v_add_f32_e32 v109, v230, v231
	s_cbranch_vccz .Ls4_u25
	v_cvt_pk_bf16_f32 v233, -v109, v109
	global_store_short v6, v233, s[8:9] offset:2304
	s_branch .Ls4_n25

; #define LAS __attribute__((address_space(3)))
; __device__ __forceinline__ float bf2f(unsigned short x) { return __uint_as_float(((unsigned)x) << 16); }
; __device__ __forceinline__ void chunk_prep_phase(const Params& p, int bid, int nblk, LAS unsigned char* lds0) {
;     ...
;             { const float br = betg[26]; ab0 = (f32x2){bf2f(*(const LAS bf16_t*)(lg + P5_VS + 7072 + c * 2)) * br, bf2f(*(const LAS bf16_t*)(lg + P5_KS + 7072 + c * 2)) * br * __expf(decg[26])}; ab1 = (f32x2){0.f, 0.f}; } ab0 -= mq[1][0] * xy[0]; ab1 -= mq[1][1] * xy[1]; ab0 -= mq[1][2] * xy[2]; ab1 -= mq[1][3] * xy[3]; mq[1] = *(const LAS f32x4*)(Mg + 1688);
;             ab0 -= mq[2][0] * xy[4]; ab1 -= mq[2][1] * xy[5]; ab0 -= mq[2][2] * xy[6]; ab1 -= mq[2][3] * xy[7]; mq[2] = *(const LAS f32x4*)(Mg + 1728);
;             ab0 -= mq[3][0] * xy[8]; ab1 -= mq[3][1] * xy[9]; ab0 -= mq[3][2] * xy[10]; ab1 -= mq[3][3] * xy[11]; mq[3] = *(const LAS f32x4*)(Mg + 1732);
;             ab0 -= mq[4][0] * xy[12]; ab1 -= mq[4][1] * xy[13]; ab0 -= mq[4][2] * xy[14]; ab1 -= mq[4][3] * xy[15]; mq[4] = *(const LAS f32x4*)(Mg + 1736);
;             ab0 -= mq[5][0] * xy[16]; ab1 -= mq[5][1] * xy[17]; ab0 -= mq[5][2] * xy[18]; ab1 -= mq[5][3] * xy[19]; mq[5] = *(const LAS f32x4*)(Mg + 1740);
;             ab0 -= mq[0][0] * xy[20]; ab1 -= mq[0][1] * xy[21]; ab0 -= mq[0][2] * xy[22]; ab1 -= mq[0][3] * xy[23]; mq[0] = *(const LAS f32x4*)(Mg + 1744);
;             ab0 -= mq[1][0] * xy[24]; ab1 -= mq[1][1] * xy[25]; xy[26] = ab0 + ab1; up[3328] = xy[26][0]; wp[3328] = f2bf(-xy[26][1]); mq[1] = *(const LAS f32x4*)(Mg + 1748);
.Ls4_n25:
	v_lshlrev_b32_e32 v228, 16, v228
	v_mul_f32_e32 v232, v228, v218
	v_mul_f32_e32 v230, v232, v2
	v_mov_b32_e32 v231, 0
	ds_read_u16 v229, v7 offset:7344
	s_waitcnt lgkmcnt(6)
	v_pk_fma_f32 v[230:231], v[196:197], v[84:85], v[230:231] neg_lo:[1,0,0] neg_hi:[1,0,0]
	v_pk_fma_f32 v[230:231], v[198:199], v[86:87], v[230:231] neg_lo:[1,0,0] neg_hi:[1,0,0]
	ds_read_b128 v[196:199], v8 offset:6752
	s_waitcnt lgkmcnt(6)
	v_pk_fma_f32 v[230:231], v[200:201], v[88:89], v[230:231] neg_lo:[1,0,0] neg_hi:[1,0,0]
	v_pk_fma_f32 v[230:231], v[202:203], v[90:91], v[230:231] neg_lo:[1,0,0] neg_hi:[1,0,0]
	ds_read_b128 v[200:203], v8 offset:6912
	s_waitcnt lgkmcnt(6)
	v_pk_fma_f32 v[230:231], v[204:205], v[92:93], v[230:231] neg_lo:[1,0,0] neg_hi:[1,0,0]
	v_pk_fma_f32 v[230:231], v[206:207], v[94:95], v[230:231] neg_lo:[1,0,0] neg_hi:[1,0,0]
	ds_read_b128 v[204:207], v8 offset:6928
	s_waitcnt lgkmcnt(6)
	v_pk_fma_f32 v[230:231], v[208:209], v[96:97], v[230:231] neg_lo:[1,0,0] neg_hi:[1,0,0]
	v_pk_fma_f32 v[230:231], v[210:211], v[98:99], v[230:231] neg_lo:[1,0,0] neg_hi:[1,0,0]
	ds_read_b128 v[208:211], v8 offset:6944
	s_waitcnt lgkmcnt(6)
	v_pk_fma_f32 v[230:231], v[212:213], v[100:101], v[230:231] neg_lo:[1,0,0] neg_hi:[1,0,0]
	v_pk_fma_f32 v[230:231], v[214:215], v[102:103], v[230:231] neg_lo:[1,0,0] neg_hi:[1,0,0]
	ds_read_b128 v[212:215], v8 offset:6960
	s_waitcnt lgkmcnt(6)
	v_pk_fma_f32 v[230:231], v[192:193], v[104:105], v[230:231] neg_lo:[1,0,0] neg_hi:[1,0,0]
	v_pk_fma_f32 v[230:231], v[194:195], v[106:107], v[230:231] neg_lo:[1,0,0] neg_hi:[1,0,0]
	ds_read_b128 v[192:195], v8 offset:6976
	s_waitcnt lgkmcnt(5)
	v_pk_fma_f32 v[230:231], v[196:197], v[108:109], v[230:231] neg_lo:[1,0,0] neg_hi:[1,0,0]
	ds_read_b128 v[196:199], v8 offset:6992
	v_add_f32_e32 v110, v230, v231
	s_cbranch_vccz .Ls4_u26
	v_cvt_pk_bf16_f32 v233, -v110, v110
	global_store_short v6, v233, s[8:9] offset:2560
	s_branch .Ls4_n26

; #define LAS __attribute__((address_space(3)))
; __device__ __forceinline__ float bf2f(unsigned short x) { return __uint_as_float(((unsigned)x) << 16); }
; __device__ __forceinline__ void chunk_prep_phase(const Params& p, int bid, int nblk, LAS unsigned char* lds0) {
;     ...
;             { const float br = betg[27]; ab0 = (f32x2){bf2f(*(const LAS bf16_t*)(lg + P5_VS + 7344 + c * 2)) * br, bf2f(*(const LAS bf16_t*)(lg + P5_KS + 7344 + c * 2)) * br * __expf(decg[27])}; ab1 = (f32x2){0.f, 0.f}; } ab0 -= mq[2][0] * xy[0]; ab1 -= mq[2][1] * xy[1]; ab0 -= mq[2][2] * xy[2]; ab1 -= mq[2][3] * xy[3]; mq[2] = *(const LAS f32x4*)(Mg + 1752);
;             ab0 -= mq[3][0] * xy[4]; ab1 -= mq[3][1] * xy[5]; ab0 -= mq[3][2] * xy[6]; ab1 -= mq[3][3] * xy[7]; mq[3] = *(const LAS f32x4*)(Mg + 1792);
;             ab0 -= mq[4][0] * xy[8]; ab1 -= mq[4][1] * xy[9]; ab0 -= mq[4][2] * xy[10]; ab1 -= mq[4][3] * xy[11]; mq[4] = *(const LAS f32x4*)(Mg + 1796);
;             ab0 -= mq[5][0] * xy[12]; ab1 -= mq[5][1] * xy[13]; ab0 -= mq[5][2] * xy[14]; ab1 -= mq[5][3] * xy[15]; mq[5] = *(const LAS f32x4*)(Mg + 1800);
;             ab0 -= mq[0][0] * xy[16]; ab1 -= mq[0][1] * xy[17]; ab0 -= mq[0][2] * xy[18]; ab1 -= mq[0][3] * xy[19]; mq[0] = *(const LAS f32x4*)(Mg + 1804);
;             ab0 -= mq[1][0] * xy[20]; ab1 -= mq[1][1] * xy[21]; ab0 -= mq[1][2] * xy[22]; ab1 -= mq[1][3] * xy[23]; mq[1] = *(const LAS f32x4*)(Mg + 1808);
;             ab0 -= mq[2][0] * xy[24]; ab1 -= mq[2][1] * xy[25]; ab0 -= mq[2][2] * xy[26]; xy[27] = ab0 + ab1; up[3456] = xy[27][0]; wp[3456] = f2bf(-xy[27][1]); mq[2] = *(const LAS f32x4*)(Mg + 1812);
.Ls4_n26:
	v_lshlrev_b32_e32 v229, 16, v229
	v_mul_f32_e32 v232, v229, v219
	v_mul_f32_e32 v230, v232, v3
	v_mov_b32_e32 v231, 0
	ds_read_u16 v228, v7 offset:7616
	ds_read_b128 v[216:219], v8 offset:16768
	ds_read_b128 v[0:3], v8 offset:16512
	s_waitcnt lgkmcnt(8)
	v_pk_fma_f32 v[230:231], v[200:201], v[84:85], v[230:231] neg_lo:[1,0,0] neg_hi:[1,0,0]
	v_pk_fma_f32 v[230:231], v[202:203], v[86:87], v[230:231] neg_lo:[1,0,0] neg_hi:[1,0,0]
	ds_read_b128 v[200:203], v8 offset:7008
	s_waitcnt lgkmcnt(8)
	v_pk_fma_f32 v[230:231], v[204:205], v[88:89], v[230:231] neg_lo:[1,0,0] neg_hi:[1,0,0]
	v_pk_fma_f32 v[230:231], v[206:207], v[90:91], v[230:231] neg_lo:[1,0,0] neg_hi:[1,0,0]
	ds_read_b128 v[204:207], v8 offset:7168
	s_waitcnt lgkmcnt(8)
	v_pk_fma_f32 v[230:231], v[208:209], v[92:93], v[230:231] neg_lo:[1,0,0] neg_hi:[1,0,0]
	v_pk_fma_f32 v[230:231], v[210:211], v[94:95], v[230:231] neg_lo:[1,0,0] neg_hi:[1,0,0]
	ds_read_b128 v[208:211], v8 offset:7184
	s_waitcnt lgkmcnt(8)
	v_pk_fma_f32 v[230:231], v[212:213], v[96:97], v[230:231] neg_lo:[1,0,0] neg_hi:[1,0,0]
	v_pk_fma_f32 v[230:231], v[214:215], v[98:99], v[230:231] neg_lo:[1,0,0] neg_hi:[1,0,0]
	ds_read_b128 v[212:215], v8 offset:7200
	s_waitcnt lgkmcnt(8)
	v_pk_fma_f32 v[230:231], v[192:193], v[100:101], v[230:231] neg_lo:[1,0,0] neg_hi:[1,0,0]
	v_pk_fma_f32 v[230:231], v[194:195], v[102:103], v[230:231] neg_lo:[1,0,0] neg_hi:[1,0,0]
	ds_read_b128 v[192:195], v8 offset:7216
	s_waitcnt lgkmcnt(8)
	v_pk_fma_f32 v[230:231], v[196:197], v[104:105], v[230:231] neg_lo:[1,0,0] neg_hi:[1,0,0]
	v_pk_fma_f32 v[230:231], v[198:199], v[106:107], v[230:231] neg_lo:[1,0,0] neg_hi:[1,0,0]
	ds_read_b128 v[196:199], v8 offset:7232
	s_waitcnt lgkmcnt(5)
	v_pk_fma_f32 v[230:231], v[200:201], v[108:109], v[230:231] neg_lo:[1,0,0] neg_hi:[1,0,0]
	v_fma_f32 v230, -v202, v110, v230
	ds_read_b128 v[200:203], v8 offset:7248
	v_add_f32_e32 v111, v230, v231
	s_cbranch_vccz .Ls4_u27
	v_cvt_pk_bf16_f32 v233, -v111, v111
	global_store_short v6, v233, s[8:9] offset:2816
	s_branch .Ls4_n27

; #define LAS __attribute__((address_space(3)))
; __device__ __forceinline__ float bf2f(unsigned short x) { return __uint_as_float(((unsigned)x) << 16); }
; __device__ __forceinline__ void chunk_prep_phase(const Params& p, int bid, int nblk, LAS unsigned char* lds0) {
;     ...
;             { const float br = betg[28]; ab0 = (f32x2){bf2f(*(const LAS bf16_t*)(lg + P5_VS + 7616 + c * 2)) * br, bf2f(*(const LAS bf16_t*)(lg + P5_KS + 7616 + c * 2)) * br * __expf(decg[28])}; ab1 = (f32x2){0.f, 0.f}; } ab0 -= mq[3][0] * xy[0]; ab1 -= mq[3][1] * xy[1]; ab0 -= mq[3][2] * xy[2]; ab1 -= mq[3][3] * xy[3]; mq[3] = *(const LAS f32x4*)(Mg + 1816);
;             ab0 -= mq[4][0] * xy[4]; ab1 -= mq[4][1] * xy[5]; ab0 -= mq[4][2] * xy[6]; ab1 -= mq[4][3] * xy[7]; mq[4] = *(const LAS f32x4*)(Mg + 1856);
;             ab0 -= mq[5][0] * xy[8]; ab1 -= mq[5][1] * xy[9]; ab0 -= mq[5][2] * xy[10]; ab1 -= mq[5][3] * xy[11]; mq[5] = *(const LAS f32x4*)(Mg + 1860);
;             ab0 -= mq[0][0] * xy[12]; ab1 -= mq[0][1] * xy[13]; ab0 -= mq[0][2] * xy[14]; ab1 -= mq[0][3] * xy[15]; mq[0] = *(const LAS f32x4*)(Mg + 1864);
;             ab0 -= mq[1][0] * xy[16]; ab1 -= mq[1][1] * xy[17]; ab0 -= mq[1][2] * xy[18]; ab1 -= mq[1][3] * xy[19]; mq[1] = *(const LAS f32x4*)(Mg + 1868);
;             ab0 -= mq[2][0] * xy[20]; ab1 -= mq[2][1] * xy[21]; ab0 -= mq[2][2] * xy[22]; ab1 -= mq[2][3] * xy[23]; mq[2] = *(const LAS f32x4*)(Mg + 1872);
;             ab0 -= mq[3][0] * xy[24]; ab1 -= mq[3][1] * xy[25]; ab0 -= mq[3][2] * xy[26]; ab1 -= mq[3][3] * xy[27]; xy[28] = ab0 + ab1; up[3584] = xy[28][0]; wp[3584] = f2bf(-xy[28][1]); mq[3] = *(const LAS f32x4*)(Mg + 1876);
.Ls4_n27:
	v_mul_f32_e32 v224, s16, v224
	v_mul_f32_e32 v225, s16, v225
	v_mul_f32_e32 v226, s16, v226
	v_mul_f32_e32 v227, s16, v227
	v_exp_f32_e32 v224, v224
	v_exp_f32_e32 v225, v225
	v_exp_f32_e32 v226, v226
	v_exp_f32_e32 v227, v227
	s_nop 0
	v_lshlrev_b32_e32 v228, 16, v228
	v_mul_f32_e32 v232, v228, v220
	v_mul_f32_e32 v230, v232, v224
	v_mov_b32_e32 v231, 0
	ds_read_u16 v229, v7 offset:7888
	s_waitcnt lgkmcnt(6)
	v_pk_fma_f32 v[230:231], v[204:205], v[84:85], v[230:231] neg_lo:[1,0,0] neg_hi:[1,0,0]
	v_pk_fma_f32 v[230:231], v[206:207], v[86:87], v[230:231] neg_lo:[1,0,0] neg_hi:[1,0,0]
	ds_read_b128 v[204:207], v8 offset:7264
	s_waitcnt lgkmcnt(6)
	v_pk_fma_f32 v[230:231], v[208:209], v[88:89], v[230:231] neg_lo:[1,0,0] neg_hi:[1,0,0]
	v_pk_fma_f32 v[230:231], v[210:211], v[90:91], v[230:231] neg_lo:[1,0,0] neg_hi:[1,0,0]
	ds_read_b128 v[208:211], v8 offset:7424
	s_waitcnt lgkmcnt(6)
	v_pk_fma_f32 v[230:231], v[212:213], v[92:93], v[230:231] neg_lo:[1,0,0] neg_hi:[1,0,0]
	v_pk_fma_f32 v[230:231], v[214:215], v[94:95], v[230:231] neg_lo:[1,0,0] neg_hi:[1,0,0]
	ds_read_b128 v[212:215], v8 offset:7440
	s_waitcnt lgkmcnt(6)
	v_pk_fma_f32 v[230:231], v[192:193], v[96:97], v[230:231] neg_lo:[1,0,0] neg_hi:[1,0,0]
	v_pk_fma_f32 v[230:231], v[194:195], v[98:99], v[230:231] neg_lo:[1,0,0] neg_hi:[1,0,0]
	ds_read_b128 v[192:195], v8 offset:7456
	s_waitcnt lgkmcnt(6)
	v_pk_fma_f32 v[230:231], v[196:197], v[100:101], v[230:231] neg_lo:[1,0,0] neg_hi:[1,0,0]
	v_pk_fma_f32 v[230:231], v[198:199], v[102:103], v[230:231] neg_lo:[1,0,0] neg_hi:[1,0,0]
	ds_read_b128 v[196:199], v8 offset:7472
	s_waitcnt lgkmcnt(6)
	v_pk_fma_f32 v[230:231], v[200:201], v[104:105], v[230:231] neg_lo:[1,0,0] neg_hi:[1,0,0]
	v_pk_fma_f32 v[230:231], v[202:203], v[106:107], v[230:231] neg_lo:[1,0,0] neg_hi:[1,0,0]
	ds_read_b128 v[200:203], v8 offset:7488
	s_waitcnt lgkmcnt(5)
	v_pk_fma_f32 v[230:231], v[204:205], v[108:109], v[230:231] neg_lo:[1,0,0] neg_hi:[1,0,0]
	v_pk_fma_f32 v[230:231], v[206:207], v[110:111], v[230:231] neg_lo:[1,0,0] neg_hi:[1,0,0]
	ds_read_b128 v[204:207], v8 offset:7504
	v_add_f32_e32 v112, v230, v231
	s_cbranch_vccz .Ls4_u28
	v_cvt_pk_bf16_f32 v233, -v112, v112
	global_store_short v6, v233, s[8:9] offset:3072
	s_branch .Ls4_n28

; #define LAS __attribute__((address_space(3)))
; __device__ __forceinline__ float bf2f(unsigned short x) { return __uint_as_float(((unsigned)x) << 16); }
; __device__ __forceinline__ void chunk_prep_phase(const Params& p, int bid, int nblk, LAS unsigned char* lds0) {
;     ...
;             { const float br = betg[29]; ab0 = (f32x2){bf2f(*(const LAS bf16_t*)(lg + P5_VS + 7888 + c * 2)) * br, bf2f(*(const LAS bf16_t*)(lg + P5_KS + 7888 + c * 2)) * br * __expf(decg[29])}; ab1 = (f32x2){0.f, 0.f}; } ab0 -= mq[4][0] * xy[0]; ab1 -= mq[4][1] * xy[1]; ab0 -= mq[4][2] * xy[2]; ab1 -= mq[4][3] * xy[3]; mq[4] = *(const LAS f32x4*)(Mg + 1880);
;             ab0 -= mq[5][0] * xy[4]; ab1 -= mq[5][1] * xy[5]; ab0 -= mq[5][2] * xy[6]; ab1 -= mq[5][3] * xy[7]; mq[5] = *(const LAS f32x4*)(Mg + 1884);
;             ab0 -= mq[0][0] * xy[8]; ab1 -= mq[0][1] * xy[9]; ab0 -= mq[0][2] * xy[10]; ab1 -= mq[0][3] * xy[11]; mq[0] = *(const LAS f32x4*)(Mg + 1920);
;             ab0 -= mq[1][0] * xy[12]; ab1 -= mq[1][1] * xy[13]; ab0 -= mq[1][2] * xy[14]; ab1 -= mq[1][3] * xy[15]; mq[1] = *(const LAS f32x4*)(Mg + 1924);
;             ab0 -= mq[2][0] * xy[16]; ab1 -= mq[2][1] * xy[17]; ab0 -= mq[2][2] * xy[18]; ab1 -= mq[2][3] * xy[19]; mq[2] = *(const LAS f32x4*)(Mg + 1928);
;             ab0 -= mq[3][0] * xy[20]; ab1 -= mq[3][1] * xy[21]; ab0 -= mq[3][2] * xy[22]; ab1 -= mq[3][3] * xy[23]; mq[3] = *(const LAS f32x4*)(Mg + 1932);
;             ab0 -= mq[4][0] * xy[24]; ab1 -= mq[4][1] * xy[25]; ab0 -= mq[4][2] * xy[26]; ab1 -= mq[4][3] * xy[27]; mq[4] = *(const LAS f32x4*)(Mg + 1936);
;             ab0 -= mq[5][0] * xy[28]; xy[29] = ab0 + ab1; up[3712] = xy[29][0]; wp[3712] = f2bf(-xy[29][1]); mq[5] = *(const LAS f32x4*)(Mg + 1940);
.Ls4_n28:
	v_lshlrev_b32_e32 v229, 16, v229
	v_mul_f32_e32 v232, v229, v221
	v_mul_f32_e32 v230, v232, v225
	v_mov_b32_e32 v231, 0
	ds_read_u16 v228, v7 offset:8160
	s_waitcnt lgkmcnt(6)
	v_pk_fma_f32 v[230:231], v[208:209], v[84:85], v[230:231] neg_lo:[1,0,0] neg_hi:[1,0,0]
	v_pk_fma_f32 v[230:231], v[210:211], v[86:87], v[230:231] neg_lo:[1,0,0] neg_hi:[1,0,0]
	ds_read_b128 v[208:211], v8 offset:7520
	s_waitcnt lgkmcnt(6)
	v_pk_fma_f32 v[230:231], v[212:213], v[88:89], v[230:231] neg_lo:[1,0,0] neg_hi:[1,0,0]
	v_pk_fma_f32 v[230:231], v[214:215], v[90:91], v[230:231] neg_lo:[1,0,0] neg_hi:[1,0,0]
	ds_read_b128 v[212:215], v8 offset:7536
	s_waitcnt lgkmcnt(6)
	v_pk_fma_f32 v[230:231], v[192:193], v[92:93], v[230:231] neg_lo:[1,0,0] neg_hi:[1,0,0]
	v_pk_fma_f32 v[230:231], v[194:195], v[94:95], v[230:231] neg_lo:[1,0,0] neg_hi:[1,0,0]
	ds_read_b128 v[192:195], v8 offset:7680
	s_waitcnt lgkmcnt(6)
	v_pk_fma_f32 v[230:231], v[196:197], v[96:97], v[230:231] neg_lo:[1,0,0] neg_hi:[1,0,0]
	v_pk_fma_f32 v[230:231], v[198:199], v[98:99], v[230:231] neg_lo:[1,0,0] neg_hi:[1,0,0]
	ds_read_b128 v[196:199], v8 offset:7696
	s_waitcnt lgkmcnt(6)
	v_pk_fma_f32 v[230:231], v[200:201], v[100:101], v[230:231] neg_lo:[1,0,0] neg_hi:[1,0,0]
	v_pk_fma_f32 v[230:231], v[202:203], v[102:103], v[230:231] neg_lo:[1,0,0] neg_hi:[1,0,0]
	ds_read_b128 v[200:203], v8 offset:7712
	s_waitcnt lgkmcnt(6)
	v_pk_fma_f32 v[230:231], v[204:205], v[104:105], v[230:231] neg_lo:[1,0,0] neg_hi:[1,0,0]
	v_pk_fma_f32 v[230:231], v[206:207], v[106:107], v[230:231] neg_lo:[1,0,0] neg_hi:[1,0,0]
	ds_read_b128 v[204:207], v8 offset:7728
	s_waitcnt lgkmcnt(5)
	v_pk_fma_f32 v[230:231], v[208:209], v[108:109], v[230:231] neg_lo:[1,0,0] neg_hi:[1,0,0]
	v_pk_fma_f32 v[230:231], v[210:211], v[110:111], v[230:231] neg_lo:[1,0,0] neg_hi:[1,0,0]
	ds_read_b128 v[208:211], v8 offset:7744
	s_waitcnt lgkmcnt(5)
	v_fma_f32 v230, -v212, v112, v230
	ds_read_b128 v[212:215], v8 offset:7760
	v_add_f32_e32 v113, v230, v231
	s_cbranch_vccz .Ls4_u29
	v_cvt_pk_bf16_f32 v233, -v113, v113
	global_store_short v6, v233, s[8:9] offset:3328
	s_branch .Ls4_n29

; #define LAS __attribute__((address_space(3)))
; __device__ __forceinline__ float bf2f(unsigned short x) { return __uint_as_float(((unsigned)x) << 16); }
; __device__ __forceinline__ void chunk_prep_phase(const Params& p, int bid, int nblk, LAS unsigned char* lds0) {
;     ...
;             { const float br = betg[30]; ab0 = (f32x2){bf2f(*(const LAS bf16_t*)(lg + P5_VS + 8160 + c * 2)) * br, bf2f(*(const LAS bf16_t*)(lg + P5_KS + 8160 + c * 2)) * br * __expf(decg[30])}; ab1 = (f32x2){0.f, 0.f}; } ab0 -= mq[0][0] * xy[0]; ab1 -= mq[0][1] * xy[1]; ab0 -= mq[0][2] * xy[2]; ab1 -= mq[0][3] * xy[3]; mq[0] = *(const LAS f32x4*)(Mg + 1944);
;             ab0 -= mq[1][0] * xy[4]; ab1 -= mq[1][1] * xy[5]; ab0 -= mq[1][2] * xy[6]; ab1 -= mq[1][3] * xy[7]; mq[1] = *(const LAS f32x4*)(Mg + 1948);
;             ab0 -= mq[2][0] * xy[8]; ab1 -= mq[2][1] * xy[9]; ab0 -= mq[2][2] * xy[10]; ab1 -= mq[2][3] * xy[11]; mq[2] = *(const LAS f32x4*)(Mg + 1984);
;             ab0 -= mq[3][0] * xy[12]; ab1 -= mq[3][1] * xy[13]; ab0 -= mq[3][2] * xy[14]; ab1 -= mq[3][3] * xy[15]; mq[3] = *(const LAS f32x4*)(Mg + 1988);
;             ab0 -= mq[4][0] * xy[16]; ab1 -= mq[4][1] * xy[17]; ab0 -= mq[4][2] * xy[18]; ab1 -= mq[4][3] * xy[19]; mq[4] = *(const LAS f32x4*)(Mg + 1992);
;             ab0 -= mq[5][0] * xy[20]; ab1 -= mq[5][1] * xy[21]; ab0 -= mq[5][2] * xy[22]; ab1 -= mq[5][3] * xy[23]; mq[5] = *(const LAS f32x4*)(Mg + 1996);
;             ab0 -= mq[0][0] * xy[24]; ab1 -= mq[0][1] * xy[25]; ab0 -= mq[0][2] * xy[26]; ab1 -= mq[0][3] * xy[27]; mq[0] = *(const LAS f32x4*)(Mg + 2000);
;             ab0 -= mq[1][0] * xy[28]; ab1 -= mq[1][1] * xy[29]; xy[30] = ab0 + ab1; up[3840] = xy[30][0]; wp[3840] = f2bf(-xy[30][1]); mq[1] = *(const LAS f32x4*)(Mg + 2004);
.Ls4_n29:
	v_lshlrev_b32_e32 v228, 16, v228
	v_mul_f32_e32 v232, v228, v222
	v_mul_f32_e32 v230, v232, v226
	v_mov_b32_e32 v231, 0
	ds_read_u16 v229, v7 offset:8432
	s_waitcnt lgkmcnt(6)
	v_pk_fma_f32 v[230:231], v[192:193], v[84:85], v[230:231] neg_lo:[1,0,0] neg_hi:[1,0,0]
	v_pk_fma_f32 v[230:231], v[194:195], v[86:87], v[230:231] neg_lo:[1,0,0] neg_hi:[1,0,0]
	ds_read_b128 v[192:195], v8 offset:7776
	s_waitcnt lgkmcnt(6)
	v_pk_fma_f32 v[230:231], v[196:197], v[88:89], v[230:231] neg_lo:[1,0,0] neg_hi:[1,0,0]
	v_pk_fma_f32 v[230:231], v[198:199], v[90:91], v[230:231] neg_lo:[1,0,0] neg_hi:[1,0,0]
	ds_read_b128 v[196:199], v8 offset:7792
	s_waitcnt lgkmcnt(6)
	v_pk_fma_f32 v[230:231], v[200:201], v[92:93], v[230:231] neg_lo:[1,0,0] neg_hi:[1,0,0]
	v_pk_fma_f32 v[230:231], v[202:203], v[94:95], v[230:231] neg_lo:[1,0,0] neg_hi:[1,0,0]
	ds_read_b128 v[200:203], v8 offset:7936
	s_waitcnt lgkmcnt(6)
	v_pk_fma_f32 v[230:231], v[204:205], v[96:97], v[230:231] neg_lo:[1,0,0] neg_hi:[1,0,0]
	v_pk_fma_f32 v[230:231], v[206:207], v[98:99], v[230:231] neg_lo:[1,0,0] neg_hi:[1,0,0]
	ds_read_b128 v[204:207], v8 offset:7952
	s_waitcnt lgkmcnt(6)
	v_pk_fma_f32 v[230:231], v[208:209], v[100:101], v[230:231] neg_lo:[1,0,0] neg_hi:[1,0,0]
	v_pk_fma_f32 v[230:231], v[210:211], v[102:103], v[230:231] neg_lo:[1,0,0] neg_hi:[1,0,0]
	ds_read_b128 v[208:211], v8 offset:7968
	s_waitcnt lgkmcnt(6)
	v_pk_fma_f32 v[230:231], v[212:213], v[104:105], v[230:231] neg_lo:[1,0,0] neg_hi:[1,0,0]
	v_pk_fma_f32 v[230:231], v[214:215], v[106:107], v[230:231] neg_lo:[1,0,0] neg_hi:[1,0,0]
	ds_read_b128 v[212:215], v8 offset:7984
	s_waitcnt lgkmcnt(5)
	v_pk_fma_f32 v[230:231], v[192:193], v[108:109], v[230:231] neg_lo:[1,0,0] neg_hi:[1,0,0]
	v_pk_fma_f32 v[230:231], v[194:195], v[110:111], v[230:231] neg_lo:[1,0,0] neg_hi:[1,0,0]
	ds_read_b128 v[192:195], v8 offset:8000
	s_waitcnt lgkmcnt(5)
	v_pk_fma_f32 v[230:231], v[196:197], v[112:113], v[230:231] neg_lo:[1,0,0] neg_hi:[1,0,0]
	ds_read_b128 v[196:199], v8 offset:8016
	v_add_f32_e32 v114, v230, v231
	s_cbranch_vccz .Ls4_u30
	v_cvt_pk_bf16_f32 v233, -v114, v114
	global_store_short v6, v233, s[8:9] offset:3584
	s_branch .Ls4_n30

; #define LAS __attribute__((address_space(3)))
; __device__ __forceinline__ float bf2f(unsigned short x) { return __uint_as_float(((unsigned)x) << 16); }
; __device__ __forceinline__ void chunk_prep_phase(const Params& p, int bid, int nblk, LAS unsigned char* lds0) {
;     ...
;             { const float br = betg[31]; ab0 = (f32x2){bf2f(*(const LAS bf16_t*)(lg + P5_VS + 8432 + c * 2)) * br, bf2f(*(const LAS bf16_t*)(lg + P5_KS + 8432 + c * 2)) * br * __expf(decg[31])}; ab1 = (f32x2){0.f, 0.f}; } ab0 -= mq[2][0] * xy[0]; ab1 -= mq[2][1] * xy[1]; ab0 -= mq[2][2] * xy[2]; ab1 -= mq[2][3] * xy[3]; mq[2] = *(const LAS f32x4*)(Mg + 2008);
;             ab0 -= mq[3][0] * xy[4]; ab1 -= mq[3][1] * xy[5]; ab0 -= mq[3][2] * xy[6]; ab1 -= mq[3][3] * xy[7]; mq[3] = *(const LAS f32x4*)(Mg + 2012);
;             ab0 -= mq[4][0] * xy[8]; ab1 -= mq[4][1] * xy[9]; ab0 -= mq[4][2] * xy[10]; ab1 -= mq[4][3] * xy[11]; mq[4] = *(const LAS f32x4*)(Mg + 2048);
;             ab0 -= mq[5][0] * xy[12]; ab1 -= mq[5][1] * xy[13]; ab0 -= mq[5][2] * xy[14]; ab1 -= mq[5][3] * xy[15]; mq[5] = *(const LAS f32x4*)(Mg + 2052);
;             ab0 -= mq[0][0] * xy[16]; ab1 -= mq[0][1] * xy[17]; ab0 -= mq[0][2] * xy[18]; ab1 -= mq[0][3] * xy[19]; mq[0] = *(const LAS f32x4*)(Mg + 2056);
;             ab0 -= mq[1][0] * xy[20]; ab1 -= mq[1][1] * xy[21]; ab0 -= mq[1][2] * xy[22]; ab1 -= mq[1][3] * xy[23]; mq[1] = *(const LAS f32x4*)(Mg + 2060);
;             ab0 -= mq[2][0] * xy[24]; ab1 -= mq[2][1] * xy[25]; ab0 -= mq[2][2] * xy[26]; ab1 -= mq[2][3] * xy[27]; mq[2] = *(const LAS f32x4*)(Mg + 2064);
;             ab0 -= mq[3][0] * xy[28]; ab1 -= mq[3][1] * xy[29]; ab0 -= mq[3][2] * xy[30]; xy[31] = ab0 + ab1; up[3968] = xy[31][0]; wp[3968] = f2bf(-xy[31][1]); mq[3] = *(const LAS f32x4*)(Mg + 2068);
.Ls4_n30:
	v_lshlrev_b32_e32 v229, 16, v229
	v_mul_f32_e32 v232, v229, v223
	v_mul_f32_e32 v230, v232, v227
	v_mov_b32_e32 v231, 0
	ds_read_u16 v228, v7 offset:8704
	ds_read_b128 v[220:223], v8 offset:16784
	ds_read_b128 v[224:227], v8 offset:16528
	s_waitcnt lgkmcnt(8)
	v_pk_fma_f32 v[230:231], v[200:201], v[84:85], v[230:231] neg_lo:[1,0,0] neg_hi:[1,0,0]
	v_pk_fma_f32 v[230:231], v[202:203], v[86:87], v[230:231] neg_lo:[1,0,0] neg_hi:[1,0,0]
	ds_read_b128 v[200:203], v8 offset:8032
	s_waitcnt lgkmcnt(8)
	v_pk_fma_f32 v[230:231], v[204:205], v[88:89], v[230:231] neg_lo:[1,0,0] neg_hi:[1,0,0]
	v_pk_fma_f32 v[230:231], v[206:207], v[90:91], v[230:231] neg_lo:[1,0,0] neg_hi:[1,0,0]
	ds_read_b128 v[204:207], v8 offset:8048
	s_waitcnt lgkmcnt(8)
	v_pk_fma_f32 v[230:231], v[208:209], v[92:93], v[230:231] neg_lo:[1,0,0] neg_hi:[1,0,0]
	v_pk_fma_f32 v[230:231], v[210:211], v[94:95], v[230:231] neg_lo:[1,0,0] neg_hi:[1,0,0]
	ds_read_b128 v[208:211], v8 offset:8192
	s_waitcnt lgkmcnt(8)
	v_pk_fma_f32 v[230:231], v[212:213], v[96:97], v[230:231] neg_lo:[1,0,0] neg_hi:[1,0,0]
	v_pk_fma_f32 v[230:231], v[214:215], v[98:99], v[230:231] neg_lo:[1,0,0] neg_hi:[1,0,0]
	ds_read_b128 v[212:215], v8 offset:8208
	s_waitcnt lgkmcnt(8)
	v_pk_fma_f32 v[230:231], v[192:193], v[100:101], v[230:231] neg_lo:[1,0,0] neg_hi:[1,0,0]
	v_pk_fma_f32 v[230:231], v[194:195], v[102:103], v[230:231] neg_lo:[1,0,0] neg_hi:[1,0,0]
	ds_read_b128 v[192:195], v8 offset:8224
	s_waitcnt lgkmcnt(8)
	v_pk_fma_f32 v[230:231], v[196:197], v[104:105], v[230:231] neg_lo:[1,0,0] neg_hi:[1,0,0]
	v_pk_fma_f32 v[230:231], v[198:199], v[106:107], v[230:231] neg_lo:[1,0,0] neg_hi:[1,0,0]
	ds_read_b128 v[196:199], v8 offset:8240
	s_waitcnt lgkmcnt(5)
	v_pk_fma_f32 v[230:231], v[200:201], v[108:109], v[230:231] neg_lo:[1,0,0] neg_hi:[1,0,0]
	v_pk_fma_f32 v[230:231], v[202:203], v[110:111], v[230:231] neg_lo:[1,0,0] neg_hi:[1,0,0]
	ds_read_b128 v[200:203], v8 offset:8256
	s_waitcnt lgkmcnt(5)
	v_pk_fma_f32 v[230:231], v[204:205], v[112:113], v[230:231] neg_lo:[1,0,0] neg_hi:[1,0,0]
	v_fma_f32 v230, -v206, v114, v230
	ds_read_b128 v[204:207], v8 offset:8272
	v_add_f32_e32 v115, v230, v231
	s_cbranch_vccz .Ls4_u31
	v_cvt_pk_bf16_f32 v233, -v115, v115
	global_store_short v6, v233, s[8:9] offset:3840
	s_branch .Ls4_n31

; #define LAS __attribute__((address_space(3)))
; __device__ __forceinline__ float bf2f(unsigned short x) { return __uint_as_float(((unsigned)x) << 16); }
; __device__ __forceinline__ void chunk_prep_phase(const Params& p, int bid, int nblk, LAS unsigned char* lds0) {
;     ...
;             { const float br = betg[32]; ab0 = (f32x2){bf2f(*(const LAS bf16_t*)(lg + P5_VS + 8704 + c * 2)) * br, bf2f(*(const LAS bf16_t*)(lg + P5_KS + 8704 + c * 2)) * br * __expf(decg[32])}; ab1 = (f32x2){0.f, 0.f}; } ab0 -= mq[4][0] * xy[0]; ab1 -= mq[4][1] * xy[1]; ab0 -= mq[4][2] * xy[2]; ab1 -= mq[4][3] * xy[3]; mq[4] = *(const LAS f32x4*)(Mg + 2072);
;             ab0 -= mq[5][0] * xy[4]; ab1 -= mq[5][1] * xy[5]; ab0 -= mq[5][2] * xy[6]; ab1 -= mq[5][3] * xy[7]; mq[5] = *(const LAS f32x4*)(Mg + 2076);
;             ab0 -= mq[0][0] * xy[8]; ab1 -= mq[0][1] * xy[9]; ab0 -= mq[0][2] * xy[10]; ab1 -= mq[0][3] * xy[11]; mq[0] = *(const LAS f32x4*)(Mg + 2112);
;             ab0 -= mq[1][0] * xy[12]; ab1 -= mq[1][1] * xy[13]; ab0 -= mq[1][2] * xy[14]; ab1 -= mq[1][3] * xy[15]; mq[1] = *(const LAS f32x4*)(Mg + 2116);
;             ab0 -= mq[2][0] * xy[16]; ab1 -= mq[2][1] * xy[17]; ab0 -= mq[2][2] * xy[18]; ab1 -= mq[2][3] * xy[19]; mq[2] = *(const LAS f32x4*)(Mg + 2120);
;             ab0 -= mq[3][0] * xy[20]; ab1 -= mq[3][1] * xy[21]; ab0 -= mq[3][2] * xy[22]; ab1 -= mq[3][3] * xy[23]; mq[3] = *(const LAS f32x4*)(Mg + 2124);
;             ab0 -= mq[4][0] * xy[24]; ab1 -= mq[4][1] * xy[25]; ab0 -= mq[4][2] * xy[26]; ab1 -= mq[4][3] * xy[27]; mq[4] = *(const LAS f32x4*)(Mg + 2128);
;             ab0 -= mq[5][0] * xy[28]; ab1 -= mq[5][1] * xy[29]; ab0 -= mq[5][2] * xy[30]; ab1 -= mq[5][3] * xy[31]; xy[32] = ab0 + ab1; up[4096] = xy[32][0]; wp[4096] = f2bf(-xy[32][1]); mq[5] = *(const LAS f32x4*)(Mg + 2132);
.Ls4_n31:
	v_mul_f32_e32 v0, s16, v0
	v_mul_f32_e32 v1, s16, v1
	v_mul_f32_e32 v2, s16, v2
	v_mul_f32_e32 v3, s16, v3
	v_exp_f32_e32 v0, v0
	v_exp_f32_e32 v1, v1
	v_exp_f32_e32 v2, v2
	v_exp_f32_e32 v3, v3
	s_nop 0
	v_lshlrev_b32_e32 v228, 16, v228
	v_mul_f32_e32 v232, v228, v216
	v_mul_f32_e32 v230, v232, v0
	v_mov_b32_e32 v231, 0
	ds_read_u16 v229, v7 offset:8976
	s_waitcnt lgkmcnt(6)
	v_pk_fma_f32 v[230:231], v[208:209], v[84:85], v[230:231] neg_lo:[1,0,0] neg_hi:[1,0,0]
	v_pk_fma_f32 v[230:231], v[210:211], v[86:87], v[230:231] neg_lo:[1,0,0] neg_hi:[1,0,0]
	ds_read_b128 v[208:211], v8 offset:8288
	s_waitcnt lgkmcnt(6)
	v_pk_fma_f32 v[230:231], v[212:213], v[88:89], v[230:231] neg_lo:[1,0,0] neg_hi:[1,0,0]
	v_pk_fma_f32 v[230:231], v[214:215], v[90:91], v[230:231] neg_lo:[1,0,0] neg_hi:[1,0,0]
	ds_read_b128 v[212:215], v8 offset:8304
	s_waitcnt lgkmcnt(6)
	v_pk_fma_f32 v[230:231], v[192:193], v[92:93], v[230:231] neg_lo:[1,0,0] neg_hi:[1,0,0]
	v_pk_fma_f32 v[230:231], v[194:195], v[94:95], v[230:231] neg_lo:[1,0,0] neg_hi:[1,0,0]
	ds_read_b128 v[192:195], v8 offset:8448
	s_waitcnt lgkmcnt(6)
	v_pk_fma_f32 v[230:231], v[196:197], v[96:97], v[230:231] neg_lo:[1,0,0] neg_hi:[1,0,0]
	v_pk_fma_f32 v[230:231], v[198:199], v[98:99], v[230:231] neg_lo:[1,0,0] neg_hi:[1,0,0]
	ds_read_b128 v[196:199], v8 offset:8464
	s_waitcnt lgkmcnt(6)
	v_pk_fma_f32 v[230:231], v[200:201], v[100:101], v[230:231] neg_lo:[1,0,0] neg_hi:[1,0,0]
	v_pk_fma_f32 v[230:231], v[202:203], v[102:103], v[230:231] neg_lo:[1,0,0] neg_hi:[1,0,0]
	ds_read_b128 v[200:203], v8 offset:8480
	s_waitcnt lgkmcnt(6)
	v_pk_fma_f32 v[230:231], v[204:205], v[104:105], v[230:231] neg_lo:[1,0,0] neg_hi:[1,0,0]
	v_pk_fma_f32 v[230:231], v[206:207], v[106:107], v[230:231] neg_lo:[1,0,0] neg_hi:[1,0,0]
	ds_read_b128 v[204:207], v8 offset:8496
	s_waitcnt lgkmcnt(5)
	v_pk_fma_f32 v[230:231], v[208:209], v[108:109], v[230:231] neg_lo:[1,0,0] neg_hi:[1,0,0]
	v_pk_fma_f32 v[230:231], v[210:211], v[110:111], v[230:231] neg_lo:[1,0,0] neg_hi:[1,0,0]
	ds_read_b128 v[208:211], v8 offset:8512
	s_waitcnt lgkmcnt(5)
	v_pk_fma_f32 v[230:231], v[212:213], v[112:113], v[230:231] neg_lo:[1,0,0] neg_hi:[1,0,0]
	v_pk_fma_f32 v[230:231], v[214:215], v[114:115], v[230:231] neg_lo:[1,0,0] neg_hi:[1,0,0]
	ds_read_b128 v[212:215], v8 offset:8528
	v_add_f32_e32 v116, v230, v231
	s_cbranch_vccz .Ls4_u32
	s_add_u32 s8, s8, 0x1000
	s_addc_u32 s9, s9, 0
	v_cvt_pk_bf16_f32 v233, -v116, v116
	global_store_short v6, v233, s[8:9] offset:0
	s_branch .Ls4_n32

; #define LAS __attribute__((address_space(3)))
; __device__ __forceinline__ float bf2f(unsigned short x) { return __uint_as_float(((unsigned)x) << 16); }
; __device__ __forceinline__ void chunk_prep_phase(const Params& p, int bid, int nblk, LAS unsigned char* lds0) {
;     ...
;             { const float br = betg[33]; ab0 = (f32x2){bf2f(*(const LAS bf16_t*)(lg + P5_VS + 8976 + c * 2)) * br, bf2f(*(const LAS bf16_t*)(lg + P5_KS + 8976 + c * 2)) * br * __expf(decg[33])}; ab1 = (f32x2){0.f, 0.f}; } ab0 -= mq[0][0] * xy[0]; ab1 -= mq[0][1] * xy[1]; ab0 -= mq[0][2] * xy[2]; ab1 -= mq[0][3] * xy[3]; mq[0] = *(const LAS f32x4*)(Mg + 2136);
;             ab0 -= mq[1][0] * xy[4]; ab1 -= mq[1][1] * xy[5]; ab0 -= mq[1][2] * xy[6]; ab1 -= mq[1][3] * xy[7]; mq[1] = *(const LAS f32x4*)(Mg + 2140);
;             ab0 -= mq[2][0] * xy[8]; ab1 -= mq[2][1] * xy[9]; ab0 -= mq[2][2] * xy[10]; ab1 -= mq[2][3] * xy[11]; mq[2] = *(const LAS f32x4*)(Mg + 2144);
;             ab0 -= mq[3][0] * xy[12]; ab1 -= mq[3][1] * xy[13]; ab0 -= mq[3][2] * xy[14]; ab1 -= mq[3][3] * xy[15]; mq[3] = *(const LAS f32x4*)(Mg + 2176);
;             ab0 -= mq[4][0] * xy[16]; ab1 -= mq[4][1] * xy[17]; ab0 -= mq[4][2] * xy[18]; ab1 -= mq[4][3] * xy[19]; mq[4] = *(const LAS f32x4*)(Mg + 2180);
;             ab0 -= mq[5][0] * xy[20]; ab1 -= mq[5][1] * xy[21]; ab0 -= mq[5][2] * xy[22]; ab1 -= mq[5][3] * xy[23]; mq[5] = *(const LAS f32x4*)(Mg + 2184);
;             ab0 -= mq[0][0] * xy[24]; ab1 -= mq[0][1] * xy[25]; ab0 -= mq[0][2] * xy[26]; ab1 -= mq[0][3] * xy[27]; mq[0] = *(const LAS f32x4*)(Mg + 2188);
;             ab0 -= mq[1][0] * xy[28]; ab1 -= mq[1][1] * xy[29]; ab0 -= mq[1][2] * xy[30]; ab1 -= mq[1][3] * xy[31]; mq[1] = *(const LAS f32x4*)(Mg + 2192);
;             ab0 -= mq[2][0] * xy[32]; xy[33] = ab0 + ab1; up[4224] = xy[33][0]; wp[4224] = f2bf(-xy[33][1]); mq[2] = *(const LAS f32x4*)(Mg + 2196);
.Ls4_n32:
	v_lshlrev_b32_e32 v229, 16, v229
	v_mul_f32_e32 v232, v229, v217
	v_mul_f32_e32 v230, v232, v1
	v_mov_b32_e32 v231, 0
	ds_read_u16 v228, v7 offset:9248
	s_waitcnt lgkmcnt(6)
	v_pk_fma_f32 v[230:231], v[192:193], v[84:85], v[230:231] neg_lo:[1,0,0] neg_hi:[1,0,0]
	v_pk_fma_f32 v[230:231], v[194:195], v[86:87], v[230:231] neg_lo:[1,0,0] neg_hi:[1,0,0]
	ds_read_b128 v[192:195], v8 offset:8544
	s_waitcnt lgkmcnt(6)
	v_pk_fma_f32 v[230:231], v[196:197], v[88:89], v[230:231] neg_lo:[1,0,0] neg_hi:[1,0,0]
	v_pk_fma_f32 v[230:231], v[198:199], v[90:91], v[230:231] neg_lo:[1,0,0] neg_hi:[1,0,0]
	ds_read_b128 v[196:199], v8 offset:8560
	s_waitcnt lgkmcnt(6)
	v_pk_fma_f32 v[230:231], v[200:201], v[92:93], v[230:231] neg_lo:[1,0,0] neg_hi:[1,0,0]
	v_pk_fma_f32 v[230:231], v[202:203], v[94:95], v[230:231] neg_lo:[1,0,0] neg_hi:[1,0,0]
	ds_read_b128 v[200:203], v8 offset:8576
	s_waitcnt lgkmcnt(6)
	v_pk_fma_f32 v[230:231], v[204:205], v[96:97], v[230:231] neg_lo:[1,0,0] neg_hi:[1,0,0]
	v_pk_fma_f32 v[230:231], v[206:207], v[98:99], v[230:231] neg_lo:[1,0,0] neg_hi:[1,0,0]
	ds_read_b128 v[204:207], v8 offset:8704
	s_waitcnt lgkmcnt(6)
	v_pk_fma_f32 v[230:231], v[208:209], v[100:101], v[230:231] neg_lo:[1,0,0] neg_hi:[1,0,0]
	v_pk_fma_f32 v[230:231], v[210:211], v[102:103], v[230:231] neg_lo:[1,0,0] neg_hi:[1,0,0]
	ds_read_b128 v[208:211], v8 offset:8720
	s_waitcnt lgkmcnt(6)
	v_pk_fma_f32 v[230:231], v[212:213], v[104:105], v[230:231] neg_lo:[1,0,0] neg_hi:[1,0,0]
	v_pk_fma_f32 v[230:231], v[214:215], v[106:107], v[230:231] neg_lo:[1,0,0] neg_hi:[1,0,0]
	ds_read_b128 v[212:215], v8 offset:8736
	s_waitcnt lgkmcnt(5)
	v_pk_fma_f32 v[230:231], v[192:193], v[108:109], v[230:231] neg_lo:[1,0,0] neg_hi:[1,0,0]
	v_pk_fma_f32 v[230:231], v[194:195], v[110:111], v[230:231] neg_lo:[1,0,0] neg_hi:[1,0,0]
	ds_read_b128 v[192:195], v8 offset:8752
	s_waitcnt lgkmcnt(5)
	v_pk_fma_f32 v[230:231], v[196:197], v[112:113], v[230:231] neg_lo:[1,0,0] neg_hi:[1,0,0]
	v_pk_fma_f32 v[230:231], v[198:199], v[114:115], v[230:231] neg_lo:[1,0,0] neg_hi:[1,0,0]
	ds_read_b128 v[196:199], v8 offset:8768
	s_waitcnt lgkmcnt(5)
	v_fma_f32 v230, -v200, v116, v230
	ds_read_b128 v[200:203], v8 offset:8784
	v_add_f32_e32 v117, v230, v231
	s_cbranch_vccz .Ls4_u33
	v_cvt_pk_bf16_f32 v233, -v117, v117
	global_store_short v6, v233, s[8:9] offset:256
	s_branch .Ls4_n33

; #define LAS __attribute__((address_space(3)))
; __device__ __forceinline__ float bf2f(unsigned short x) { return __uint_as_float(((unsigned)x) << 16); }
; __device__ __forceinline__ void chunk_prep_phase(const Params& p, int bid, int nblk, LAS unsigned char* lds0) {
;     ...
;             { const float br = betg[34]; ab0 = (f32x2){bf2f(*(const LAS bf16_t*)(lg + P5_VS + 9248 + c * 2)) * br, bf2f(*(const LAS bf16_t*)(lg + P5_KS + 9248 + c * 2)) * br * __expf(decg[34])}; ab1 = (f32x2){0.f, 0.f}; } ab0 -= mq[3][0] * xy[0]; ab1 -= mq[3][1] * xy[1]; ab0 -= mq[3][2] * xy[2]; ab1 -= mq[3][3] * xy[3]; mq[3] = *(const LAS f32x4*)(Mg + 2200);
;             ab0 -= mq[4][0] * xy[4]; ab1 -= mq[4][1] * xy[5]; ab0 -= mq[4][2] * xy[6]; ab1 -= mq[4][3] * xy[7]; mq[4] = *(const LAS f32x4*)(Mg + 2204);
;             ab0 -= mq[5][0] * xy[8]; ab1 -= mq[5][1] * xy[9]; ab0 -= mq[5][2] * xy[10]; ab1 -= mq[5][3] * xy[11]; mq[5] = *(const LAS f32x4*)(Mg + 2208);
;             ab0 -= mq[0][0] * xy[12]; ab1 -= mq[0][1] * xy[13]; ab0 -= mq[0][2] * xy[14]; ab1 -= mq[0][3] * xy[15]; mq[0] = *(const LAS f32x4*)(Mg + 2240);
;             ab0 -= mq[1][0] * xy[16]; ab1 -= mq[1][1] * xy[17]; ab0 -= mq[1][2] * xy[18]; ab1 -= mq[1][3] * xy[19]; mq[1] = *(const LAS f32x4*)(Mg + 2244);
;             ab0 -= mq[2][0] * xy[20]; ab1 -= mq[2][1] * xy[21]; ab0 -= mq[2][2] * xy[22]; ab1 -= mq[2][3] * xy[23]; mq[2] = *(const LAS f32x4*)(Mg + 2248);
;             ab0 -= mq[3][0] * xy[24]; ab1 -= mq[3][1] * xy[25]; ab0 -= mq[3][2] * xy[26]; ab1 -= mq[3][3] * xy[27]; mq[3] = *(const LAS f32x4*)(Mg + 2252);
;             ab0 -= mq[4][0] * xy[28]; ab1 -= mq[4][1] * xy[29]; ab0 -= mq[4][2] * xy[30]; ab1 -= mq[4][3] * xy[31]; mq[4] = *(const LAS f32x4*)(Mg + 2256);
;             ab0 -= mq[5][0] * xy[32]; ab1 -= mq[5][1] * xy[33]; xy[34] = ab0 + ab1; up[4352] = xy[34][0]; wp[4352] = f2bf(-xy[34][1]); mq[5] = *(const LAS f32x4*)(Mg + 2260);
.Ls4_n33:
	v_lshlrev_b32_e32 v228, 16, v228
	v_mul_f32_e32 v232, v228, v218
	v_mul_f32_e32 v230, v232, v2
	v_mov_b32_e32 v231, 0
	ds_read_u16 v229, v7 offset:9520
	s_waitcnt lgkmcnt(6)
	v_pk_fma_f32 v[230:231], v[204:205], v[84:85], v[230:231] neg_lo:[1,0,0] neg_hi:[1,0,0]
	v_pk_fma_f32 v[230:231], v[206:207], v[86:87], v[230:231] neg_lo:[1,0,0] neg_hi:[1,0,0]
	ds_read_b128 v[204:207], v8 offset:8800
	s_waitcnt lgkmcnt(6)
	v_pk_fma_f32 v[230:231], v[208:209], v[88:89], v[230:231] neg_lo:[1,0,0] neg_hi:[1,0,0]
	v_pk_fma_f32 v[230:231], v[210:211], v[90:91], v[230:231] neg_lo:[1,0,0] neg_hi:[1,0,0]
	ds_read_b128 v[208:211], v8 offset:8816
	s_waitcnt lgkmcnt(6)
	v_pk_fma_f32 v[230:231], v[212:213], v[92:93], v[230:231] neg_lo:[1,0,0] neg_hi:[1,0,0]
	v_pk_fma_f32 v[230:231], v[214:215], v[94:95], v[230:231] neg_lo:[1,0,0] neg_hi:[1,0,0]
	ds_read_b128 v[212:215], v8 offset:8832
	s_waitcnt lgkmcnt(6)
	v_pk_fma_f32 v[230:231], v[192:193], v[96:97], v[230:231] neg_lo:[1,0,0] neg_hi:[1,0,0]
	v_pk_fma_f32 v[230:231], v[194:195], v[98:99], v[230:231] neg_lo:[1,0,0] neg_hi:[1,0,0]
	ds_read_b128 v[192:195], v8 offset:8960
	s_waitcnt lgkmcnt(6)
	v_pk_fma_f32 v[230:231], v[196:197], v[100:101], v[230:231] neg_lo:[1,0,0] neg_hi:[1,0,0]
	v_pk_fma_f32 v[230:231], v[198:199], v[102:103], v[230:231] neg_lo:[1,0,0] neg_hi:[1,0,0]
	ds_read_b128 v[196:199], v8 offset:8976
	s_waitcnt lgkmcnt(6)
	v_pk_fma_f32 v[230:231], v[200:201], v[104:105], v[230:231] neg_lo:[1,0,0] neg_hi:[1,0,0]
	v_pk_fma_f32 v[230:231], v[202:203], v[106:107], v[230:231] neg_lo:[1,0,0] neg_hi:[1,0,0]
	ds_read_b128 v[200:203], v8 offset:8992
	s_waitcnt lgkmcnt(5)
	v_pk_fma_f32 v[230:231], v[204:205], v[108:109], v[230:231] neg_lo:[1,0,0] neg_hi:[1,0,0]
	v_pk_fma_f32 v[230:231], v[206:207], v[110:111], v[230:231] neg_lo:[1,0,0] neg_hi:[1,0,0]
	ds_read_b128 v[204:207], v8 offset:9008
	s_waitcnt lgkmcnt(5)
	v_pk_fma_f32 v[230:231], v[208:209], v[112:113], v[230:231] neg_lo:[1,0,0] neg_hi:[1,0,0]
	v_pk_fma_f32 v[230:231], v[210:211], v[114:115], v[230:231] neg_lo:[1,0,0] neg_hi:[1,0,0]
	ds_read_b128 v[208:211], v8 offset:9024
	s_waitcnt lgkmcnt(5)
	v_pk_fma_f32 v[230:231], v[212:213], v[116:117], v[230:231] neg_lo:[1,0,0] neg_hi:[1,0,0]
	ds_read_b128 v[212:215], v8 offset:9040
	v_add_f32_e32 v118, v230, v231
	s_cbranch_vccz .Ls4_u34
	v_cvt_pk_bf16_f32 v233, -v118, v118
	global_store_short v6, v233, s[8:9] offset:512
	s_branch .Ls4_n34

; #define LAS __attribute__((address_space(3)))
; __device__ __forceinline__ float bf2f(unsigned short x) { return __uint_as_float(((unsigned)x) << 16); }
; __device__ __forceinline__ void chunk_prep_phase(const Params& p, int bid, int nblk, LAS unsigned char* lds0) {
;     ...
;             { const float br = betg[35]; ab0 = (f32x2){bf2f(*(const LAS bf16_t*)(lg + P5_VS + 9520 + c * 2)) * br, bf2f(*(const LAS bf16_t*)(lg + P5_KS + 9520 + c * 2)) * br * __expf(decg[35])}; ab1 = (f32x2){0.f, 0.f}; } ab0 -= mq[0][0] * xy[0]; ab1 -= mq[0][1] * xy[1]; ab0 -= mq[0][2] * xy[2]; ab1 -= mq[0][3] * xy[3]; mq[0] = *(const LAS f32x4*)(Mg + 2264);
;             ab0 -= mq[1][0] * xy[4]; ab1 -= mq[1][1] * xy[5]; ab0 -= mq[1][2] * xy[6]; ab1 -= mq[1][3] * xy[7]; mq[1] = *(const LAS f32x4*)(Mg + 2268);
;             ab0 -= mq[2][0] * xy[8]; ab1 -= mq[2][1] * xy[9]; ab0 -= mq[2][2] * xy[10]; ab1 -= mq[2][3] * xy[11]; mq[2] = *(const LAS f32x4*)(Mg + 2272);
;             ab0 -= mq[3][0] * xy[12]; ab1 -= mq[3][1] * xy[13]; ab0 -= mq[3][2] * xy[14]; ab1 -= mq[3][3] * xy[15]; mq[3] = *(const LAS f32x4*)(Mg + 2304);
;             ab0 -= mq[4][0] * xy[16]; ab1 -= mq[4][1] * xy[17]; ab0 -= mq[4][2] * xy[18]; ab1 -= mq[4][3] * xy[19]; mq[4] = *(const LAS f32x4*)(Mg + 2308);
;             ab0 -= mq[5][0] * xy[20]; ab1 -= mq[5][1] * xy[21]; ab0 -= mq[5][2] * xy[22]; ab1 -= mq[5][3] * xy[23]; mq[5] = *(const LAS f32x4*)(Mg + 2312);
;             ab0 -= mq[0][0] * xy[24]; ab1 -= mq[0][1] * xy[25]; ab0 -= mq[0][2] * xy[26]; ab1 -= mq[0][3] * xy[27]; mq[0] = *(const LAS f32x4*)(Mg + 2316);
;             ab0 -= mq[1][0] * xy[28]; ab1 -= mq[1][1] * xy[29]; ab0 -= mq[1][2] * xy[30]; ab1 -= mq[1][3] * xy[31]; mq[1] = *(const LAS f32x4*)(Mg + 2320);
;             ab0 -= mq[2][0] * xy[32]; ab1 -= mq[2][1] * xy[33]; ab0 -= mq[2][2] * xy[34]; xy[35] = ab0 + ab1; up[4480] = xy[35][0]; wp[4480] = f2bf(-xy[35][1]); mq[2] = *(const LAS f32x4*)(Mg + 2324);
.Ls4_n34:
	v_lshlrev_b32_e32 v229, 16, v229
	v_mul_f32_e32 v232, v229, v219
	v_mul_f32_e32 v230, v232, v3
	v_mov_b32_e32 v231, 0
	ds_read_u16 v228, v7 offset:9792
	ds_read_b128 v[216:219], v8 offset:16800
	ds_read_b128 v[0:3], v8 offset:16544
	s_waitcnt lgkmcnt(8)
	v_pk_fma_f32 v[230:231], v[192:193], v[84:85], v[230:231] neg_lo:[1,0,0] neg_hi:[1,0,0]
	v_pk_fma_f32 v[230:231], v[194:195], v[86:87], v[230:231] neg_lo:[1,0,0] neg_hi:[1,0,0]
	ds_read_b128 v[192:195], v8 offset:9056
	s_waitcnt lgkmcnt(8)
	v_pk_fma_f32 v[230:231], v[196:197], v[88:89], v[230:231] neg_lo:[1,0,0] neg_hi:[1,0,0]
	v_pk_fma_f32 v[230:231], v[198:199], v[90:91], v[230:231] neg_lo:[1,0,0] neg_hi:[1,0,0]
	ds_read_b128 v[196:199], v8 offset:9072
	s_waitcnt lgkmcnt(8)
	v_pk_fma_f32 v[230:231], v[200:201], v[92:93], v[230:231] neg_lo:[1,0,0] neg_hi:[1,0,0]
	v_pk_fma_f32 v[230:231], v[202:203], v[94:95], v[230:231] neg_lo:[1,0,0] neg_hi:[1,0,0]
	ds_read_b128 v[200:203], v8 offset:9088
	s_waitcnt lgkmcnt(8)
	v_pk_fma_f32 v[230:231], v[204:205], v[96:97], v[230:231] neg_lo:[1,0,0] neg_hi:[1,0,0]
	v_pk_fma_f32 v[230:231], v[206:207], v[98:99], v[230:231] neg_lo:[1,0,0] neg_hi:[1,0,0]
	ds_read_b128 v[204:207], v8 offset:9216
	s_waitcnt lgkmcnt(8)
	v_pk_fma_f32 v[230:231], v[208:209], v[100:101], v[230:231] neg_lo:[1,0,0] neg_hi:[1,0,0]
	v_pk_fma_f32 v[230:231], v[210:211], v[102:103], v[230:231] neg_lo:[1,0,0] neg_hi:[1,0,0]
	ds_read_b128 v[208:211], v8 offset:9232
	s_waitcnt lgkmcnt(8)
	v_pk_fma_f32 v[230:231], v[212:213], v[104:105], v[230:231] neg_lo:[1,0,0] neg_hi:[1,0,0]
	v_pk_fma_f32 v[230:231], v[214:215], v[106:107], v[230:231] neg_lo:[1,0,0] neg_hi:[1,0,0]
	ds_read_b128 v[212:215], v8 offset:9248
	s_waitcnt lgkmcnt(5)
	v_pk_fma_f32 v[230:231], v[192:193], v[108:109], v[230:231] neg_lo:[1,0,0] neg_hi:[1,0,0]
	v_pk_fma_f32 v[230:231], v[194:195], v[110:111], v[230:231] neg_lo:[1,0,0] neg_hi:[1,0,0]
	ds_read_b128 v[192:195], v8 offset:9264
	s_waitcnt lgkmcnt(5)
	v_pk_fma_f32 v[230:231], v[196:197], v[112:113], v[230:231] neg_lo:[1,0,0] neg_hi:[1,0,0]
	v_pk_fma_f32 v[230:231], v[198:199], v[114:115], v[230:231] neg_lo:[1,0,0] neg_hi:[1,0,0]
	ds_read_b128 v[196:199], v8 offset:9280
	s_waitcnt lgkmcnt(5)
	v_pk_fma_f32 v[230:231], v[200:201], v[116:117], v[230:231] neg_lo:[1,0,0] neg_hi:[1,0,0]
	v_fma_f32 v230, -v202, v118, v230
	ds_read_b128 v[200:203], v8 offset:9296
	v_add_f32_e32 v119, v230, v231
	s_cbranch_vccz .Ls4_u35
	v_cvt_pk_bf16_f32 v233, -v119, v119
	global_store_short v6, v233, s[8:9] offset:768
	s_branch .Ls4_n35

; #define LAS __attribute__((address_space(3)))
; __device__ __forceinline__ float bf2f(unsigned short x) { return __uint_as_float(((unsigned)x) << 16); }
; __device__ __forceinline__ void chunk_prep_phase(const Params& p, int bid, int nblk, LAS unsigned char* lds0) {
;     ...
;             { const float br = betg[36]; ab0 = (f32x2){bf2f(*(const LAS bf16_t*)(lg + P5_VS + 9792 + c * 2)) * br, bf2f(*(const LAS bf16_t*)(lg + P5_KS + 9792 + c * 2)) * br * __expf(decg[36])}; ab1 = (f32x2){0.f, 0.f}; } ab0 -= mq[3][0] * xy[0]; ab1 -= mq[3][1] * xy[1]; ab0 -= mq[3][2] * xy[2]; ab1 -= mq[3][3] * xy[3]; mq[3] = *(const LAS f32x4*)(Mg + 2328);
;             ab0 -= mq[4][0] * xy[4]; ab1 -= mq[4][1] * xy[5]; ab0 -= mq[4][2] * xy[6]; ab1 -= mq[4][3] * xy[7]; mq[4] = *(const LAS f32x4*)(Mg + 2332);
;             ab0 -= mq[5][0] * xy[8]; ab1 -= mq[5][1] * xy[9]; ab0 -= mq[5][2] * xy[10]; ab1 -= mq[5][3] * xy[11]; mq[5] = *(const LAS f32x4*)(Mg + 2336);
;             ab0 -= mq[0][0] * xy[12]; ab1 -= mq[0][1] * xy[13]; ab0 -= mq[0][2] * xy[14]; ab1 -= mq[0][3] * xy[15]; mq[0] = *(const LAS f32x4*)(Mg + 2368);
;             ab0 -= mq[1][0] * xy[16]; ab1 -= mq[1][1] * xy[17]; ab0 -= mq[1][2] * xy[18]; ab1 -= mq[1][3] * xy[19]; mq[1] = *(const LAS f32x4*)(Mg + 2372);
;             ab0 -= mq[2][0] * xy[20]; ab1 -= mq[2][1] * xy[21]; ab0 -= mq[2][2] * xy[22]; ab1 -= mq[2][3] * xy[23]; mq[2] = *(const LAS f32x4*)(Mg + 2376);
;             ab0 -= mq[3][0] * xy[24]; ab1 -= mq[3][1] * xy[25]; ab0 -= mq[3][2] * xy[26]; ab1 -= mq[3][3] * xy[27]; mq[3] = *(const LAS f32x4*)(Mg + 2380);
;             ab0 -= mq[4][0] * xy[28]; ab1 -= mq[4][1] * xy[29]; ab0 -= mq[4][2] * xy[30]; ab1 -= mq[4][3] * xy[31]; mq[4] = *(const LAS f32x4*)(Mg + 2384);
;             ab0 -= mq[5][0] * xy[32]; ab1 -= mq[5][1] * xy[33]; ab0 -= mq[5][2] * xy[34]; ab1 -= mq[5][3] * xy[35]; xy[36] = ab0 + ab1; up[4608] = xy[36][0]; wp[4608] = f2bf(-xy[36][1]); mq[5] = *(const LAS f32x4*)(Mg + 2388);
.Ls4_n35:
	v_mul_f32_e32 v224, s16, v224
	v_mul_f32_e32 v225, s16, v225
	v_mul_f32_e32 v226, s16, v226
	v_mul_f32_e32 v227, s16, v227
	v_exp_f32_e32 v224, v224
	v_exp_f32_e32 v225, v225
	v_exp_f32_e32 v226, v226
	v_exp_f32_e32 v227, v227
	s_nop 0
	v_lshlrev_b32_e32 v228, 16, v228
	v_mul_f32_e32 v232, v228, v220
	v_mul_f32_e32 v230, v232, v224
	v_mov_b32_e32 v231, 0
	ds_read_u16 v229, v7 offset:10064
	s_waitcnt lgkmcnt(6)
	v_pk_fma_f32 v[230:231], v[204:205], v[84:85], v[230:231] neg_lo:[1,0,0] neg_hi:[1,0,0]
	v_pk_fma_f32 v[230:231], v[206:207], v[86:87], v[230:231] neg_lo:[1,0,0] neg_hi:[1,0,0]
	ds_read_b128 v[204:207], v8 offset:9312
	s_waitcnt lgkmcnt(6)
	v_pk_fma_f32 v[230:231], v[208:209], v[88:89], v[230:231] neg_lo:[1,0,0] neg_hi:[1,0,0]
	v_pk_fma_f32 v[230:231], v[210:211], v[90:91], v[230:231] neg_lo:[1,0,0] neg_hi:[1,0,0]
	ds_read_b128 v[208:211], v8 offset:9328
	s_waitcnt lgkmcnt(6)
	v_pk_fma_f32 v[230:231], v[212:213], v[92:93], v[230:231] neg_lo:[1,0,0] neg_hi:[1,0,0]
	v_pk_fma_f32 v[230:231], v[214:215], v[94:95], v[230:231] neg_lo:[1,0,0] neg_hi:[1,0,0]
	ds_read_b128 v[212:215], v8 offset:9344
	s_waitcnt lgkmcnt(6)
	v_pk_fma_f32 v[230:231], v[192:193], v[96:97], v[230:231] neg_lo:[1,0,0] neg_hi:[1,0,0]
	v_pk_fma_f32 v[230:231], v[194:195], v[98:99], v[230:231] neg_lo:[1,0,0] neg_hi:[1,0,0]
	ds_read_b128 v[192:195], v8 offset:9472
	s_waitcnt lgkmcnt(6)
	v_pk_fma_f32 v[230:231], v[196:197], v[100:101], v[230:231] neg_lo:[1,0,0] neg_hi:[1,0,0]
	v_pk_fma_f32 v[230:231], v[198:199], v[102:103], v[230:231] neg_lo:[1,0,0] neg_hi:[1,0,0]
	ds_read_b128 v[196:199], v8 offset:9488
	s_waitcnt lgkmcnt(6)
	v_pk_fma_f32 v[230:231], v[200:201], v[104:105], v[230:231] neg_lo:[1,0,0] neg_hi:[1,0,0]
	v_pk_fma_f32 v[230:231], v[202:203], v[106:107], v[230:231] neg_lo:[1,0,0] neg_hi:[1,0,0]
	ds_read_b128 v[200:203], v8 offset:9504
	s_waitcnt lgkmcnt(5)
	v_pk_fma_f32 v[230:231], v[204:205], v[108:109], v[230:231] neg_lo:[1,0,0] neg_hi:[1,0,0]
	v_pk_fma_f32 v[230:231], v[206:207], v[110:111], v[230:231] neg_lo:[1,0,0] neg_hi:[1,0,0]
	ds_read_b128 v[204:207], v8 offset:9520
	s_waitcnt lgkmcnt(5)
	v_pk_fma_f32 v[230:231], v[208:209], v[112:113], v[230:231] neg_lo:[1,0,0] neg_hi:[1,0,0]
	v_pk_fma_f32 v[230:231], v[210:211], v[114:115], v[230:231] neg_lo:[1,0,0] neg_hi:[1,0,0]
	ds_read_b128 v[208:211], v8 offset:9536
	s_waitcnt lgkmcnt(5)
	v_pk_fma_f32 v[230:231], v[212:213], v[116:117], v[230:231] neg_lo:[1,0,0] neg_hi:[1,0,0]
	v_pk_fma_f32 v[230:231], v[214:215], v[118:119], v[230:231] neg_lo:[1,0,0] neg_hi:[1,0,0]
	ds_read_b128 v[212:215], v8 offset:9552
	v_add_f32_e32 v120, v230, v231
	s_cbranch_vccz .Ls4_u36
	v_cvt_pk_bf16_f32 v233, -v120, v120
	global_store_short v6, v233, s[8:9] offset:1024
	s_branch .Ls4_n36

; #define LAS __attribute__((address_space(3)))
; __device__ __forceinline__ float bf2f(unsigned short x) { return __uint_as_float(((unsigned)x) << 16); }
; __device__ __forceinline__ void chunk_prep_phase(const Params& p, int bid, int nblk, LAS unsigned char* lds0) {
;     ...
;             { const float br = betg[37]; ab0 = (f32x2){bf2f(*(const LAS bf16_t*)(lg + P5_VS + 10064 + c * 2)) * br, bf2f(*(const LAS bf16_t*)(lg + P5_KS + 10064 + c * 2)) * br * __expf(decg[37])}; ab1 = (f32x2){0.f, 0.f}; } ab0 -= mq[0][0] * xy[0]; ab1 -= mq[0][1] * xy[1]; ab0 -= mq[0][2] * xy[2]; ab1 -= mq[0][3] * xy[3]; mq[0] = *(const LAS f32x4*)(Mg + 2392);
;             ab0 -= mq[1][0] * xy[4]; ab1 -= mq[1][1] * xy[5]; ab0 -= mq[1][2] * xy[6]; ab1 -= mq[1][3] * xy[7]; mq[1] = *(const LAS f32x4*)(Mg + 2396);
;             ab0 -= mq[2][0] * xy[8]; ab1 -= mq[2][1] * xy[9]; ab0 -= mq[2][2] * xy[10]; ab1 -= mq[2][3] * xy[11]; mq[2] = *(const LAS f32x4*)(Mg + 2400);
;             ab0 -= mq[3][0] * xy[12]; ab1 -= mq[3][1] * xy[13]; ab0 -= mq[3][2] * xy[14]; ab1 -= mq[3][3] * xy[15]; mq[3] = *(const LAS f32x4*)(Mg + 2404);
;             ab0 -= mq[4][0] * xy[16]; ab1 -= mq[4][1] * xy[17]; ab0 -= mq[4][2] * xy[18]; ab1 -= mq[4][3] * xy[19]; mq[4] = *(const LAS f32x4*)(Mg + 2432);
;             ab0 -= mq[5][0] * xy[20]; ab1 -= mq[5][1] * xy[21]; ab0 -= mq[5][2] * xy[22]; ab1 -= mq[5][3] * xy[23]; mq[5] = *(const LAS f32x4*)(Mg + 2436);
;             ab0 -= mq[0][0] * xy[24]; ab1 -= mq[0][1] * xy[25]; ab0 -= mq[0][2] * xy[26]; ab1 -= mq[0][3] * xy[27]; mq[0] = *(const LAS f32x4*)(Mg + 2440);
;             ab0 -= mq[1][0] * xy[28]; ab1 -= mq[1][1] * xy[29]; ab0 -= mq[1][2] * xy[30]; ab1 -= mq[1][3] * xy[31]; mq[1] = *(const LAS f32x4*)(Mg + 2444);
;             ab0 -= mq[2][0] * xy[32]; ab1 -= mq[2][1] * xy[33]; ab0 -= mq[2][2] * xy[34]; ab1 -= mq[2][3] * xy[35]; mq[2] = *(const LAS f32x4*)(Mg + 2448);
;             ab0 -= mq[3][0] * xy[36]; xy[37] = ab0 + ab1; up[4736] = xy[37][0]; wp[4736] = f2bf(-xy[37][1]); mq[3] = *(const LAS f32x4*)(Mg + 2452);
.Ls4_n36:
	v_lshlrev_b32_e32 v229, 16, v229
	v_mul_f32_e32 v232, v229, v221
	v_mul_f32_e32 v230, v232, v225
	v_mov_b32_e32 v231, 0
	ds_read_u16 v228, v7 offset:10336
	s_waitcnt lgkmcnt(6)
	v_pk_fma_f32 v[230:231], v[192:193], v[84:85], v[230:231] neg_lo:[1,0,0] neg_hi:[1,0,0]
	v_pk_fma_f32 v[230:231], v[194:195], v[86:87], v[230:231] neg_lo:[1,0,0] neg_hi:[1,0,0]
	ds_read_b128 v[192:195], v8 offset:9568
	s_waitcnt lgkmcnt(6)
	v_pk_fma_f32 v[230:231], v[196:197], v[88:89], v[230:231] neg_lo:[1,0,0] neg_hi:[1,0,0]
	v_pk_fma_f32 v[230:231], v[198:199], v[90:91], v[230:231] neg_lo:[1,0,0] neg_hi:[1,0,0]
	ds_read_b128 v[196:199], v8 offset:9584
	s_waitcnt lgkmcnt(6)
	v_pk_fma_f32 v[230:231], v[200:201], v[92:93], v[230:231] neg_lo:[1,0,0] neg_hi:[1,0,0]
	v_pk_fma_f32 v[230:231], v[202:203], v[94:95], v[230:231] neg_lo:[1,0,0] neg_hi:[1,0,0]
	ds_read_b128 v[200:203], v8 offset:9600
	s_waitcnt lgkmcnt(6)
	v_pk_fma_f32 v[230:231], v[204:205], v[96:97], v[230:231] neg_lo:[1,0,0] neg_hi:[1,0,0]
	v_pk_fma_f32 v[230:231], v[206:207], v[98:99], v[230:231] neg_lo:[1,0,0] neg_hi:[1,0,0]
	ds_read_b128 v[204:207], v8 offset:9616
	s_waitcnt lgkmcnt(6)
	v_pk_fma_f32 v[230:231], v[208:209], v[100:101], v[230:231] neg_lo:[1,0,0] neg_hi:[1,0,0]
	v_pk_fma_f32 v[230:231], v[210:211], v[102:103], v[230:231] neg_lo:[1,0,0] neg_hi:[1,0,0]
	ds_read_b128 v[208:211], v8 offset:9728
	s_waitcnt lgkmcnt(6)
	v_pk_fma_f32 v[230:231], v[212:213], v[104:105], v[230:231] neg_lo:[1,0,0] neg_hi:[1,0,0]
	v_pk_fma_f32 v[230:231], v[214:215], v[106:107], v[230:231] neg_lo:[1,0,0] neg_hi:[1,0,0]
	ds_read_b128 v[212:215], v8 offset:9744
	s_waitcnt lgkmcnt(5)
	v_pk_fma_f32 v[230:231], v[192:193], v[108:109], v[230:231] neg_lo:[1,0,0] neg_hi:[1,0,0]
	v_pk_fma_f32 v[230:231], v[194:195], v[110:111], v[230:231] neg_lo:[1,0,0] neg_hi:[1,0,0]
	ds_read_b128 v[192:195], v8 offset:9760
	s_waitcnt lgkmcnt(5)
	v_pk_fma_f32 v[230:231], v[196:197], v[112:113], v[230:231] neg_lo:[1,0,0] neg_hi:[1,0,0]
	v_pk_fma_f32 v[230:231], v[198:199], v[114:115], v[230:231] neg_lo:[1,0,0] neg_hi:[1,0,0]
	ds_read_b128 v[196:199], v8 offset:9776
	s_waitcnt lgkmcnt(5)
	v_pk_fma_f32 v[230:231], v[200:201], v[116:117], v[230:231] neg_lo:[1,0,0] neg_hi:[1,0,0]
	v_pk_fma_f32 v[230:231], v[202:203], v[118:119], v[230:231] neg_lo:[1,0,0] neg_hi:[1,0,0]
	ds_read_b128 v[200:203], v8 offset:9792
	s_waitcnt lgkmcnt(5)
	v_fma_f32 v230, -v204, v120, v230
	ds_read_b128 v[204:207], v8 offset:9808
	v_add_f32_e32 v121, v230, v231
	s_cbranch_vccz .Ls4_u37
	v_cvt_pk_bf16_f32 v233, -v121, v121
	global_store_short v6, v233, s[8:9] offset:1280
	s_branch .Ls4_n37

; #define LAS __attribute__((address_space(3)))
; __device__ __forceinline__ float bf2f(unsigned short x) { return __uint_as_float(((unsigned)x) << 16); }
; __device__ __forceinline__ void chunk_prep_phase(const Params& p, int bid, int nblk, LAS unsigned char* lds0) {
;     ...
;             { const float br = betg[38]; ab0 = (f32x2){bf2f(*(const LAS bf16_t*)(lg + P5_VS + 10336 + c * 2)) * br, bf2f(*(const LAS bf16_t*)(lg + P5_KS + 10336 + c * 2)) * br * __expf(decg[38])}; ab1 = (f32x2){0.f, 0.f}; } ab0 -= mq[4][0] * xy[0]; ab1 -= mq[4][1] * xy[1]; ab0 -= mq[4][2] * xy[2]; ab1 -= mq[4][3] * xy[3]; mq[4] = *(const LAS f32x4*)(Mg + 2456);
;             ab0 -= mq[5][0] * xy[4]; ab1 -= mq[5][1] * xy[5]; ab0 -= mq[5][2] * xy[6]; ab1 -= mq[5][3] * xy[7]; mq[5] = *(const LAS f32x4*)(Mg + 2460);
;             ab0 -= mq[0][0] * xy[8]; ab1 -= mq[0][1] * xy[9]; ab0 -= mq[0][2] * xy[10]; ab1 -= mq[0][3] * xy[11]; mq[0] = *(const LAS f32x4*)(Mg + 2464);
;             ab0 -= mq[1][0] * xy[12]; ab1 -= mq[1][1] * xy[13]; ab0 -= mq[1][2] * xy[14]; ab1 -= mq[1][3] * xy[15]; mq[1] = *(const LAS f32x4*)(Mg + 2468);
;             ab0 -= mq[2][0] * xy[16]; ab1 -= mq[2][1] * xy[17]; ab0 -= mq[2][2] * xy[18]; ab1 -= mq[2][3] * xy[19]; mq[2] = *(const LAS f32x4*)(Mg + 2496);
;             ab0 -= mq[3][0] * xy[20]; ab1 -= mq[3][1] * xy[21]; ab0 -= mq[3][2] * xy[22]; ab1 -= mq[3][3] * xy[23]; mq[3] = *(const LAS f32x4*)(Mg + 2500);
;             ab0 -= mq[4][0] * xy[24]; ab1 -= mq[4][1] * xy[25]; ab0 -= mq[4][2] * xy[26]; ab1 -= mq[4][3] * xy[27]; mq[4] = *(const LAS f32x4*)(Mg + 2504);
;             ab0 -= mq[5][0] * xy[28]; ab1 -= mq[5][1] * xy[29]; ab0 -= mq[5][2] * xy[30]; ab1 -= mq[5][3] * xy[31]; mq[5] = *(const LAS f32x4*)(Mg + 2508);
;             ab0 -= mq[0][0] * xy[32]; ab1 -= mq[0][1] * xy[33]; ab0 -= mq[0][2] * xy[34]; ab1 -= mq[0][3] * xy[35]; mq[0] = *(const LAS f32x4*)(Mg + 2512);
;             ab0 -= mq[1][0] * xy[36]; ab1 -= mq[1][1] * xy[37]; xy[38] = ab0 + ab1; up[4864] = xy[38][0]; wp[4864] = f2bf(-xy[38][1]); mq[1] = *(const LAS f32x4*)(Mg + 2516);
.Ls4_n37:
	v_lshlrev_b32_e32 v228, 16, v228
	v_mul_f32_e32 v232, v228, v222
	v_mul_f32_e32 v230, v232, v226
	v_mov_b32_e32 v231, 0
	ds_read_u16 v229, v7 offset:10608
	s_waitcnt lgkmcnt(6)
	v_pk_fma_f32 v[230:231], v[208:209], v[84:85], v[230:231] neg_lo:[1,0,0] neg_hi:[1,0,0]
	v_pk_fma_f32 v[230:231], v[210:211], v[86:87], v[230:231] neg_lo:[1,0,0] neg_hi:[1,0,0]
	ds_read_b128 v[208:211], v8 offset:9824
	s_waitcnt lgkmcnt(6)
	v_pk_fma_f32 v[230:231], v[212:213], v[88:89], v[230:231] neg_lo:[1,0,0] neg_hi:[1,0,0]
	v_pk_fma_f32 v[230:231], v[214:215], v[90:91], v[230:231] neg_lo:[1,0,0] neg_hi:[1,0,0]
	ds_read_b128 v[212:215], v8 offset:9840
	s_waitcnt lgkmcnt(6)
	v_pk_fma_f32 v[230:231], v[192:193], v[92:93], v[230:231] neg_lo:[1,0,0] neg_hi:[1,0,0]
	v_pk_fma_f32 v[230:231], v[194:195], v[94:95], v[230:231] neg_lo:[1,0,0] neg_hi:[1,0,0]
	ds_read_b128 v[192:195], v8 offset:9856
	s_waitcnt lgkmcnt(6)
	v_pk_fma_f32 v[230:231], v[196:197], v[96:97], v[230:231] neg_lo:[1,0,0] neg_hi:[1,0,0]
	v_pk_fma_f32 v[230:231], v[198:199], v[98:99], v[230:231] neg_lo:[1,0,0] neg_hi:[1,0,0]
	ds_read_b128 v[196:199], v8 offset:9872
	s_waitcnt lgkmcnt(6)
	v_pk_fma_f32 v[230:231], v[200:201], v[100:101], v[230:231] neg_lo:[1,0,0] neg_hi:[1,0,0]
	v_pk_fma_f32 v[230:231], v[202:203], v[102:103], v[230:231] neg_lo:[1,0,0] neg_hi:[1,0,0]
	ds_read_b128 v[200:203], v8 offset:9984
	s_waitcnt lgkmcnt(6)
	v_pk_fma_f32 v[230:231], v[204:205], v[104:105], v[230:231] neg_lo:[1,0,0] neg_hi:[1,0,0]
	v_pk_fma_f32 v[230:231], v[206:207], v[106:107], v[230:231] neg_lo:[1,0,0] neg_hi:[1,0,0]
	ds_read_b128 v[204:207], v8 offset:10000
	s_waitcnt lgkmcnt(5)
	v_pk_fma_f32 v[230:231], v[208:209], v[108:109], v[230:231] neg_lo:[1,0,0] neg_hi:[1,0,0]
	v_pk_fma_f32 v[230:231], v[210:211], v[110:111], v[230:231] neg_lo:[1,0,0] neg_hi:[1,0,0]
	ds_read_b128 v[208:211], v8 offset:10016
	s_waitcnt lgkmcnt(5)
	v_pk_fma_f32 v[230:231], v[212:213], v[112:113], v[230:231] neg_lo:[1,0,0] neg_hi:[1,0,0]
	v_pk_fma_f32 v[230:231], v[214:215], v[114:115], v[230:231] neg_lo:[1,0,0] neg_hi:[1,0,0]
	ds_read_b128 v[212:215], v8 offset:10032
	s_waitcnt lgkmcnt(5)
	v_pk_fma_f32 v[230:231], v[192:193], v[116:117], v[230:231] neg_lo:[1,0,0] neg_hi:[1,0,0]
	v_pk_fma_f32 v[230:231], v[194:195], v[118:119], v[230:231] neg_lo:[1,0,0] neg_hi:[1,0,0]
	ds_read_b128 v[192:195], v8 offset:10048
	s_waitcnt lgkmcnt(5)
	v_pk_fma_f32 v[230:231], v[196:197], v[120:121], v[230:231] neg_lo:[1,0,0] neg_hi:[1,0,0]
	ds_read_b128 v[196:199], v8 offset:10064
	v_add_f32_e32 v122, v230, v231
	s_cbranch_vccz .Ls4_u38
	v_cvt_pk_bf16_f32 v233, -v122, v122
	global_store_short v6, v233, s[8:9] offset:1536
	s_branch .Ls4_n38

; #define LAS __attribute__((address_space(3)))
; __device__ __forceinline__ float bf2f(unsigned short x) { return __uint_as_float(((unsigned)x) << 16); }
; __device__ __forceinline__ void chunk_prep_phase(const Params& p, int bid, int nblk, LAS unsigned char* lds0) {
;     ...
;             { const float br = betg[39]; ab0 = (f32x2){bf2f(*(const LAS bf16_t*)(lg + P5_VS + 10608 + c * 2)) * br, bf2f(*(const LAS bf16_t*)(lg + P5_KS + 10608 + c * 2)) * br * __expf(decg[39])}; ab1 = (f32x2){0.f, 0.f}; } ab0 -= mq[2][0] * xy[0]; ab1 -= mq[2][1] * xy[1]; ab0 -= mq[2][2] * xy[2]; ab1 -= mq[2][3] * xy[3]; mq[2] = *(const LAS f32x4*)(Mg + 2520);
;             ab0 -= mq[3][0] * xy[4]; ab1 -= mq[3][1] * xy[5]; ab0 -= mq[3][2] * xy[6]; ab1 -= mq[3][3] * xy[7]; mq[3] = *(const LAS f32x4*)(Mg + 2524);
;             ab0 -= mq[4][0] * xy[8]; ab1 -= mq[4][1] * xy[9]; ab0 -= mq[4][2] * xy[10]; ab1 -= mq[4][3] * xy[11]; mq[4] = *(const LAS f32x4*)(Mg + 2528);
;             ab0 -= mq[5][0] * xy[12]; ab1 -= mq[5][1] * xy[13]; ab0 -= mq[5][2] * xy[14]; ab1 -= mq[5][3] * xy[15]; mq[5] = *(const LAS f32x4*)(Mg + 2532);
;             ab0 -= mq[0][0] * xy[16]; ab1 -= mq[0][1] * xy[17]; ab0 -= mq[0][2] * xy[18]; ab1 -= mq[0][3] * xy[19]; mq[0] = *(const LAS f32x4*)(Mg + 2560);
;             ab0 -= mq[1][0] * xy[20]; ab1 -= mq[1][1] * xy[21]; ab0 -= mq[1][2] * xy[22]; ab1 -= mq[1][3] * xy[23]; mq[1] = *(const LAS f32x4*)(Mg + 2564);
;             ab0 -= mq[2][0] * xy[24]; ab1 -= mq[2][1] * xy[25]; ab0 -= mq[2][2] * xy[26]; ab1 -= mq[2][3] * xy[27]; mq[2] = *(const LAS f32x4*)(Mg + 2568);
;             ab0 -= mq[3][0] * xy[28]; ab1 -= mq[3][1] * xy[29]; ab0 -= mq[3][2] * xy[30]; ab1 -= mq[3][3] * xy[31]; mq[3] = *(const LAS f32x4*)(Mg + 2572);
;             ab0 -= mq[4][0] * xy[32]; ab1 -= mq[4][1] * xy[33]; ab0 -= mq[4][2] * xy[34]; ab1 -= mq[4][3] * xy[35]; mq[4] = *(const LAS f32x4*)(Mg + 2576);
;             ab0 -= mq[5][0] * xy[36]; ab1 -= mq[5][1] * xy[37]; ab0 -= mq[5][2] * xy[38]; xy[39] = ab0 + ab1; up[4992] = xy[39][0]; wp[4992] = f2bf(-xy[39][1]); mq[5] = *(const LAS f32x4*)(Mg + 2580);
.Ls4_n38:
	v_lshlrev_b32_e32 v229, 16, v229
	v_mul_f32_e32 v232, v229, v223
	v_mul_f32_e32 v230, v232, v227
	v_mov_b32_e32 v231, 0
	ds_read_u16 v228, v7 offset:10880
	ds_read_b128 v[220:223], v8 offset:16816
	ds_read_b128 v[224:227], v8 offset:16560
	s_waitcnt lgkmcnt(8)
	v_pk_fma_f32 v[230:231], v[200:201], v[84:85], v[230:231] neg_lo:[1,0,0] neg_hi:[1,0,0]
	v_pk_fma_f32 v[230:231], v[202:203], v[86:87], v[230:231] neg_lo:[1,0,0] neg_hi:[1,0,0]
	ds_read_b128 v[200:203], v8 offset:10080
	s_waitcnt lgkmcnt(8)
	v_pk_fma_f32 v[230:231], v[204:205], v[88:89], v[230:231] neg_lo:[1,0,0] neg_hi:[1,0,0]
	v_pk_fma_f32 v[230:231], v[206:207], v[90:91], v[230:231] neg_lo:[1,0,0] neg_hi:[1,0,0]
	ds_read_b128 v[204:207], v8 offset:10096
	s_waitcnt lgkmcnt(8)
	v_pk_fma_f32 v[230:231], v[208:209], v[92:93], v[230:231] neg_lo:[1,0,0] neg_hi:[1,0,0]
	v_pk_fma_f32 v[230:231], v[210:211], v[94:95], v[230:231] neg_lo:[1,0,0] neg_hi:[1,0,0]
	ds_read_b128 v[208:211], v8 offset:10112
	s_waitcnt lgkmcnt(8)
	v_pk_fma_f32 v[230:231], v[212:213], v[96:97], v[230:231] neg_lo:[1,0,0] neg_hi:[1,0,0]
	v_pk_fma_f32 v[230:231], v[214:215], v[98:99], v[230:231] neg_lo:[1,0,0] neg_hi:[1,0,0]
	ds_read_b128 v[212:215], v8 offset:10128
	s_waitcnt lgkmcnt(8)
	v_pk_fma_f32 v[230:231], v[192:193], v[100:101], v[230:231] neg_lo:[1,0,0] neg_hi:[1,0,0]
	v_pk_fma_f32 v[230:231], v[194:195], v[102:103], v[230:231] neg_lo:[1,0,0] neg_hi:[1,0,0]
	ds_read_b128 v[192:195], v8 offset:10240
	s_waitcnt lgkmcnt(8)
	v_pk_fma_f32 v[230:231], v[196:197], v[104:105], v[230:231] neg_lo:[1,0,0] neg_hi:[1,0,0]
	v_pk_fma_f32 v[230:231], v[198:199], v[106:107], v[230:231] neg_lo:[1,0,0] neg_hi:[1,0,0]
	ds_read_b128 v[196:199], v8 offset:10256
	s_waitcnt lgkmcnt(5)
	v_pk_fma_f32 v[230:231], v[200:201], v[108:109], v[230:231] neg_lo:[1,0,0] neg_hi:[1,0,0]
	v_pk_fma_f32 v[230:231], v[202:203], v[110:111], v[230:231] neg_lo:[1,0,0] neg_hi:[1,0,0]
	ds_read_b128 v[200:203], v8 offset:10272
	s_waitcnt lgkmcnt(5)
	v_pk_fma_f32 v[230:231], v[204:205], v[112:113], v[230:231] neg_lo:[1,0,0] neg_hi:[1,0,0]
	v_pk_fma_f32 v[230:231], v[206:207], v[114:115], v[230:231] neg_lo:[1,0,0] neg_hi:[1,0,0]
	ds_read_b128 v[204:207], v8 offset:10288
	s_waitcnt lgkmcnt(5)
	v_pk_fma_f32 v[230:231], v[208:209], v[116:117], v[230:231] neg_lo:[1,0,0] neg_hi:[1,0,0]
	v_pk_fma_f32 v[230:231], v[210:211], v[118:119], v[230:231] neg_lo:[1,0,0] neg_hi:[1,0,0]
	ds_read_b128 v[208:211], v8 offset:10304
	s_waitcnt lgkmcnt(5)
	v_pk_fma_f32 v[230:231], v[212:213], v[120:121], v[230:231] neg_lo:[1,0,0] neg_hi:[1,0,0]
	v_fma_f32 v230, -v214, v122, v230
	ds_read_b128 v[212:215], v8 offset:10320
	v_add_f32_e32 v123, v230, v231
	s_cbranch_vccz .Ls4_u39
	v_cvt_pk_bf16_f32 v233, -v123, v123
	global_store_short v6, v233, s[8:9] offset:1792
	s_branch .Ls4_n39

; #define LAS __attribute__((address_space(3)))
; __device__ __forceinline__ float bf2f(unsigned short x) { return __uint_as_float(((unsigned)x) << 16); }
; __device__ __forceinline__ void chunk_prep_phase(const Params& p, int bid, int nblk, LAS unsigned char* lds0) {
;     ...
;             { const float br = betg[40]; ab0 = (f32x2){bf2f(*(const LAS bf16_t*)(lg + P5_VS + 10880 + c * 2)) * br, bf2f(*(const LAS bf16_t*)(lg + P5_KS + 10880 + c * 2)) * br * __expf(decg[40])}; ab1 = (f32x2){0.f, 0.f}; } ab0 -= mq[0][0] * xy[0]; ab1 -= mq[0][1] * xy[1]; ab0 -= mq[0][2] * xy[2]; ab1 -= mq[0][3] * xy[3]; mq[0] = *(const LAS f32x4*)(Mg + 2584);
;             ab0 -= mq[1][0] * xy[4]; ab1 -= mq[1][1] * xy[5]; ab0 -= mq[1][2] * xy[6]; ab1 -= mq[1][3] * xy[7]; mq[1] = *(const LAS f32x4*)(Mg + 2588);
;             ab0 -= mq[2][0] * xy[8]; ab1 -= mq[2][1] * xy[9]; ab0 -= mq[2][2] * xy[10]; ab1 -= mq[2][3] * xy[11]; mq[2] = *(const LAS f32x4*)(Mg + 2592);
;             ab0 -= mq[3][0] * xy[12]; ab1 -= mq[3][1] * xy[13]; ab0 -= mq[3][2] * xy[14]; ab1 -= mq[3][3] * xy[15]; mq[3] = *(const LAS f32x4*)(Mg + 2596);
;             ab0 -= mq[4][0] * xy[16]; ab1 -= mq[4][1] * xy[17]; ab0 -= mq[4][2] * xy[18]; ab1 -= mq[4][3] * xy[19]; mq[4] = *(const LAS f32x4*)(Mg + 2624);
;             ab0 -= mq[5][0] * xy[20]; ab1 -= mq[5][1] * xy[21]; ab0 -= mq[5][2] * xy[22]; ab1 -= mq[5][3] * xy[23]; mq[5] = *(const LAS f32x4*)(Mg + 2628);
;             ab0 -= mq[0][0] * xy[24]; ab1 -= mq[0][1] * xy[25]; ab0 -= mq[0][2] * xy[26]; ab1 -= mq[0][3] * xy[27]; mq[0] = *(const LAS f32x4*)(Mg + 2632);
;             ab0 -= mq[1][0] * xy[28]; ab1 -= mq[1][1] * xy[29]; ab0 -= mq[1][2] * xy[30]; ab1 -= mq[1][3] * xy[31]; mq[1] = *(const LAS f32x4*)(Mg + 2636);
;             ab0 -= mq[2][0] * xy[32]; ab1 -= mq[2][1] * xy[33]; ab0 -= mq[2][2] * xy[34]; ab1 -= mq[2][3] * xy[35]; mq[2] = *(const LAS f32x4*)(Mg + 2640);
;             ab0 -= mq[3][0] * xy[36]; ab1 -= mq[3][1] * xy[37]; ab0 -= mq[3][2] * xy[38]; ab1 -= mq[3][3] * xy[39]; xy[40] = ab0 + ab1; up[5120] = xy[40][0]; wp[5120] = f2bf(-xy[40][1]); mq[3] = *(const LAS f32x4*)(Mg + 2644);
.Ls4_n39:
	v_mul_f32_e32 v0, s16, v0
	v_mul_f32_e32 v1, s16, v1
	v_mul_f32_e32 v2, s16, v2
	v_mul_f32_e32 v3, s16, v3
	v_exp_f32_e32 v0, v0
	v_exp_f32_e32 v1, v1
	v_exp_f32_e32 v2, v2
	v_exp_f32_e32 v3, v3
	s_nop 0
	v_lshlrev_b32_e32 v228, 16, v228
	v_mul_f32_e32 v232, v228, v216
	v_mul_f32_e32 v230, v232, v0
	v_mov_b32_e32 v231, 0
	ds_read_u16 v229, v7 offset:11152
	s_waitcnt lgkmcnt(6)
	v_pk_fma_f32 v[230:231], v[192:193], v[84:85], v[230:231] neg_lo:[1,0,0] neg_hi:[1,0,0]
	v_pk_fma_f32 v[230:231], v[194:195], v[86:87], v[230:231] neg_lo:[1,0,0] neg_hi:[1,0,0]
	ds_read_b128 v[192:195], v8 offset:10336
	s_waitcnt lgkmcnt(6)
	v_pk_fma_f32 v[230:231], v[196:197], v[88:89], v[230:231] neg_lo:[1,0,0] neg_hi:[1,0,0]
	v_pk_fma_f32 v[230:231], v[198:199], v[90:91], v[230:231] neg_lo:[1,0,0] neg_hi:[1,0,0]
	ds_read_b128 v[196:199], v8 offset:10352
	s_waitcnt lgkmcnt(6)
	v_pk_fma_f32 v[230:231], v[200:201], v[92:93], v[230:231] neg_lo:[1,0,0] neg_hi:[1,0,0]
	v_pk_fma_f32 v[230:231], v[202:203], v[94:95], v[230:231] neg_lo:[1,0,0] neg_hi:[1,0,0]
	ds_read_b128 v[200:203], v8 offset:10368
	s_waitcnt lgkmcnt(6)
	v_pk_fma_f32 v[230:231], v[204:205], v[96:97], v[230:231] neg_lo:[1,0,0] neg_hi:[1,0,0]
	v_pk_fma_f32 v[230:231], v[206:207], v[98:99], v[230:231] neg_lo:[1,0,0] neg_hi:[1,0,0]
	ds_read_b128 v[204:207], v8 offset:10384
	s_waitcnt lgkmcnt(6)
	v_pk_fma_f32 v[230:231], v[208:209], v[100:101], v[230:231] neg_lo:[1,0,0] neg_hi:[1,0,0]
	v_pk_fma_f32 v[230:231], v[210:211], v[102:103], v[230:231] neg_lo:[1,0,0] neg_hi:[1,0,0]
	ds_read_b128 v[208:211], v8 offset:10496
	s_waitcnt lgkmcnt(6)
	v_pk_fma_f32 v[230:231], v[212:213], v[104:105], v[230:231] neg_lo:[1,0,0] neg_hi:[1,0,0]
	v_pk_fma_f32 v[230:231], v[214:215], v[106:107], v[230:231] neg_lo:[1,0,0] neg_hi:[1,0,0]
	ds_read_b128 v[212:215], v8 offset:10512
	s_waitcnt lgkmcnt(5)
	v_pk_fma_f32 v[230:231], v[192:193], v[108:109], v[230:231] neg_lo:[1,0,0] neg_hi:[1,0,0]
	v_pk_fma_f32 v[230:231], v[194:195], v[110:111], v[230:231] neg_lo:[1,0,0] neg_hi:[1,0,0]
	ds_read_b128 v[192:195], v8 offset:10528
	s_waitcnt lgkmcnt(5)
	v_pk_fma_f32 v[230:231], v[196:197], v[112:113], v[230:231] neg_lo:[1,0,0] neg_hi:[1,0,0]
	v_pk_fma_f32 v[230:231], v[198:199], v[114:115], v[230:231] neg_lo:[1,0,0] neg_hi:[1,0,0]
	ds_read_b128 v[196:199], v8 offset:10544
	s_waitcnt lgkmcnt(5)
	v_pk_fma_f32 v[230:231], v[200:201], v[116:117], v[230:231] neg_lo:[1,0,0] neg_hi:[1,0,0]
	v_pk_fma_f32 v[230:231], v[202:203], v[118:119], v[230:231] neg_lo:[1,0,0] neg_hi:[1,0,0]
	ds_read_b128 v[200:203], v8 offset:10560
	s_waitcnt lgkmcnt(5)
	v_pk_fma_f32 v[230:231], v[204:205], v[120:121], v[230:231] neg_lo:[1,0,0] neg_hi:[1,0,0]
	v_pk_fma_f32 v[230:231], v[206:207], v[122:123], v[230:231] neg_lo:[1,0,0] neg_hi:[1,0,0]
	ds_read_b128 v[204:207], v8 offset:10576
	v_add_f32_e32 v124, v230, v231
	s_cbranch_vccz .Ls4_u40
	v_cvt_pk_bf16_f32 v233, -v124, v124
	global_store_short v6, v233, s[8:9] offset:2048
	s_branch .Ls4_n40

; #define LAS __attribute__((address_space(3)))
; __device__ __forceinline__ float bf2f(unsigned short x) { return __uint_as_float(((unsigned)x) << 16); }
; __device__ __forceinline__ void chunk_prep_phase(const Params& p, int bid, int nblk, LAS unsigned char* lds0) {
;     ...
;             { const float br = betg[41]; ab0 = (f32x2){bf2f(*(const LAS bf16_t*)(lg + P5_VS + 11152 + c * 2)) * br, bf2f(*(const LAS bf16_t*)(lg + P5_KS + 11152 + c * 2)) * br * __expf(decg[41])}; ab1 = (f32x2){0.f, 0.f}; } ab0 -= mq[4][0] * xy[0]; ab1 -= mq[4][1] * xy[1]; ab0 -= mq[4][2] * xy[2]; ab1 -= mq[4][3] * xy[3]; mq[4] = *(const LAS f32x4*)(Mg + 2648);
;             ab0 -= mq[5][0] * xy[4]; ab1 -= mq[5][1] * xy[5]; ab0 -= mq[5][2] * xy[6]; ab1 -= mq[5][3] * xy[7]; mq[5] = *(const LAS f32x4*)(Mg + 2652);
;             ab0 -= mq[0][0] * xy[8]; ab1 -= mq[0][1] * xy[9]; ab0 -= mq[0][2] * xy[10]; ab1 -= mq[0][3] * xy[11]; mq[0] = *(const LAS f32x4*)(Mg + 2656);
;             ab0 -= mq[1][0] * xy[12]; ab1 -= mq[1][1] * xy[13]; ab0 -= mq[1][2] * xy[14]; ab1 -= mq[1][3] * xy[15]; mq[1] = *(const LAS f32x4*)(Mg + 2660);
;             ab0 -= mq[2][0] * xy[16]; ab1 -= mq[2][1] * xy[17]; ab0 -= mq[2][2] * xy[18]; ab1 -= mq[2][3] * xy[19]; mq[2] = *(const LAS f32x4*)(Mg + 2664);
;             ab0 -= mq[3][0] * xy[20]; ab1 -= mq[3][1] * xy[21]; ab0 -= mq[3][2] * xy[22]; ab1 -= mq[3][3] * xy[23]; mq[3] = *(const LAS f32x4*)(Mg + 2688);
;             ab0 -= mq[4][0] * xy[24]; ab1 -= mq[4][1] * xy[25]; ab0 -= mq[4][2] * xy[26]; ab1 -= mq[4][3] * xy[27]; mq[4] = *(const LAS f32x4*)(Mg + 2692);
;             ab0 -= mq[5][0] * xy[28]; ab1 -= mq[5][1] * xy[29]; ab0 -= mq[5][2] * xy[30]; ab1 -= mq[5][3] * xy[31]; mq[5] = *(const LAS f32x4*)(Mg + 2696);
;             ab0 -= mq[0][0] * xy[32]; ab1 -= mq[0][1] * xy[33]; ab0 -= mq[0][2] * xy[34]; ab1 -= mq[0][3] * xy[35]; mq[0] = *(const LAS f32x4*)(Mg + 2700);
;             ab0 -= mq[1][0] * xy[36]; ab1 -= mq[1][1] * xy[37]; ab0 -= mq[1][2] * xy[38]; ab1 -= mq[1][3] * xy[39]; mq[1] = *(const LAS f32x4*)(Mg + 2704);
;             ab0 -= mq[2][0] * xy[40]; xy[41] = ab0 + ab1; up[5248] = xy[41][0]; wp[5248] = f2bf(-xy[41][1]); mq[2] = *(const LAS f32x4*)(Mg + 2708);
.Ls4_n40:
	v_lshlrev_b32_e32 v229, 16, v229
	v_mul_f32_e32 v232, v229, v217
	v_mul_f32_e32 v230, v232, v1
	v_mov_b32_e32 v231, 0
	ds_read_u16 v228, v7 offset:11424
	s_waitcnt lgkmcnt(6)
	v_pk_fma_f32 v[230:231], v[208:209], v[84:85], v[230:231] neg_lo:[1,0,0] neg_hi:[1,0,0]
	v_pk_fma_f32 v[230:231], v[210:211], v[86:87], v[230:231] neg_lo:[1,0,0] neg_hi:[1,0,0]
	ds_read_b128 v[208:211], v8 offset:10592
	s_waitcnt lgkmcnt(6)
	v_pk_fma_f32 v[230:231], v[212:213], v[88:89], v[230:231] neg_lo:[1,0,0] neg_hi:[1,0,0]
	v_pk_fma_f32 v[230:231], v[214:215], v[90:91], v[230:231] neg_lo:[1,0,0] neg_hi:[1,0,0]
	ds_read_b128 v[212:215], v8 offset:10608
	s_waitcnt lgkmcnt(6)
	v_pk_fma_f32 v[230:231], v[192:193], v[92:93], v[230:231] neg_lo:[1,0,0] neg_hi:[1,0,0]
	v_pk_fma_f32 v[230:231], v[194:195], v[94:95], v[230:231] neg_lo:[1,0,0] neg_hi:[1,0,0]
	ds_read_b128 v[192:195], v8 offset:10624
	s_waitcnt lgkmcnt(6)
	v_pk_fma_f32 v[230:231], v[196:197], v[96:97], v[230:231] neg_lo:[1,0,0] neg_hi:[1,0,0]
	v_pk_fma_f32 v[230:231], v[198:199], v[98:99], v[230:231] neg_lo:[1,0,0] neg_hi:[1,0,0]
	ds_read_b128 v[196:199], v8 offset:10640
	s_waitcnt lgkmcnt(6)
	v_pk_fma_f32 v[230:231], v[200:201], v[100:101], v[230:231] neg_lo:[1,0,0] neg_hi:[1,0,0]
	v_pk_fma_f32 v[230:231], v[202:203], v[102:103], v[230:231] neg_lo:[1,0,0] neg_hi:[1,0,0]
	ds_read_b128 v[200:203], v8 offset:10656
	s_waitcnt lgkmcnt(6)
	v_pk_fma_f32 v[230:231], v[204:205], v[104:105], v[230:231] neg_lo:[1,0,0] neg_hi:[1,0,0]
	v_pk_fma_f32 v[230:231], v[206:207], v[106:107], v[230:231] neg_lo:[1,0,0] neg_hi:[1,0,0]
	ds_read_b128 v[204:207], v8 offset:10752
	s_waitcnt lgkmcnt(5)
	v_pk_fma_f32 v[230:231], v[208:209], v[108:109], v[230:231] neg_lo:[1,0,0] neg_hi:[1,0,0]
	v_pk_fma_f32 v[230:231], v[210:211], v[110:111], v[230:231] neg_lo:[1,0,0] neg_hi:[1,0,0]
	ds_read_b128 v[208:211], v8 offset:10768
	s_waitcnt lgkmcnt(5)
	v_pk_fma_f32 v[230:231], v[212:213], v[112:113], v[230:231] neg_lo:[1,0,0] neg_hi:[1,0,0]
	v_pk_fma_f32 v[230:231], v[214:215], v[114:115], v[230:231] neg_lo:[1,0,0] neg_hi:[1,0,0]
	ds_read_b128 v[212:215], v8 offset:10784
	s_waitcnt lgkmcnt(5)
	v_pk_fma_f32 v[230:231], v[192:193], v[116:117], v[230:231] neg_lo:[1,0,0] neg_hi:[1,0,0]
	v_pk_fma_f32 v[230:231], v[194:195], v[118:119], v[230:231] neg_lo:[1,0,0] neg_hi:[1,0,0]
	ds_read_b128 v[192:195], v8 offset:10800
	s_waitcnt lgkmcnt(5)
	v_pk_fma_f32 v[230:231], v[196:197], v[120:121], v[230:231] neg_lo:[1,0,0] neg_hi:[1,0,0]
	v_pk_fma_f32 v[230:231], v[198:199], v[122:123], v[230:231] neg_lo:[1,0,0] neg_hi:[1,0,0]
	ds_read_b128 v[196:199], v8 offset:10816
	s_waitcnt lgkmcnt(5)
	v_fma_f32 v230, -v200, v124, v230
	ds_read_b128 v[200:203], v8 offset:10832
	v_add_f32_e32 v125, v230, v231
	s_cbranch_vccz .Ls4_u41
	v_cvt_pk_bf16_f32 v233, -v125, v125
	global_store_short v6, v233, s[8:9] offset:2304
	s_branch .Ls4_n41

; #define LAS __attribute__((address_space(3)))
; __device__ __forceinline__ float bf2f(unsigned short x) { return __uint_as_float(((unsigned)x) << 16); }
; __device__ __forceinline__ void chunk_prep_phase(const Params& p, int bid, int nblk, LAS unsigned char* lds0) {
;     ...
;             { const float br = betg[42]; ab0 = (f32x2){bf2f(*(const LAS bf16_t*)(lg + P5_VS + 11424 + c * 2)) * br, bf2f(*(const LAS bf16_t*)(lg + P5_KS + 11424 + c * 2)) * br * __expf(decg[42])}; ab1 = (f32x2){0.f, 0.f}; } ab0 -= mq[3][0] * xy[0]; ab1 -= mq[3][1] * xy[1]; ab0 -= mq[3][2] * xy[2]; ab1 -= mq[3][3] * xy[3]; mq[3] = *(const LAS f32x4*)(Mg + 2712);
;             ab0 -= mq[4][0] * xy[4]; ab1 -= mq[4][1] * xy[5]; ab0 -= mq[4][2] * xy[6]; ab1 -= mq[4][3] * xy[7]; mq[4] = *(const LAS f32x4*)(Mg + 2716);
;             ab0 -= mq[5][0] * xy[8]; ab1 -= mq[5][1] * xy[9]; ab0 -= mq[5][2] * xy[10]; ab1 -= mq[5][3] * xy[11]; mq[5] = *(const LAS f32x4*)(Mg + 2720);
;             ab0 -= mq[0][0] * xy[12]; ab1 -= mq[0][1] * xy[13]; ab0 -= mq[0][2] * xy[14]; ab1 -= mq[0][3] * xy[15]; mq[0] = *(const LAS f32x4*)(Mg + 2724);
;             ab0 -= mq[1][0] * xy[16]; ab1 -= mq[1][1] * xy[17]; ab0 -= mq[1][2] * xy[18]; ab1 -= mq[1][3] * xy[19]; mq[1] = *(const LAS f32x4*)(Mg + 2728);
;             ab0 -= mq[2][0] * xy[20]; ab1 -= mq[2][1] * xy[21]; ab0 -= mq[2][2] * xy[22]; ab1 -= mq[2][3] * xy[23]; mq[2] = *(const LAS f32x4*)(Mg + 2752);
;             ab0 -= mq[3][0] * xy[24]; ab1 -= mq[3][1] * xy[25]; ab0 -= mq[3][2] * xy[26]; ab1 -= mq[3][3] * xy[27]; mq[3] = *(const LAS f32x4*)(Mg + 2756);
;             ab0 -= mq[4][0] * xy[28]; ab1 -= mq[4][1] * xy[29]; ab0 -= mq[4][2] * xy[30]; ab1 -= mq[4][3] * xy[31]; mq[4] = *(const LAS f32x4*)(Mg + 2760);
;             ab0 -= mq[5][0] * xy[32]; ab1 -= mq[5][1] * xy[33]; ab0 -= mq[5][2] * xy[34]; ab1 -= mq[5][3] * xy[35]; mq[5] = *(const LAS f32x4*)(Mg + 2764);
;             ab0 -= mq[0][0] * xy[36]; ab1 -= mq[0][1] * xy[37]; ab0 -= mq[0][2] * xy[38]; ab1 -= mq[0][3] * xy[39]; mq[0] = *(const LAS f32x4*)(Mg + 2768);
;             ab0 -= mq[1][0] * xy[40]; ab1 -= mq[1][1] * xy[41]; xy[42] = ab0 + ab1; up[5376] = xy[42][0]; wp[5376] = f2bf(-xy[42][1]); mq[1] = *(const LAS f32x4*)(Mg + 2772);
.Ls4_n41:
	v_lshlrev_b32_e32 v228, 16, v228
	v_mul_f32_e32 v232, v228, v218
	v_mul_f32_e32 v230, v232, v2
	v_mov_b32_e32 v231, 0
	ds_read_u16 v229, v7 offset:11696
	s_waitcnt lgkmcnt(6)
	v_pk_fma_f32 v[230:231], v[204:205], v[84:85], v[230:231] neg_lo:[1,0,0] neg_hi:[1,0,0]
	v_pk_fma_f32 v[230:231], v[206:207], v[86:87], v[230:231] neg_lo:[1,0,0] neg_hi:[1,0,0]
	ds_read_b128 v[204:207], v8 offset:10848
	s_waitcnt lgkmcnt(6)
	v_pk_fma_f32 v[230:231], v[208:209], v[88:89], v[230:231] neg_lo:[1,0,0] neg_hi:[1,0,0]
	v_pk_fma_f32 v[230:231], v[210:211], v[90:91], v[230:231] neg_lo:[1,0,0] neg_hi:[1,0,0]
	ds_read_b128 v[208:211], v8 offset:10864
	s_waitcnt lgkmcnt(6)
	v_pk_fma_f32 v[230:231], v[212:213], v[92:93], v[230:231] neg_lo:[1,0,0] neg_hi:[1,0,0]
	v_pk_fma_f32 v[230:231], v[214:215], v[94:95], v[230:231] neg_lo:[1,0,0] neg_hi:[1,0,0]
	ds_read_b128 v[212:215], v8 offset:10880
	s_waitcnt lgkmcnt(6)
	v_pk_fma_f32 v[230:231], v[192:193], v[96:97], v[230:231] neg_lo:[1,0,0] neg_hi:[1,0,0]
	v_pk_fma_f32 v[230:231], v[194:195], v[98:99], v[230:231] neg_lo:[1,0,0] neg_hi:[1,0,0]
	ds_read_b128 v[192:195], v8 offset:10896
	s_waitcnt lgkmcnt(6)
	v_pk_fma_f32 v[230:231], v[196:197], v[100:101], v[230:231] neg_lo:[1,0,0] neg_hi:[1,0,0]
	v_pk_fma_f32 v[230:231], v[198:199], v[102:103], v[230:231] neg_lo:[1,0,0] neg_hi:[1,0,0]
	ds_read_b128 v[196:199], v8 offset:10912
	s_waitcnt lgkmcnt(6)
	v_pk_fma_f32 v[230:231], v[200:201], v[104:105], v[230:231] neg_lo:[1,0,0] neg_hi:[1,0,0]
	v_pk_fma_f32 v[230:231], v[202:203], v[106:107], v[230:231] neg_lo:[1,0,0] neg_hi:[1,0,0]
	ds_read_b128 v[200:203], v8 offset:11008
	s_waitcnt lgkmcnt(5)
	v_pk_fma_f32 v[230:231], v[204:205], v[108:109], v[230:231] neg_lo:[1,0,0] neg_hi:[1,0,0]
	v_pk_fma_f32 v[230:231], v[206:207], v[110:111], v[230:231] neg_lo:[1,0,0] neg_hi:[1,0,0]
	ds_read_b128 v[204:207], v8 offset:11024
	s_waitcnt lgkmcnt(5)
	v_pk_fma_f32 v[230:231], v[208:209], v[112:113], v[230:231] neg_lo:[1,0,0] neg_hi:[1,0,0]
	v_pk_fma_f32 v[230:231], v[210:211], v[114:115], v[230:231] neg_lo:[1,0,0] neg_hi:[1,0,0]
	ds_read_b128 v[208:211], v8 offset:11040
	s_waitcnt lgkmcnt(5)
	v_pk_fma_f32 v[230:231], v[212:213], v[116:117], v[230:231] neg_lo:[1,0,0] neg_hi:[1,0,0]
	v_pk_fma_f32 v[230:231], v[214:215], v[118:119], v[230:231] neg_lo:[1,0,0] neg_hi:[1,0,0]
	ds_read_b128 v[212:215], v8 offset:11056
	s_waitcnt lgkmcnt(5)
	v_pk_fma_f32 v[230:231], v[192:193], v[120:121], v[230:231] neg_lo:[1,0,0] neg_hi:[1,0,0]
	v_pk_fma_f32 v[230:231], v[194:195], v[122:123], v[230:231] neg_lo:[1,0,0] neg_hi:[1,0,0]
	ds_read_b128 v[192:195], v8 offset:11072
	s_waitcnt lgkmcnt(5)
	v_pk_fma_f32 v[230:231], v[196:197], v[124:125], v[230:231] neg_lo:[1,0,0] neg_hi:[1,0,0]
	ds_read_b128 v[196:199], v8 offset:11088
	v_add_f32_e32 v126, v230, v231
	s_cbranch_vccz .Ls4_u42
	v_cvt_pk_bf16_f32 v233, -v126, v126
	global_store_short v6, v233, s[8:9] offset:2560
	s_branch .Ls4_n42

; #define LAS __attribute__((address_space(3)))
; __device__ __forceinline__ float bf2f(unsigned short x) { return __uint_as_float(((unsigned)x) << 16); }
; __device__ __forceinline__ void chunk_prep_phase(const Params& p, int bid, int nblk, LAS unsigned char* lds0) {
;     ...
;             { const float br = betg[43]; ab0 = (f32x2){bf2f(*(const LAS bf16_t*)(lg + P5_VS + 11696 + c * 2)) * br, bf2f(*(const LAS bf16_t*)(lg + P5_KS + 11696 + c * 2)) * br * __expf(decg[43])}; ab1 = (f32x2){0.f, 0.f}; } ab0 -= mq[2][0] * xy[0]; ab1 -= mq[2][1] * xy[1]; ab0 -= mq[2][2] * xy[2]; ab1 -= mq[2][3] * xy[3]; mq[2] = *(const LAS f32x4*)(Mg + 2776);
;             ab0 -= mq[3][0] * xy[4]; ab1 -= mq[3][1] * xy[5]; ab0 -= mq[3][2] * xy[6]; ab1 -= mq[3][3] * xy[7]; mq[3] = *(const LAS f32x4*)(Mg + 2780);
;             ab0 -= mq[4][0] * xy[8]; ab1 -= mq[4][1] * xy[9]; ab0 -= mq[4][2] * xy[10]; ab1 -= mq[4][3] * xy[11]; mq[4] = *(const LAS f32x4*)(Mg + 2784);
;             ab0 -= mq[5][0] * xy[12]; ab1 -= mq[5][1] * xy[13]; ab0 -= mq[5][2] * xy[14]; ab1 -= mq[5][3] * xy[15]; mq[5] = *(const LAS f32x4*)(Mg + 2788);
;             ab0 -= mq[0][0] * xy[16]; ab1 -= mq[0][1] * xy[17]; ab0 -= mq[0][2] * xy[18]; ab1 -= mq[0][3] * xy[19]; mq[0] = *(const LAS f32x4*)(Mg + 2792);
;             ab0 -= mq[1][0] * xy[20]; ab1 -= mq[1][1] * xy[21]; ab0 -= mq[1][2] * xy[22]; ab1 -= mq[1][3] * xy[23]; mq[1] = *(const LAS f32x4*)(Mg + 2816);
;             ab0 -= mq[2][0] * xy[24]; ab1 -= mq[2][1] * xy[25]; ab0 -= mq[2][2] * xy[26]; ab1 -= mq[2][3] * xy[27]; mq[2] = *(const LAS f32x4*)(Mg + 2820);
;             ab0 -= mq[3][0] * xy[28]; ab1 -= mq[3][1] * xy[29]; ab0 -= mq[3][2] * xy[30]; ab1 -= mq[3][3] * xy[31]; mq[3] = *(const LAS f32x4*)(Mg + 2824);
;             ab0 -= mq[4][0] * xy[32]; ab1 -= mq[4][1] * xy[33]; ab0 -= mq[4][2] * xy[34]; ab1 -= mq[4][3] * xy[35]; mq[4] = *(const LAS f32x4*)(Mg + 2828);
;             ab0 -= mq[5][0] * xy[36]; ab1 -= mq[5][1] * xy[37]; ab0 -= mq[5][2] * xy[38]; ab1 -= mq[5][3] * xy[39]; mq[5] = *(const LAS f32x4*)(Mg + 2832);
;             ab0 -= mq[0][0] * xy[40]; ab1 -= mq[0][1] * xy[41]; ab0 -= mq[0][2] * xy[42]; xy[43] = ab0 + ab1; up[5504] = xy[43][0]; wp[5504] = f2bf(-xy[43][1]); mq[0] = *(const LAS f32x4*)(Mg + 2836);
.Ls4_n42:
	v_lshlrev_b32_e32 v229, 16, v229
	v_mul_f32_e32 v232, v229, v219
	v_mul_f32_e32 v230, v232, v3
	v_mov_b32_e32 v231, 0
	ds_read_u16 v228, v7 offset:11968
	ds_read_b128 v[216:219], v8 offset:16832
	ds_read_b128 v[0:3], v8 offset:16576
	s_waitcnt lgkmcnt(8)
	v_pk_fma_f32 v[230:231], v[200:201], v[84:85], v[230:231] neg_lo:[1,0,0] neg_hi:[1,0,0]
	v_pk_fma_f32 v[230:231], v[202:203], v[86:87], v[230:231] neg_lo:[1,0,0] neg_hi:[1,0,0]
	ds_read_b128 v[200:203], v8 offset:11104
	s_waitcnt lgkmcnt(8)
	v_pk_fma_f32 v[230:231], v[204:205], v[88:89], v[230:231] neg_lo:[1,0,0] neg_hi:[1,0,0]
	v_pk_fma_f32 v[230:231], v[206:207], v[90:91], v[230:231] neg_lo:[1,0,0] neg_hi:[1,0,0]
	ds_read_b128 v[204:207], v8 offset:11120
	s_waitcnt lgkmcnt(8)
	v_pk_fma_f32 v[230:231], v[208:209], v[92:93], v[230:231] neg_lo:[1,0,0] neg_hi:[1,0,0]
	v_pk_fma_f32 v[230:231], v[210:211], v[94:95], v[230:231] neg_lo:[1,0,0] neg_hi:[1,0,0]
	ds_read_b128 v[208:211], v8 offset:11136
	s_waitcnt lgkmcnt(8)
	v_pk_fma_f32 v[230:231], v[212:213], v[96:97], v[230:231] neg_lo:[1,0,0] neg_hi:[1,0,0]
	v_pk_fma_f32 v[230:231], v[214:215], v[98:99], v[230:231] neg_lo:[1,0,0] neg_hi:[1,0,0]
	ds_read_b128 v[212:215], v8 offset:11152
	s_waitcnt lgkmcnt(8)
	v_pk_fma_f32 v[230:231], v[192:193], v[100:101], v[230:231] neg_lo:[1,0,0] neg_hi:[1,0,0]
	v_pk_fma_f32 v[230:231], v[194:195], v[102:103], v[230:231] neg_lo:[1,0,0] neg_hi:[1,0,0]
	ds_read_b128 v[192:195], v8 offset:11168
	s_waitcnt lgkmcnt(8)
	v_pk_fma_f32 v[230:231], v[196:197], v[104:105], v[230:231] neg_lo:[1,0,0] neg_hi:[1,0,0]
	v_pk_fma_f32 v[230:231], v[198:199], v[106:107], v[230:231] neg_lo:[1,0,0] neg_hi:[1,0,0]
	ds_read_b128 v[196:199], v8 offset:11264
	s_waitcnt lgkmcnt(5)
	v_pk_fma_f32 v[230:231], v[200:201], v[108:109], v[230:231] neg_lo:[1,0,0] neg_hi:[1,0,0]
	v_pk_fma_f32 v[230:231], v[202:203], v[110:111], v[230:231] neg_lo:[1,0,0] neg_hi:[1,0,0]
	ds_read_b128 v[200:203], v8 offset:11280
	s_waitcnt lgkmcnt(5)
	v_pk_fma_f32 v[230:231], v[204:205], v[112:113], v[230:231] neg_lo:[1,0,0] neg_hi:[1,0,0]
	v_pk_fma_f32 v[230:231], v[206:207], v[114:115], v[230:231] neg_lo:[1,0,0] neg_hi:[1,0,0]
	ds_read_b128 v[204:207], v8 offset:11296
	s_waitcnt lgkmcnt(5)
	v_pk_fma_f32 v[230:231], v[208:209], v[116:117], v[230:231] neg_lo:[1,0,0] neg_hi:[1,0,0]
	v_pk_fma_f32 v[230:231], v[210:211], v[118:119], v[230:231] neg_lo:[1,0,0] neg_hi:[1,0,0]
	ds_read_b128 v[208:211], v8 offset:11312
	s_waitcnt lgkmcnt(5)
	v_pk_fma_f32 v[230:231], v[212:213], v[120:121], v[230:231] neg_lo:[1,0,0] neg_hi:[1,0,0]
	v_pk_fma_f32 v[230:231], v[214:215], v[122:123], v[230:231] neg_lo:[1,0,0] neg_hi:[1,0,0]
	ds_read_b128 v[212:215], v8 offset:11328
	s_waitcnt lgkmcnt(5)
	v_pk_fma_f32 v[230:231], v[192:193], v[124:125], v[230:231] neg_lo:[1,0,0] neg_hi:[1,0,0]
	v_fma_f32 v230, -v194, v126, v230
	ds_read_b128 v[192:195], v8 offset:11344
	v_add_f32_e32 v127, v230, v231
	s_cbranch_vccz .Ls4_u43
	v_cvt_pk_bf16_f32 v233, -v127, v127
	global_store_short v6, v233, s[8:9] offset:2816
	s_branch .Ls4_n43

; #define LAS __attribute__((address_space(3)))
; __device__ __forceinline__ float bf2f(unsigned short x) { return __uint_as_float(((unsigned)x) << 16); }
; __device__ __forceinline__ void chunk_prep_phase(const Params& p, int bid, int nblk, LAS unsigned char* lds0) {
;     ...
;             { const float br = betg[44]; ab0 = (f32x2){bf2f(*(const LAS bf16_t*)(lg + P5_VS + 11968 + c * 2)) * br, bf2f(*(const LAS bf16_t*)(lg + P5_KS + 11968 + c * 2)) * br * __expf(decg[44])}; ab1 = (f32x2){0.f, 0.f}; } ab0 -= mq[1][0] * xy[0]; ab1 -= mq[1][1] * xy[1]; ab0 -= mq[1][2] * xy[2]; ab1 -= mq[1][3] * xy[3]; mq[1] = *(const LAS f32x4*)(Mg + 2840);
;             ab0 -= mq[2][0] * xy[4]; ab1 -= mq[2][1] * xy[5]; ab0 -= mq[2][2] * xy[6]; ab1 -= mq[2][3] * xy[7]; mq[2] = *(const LAS f32x4*)(Mg + 2844);
;             ab0 -= mq[3][0] * xy[8]; ab1 -= mq[3][1] * xy[9]; ab0 -= mq[3][2] * xy[10]; ab1 -= mq[3][3] * xy[11]; mq[3] = *(const LAS f32x4*)(Mg + 2848);
;             ab0 -= mq[4][0] * xy[12]; ab1 -= mq[4][1] * xy[13]; ab0 -= mq[4][2] * xy[14]; ab1 -= mq[4][3] * xy[15]; mq[4] = *(const LAS f32x4*)(Mg + 2852);
;             ab0 -= mq[5][0] * xy[16]; ab1 -= mq[5][1] * xy[17]; ab0 -= mq[5][2] * xy[18]; ab1 -= mq[5][3] * xy[19]; mq[5] = *(const LAS f32x4*)(Mg + 2856);
;             ab0 -= mq[0][0] * xy[20]; ab1 -= mq[0][1] * xy[21]; ab0 -= mq[0][2] * xy[22]; ab1 -= mq[0][3] * xy[23]; mq[0] = *(const LAS f32x4*)(Mg + 2880);
;             ab0 -= mq[1][0] * xy[24]; ab1 -= mq[1][1] * xy[25]; ab0 -= mq[1][2] * xy[26]; ab1 -= mq[1][3] * xy[27]; mq[1] = *(const LAS f32x4*)(Mg + 2884);
;             ab0 -= mq[2][0] * xy[28]; ab1 -= mq[2][1] * xy[29]; ab0 -= mq[2][2] * xy[30]; ab1 -= mq[2][3] * xy[31]; mq[2] = *(const LAS f32x4*)(Mg + 2888);
;             ab0 -= mq[3][0] * xy[32]; ab1 -= mq[3][1] * xy[33]; ab0 -= mq[3][2] * xy[34]; ab1 -= mq[3][3] * xy[35]; mq[3] = *(const LAS f32x4*)(Mg + 2892);
;             ab0 -= mq[4][0] * xy[36]; ab1 -= mq[4][1] * xy[37]; ab0 -= mq[4][2] * xy[38]; ab1 -= mq[4][3] * xy[39]; mq[4] = *(const LAS f32x4*)(Mg + 2896);
;             ab0 -= mq[5][0] * xy[40]; ab1 -= mq[5][1] * xy[41]; ab0 -= mq[5][2] * xy[42]; ab1 -= mq[5][3] * xy[43]; xy[44] = ab0 + ab1; up[5632] = xy[44][0]; wp[5632] = f2bf(-xy[44][1]); mq[5] = *(const LAS f32x4*)(Mg + 2900);
.Ls4_n43:
	v_mul_f32_e32 v224, s16, v224
	v_mul_f32_e32 v225, s16, v225
	v_mul_f32_e32 v226, s16, v226
	v_mul_f32_e32 v227, s16, v227
	v_exp_f32_e32 v224, v224
	v_exp_f32_e32 v225, v225
	v_exp_f32_e32 v226, v226
	v_exp_f32_e32 v227, v227
	s_nop 0
	v_lshlrev_b32_e32 v228, 16, v228
	v_mul_f32_e32 v232, v228, v220
	v_mul_f32_e32 v230, v232, v224
	v_mov_b32_e32 v231, 0
	ds_read_u16 v229, v7 offset:12240
	s_waitcnt lgkmcnt(6)
	v_pk_fma_f32 v[230:231], v[196:197], v[84:85], v[230:231] neg_lo:[1,0,0] neg_hi:[1,0,0]
	v_pk_fma_f32 v[230:231], v[198:199], v[86:87], v[230:231] neg_lo:[1,0,0] neg_hi:[1,0,0]
	ds_read_b128 v[196:199], v8 offset:11360
	s_waitcnt lgkmcnt(6)
	v_pk_fma_f32 v[230:231], v[200:201], v[88:89], v[230:231] neg_lo:[1,0,0] neg_hi:[1,0,0]
	v_pk_fma_f32 v[230:231], v[202:203], v[90:91], v[230:231] neg_lo:[1,0,0] neg_hi:[1,0,0]
	ds_read_b128 v[200:203], v8 offset:11376
	s_waitcnt lgkmcnt(6)
	v_pk_fma_f32 v[230:231], v[204:205], v[92:93], v[230:231] neg_lo:[1,0,0] neg_hi:[1,0,0]
	v_pk_fma_f32 v[230:231], v[206:207], v[94:95], v[230:231] neg_lo:[1,0,0] neg_hi:[1,0,0]
	ds_read_b128 v[204:207], v8 offset:11392
	s_waitcnt lgkmcnt(6)
	v_pk_fma_f32 v[230:231], v[208:209], v[96:97], v[230:231] neg_lo:[1,0,0] neg_hi:[1,0,0]
	v_pk_fma_f32 v[230:231], v[210:211], v[98:99], v[230:231] neg_lo:[1,0,0] neg_hi:[1,0,0]
	ds_read_b128 v[208:211], v8 offset:11408
	s_waitcnt lgkmcnt(6)
	v_pk_fma_f32 v[230:231], v[212:213], v[100:101], v[230:231] neg_lo:[1,0,0] neg_hi:[1,0,0]
	v_pk_fma_f32 v[230:231], v[214:215], v[102:103], v[230:231] neg_lo:[1,0,0] neg_hi:[1,0,0]
	ds_read_b128 v[212:215], v8 offset:11424
	s_waitcnt lgkmcnt(6)
	v_pk_fma_f32 v[230:231], v[192:193], v[104:105], v[230:231] neg_lo:[1,0,0] neg_hi:[1,0,0]
	v_pk_fma_f32 v[230:231], v[194:195], v[106:107], v[230:231] neg_lo:[1,0,0] neg_hi:[1,0,0]
	ds_read_b128 v[192:195], v8 offset:11520
	s_waitcnt lgkmcnt(5)
	v_pk_fma_f32 v[230:231], v[196:197], v[108:109], v[230:231] neg_lo:[1,0,0] neg_hi:[1,0,0]
	v_pk_fma_f32 v[230:231], v[198:199], v[110:111], v[230:231] neg_lo:[1,0,0] neg_hi:[1,0,0]
	ds_read_b128 v[196:199], v8 offset:11536
	s_waitcnt lgkmcnt(5)
	v_pk_fma_f32 v[230:231], v[200:201], v[112:113], v[230:231] neg_lo:[1,0,0] neg_hi:[1,0,0]
	v_pk_fma_f32 v[230:231], v[202:203], v[114:115], v[230:231] neg_lo:[1,0,0] neg_hi:[1,0,0]
	ds_read_b128 v[200:203], v8 offset:11552
	s_waitcnt lgkmcnt(5)
	v_pk_fma_f32 v[230:231], v[204:205], v[116:117], v[230:231] neg_lo:[1,0,0] neg_hi:[1,0,0]
	v_pk_fma_f32 v[230:231], v[206:207], v[118:119], v[230:231] neg_lo:[1,0,0] neg_hi:[1,0,0]
	ds_read_b128 v[204:207], v8 offset:11568
	s_waitcnt lgkmcnt(5)
	v_pk_fma_f32 v[230:231], v[208:209], v[120:121], v[230:231] neg_lo:[1,0,0] neg_hi:[1,0,0]
	v_pk_fma_f32 v[230:231], v[210:211], v[122:123], v[230:231] neg_lo:[1,0,0] neg_hi:[1,0,0]
	ds_read_b128 v[208:211], v8 offset:11584
	s_waitcnt lgkmcnt(5)
	v_pk_fma_f32 v[230:231], v[212:213], v[124:125], v[230:231] neg_lo:[1,0,0] neg_hi:[1,0,0]
	v_pk_fma_f32 v[230:231], v[214:215], v[126:127], v[230:231] neg_lo:[1,0,0] neg_hi:[1,0,0]
	ds_read_b128 v[212:215], v8 offset:11600
	v_add_f32_e32 v128, v230, v231
	s_cbranch_vccz .Ls4_u44
	v_cvt_pk_bf16_f32 v233, -v128, v128
	global_store_short v6, v233, s[8:9] offset:3072
	s_branch .Ls4_n44

; #define LAS __attribute__((address_space(3)))
; __device__ __forceinline__ float bf2f(unsigned short x) { return __uint_as_float(((unsigned)x) << 16); }
; __device__ __forceinline__ void chunk_prep_phase(const Params& p, int bid, int nblk, LAS unsigned char* lds0) {
;     ...
;             { const float br = betg[45]; ab0 = (f32x2){bf2f(*(const LAS bf16_t*)(lg + P5_VS + 12240 + c * 2)) * br, bf2f(*(const LAS bf16_t*)(lg + P5_KS + 12240 + c * 2)) * br * __expf(decg[45])}; ab1 = (f32x2){0.f, 0.f}; } ab0 -= mq[0][0] * xy[0]; ab1 -= mq[0][1] * xy[1]; ab0 -= mq[0][2] * xy[2]; ab1 -= mq[0][3] * xy[3]; mq[0] = *(const LAS f32x4*)(Mg + 2904);
;             ab0 -= mq[1][0] * xy[4]; ab1 -= mq[1][1] * xy[5]; ab0 -= mq[1][2] * xy[6]; ab1 -= mq[1][3] * xy[7]; mq[1] = *(const LAS f32x4*)(Mg + 2908);
;             ab0 -= mq[2][0] * xy[8]; ab1 -= mq[2][1] * xy[9]; ab0 -= mq[2][2] * xy[10]; ab1 -= mq[2][3] * xy[11]; mq[2] = *(const LAS f32x4*)(Mg + 2912);
;             ab0 -= mq[3][0] * xy[12]; ab1 -= mq[3][1] * xy[13]; ab0 -= mq[3][2] * xy[14]; ab1 -= mq[3][3] * xy[15]; mq[3] = *(const LAS f32x4*)(Mg + 2916);
;             ab0 -= mq[4][0] * xy[16]; ab1 -= mq[4][1] * xy[17]; ab0 -= mq[4][2] * xy[18]; ab1 -= mq[4][3] * xy[19]; mq[4] = *(const LAS f32x4*)(Mg + 2920);
;             ab0 -= mq[5][0] * xy[20]; ab1 -= mq[5][1] * xy[21]; ab0 -= mq[5][2] * xy[22]; ab1 -= mq[5][3] * xy[23]; mq[5] = *(const LAS f32x4*)(Mg + 2924);
;             ab0 -= mq[0][0] * xy[24]; ab1 -= mq[0][1] * xy[25]; ab0 -= mq[0][2] * xy[26]; ab1 -= mq[0][3] * xy[27]; mq[0] = *(const LAS f32x4*)(Mg + 2944);
;             ab0 -= mq[1][0] * xy[28]; ab1 -= mq[1][1] * xy[29]; ab0 -= mq[1][2] * xy[30]; ab1 -= mq[1][3] * xy[31]; mq[1] = *(const LAS f32x4*)(Mg + 2948);
;             ab0 -= mq[2][0] * xy[32]; ab1 -= mq[2][1] * xy[33]; ab0 -= mq[2][2] * xy[34]; ab1 -= mq[2][3] * xy[35]; mq[2] = *(const LAS f32x4*)(Mg + 2952);
;             ab0 -= mq[3][0] * xy[36]; ab1 -= mq[3][1] * xy[37]; ab0 -= mq[3][2] * xy[38]; ab1 -= mq[3][3] * xy[39]; mq[3] = *(const LAS f32x4*)(Mg + 2956);
;             ab0 -= mq[4][0] * xy[40]; ab1 -= mq[4][1] * xy[41]; ab0 -= mq[4][2] * xy[42]; ab1 -= mq[4][3] * xy[43]; mq[4] = *(const LAS f32x4*)(Mg + 2960);
;             ab0 -= mq[5][0] * xy[44]; xy[45] = ab0 + ab1; up[5760] = xy[45][0]; wp[5760] = f2bf(-xy[45][1]); mq[5] = *(const LAS f32x4*)(Mg + 2964);
.Ls4_n44:
	v_lshlrev_b32_e32 v229, 16, v229
	v_mul_f32_e32 v232, v229, v221
	v_mul_f32_e32 v230, v232, v225
	v_mov_b32_e32 v231, 0
	ds_read_u16 v228, v7 offset:12512
	s_waitcnt lgkmcnt(6)
	v_pk_fma_f32 v[230:231], v[192:193], v[84:85], v[230:231] neg_lo:[1,0,0] neg_hi:[1,0,0]
	v_pk_fma_f32 v[230:231], v[194:195], v[86:87], v[230:231] neg_lo:[1,0,0] neg_hi:[1,0,0]
	ds_read_b128 v[192:195], v8 offset:11616
	s_waitcnt lgkmcnt(6)
	v_pk_fma_f32 v[230:231], v[196:197], v[88:89], v[230:231] neg_lo:[1,0,0] neg_hi:[1,0,0]
	v_pk_fma_f32 v[230:231], v[198:199], v[90:91], v[230:231] neg_lo:[1,0,0] neg_hi:[1,0,0]
	ds_read_b128 v[196:199], v8 offset:11632
	s_waitcnt lgkmcnt(6)
	v_pk_fma_f32 v[230:231], v[200:201], v[92:93], v[230:231] neg_lo:[1,0,0] neg_hi:[1,0,0]
	v_pk_fma_f32 v[230:231], v[202:203], v[94:95], v[230:231] neg_lo:[1,0,0] neg_hi:[1,0,0]
	ds_read_b128 v[200:203], v8 offset:11648
	s_waitcnt lgkmcnt(6)
	v_pk_fma_f32 v[230:231], v[204:205], v[96:97], v[230:231] neg_lo:[1,0,0] neg_hi:[1,0,0]
	v_pk_fma_f32 v[230:231], v[206:207], v[98:99], v[230:231] neg_lo:[1,0,0] neg_hi:[1,0,0]
	ds_read_b128 v[204:207], v8 offset:11664
	s_waitcnt lgkmcnt(6)
	v_pk_fma_f32 v[230:231], v[208:209], v[100:101], v[230:231] neg_lo:[1,0,0] neg_hi:[1,0,0]
	v_pk_fma_f32 v[230:231], v[210:211], v[102:103], v[230:231] neg_lo:[1,0,0] neg_hi:[1,0,0]
	ds_read_b128 v[208:211], v8 offset:11680
	s_waitcnt lgkmcnt(6)
	v_pk_fma_f32 v[230:231], v[212:213], v[104:105], v[230:231] neg_lo:[1,0,0] neg_hi:[1,0,0]
	v_pk_fma_f32 v[230:231], v[214:215], v[106:107], v[230:231] neg_lo:[1,0,0] neg_hi:[1,0,0]
	ds_read_b128 v[212:215], v8 offset:11696
	s_waitcnt lgkmcnt(5)
	v_pk_fma_f32 v[230:231], v[192:193], v[108:109], v[230:231] neg_lo:[1,0,0] neg_hi:[1,0,0]
	v_pk_fma_f32 v[230:231], v[194:195], v[110:111], v[230:231] neg_lo:[1,0,0] neg_hi:[1,0,0]
	ds_read_b128 v[192:195], v8 offset:11776
	s_waitcnt lgkmcnt(5)
	v_pk_fma_f32 v[230:231], v[196:197], v[112:113], v[230:231] neg_lo:[1,0,0] neg_hi:[1,0,0]
	v_pk_fma_f32 v[230:231], v[198:199], v[114:115], v[230:231] neg_lo:[1,0,0] neg_hi:[1,0,0]
	ds_read_b128 v[196:199], v8 offset:11792
	s_waitcnt lgkmcnt(5)
	v_pk_fma_f32 v[230:231], v[200:201], v[116:117], v[230:231] neg_lo:[1,0,0] neg_hi:[1,0,0]
	v_pk_fma_f32 v[230:231], v[202:203], v[118:119], v[230:231] neg_lo:[1,0,0] neg_hi:[1,0,0]
	ds_read_b128 v[200:203], v8 offset:11808
	s_waitcnt lgkmcnt(5)
	v_pk_fma_f32 v[230:231], v[204:205], v[120:121], v[230:231] neg_lo:[1,0,0] neg_hi:[1,0,0]
	v_pk_fma_f32 v[230:231], v[206:207], v[122:123], v[230:231] neg_lo:[1,0,0] neg_hi:[1,0,0]
	ds_read_b128 v[204:207], v8 offset:11824
	s_waitcnt lgkmcnt(5)
	v_pk_fma_f32 v[230:231], v[208:209], v[124:125], v[230:231] neg_lo:[1,0,0] neg_hi:[1,0,0]
	v_pk_fma_f32 v[230:231], v[210:211], v[126:127], v[230:231] neg_lo:[1,0,0] neg_hi:[1,0,0]
	ds_read_b128 v[208:211], v8 offset:11840
	s_waitcnt lgkmcnt(5)
	v_fma_f32 v230, -v212, v128, v230
	ds_read_b128 v[212:215], v8 offset:11856
	v_add_f32_e32 v129, v230, v231
	s_cbranch_vccz .Ls4_u45
	v_cvt_pk_bf16_f32 v233, -v129, v129
	global_store_short v6, v233, s[8:9] offset:3328
	s_branch .Ls4_n45

; #define LAS __attribute__((address_space(3)))
; __device__ __forceinline__ float bf2f(unsigned short x) { return __uint_as_float(((unsigned)x) << 16); }
; __device__ __forceinline__ void chunk_prep_phase(const Params& p, int bid, int nblk, LAS unsigned char* lds0) {
;     ...
;             { const float br = betg[46]; ab0 = (f32x2){bf2f(*(const LAS bf16_t*)(lg + P5_VS + 12512 + c * 2)) * br, bf2f(*(const LAS bf16_t*)(lg + P5_KS + 12512 + c * 2)) * br * __expf(decg[46])}; ab1 = (f32x2){0.f, 0.f}; } ab0 -= mq[0][0] * xy[0]; ab1 -= mq[0][1] * xy[1]; ab0 -= mq[0][2] * xy[2]; ab1 -= mq[0][3] * xy[3]; mq[0] = *(const LAS f32x4*)(Mg + 2968);
;             ab0 -= mq[1][0] * xy[4]; ab1 -= mq[1][1] * xy[5]; ab0 -= mq[1][2] * xy[6]; ab1 -= mq[1][3] * xy[7]; mq[1] = *(const LAS f32x4*)(Mg + 2972);
;             ab0 -= mq[2][0] * xy[8]; ab1 -= mq[2][1] * xy[9]; ab0 -= mq[2][2] * xy[10]; ab1 -= mq[2][3] * xy[11]; mq[2] = *(const LAS f32x4*)(Mg + 2976);
;             ab0 -= mq[3][0] * xy[12]; ab1 -= mq[3][1] * xy[13]; ab0 -= mq[3][2] * xy[14]; ab1 -= mq[3][3] * xy[15]; mq[3] = *(const LAS f32x4*)(Mg + 2980);
;             ab0 -= mq[4][0] * xy[16]; ab1 -= mq[4][1] * xy[17]; ab0 -= mq[4][2] * xy[18]; ab1 -= mq[4][3] * xy[19]; mq[4] = *(const LAS f32x4*)(Mg + 2984);
;             ab0 -= mq[5][0] * xy[20]; ab1 -= mq[5][1] * xy[21]; ab0 -= mq[5][2] * xy[22]; ab1 -= mq[5][3] * xy[23]; mq[5] = *(const LAS f32x4*)(Mg + 2988);
;             ab0 -= mq[0][0] * xy[24]; ab1 -= mq[0][1] * xy[25]; ab0 -= mq[0][2] * xy[26]; ab1 -= mq[0][3] * xy[27]; mq[0] = *(const LAS f32x4*)(Mg + 3008);
;             ab0 -= mq[1][0] * xy[28]; ab1 -= mq[1][1] * xy[29]; ab0 -= mq[1][2] * xy[30]; ab1 -= mq[1][3] * xy[31]; mq[1] = *(const LAS f32x4*)(Mg + 3012);
;             ab0 -= mq[2][0] * xy[32]; ab1 -= mq[2][1] * xy[33]; ab0 -= mq[2][2] * xy[34]; ab1 -= mq[2][3] * xy[35]; mq[2] = *(const LAS f32x4*)(Mg + 3016);
;             ab0 -= mq[3][0] * xy[36]; ab1 -= mq[3][1] * xy[37]; ab0 -= mq[3][2] * xy[38]; ab1 -= mq[3][3] * xy[39]; mq[3] = *(const LAS f32x4*)(Mg + 3020);
;             ab0 -= mq[4][0] * xy[40]; ab1 -= mq[4][1] * xy[41]; ab0 -= mq[4][2] * xy[42]; ab1 -= mq[4][3] * xy[43]; mq[4] = *(const LAS f32x4*)(Mg + 3024);
;             ab0 -= mq[5][0] * xy[44]; ab1 -= mq[5][1] * xy[45]; xy[46] = ab0 + ab1; up[5888] = xy[46][0]; wp[5888] = f2bf(-xy[46][1]); mq[5] = *(const LAS f32x4*)(Mg + 3028);
.Ls4_n45:
	v_lshlrev_b32_e32 v228, 16, v228
	v_mul_f32_e32 v232, v228, v222
	v_mul_f32_e32 v230, v232, v226
	v_mov_b32_e32 v231, 0
	ds_read_u16 v229, v7 offset:12784
	s_waitcnt lgkmcnt(6)
	v_pk_fma_f32 v[230:231], v[192:193], v[84:85], v[230:231] neg_lo:[1,0,0] neg_hi:[1,0,0]
	v_pk_fma_f32 v[230:231], v[194:195], v[86:87], v[230:231] neg_lo:[1,0,0] neg_hi:[1,0,0]
	ds_read_b128 v[192:195], v8 offset:11872
	s_waitcnt lgkmcnt(6)
	v_pk_fma_f32 v[230:231], v[196:197], v[88:89], v[230:231] neg_lo:[1,0,0] neg_hi:[1,0,0]
	v_pk_fma_f32 v[230:231], v[198:199], v[90:91], v[230:231] neg_lo:[1,0,0] neg_hi:[1,0,0]
	ds_read_b128 v[196:199], v8 offset:11888
	s_waitcnt lgkmcnt(6)
	v_pk_fma_f32 v[230:231], v[200:201], v[92:93], v[230:231] neg_lo:[1,0,0] neg_hi:[1,0,0]
	v_pk_fma_f32 v[230:231], v[202:203], v[94:95], v[230:231] neg_lo:[1,0,0] neg_hi:[1,0,0]
	ds_read_b128 v[200:203], v8 offset:11904
	s_waitcnt lgkmcnt(6)
	v_pk_fma_f32 v[230:231], v[204:205], v[96:97], v[230:231] neg_lo:[1,0,0] neg_hi:[1,0,0]
	v_pk_fma_f32 v[230:231], v[206:207], v[98:99], v[230:231] neg_lo:[1,0,0] neg_hi:[1,0,0]
	ds_read_b128 v[204:207], v8 offset:11920
	s_waitcnt lgkmcnt(6)
	v_pk_fma_f32 v[230:231], v[208:209], v[100:101], v[230:231] neg_lo:[1,0,0] neg_hi:[1,0,0]
	v_pk_fma_f32 v[230:231], v[210:211], v[102:103], v[230:231] neg_lo:[1,0,0] neg_hi:[1,0,0]
	ds_read_b128 v[208:211], v8 offset:11936
	s_waitcnt lgkmcnt(6)
	v_pk_fma_f32 v[230:231], v[212:213], v[104:105], v[230:231] neg_lo:[1,0,0] neg_hi:[1,0,0]
	v_pk_fma_f32 v[230:231], v[214:215], v[106:107], v[230:231] neg_lo:[1,0,0] neg_hi:[1,0,0]
	ds_read_b128 v[212:215], v8 offset:11952
	s_waitcnt lgkmcnt(5)
	v_pk_fma_f32 v[230:231], v[192:193], v[108:109], v[230:231] neg_lo:[1,0,0] neg_hi:[1,0,0]
	v_pk_fma_f32 v[230:231], v[194:195], v[110:111], v[230:231] neg_lo:[1,0,0] neg_hi:[1,0,0]
	ds_read_b128 v[192:195], v8 offset:12032
	s_waitcnt lgkmcnt(5)
	v_pk_fma_f32 v[230:231], v[196:197], v[112:113], v[230:231] neg_lo:[1,0,0] neg_hi:[1,0,0]
	v_pk_fma_f32 v[230:231], v[198:199], v[114:115], v[230:231] neg_lo:[1,0,0] neg_hi:[1,0,0]
	ds_read_b128 v[196:199], v8 offset:12048
	s_waitcnt lgkmcnt(5)
	v_pk_fma_f32 v[230:231], v[200:201], v[116:117], v[230:231] neg_lo:[1,0,0] neg_hi:[1,0,0]
	v_pk_fma_f32 v[230:231], v[202:203], v[118:119], v[230:231] neg_lo:[1,0,0] neg_hi:[1,0,0]
	ds_read_b128 v[200:203], v8 offset:12064
	s_waitcnt lgkmcnt(5)
	v_pk_fma_f32 v[230:231], v[204:205], v[120:121], v[230:231] neg_lo:[1,0,0] neg_hi:[1,0,0]
	v_pk_fma_f32 v[230:231], v[206:207], v[122:123], v[230:231] neg_lo:[1,0,0] neg_hi:[1,0,0]
	ds_read_b128 v[204:207], v8 offset:12080
	s_waitcnt lgkmcnt(5)
	v_pk_fma_f32 v[230:231], v[208:209], v[124:125], v[230:231] neg_lo:[1,0,0] neg_hi:[1,0,0]
	v_pk_fma_f32 v[230:231], v[210:211], v[126:127], v[230:231] neg_lo:[1,0,0] neg_hi:[1,0,0]
	ds_read_b128 v[208:211], v8 offset:12096
	s_waitcnt lgkmcnt(5)
	v_pk_fma_f32 v[230:231], v[212:213], v[128:129], v[230:231] neg_lo:[1,0,0] neg_hi:[1,0,0]
	ds_read_b128 v[212:215], v8 offset:12112
	v_add_f32_e32 v130, v230, v231
	s_cbranch_vccz .Ls4_u46
	v_cvt_pk_bf16_f32 v233, -v130, v130
	global_store_short v6, v233, s[8:9] offset:3584
	s_branch .Ls4_n46

; #define LAS __attribute__((address_space(3)))
; __device__ __forceinline__ void chunk_prep_phase(const Params& p, int bid, int nblk, LAS unsigned char* lds0) {
;     ...
;             { const float br = betg[47]; ab0 = (f32x2){bf2f(*(const LAS bf16_t*)(lg + P5_VS + 12784 + c * 2)) * br, bf2f(*(const LAS bf16_t*)(lg + P5_KS + 12784 + c * 2)) * br * __expf(decg[47])}; ab1 = (f32x2){0.f, 0.f}; } ab0 -= mq[0][0] * xy[0]; ab1 -= mq[0][1] * xy[1]; ab0 -= mq[0][2] * xy[2]; ab1 -= mq[0][3] * xy[3]; mq[0] = *(const LAS f32x4*)(Mg + 3032);
;             ab0 -= mq[1][0] * xy[4]; ab1 -= mq[1][1] * xy[5]; ab0 -= mq[1][2] * xy[6]; ab1 -= mq[1][3] * xy[7]; mq[1] = *(const LAS f32x4*)(Mg + 3036);
;             ab0 -= mq[2][0] * xy[8]; ab1 -= mq[2][1] * xy[9]; ab0 -= mq[2][2] * xy[10]; ab1 -= mq[2][3] * xy[11]; mq[2] = *(const LAS f32x4*)(Mg + 3040);
;             ab0 -= mq[3][0] * xy[12]; ab1 -= mq[3][1] * xy[13]; ab0 -= mq[3][2] * xy[14]; ab1 -= mq[3][3] * xy[15]; mq[3] = *(const LAS f32x4*)(Mg + 3044);
;             ab0 -= mq[4][0] * xy[16]; ab1 -= mq[4][1] * xy[17]; ab0 -= mq[4][2] * xy[18]; ab1 -= mq[4][3] * xy[19]; mq[4] = *(const LAS f32x4*)(Mg + 3048);
;             ab0 -= mq[5][0] * xy[20]; ab1 -= mq[5][1] * xy[21]; ab0 -= mq[5][2] * xy[22]; ab1 -= mq[5][3] * xy[23]; mq[5] = *(const LAS f32x4*)(Mg + 3052);
;             ab0 -= mq[0][0] * xy[24]; ab1 -= mq[0][1] * xy[25]; ab0 -= mq[0][2] * xy[26]; ab1 -= mq[0][3] * xy[27]; mq[0] = *(const LAS f32x4*)(Mg + 3072);
;             ab0 -= mq[1][0] * xy[28]; ab1 -= mq[1][1] * xy[29]; ab0 -= mq[1][2] * xy[30]; ab1 -= mq[1][3] * xy[31]; mq[1] = *(const LAS f32x4*)(Mg + 3076);
;             ab0 -= mq[2][0] * xy[32]; ab1 -= mq[2][1] * xy[33]; ab0 -= mq[2][2] * xy[34]; ab1 -= mq[2][3] * xy[35]; mq[2] = *(const LAS f32x4*)(Mg + 3080);
;             ab0 -= mq[3][0] * xy[36]; ab1 -= mq[3][1] * xy[37]; ab0 -= mq[3][2] * xy[38]; ab1 -= mq[3][3] * xy[39]; mq[3] = *(const LAS f32x4*)(Mg + 3084);
;             ab0 -= mq[4][0] * xy[40]; ab1 -= mq[4][1] * xy[41]; ab0 -= mq[4][2] * xy[42]; ab1 -= mq[4][3] * xy[43]; mq[4] = *(const LAS f32x4*)(Mg + 3088);
;             ab0 -= mq[5][0] * xy[44]; ab1 -= mq[5][1] * xy[45]; ab0 -= mq[5][2] * xy[46]; xy[47] = ab0 + ab1; up[6016] = xy[47][0]; wp[6016] = f2bf(-xy[47][1]); mq[5] = *(const LAS f32x4*)(Mg + 3092);
.Ls4_n46:
	v_lshlrev_b32_e32 v229, 16, v229
	v_mul_f32_e32 v232, v229, v223
	v_mul_f32_e32 v230, v232, v227
	v_mov_b32_e32 v231, 0
	ds_read_u16 v228, v7 offset:13056
	ds_read_b128 v[220:223], v8 offset:16848
	ds_read_b128 v[224:227], v8 offset:16592
	s_waitcnt lgkmcnt(8)
	v_pk_fma_f32 v[230:231], v[192:193], v[84:85], v[230:231] neg_lo:[1,0,0] neg_hi:[1,0,0]
	v_pk_fma_f32 v[230:231], v[194:195], v[86:87], v[230:231] neg_lo:[1,0,0] neg_hi:[1,0,0]
	ds_read_b128 v[192:195], v8 offset:12128
	s_waitcnt lgkmcnt(8)
	v_pk_fma_f32 v[230:231], v[196:197], v[88:89], v[230:231] neg_lo:[1,0,0] neg_hi:[1,0,0]
	v_pk_fma_f32 v[230:231], v[198:199], v[90:91], v[230:231] neg_lo:[1,0,0] neg_hi:[1,0,0]
	ds_read_b128 v[196:199], v8 offset:12144
	s_waitcnt lgkmcnt(8)
	v_pk_fma_f32 v[230:231], v[200:201], v[92:93], v[230:231] neg_lo:[1,0,0] neg_hi:[1,0,0]
	v_pk_fma_f32 v[230:231], v[202:203], v[94:95], v[230:231] neg_lo:[1,0,0] neg_hi:[1,0,0]
	ds_read_b128 v[200:203], v8 offset:12160
	s_waitcnt lgkmcnt(8)
	v_pk_fma_f32 v[230:231], v[204:205], v[96:97], v[230:231] neg_lo:[1,0,0] neg_hi:[1,0,0]
	v_pk_fma_f32 v[230:231], v[206:207], v[98:99], v[230:231] neg_lo:[1,0,0] neg_hi:[1,0,0]
	ds_read_b128 v[204:207], v8 offset:12176
	s_waitcnt lgkmcnt(8)
	v_pk_fma_f32 v[230:231], v[208:209], v[100:101], v[230:231] neg_lo:[1,0,0] neg_hi:[1,0,0]
	v_pk_fma_f32 v[230:231], v[210:211], v[102:103], v[230:231] neg_lo:[1,0,0] neg_hi:[1,0,0]
	ds_read_b128 v[208:211], v8 offset:12192
	s_waitcnt lgkmcnt(8)
	v_pk_fma_f32 v[230:231], v[212:213], v[104:105], v[230:231] neg_lo:[1,0,0] neg_hi:[1,0,0]
	v_pk_fma_f32 v[230:231], v[214:215], v[106:107], v[230:231] neg_lo:[1,0,0] neg_hi:[1,0,0]
	ds_read_b128 v[212:215], v8 offset:12208
	s_waitcnt lgkmcnt(5)
	v_pk_fma_f32 v[230:231], v[192:193], v[108:109], v[230:231] neg_lo:[1,0,0] neg_hi:[1,0,0]
	v_pk_fma_f32 v[230:231], v[194:195], v[110:111], v[230:231] neg_lo:[1,0,0] neg_hi:[1,0,0]
	ds_read_b128 v[192:195], v8 offset:12288
	s_waitcnt lgkmcnt(5)
	v_pk_fma_f32 v[230:231], v[196:197], v[112:113], v[230:231] neg_lo:[1,0,0] neg_hi:[1,0,0]
	v_pk_fma_f32 v[230:231], v[198:199], v[114:115], v[230:231] neg_lo:[1,0,0] neg_hi:[1,0,0]
	ds_read_b128 v[196:199], v8 offset:12304
	s_waitcnt lgkmcnt(5)
	v_pk_fma_f32 v[230:231], v[200:201], v[116:117], v[230:231] neg_lo:[1,0,0] neg_hi:[1,0,0]
	v_pk_fma_f32 v[230:231], v[202:203], v[118:119], v[230:231] neg_lo:[1,0,0] neg_hi:[1,0,0]
	ds_read_b128 v[200:203], v8 offset:12320
	s_waitcnt lgkmcnt(5)
	v_pk_fma_f32 v[230:231], v[204:205], v[120:121], v[230:231] neg_lo:[1,0,0] neg_hi:[1,0,0]
	v_pk_fma_f32 v[230:231], v[206:207], v[122:123], v[230:231] neg_lo:[1,0,0] neg_hi:[1,0,0]
	ds_read_b128 v[204:207], v8 offset:12336
	s_waitcnt lgkmcnt(5)
	v_pk_fma_f32 v[230:231], v[208:209], v[124:125], v[230:231] neg_lo:[1,0,0] neg_hi:[1,0,0]
	v_pk_fma_f32 v[230:231], v[210:211], v[126:127], v[230:231] neg_lo:[1,0,0] neg_hi:[1,0,0]
	ds_read_b128 v[208:211], v8 offset:12352
	s_waitcnt lgkmcnt(5)
	v_pk_fma_f32 v[230:231], v[212:213], v[128:129], v[230:231] neg_lo:[1,0,0] neg_hi:[1,0,0]
	v_fma_f32 v230, -v214, v130, v230
	ds_read_b128 v[212:215], v8 offset:12368
	v_add_f32_e32 v131, v230, v231
	s_cbranch_vccz .Ls4_u47
	v_cvt_pk_bf16_f32 v233, -v131, v131
	global_store_short v6, v233, s[8:9] offset:3840
	s_branch .Ls4_n47

; #define LAS __attribute__((address_space(3)))
; __device__ __forceinline__ void chunk_prep_phase(const Params& p, int bid, int nblk, LAS unsigned char* lds0) {
;     ...
;             { const float br = betg[48]; ab0 = (f32x2){bf2f(*(const LAS bf16_t*)(lg + P5_VS + 13056 + c * 2)) * br, bf2f(*(const LAS bf16_t*)(lg + P5_KS + 13056 + c * 2)) * br * __expf(decg[48])}; ab1 = (f32x2){0.f, 0.f}; } ab0 -= mq[0][0] * xy[0]; ab1 -= mq[0][1] * xy[1]; ab0 -= mq[0][2] * xy[2]; ab1 -= mq[0][3] * xy[3]; mq[0] = *(const LAS f32x4*)(Mg + 3096);
;             ab0 -= mq[1][0] * xy[4]; ab1 -= mq[1][1] * xy[5]; ab0 -= mq[1][2] * xy[6]; ab1 -= mq[1][3] * xy[7]; mq[1] = *(const LAS f32x4*)(Mg + 3100);
;             ab0 -= mq[2][0] * xy[8]; ab1 -= mq[2][1] * xy[9]; ab0 -= mq[2][2] * xy[10]; ab1 -= mq[2][3] * xy[11]; mq[2] = *(const LAS f32x4*)(Mg + 3104);
;             ab0 -= mq[3][0] * xy[12]; ab1 -= mq[3][1] * xy[13]; ab0 -= mq[3][2] * xy[14]; ab1 -= mq[3][3] * xy[15]; mq[3] = *(const LAS f32x4*)(Mg + 3108);
;             ab0 -= mq[4][0] * xy[16]; ab1 -= mq[4][1] * xy[17]; ab0 -= mq[4][2] * xy[18]; ab1 -= mq[4][3] * xy[19]; mq[4] = *(const LAS f32x4*)(Mg + 3112);
;             ab0 -= mq[5][0] * xy[20]; ab1 -= mq[5][1] * xy[21]; ab0 -= mq[5][2] * xy[22]; ab1 -= mq[5][3] * xy[23]; mq[5] = *(const LAS f32x4*)(Mg + 3116);
;             ab0 -= mq[0][0] * xy[24]; ab1 -= mq[0][1] * xy[25]; ab0 -= mq[0][2] * xy[26]; ab1 -= mq[0][3] * xy[27]; mq[0] = *(const LAS f32x4*)(Mg + 3136);
;             ab0 -= mq[1][0] * xy[28]; ab1 -= mq[1][1] * xy[29]; ab0 -= mq[1][2] * xy[30]; ab1 -= mq[1][3] * xy[31]; mq[1] = *(const LAS f32x4*)(Mg + 3140);
;             ab0 -= mq[2][0] * xy[32]; ab1 -= mq[2][1] * xy[33]; ab0 -= mq[2][2] * xy[34]; ab1 -= mq[2][3] * xy[35]; mq[2] = *(const LAS f32x4*)(Mg + 3144);
;             ab0 -= mq[3][0] * xy[36]; ab1 -= mq[3][1] * xy[37]; ab0 -= mq[3][2] * xy[38]; ab1 -= mq[3][3] * xy[39]; mq[3] = *(const LAS f32x4*)(Mg + 3148);
;             ab0 -= mq[4][0] * xy[40]; ab1 -= mq[4][1] * xy[41]; ab0 -= mq[4][2] * xy[42]; ab1 -= mq[4][3] * xy[43]; mq[4] = *(const LAS f32x4*)(Mg + 3152);
;             ab0 -= mq[5][0] * xy[44]; ab1 -= mq[5][1] * xy[45]; ab0 -= mq[5][2] * xy[46]; ab1 -= mq[5][3] * xy[47]; xy[48] = ab0 + ab1; up[6144] = xy[48][0]; wp[6144] = f2bf(-xy[48][1]); mq[5] = *(const LAS f32x4*)(Mg + 3156);
.Ls4_n47:
	v_mul_f32_e32 v0, s16, v0
	v_mul_f32_e32 v1, s16, v1
	v_mul_f32_e32 v2, s16, v2
	v_mul_f32_e32 v3, s16, v3
	v_exp_f32_e32 v0, v0
	v_exp_f32_e32 v1, v1
	v_exp_f32_e32 v2, v2
	v_exp_f32_e32 v3, v3
	s_nop 0
	v_lshlrev_b32_e32 v228, 16, v228
	v_mul_f32_e32 v232, v228, v216
	v_mul_f32_e32 v230, v232, v0
	v_mov_b32_e32 v231, 0
	ds_read_u16 v229, v7 offset:13328
	s_waitcnt lgkmcnt(6)
	v_pk_fma_f32 v[230:231], v[192:193], v[84:85], v[230:231] neg_lo:[1,0,0] neg_hi:[1,0,0]
	v_pk_fma_f32 v[230:231], v[194:195], v[86:87], v[230:231] neg_lo:[1,0,0] neg_hi:[1,0,0]
	ds_read_b128 v[192:195], v8 offset:12384
	s_waitcnt lgkmcnt(6)
	v_pk_fma_f32 v[230:231], v[196:197], v[88:89], v[230:231] neg_lo:[1,0,0] neg_hi:[1,0,0]
	v_pk_fma_f32 v[230:231], v[198:199], v[90:91], v[230:231] neg_lo:[1,0,0] neg_hi:[1,0,0]
	ds_read_b128 v[196:199], v8 offset:12400
	s_waitcnt lgkmcnt(6)
	v_pk_fma_f32 v[230:231], v[200:201], v[92:93], v[230:231] neg_lo:[1,0,0] neg_hi:[1,0,0]
	v_pk_fma_f32 v[230:231], v[202:203], v[94:95], v[230:231] neg_lo:[1,0,0] neg_hi:[1,0,0]
	ds_read_b128 v[200:203], v8 offset:12416
	s_waitcnt lgkmcnt(6)
	v_pk_fma_f32 v[230:231], v[204:205], v[96:97], v[230:231] neg_lo:[1,0,0] neg_hi:[1,0,0]
	v_pk_fma_f32 v[230:231], v[206:207], v[98:99], v[230:231] neg_lo:[1,0,0] neg_hi:[1,0,0]
	ds_read_b128 v[204:207], v8 offset:12432
	s_waitcnt lgkmcnt(6)
	v_pk_fma_f32 v[230:231], v[208:209], v[100:101], v[230:231] neg_lo:[1,0,0] neg_hi:[1,0,0]
	v_pk_fma_f32 v[230:231], v[210:211], v[102:103], v[230:231] neg_lo:[1,0,0] neg_hi:[1,0,0]
	ds_read_b128 v[208:211], v8 offset:12448
	s_waitcnt lgkmcnt(6)
	v_pk_fma_f32 v[230:231], v[212:213], v[104:105], v[230:231] neg_lo:[1,0,0] neg_hi:[1,0,0]
	v_pk_fma_f32 v[230:231], v[214:215], v[106:107], v[230:231] neg_lo:[1,0,0] neg_hi:[1,0,0]
	ds_read_b128 v[212:215], v8 offset:12464
	s_waitcnt lgkmcnt(5)
	v_pk_fma_f32 v[230:231], v[192:193], v[108:109], v[230:231] neg_lo:[1,0,0] neg_hi:[1,0,0]
	v_pk_fma_f32 v[230:231], v[194:195], v[110:111], v[230:231] neg_lo:[1,0,0] neg_hi:[1,0,0]
	ds_read_b128 v[192:195], v8 offset:12544
	s_waitcnt lgkmcnt(5)
	v_pk_fma_f32 v[230:231], v[196:197], v[112:113], v[230:231] neg_lo:[1,0,0] neg_hi:[1,0,0]
	v_pk_fma_f32 v[230:231], v[198:199], v[114:115], v[230:231] neg_lo:[1,0,0] neg_hi:[1,0,0]
	ds_read_b128 v[196:199], v8 offset:12560
	s_waitcnt lgkmcnt(5)
	v_pk_fma_f32 v[230:231], v[200:201], v[116:117], v[230:231] neg_lo:[1,0,0] neg_hi:[1,0,0]
	v_pk_fma_f32 v[230:231], v[202:203], v[118:119], v[230:231] neg_lo:[1,0,0] neg_hi:[1,0,0]
	ds_read_b128 v[200:203], v8 offset:12576
	s_waitcnt lgkmcnt(5)
	v_pk_fma_f32 v[230:231], v[204:205], v[120:121], v[230:231] neg_lo:[1,0,0] neg_hi:[1,0,0]
	v_pk_fma_f32 v[230:231], v[206:207], v[122:123], v[230:231] neg_lo:[1,0,0] neg_hi:[1,0,0]
	ds_read_b128 v[204:207], v8 offset:12592
	s_waitcnt lgkmcnt(5)
	v_pk_fma_f32 v[230:231], v[208:209], v[124:125], v[230:231] neg_lo:[1,0,0] neg_hi:[1,0,0]
	v_pk_fma_f32 v[230:231], v[210:211], v[126:127], v[230:231] neg_lo:[1,0,0] neg_hi:[1,0,0]
	ds_read_b128 v[208:211], v8 offset:12608
	s_waitcnt lgkmcnt(5)
	v_pk_fma_f32 v[230:231], v[212:213], v[128:129], v[230:231] neg_lo:[1,0,0] neg_hi:[1,0,0]
	v_pk_fma_f32 v[230:231], v[214:215], v[130:131], v[230:231] neg_lo:[1,0,0] neg_hi:[1,0,0]
	ds_read_b128 v[212:215], v8 offset:12624
	v_add_f32_e32 v132, v230, v231
	s_cbranch_vccz .Ls4_u48
	s_add_u32 s8, s8, 0x1000
	s_addc_u32 s9, s9, 0
	v_cvt_pk_bf16_f32 v233, -v132, v132
	global_store_short v6, v233, s[8:9] offset:0
	s_branch .Ls4_n48

; __device__ __forceinline__ void chunk_prep_phase(const Params& p, int bid, int nblk, LAS unsigned char* lds0) {
;     ...
;             { const float br = betg[49]; ab0 = (f32x2){bf2f(*(const LAS bf16_t*)(lg + P5_VS + 13328 + c * 2)) * br, bf2f(*(const LAS bf16_t*)(lg + P5_KS + 13328 + c * 2)) * br * __expf(decg[49])}; ab1 = (f32x2){0.f, 0.f}; } ab0 -= mq[0][0] * xy[0]; ab1 -= mq[0][1] * xy[1]; ab0 -= mq[0][2] * xy[2]; ab1 -= mq[0][3] * xy[3]; mq[0] = *(const LAS f32x4*)(Mg + 3160);
;             ab0 -= mq[1][0] * xy[4]; ab1 -= mq[1][1] * xy[5]; ab0 -= mq[1][2] * xy[6]; ab1 -= mq[1][3] * xy[7]; mq[1] = *(const LAS f32x4*)(Mg + 3164);
;             ab0 -= mq[2][0] * xy[8]; ab1 -= mq[2][1] * xy[9]; ab0 -= mq[2][2] * xy[10]; ab1 -= mq[2][3] * xy[11]; mq[2] = *(const LAS f32x4*)(Mg + 3168);
;             ab0 -= mq[3][0] * xy[12]; ab1 -= mq[3][1] * xy[13]; ab0 -= mq[3][2] * xy[14]; ab1 -= mq[3][3] * xy[15]; mq[3] = *(const LAS f32x4*)(Mg + 3172);
;             ab0 -= mq[4][0] * xy[16]; ab1 -= mq[4][1] * xy[17]; ab0 -= mq[4][2] * xy[18]; ab1 -= mq[4][3] * xy[19]; mq[4] = *(const LAS f32x4*)(Mg + 3176);
;             ab0 -= mq[5][0] * xy[20]; ab1 -= mq[5][1] * xy[21]; ab0 -= mq[5][2] * xy[22]; ab1 -= mq[5][3] * xy[23]; mq[5] = *(const LAS f32x4*)(Mg + 3180);
;             ab0 -= mq[0][0] * xy[24]; ab1 -= mq[0][1] * xy[25]; ab0 -= mq[0][2] * xy[26]; ab1 -= mq[0][3] * xy[27]; mq[0] = *(const LAS f32x4*)(Mg + 3184);
;             ab0 -= mq[1][0] * xy[28]; ab1 -= mq[1][1] * xy[29]; ab0 -= mq[1][2] * xy[30]; ab1 -= mq[1][3] * xy[31]; mq[1] = *(const LAS f32x4*)(Mg + 3200);
;             ab0 -= mq[2][0] * xy[32]; ab1 -= mq[2][1] * xy[33]; ab0 -= mq[2][2] * xy[34]; ab1 -= mq[2][3] * xy[35]; mq[2] = *(const LAS f32x4*)(Mg + 3204);
;             ab0 -= mq[3][0] * xy[36]; ab1 -= mq[3][1] * xy[37]; ab0 -= mq[3][2] * xy[38]; ab1 -= mq[3][3] * xy[39]; mq[3] = *(const LAS f32x4*)(Mg + 3208);
;             ab0 -= mq[4][0] * xy[40]; ab1 -= mq[4][1] * xy[41]; ab0 -= mq[4][2] * xy[42]; ab1 -= mq[4][3] * xy[43]; mq[4] = *(const LAS f32x4*)(Mg + 3212);
;             ab0 -= mq[5][0] * xy[44]; ab1 -= mq[5][1] * xy[45]; ab0 -= mq[5][2] * xy[46]; ab1 -= mq[5][3] * xy[47]; mq[5] = *(const LAS f32x4*)(Mg + 3216);
;             ab0 -= mq[0][0] * xy[48]; xy[49] = ab0 + ab1; up[6272] = xy[49][0]; wp[6272] = f2bf(-xy[49][1]); mq[0] = *(const LAS f32x4*)(Mg + 3220);
.Ls4_n48:
	v_lshlrev_b32_e32 v229, 16, v229
	v_mul_f32_e32 v232, v229, v217
	v_mul_f32_e32 v230, v232, v1
	v_mov_b32_e32 v231, 0
	ds_read_u16 v228, v7 offset:13600
	s_waitcnt lgkmcnt(6)
	v_pk_fma_f32 v[230:231], v[192:193], v[84:85], v[230:231] neg_lo:[1,0,0] neg_hi:[1,0,0]
	v_pk_fma_f32 v[230:231], v[194:195], v[86:87], v[230:231] neg_lo:[1,0,0] neg_hi:[1,0,0]
	ds_read_b128 v[192:195], v8 offset:12640
	s_waitcnt lgkmcnt(6)
	v_pk_fma_f32 v[230:231], v[196:197], v[88:89], v[230:231] neg_lo:[1,0,0] neg_hi:[1,0,0]
	v_pk_fma_f32 v[230:231], v[198:199], v[90:91], v[230:231] neg_lo:[1,0,0] neg_hi:[1,0,0]
	ds_read_b128 v[196:199], v8 offset:12656
	s_waitcnt lgkmcnt(6)
	v_pk_fma_f32 v[230:231], v[200:201], v[92:93], v[230:231] neg_lo:[1,0,0] neg_hi:[1,0,0]
	v_pk_fma_f32 v[230:231], v[202:203], v[94:95], v[230:231] neg_lo:[1,0,0] neg_hi:[1,0,0]
	ds_read_b128 v[200:203], v8 offset:12672
	s_waitcnt lgkmcnt(6)
	v_pk_fma_f32 v[230:231], v[204:205], v[96:97], v[230:231] neg_lo:[1,0,0] neg_hi:[1,0,0]
	v_pk_fma_f32 v[230:231], v[206:207], v[98:99], v[230:231] neg_lo:[1,0,0] neg_hi:[1,0,0]
	ds_read_b128 v[204:207], v8 offset:12688
	s_waitcnt lgkmcnt(6)
	v_pk_fma_f32 v[230:231], v[208:209], v[100:101], v[230:231] neg_lo:[1,0,0] neg_hi:[1,0,0]
	v_pk_fma_f32 v[230:231], v[210:211], v[102:103], v[230:231] neg_lo:[1,0,0] neg_hi:[1,0,0]
	ds_read_b128 v[208:211], v8 offset:12704
	s_waitcnt lgkmcnt(6)
	v_pk_fma_f32 v[230:231], v[212:213], v[104:105], v[230:231] neg_lo:[1,0,0] neg_hi:[1,0,0]
	v_pk_fma_f32 v[230:231], v[214:215], v[106:107], v[230:231] neg_lo:[1,0,0] neg_hi:[1,0,0]
	ds_read_b128 v[212:215], v8 offset:12720
	s_waitcnt lgkmcnt(5)
	v_pk_fma_f32 v[230:231], v[192:193], v[108:109], v[230:231] neg_lo:[1,0,0] neg_hi:[1,0,0]
	v_pk_fma_f32 v[230:231], v[194:195], v[110:111], v[230:231] neg_lo:[1,0,0] neg_hi:[1,0,0]
	ds_read_b128 v[192:195], v8 offset:12736
	s_waitcnt lgkmcnt(5)
	v_pk_fma_f32 v[230:231], v[196:197], v[112:113], v[230:231] neg_lo:[1,0,0] neg_hi:[1,0,0]
	v_pk_fma_f32 v[230:231], v[198:199], v[114:115], v[230:231] neg_lo:[1,0,0] neg_hi:[1,0,0]
	ds_read_b128 v[196:199], v8 offset:12800
	s_waitcnt lgkmcnt(5)
	v_pk_fma_f32 v[230:231], v[200:201], v[116:117], v[230:231] neg_lo:[1,0,0] neg_hi:[1,0,0]
	v_pk_fma_f32 v[230:231], v[202:203], v[118:119], v[230:231] neg_lo:[1,0,0] neg_hi:[1,0,0]
	ds_read_b128 v[200:203], v8 offset:12816
	s_waitcnt lgkmcnt(5)
	v_pk_fma_f32 v[230:231], v[204:205], v[120:121], v[230:231] neg_lo:[1,0,0] neg_hi:[1,0,0]
	v_pk_fma_f32 v[230:231], v[206:207], v[122:123], v[230:231] neg_lo:[1,0,0] neg_hi:[1,0,0]
	ds_read_b128 v[204:207], v8 offset:12832
	s_waitcnt lgkmcnt(5)
	v_pk_fma_f32 v[230:231], v[208:209], v[124:125], v[230:231] neg_lo:[1,0,0] neg_hi:[1,0,0]
	v_pk_fma_f32 v[230:231], v[210:211], v[126:127], v[230:231] neg_lo:[1,0,0] neg_hi:[1,0,0]
	ds_read_b128 v[208:211], v8 offset:12848
	s_waitcnt lgkmcnt(5)
	v_pk_fma_f32 v[230:231], v[212:213], v[128:129], v[230:231] neg_lo:[1,0,0] neg_hi:[1,0,0]
	v_pk_fma_f32 v[230:231], v[214:215], v[130:131], v[230:231] neg_lo:[1,0,0] neg_hi:[1,0,0]
	ds_read_b128 v[212:215], v8 offset:12864
	s_waitcnt lgkmcnt(5)
	v_fma_f32 v230, -v192, v132, v230
	ds_read_b128 v[192:195], v8 offset:12880
	v_add_f32_e32 v133, v230, v231
	s_cbranch_vccz .Ls4_u49
	v_cvt_pk_bf16_f32 v233, -v133, v133
	global_store_short v6, v233, s[8:9] offset:256
	s_branch .Ls4_n49

; __device__ __forceinline__ void chunk_prep_phase(const Params& p, int bid, int nblk, LAS unsigned char* lds0) {
;     ...
;             { const float br = betg[50]; ab0 = (f32x2){bf2f(*(const LAS bf16_t*)(lg + P5_VS + 13600 + c * 2)) * br, bf2f(*(const LAS bf16_t*)(lg + P5_KS + 13600 + c * 2)) * br * __expf(decg[50])}; ab1 = (f32x2){0.f, 0.f}; } ab0 -= mq[1][0] * xy[0]; ab1 -= mq[1][1] * xy[1]; ab0 -= mq[1][2] * xy[2]; ab1 -= mq[1][3] * xy[3]; mq[1] = *(const LAS f32x4*)(Mg + 3224);
;             ab0 -= mq[2][0] * xy[4]; ab1 -= mq[2][1] * xy[5]; ab0 -= mq[2][2] * xy[6]; ab1 -= mq[2][3] * xy[7]; mq[2] = *(const LAS f32x4*)(Mg + 3228);
;             ab0 -= mq[3][0] * xy[8]; ab1 -= mq[3][1] * xy[9]; ab0 -= mq[3][2] * xy[10]; ab1 -= mq[3][3] * xy[11]; mq[3] = *(const LAS f32x4*)(Mg + 3232);
;             ab0 -= mq[4][0] * xy[12]; ab1 -= mq[4][1] * xy[13]; ab0 -= mq[4][2] * xy[14]; ab1 -= mq[4][3] * xy[15]; mq[4] = *(const LAS f32x4*)(Mg + 3236);
;             ab0 -= mq[5][0] * xy[16]; ab1 -= mq[5][1] * xy[17]; ab0 -= mq[5][2] * xy[18]; ab1 -= mq[5][3] * xy[19]; mq[5] = *(const LAS f32x4*)(Mg + 3240);
;             ab0 -= mq[0][0] * xy[20]; ab1 -= mq[0][1] * xy[21]; ab0 -= mq[0][2] * xy[22]; ab1 -= mq[0][3] * xy[23]; mq[0] = *(const LAS f32x4*)(Mg + 3244);
;             ab0 -= mq[1][0] * xy[24]; ab1 -= mq[1][1] * xy[25]; ab0 -= mq[1][2] * xy[26]; ab1 -= mq[1][3] * xy[27]; mq[1] = *(const LAS f32x4*)(Mg + 3248);
;             ab0 -= mq[2][0] * xy[28]; ab1 -= mq[2][1] * xy[29]; ab0 -= mq[2][2] * xy[30]; ab1 -= mq[2][3] * xy[31]; mq[2] = *(const LAS f32x4*)(Mg + 3264);
;             ab0 -= mq[3][0] * xy[32]; ab1 -= mq[3][1] * xy[33]; ab0 -= mq[3][2] * xy[34]; ab1 -= mq[3][3] * xy[35]; mq[3] = *(const LAS f32x4*)(Mg + 3268);
;             ab0 -= mq[4][0] * xy[36]; ab1 -= mq[4][1] * xy[37]; ab0 -= mq[4][2] * xy[38]; ab1 -= mq[4][3] * xy[39]; mq[4] = *(const LAS f32x4*)(Mg + 3272);
;             ab0 -= mq[5][0] * xy[40]; ab1 -= mq[5][1] * xy[41]; ab0 -= mq[5][2] * xy[42]; ab1 -= mq[5][3] * xy[43]; mq[5] = *(const LAS f32x4*)(Mg + 3276);
;             ab0 -= mq[0][0] * xy[44]; ab1 -= mq[0][1] * xy[45]; ab0 -= mq[0][2] * xy[46]; ab1 -= mq[0][3] * xy[47]; mq[0] = *(const LAS f32x4*)(Mg + 3280);
;             ab0 -= mq[1][0] * xy[48]; ab1 -= mq[1][1] * xy[49]; xy[50] = ab0 + ab1; up[6400] = xy[50][0]; wp[6400] = f2bf(-xy[50][1]); mq[1] = *(const LAS f32x4*)(Mg + 3284);
.Ls4_n49:
	v_lshlrev_b32_e32 v228, 16, v228
	v_mul_f32_e32 v232, v228, v218
	v_mul_f32_e32 v230, v232, v2
	v_mov_b32_e32 v231, 0
	ds_read_u16 v229, v7 offset:13872
	s_waitcnt lgkmcnt(6)
	v_pk_fma_f32 v[230:231], v[196:197], v[84:85], v[230:231] neg_lo:[1,0,0] neg_hi:[1,0,0]
	v_pk_fma_f32 v[230:231], v[198:199], v[86:87], v[230:231] neg_lo:[1,0,0] neg_hi:[1,0,0]
	ds_read_b128 v[196:199], v8 offset:12896
	s_waitcnt lgkmcnt(6)
	v_pk_fma_f32 v[230:231], v[200:201], v[88:89], v[230:231] neg_lo:[1,0,0] neg_hi:[1,0,0]
	v_pk_fma_f32 v[230:231], v[202:203], v[90:91], v[230:231] neg_lo:[1,0,0] neg_hi:[1,0,0]
	ds_read_b128 v[200:203], v8 offset:12912
	s_waitcnt lgkmcnt(6)
	v_pk_fma_f32 v[230:231], v[204:205], v[92:93], v[230:231] neg_lo:[1,0,0] neg_hi:[1,0,0]
	v_pk_fma_f32 v[230:231], v[206:207], v[94:95], v[230:231] neg_lo:[1,0,0] neg_hi:[1,0,0]
	ds_read_b128 v[204:207], v8 offset:12928
	s_waitcnt lgkmcnt(6)
	v_pk_fma_f32 v[230:231], v[208:209], v[96:97], v[230:231] neg_lo:[1,0,0] neg_hi:[1,0,0]
	v_pk_fma_f32 v[230:231], v[210:211], v[98:99], v[230:231] neg_lo:[1,0,0] neg_hi:[1,0,0]
	ds_read_b128 v[208:211], v8 offset:12944
	s_waitcnt lgkmcnt(6)
	v_pk_fma_f32 v[230:231], v[212:213], v[100:101], v[230:231] neg_lo:[1,0,0] neg_hi:[1,0,0]
	v_pk_fma_f32 v[230:231], v[214:215], v[102:103], v[230:231] neg_lo:[1,0,0] neg_hi:[1,0,0]
	ds_read_b128 v[212:215], v8 offset:12960
	s_waitcnt lgkmcnt(6)
	v_pk_fma_f32 v[230:231], v[192:193], v[104:105], v[230:231] neg_lo:[1,0,0] neg_hi:[1,0,0]
	v_pk_fma_f32 v[230:231], v[194:195], v[106:107], v[230:231] neg_lo:[1,0,0] neg_hi:[1,0,0]
	ds_read_b128 v[192:195], v8 offset:12976
	s_waitcnt lgkmcnt(5)
	v_pk_fma_f32 v[230:231], v[196:197], v[108:109], v[230:231] neg_lo:[1,0,0] neg_hi:[1,0,0]
	v_pk_fma_f32 v[230:231], v[198:199], v[110:111], v[230:231] neg_lo:[1,0,0] neg_hi:[1,0,0]
	ds_read_b128 v[196:199], v8 offset:12992
	s_waitcnt lgkmcnt(5)
	v_pk_fma_f32 v[230:231], v[200:201], v[112:113], v[230:231] neg_lo:[1,0,0] neg_hi:[1,0,0]
	v_pk_fma_f32 v[230:231], v[202:203], v[114:115], v[230:231] neg_lo:[1,0,0] neg_hi:[1,0,0]
	ds_read_b128 v[200:203], v8 offset:13056
	s_waitcnt lgkmcnt(5)
	v_pk_fma_f32 v[230:231], v[204:205], v[116:117], v[230:231] neg_lo:[1,0,0] neg_hi:[1,0,0]
	v_pk_fma_f32 v[230:231], v[206:207], v[118:119], v[230:231] neg_lo:[1,0,0] neg_hi:[1,0,0]
	ds_read_b128 v[204:207], v8 offset:13072
	s_waitcnt lgkmcnt(5)
	v_pk_fma_f32 v[230:231], v[208:209], v[120:121], v[230:231] neg_lo:[1,0,0] neg_hi:[1,0,0]
	v_pk_fma_f32 v[230:231], v[210:211], v[122:123], v[230:231] neg_lo:[1,0,0] neg_hi:[1,0,0]
	ds_read_b128 v[208:211], v8 offset:13088
	s_waitcnt lgkmcnt(5)
	v_pk_fma_f32 v[230:231], v[212:213], v[124:125], v[230:231] neg_lo:[1,0,0] neg_hi:[1,0,0]
	v_pk_fma_f32 v[230:231], v[214:215], v[126:127], v[230:231] neg_lo:[1,0,0] neg_hi:[1,0,0]
	ds_read_b128 v[212:215], v8 offset:13104
	s_waitcnt lgkmcnt(5)
	v_pk_fma_f32 v[230:231], v[192:193], v[128:129], v[230:231] neg_lo:[1,0,0] neg_hi:[1,0,0]
	v_pk_fma_f32 v[230:231], v[194:195], v[130:131], v[230:231] neg_lo:[1,0,0] neg_hi:[1,0,0]
	ds_read_b128 v[192:195], v8 offset:13120
	s_waitcnt lgkmcnt(5)
	v_pk_fma_f32 v[230:231], v[196:197], v[132:133], v[230:231] neg_lo:[1,0,0] neg_hi:[1,0,0]
	ds_read_b128 v[196:199], v8 offset:13136
	v_add_f32_e32 v134, v230, v231
	s_cbranch_vccz .Ls4_u50
	v_cvt_pk_bf16_f32 v233, -v134, v134
	global_store_short v6, v233, s[8:9] offset:512
	s_branch .Ls4_n50

; #define LAS __attribute__((address_space(3)))
; __device__ __forceinline__ float bf2f(unsigned short x) { return __uint_as_float(((unsigned)x) << 16); }
; __device__ __forceinline__ void chunk_prep_phase(const Params& p, int bid, int nblk, LAS unsigned char* lds0) {
;     ...
;             { const float br = betg[51]; ab0 = (f32x2){bf2f(*(const LAS bf16_t*)(lg + P5_VS + 13872 + c * 2)) * br, bf2f(*(const LAS bf16_t*)(lg + P5_KS + 13872 + c * 2)) * br * __expf(decg[51])}; ab1 = (f32x2){0.f, 0.f}; } ab0 -= mq[2][0] * xy[0]; ab1 -= mq[2][1] * xy[1]; ab0 -= mq[2][2] * xy[2]; ab1 -= mq[2][3] * xy[3]; mq[2] = *(const LAS f32x4*)(Mg + 3288);
;             ab0 -= mq[3][0] * xy[4]; ab1 -= mq[3][1] * xy[5]; ab0 -= mq[3][2] * xy[6]; ab1 -= mq[3][3] * xy[7]; mq[3] = *(const LAS f32x4*)(Mg + 3292);
;             ab0 -= mq[4][0] * xy[8]; ab1 -= mq[4][1] * xy[9]; ab0 -= mq[4][2] * xy[10]; ab1 -= mq[4][3] * xy[11]; mq[4] = *(const LAS f32x4*)(Mg + 3296);
;             ab0 -= mq[5][0] * xy[12]; ab1 -= mq[5][1] * xy[13]; ab0 -= mq[5][2] * xy[14]; ab1 -= mq[5][3] * xy[15]; mq[5] = *(const LAS f32x4*)(Mg + 3300);
;             ab0 -= mq[0][0] * xy[16]; ab1 -= mq[0][1] * xy[17]; ab0 -= mq[0][2] * xy[18]; ab1 -= mq[0][3] * xy[19]; mq[0] = *(const LAS f32x4*)(Mg + 3304);
;             ab0 -= mq[1][0] * xy[20]; ab1 -= mq[1][1] * xy[21]; ab0 -= mq[1][2] * xy[22]; ab1 -= mq[1][3] * xy[23]; mq[1] = *(const LAS f32x4*)(Mg + 3308);
;             ab0 -= mq[2][0] * xy[24]; ab1 -= mq[2][1] * xy[25]; ab0 -= mq[2][2] * xy[26]; ab1 -= mq[2][3] * xy[27]; mq[2] = *(const LAS f32x4*)(Mg + 3312);
;             ab0 -= mq[3][0] * xy[28]; ab1 -= mq[3][1] * xy[29]; ab0 -= mq[3][2] * xy[30]; ab1 -= mq[3][3] * xy[31]; mq[3] = *(const LAS f32x4*)(Mg + 3328);
;             ab0 -= mq[4][0] * xy[32]; ab1 -= mq[4][1] * xy[33]; ab0 -= mq[4][2] * xy[34]; ab1 -= mq[4][3] * xy[35]; mq[4] = *(const LAS f32x4*)(Mg + 3332);
;             ab0 -= mq[5][0] * xy[36]; ab1 -= mq[5][1] * xy[37]; ab0 -= mq[5][2] * xy[38]; ab1 -= mq[5][3] * xy[39]; mq[5] = *(const LAS f32x4*)(Mg + 3336);
;             ab0 -= mq[0][0] * xy[40]; ab1 -= mq[0][1] * xy[41]; ab0 -= mq[0][2] * xy[42]; ab1 -= mq[0][3] * xy[43]; mq[0] = *(const LAS f32x4*)(Mg + 3340);
;             ab0 -= mq[1][0] * xy[44]; ab1 -= mq[1][1] * xy[45]; ab0 -= mq[1][2] * xy[46]; ab1 -= mq[1][3] * xy[47]; mq[1] = *(const LAS f32x4*)(Mg + 3344);
.Ls4_n50:
	v_lshlrev_b32_e32 v229, 16, v229
	v_mul_f32_e32 v232, v229, v219
	v_mul_f32_e32 v230, v232, v3
	v_mov_b32_e32 v231, 0
	ds_read_u16 v228, v7 offset:14144
	ds_read_b128 v[216:219], v8 offset:16864
	ds_read_b128 v[0:3], v8 offset:16608
	s_waitcnt lgkmcnt(8)
	v_pk_fma_f32 v[230:231], v[200:201], v[84:85], v[230:231] neg_lo:[1,0,0] neg_hi:[1,0,0]
	v_pk_fma_f32 v[230:231], v[202:203], v[86:87], v[230:231] neg_lo:[1,0,0] neg_hi:[1,0,0]
	ds_read_b128 v[200:203], v8 offset:13152
	s_waitcnt lgkmcnt(8)
	v_pk_fma_f32 v[230:231], v[204:205], v[88:89], v[230:231] neg_lo:[1,0,0] neg_hi:[1,0,0]
	v_pk_fma_f32 v[230:231], v[206:207], v[90:91], v[230:231] neg_lo:[1,0,0] neg_hi:[1,0,0]
	ds_read_b128 v[204:207], v8 offset:13168
	s_waitcnt lgkmcnt(8)
	v_pk_fma_f32 v[230:231], v[208:209], v[92:93], v[230:231] neg_lo:[1,0,0] neg_hi:[1,0,0]
	v_pk_fma_f32 v[230:231], v[210:211], v[94:95], v[230:231] neg_lo:[1,0,0] neg_hi:[1,0,0]
	ds_read_b128 v[208:211], v8 offset:13184
	s_waitcnt lgkmcnt(8)
	v_pk_fma_f32 v[230:231], v[212:213], v[96:97], v[230:231] neg_lo:[1,0,0] neg_hi:[1,0,0]
	v_pk_fma_f32 v[230:231], v[214:215], v[98:99], v[230:231] neg_lo:[1,0,0] neg_hi:[1,0,0]
	ds_read_b128 v[212:215], v8 offset:13200
	s_waitcnt lgkmcnt(8)
	v_pk_fma_f32 v[230:231], v[192:193], v[100:101], v[230:231] neg_lo:[1,0,0] neg_hi:[1,0,0]
	v_pk_fma_f32 v[230:231], v[194:195], v[102:103], v[230:231] neg_lo:[1,0,0] neg_hi:[1,0,0]
	ds_read_b128 v[192:195], v8 offset:13216
	s_waitcnt lgkmcnt(8)
	v_pk_fma_f32 v[230:231], v[196:197], v[104:105], v[230:231] neg_lo:[1,0,0] neg_hi:[1,0,0]
	v_pk_fma_f32 v[230:231], v[198:199], v[106:107], v[230:231] neg_lo:[1,0,0] neg_hi:[1,0,0]
	ds_read_b128 v[196:199], v8 offset:13232
	s_waitcnt lgkmcnt(5)
	v_pk_fma_f32 v[230:231], v[200:201], v[108:109], v[230:231] neg_lo:[1,0,0] neg_hi:[1,0,0]
	v_pk_fma_f32 v[230:231], v[202:203], v[110:111], v[230:231] neg_lo:[1,0,0] neg_hi:[1,0,0]
	ds_read_b128 v[200:203], v8 offset:13248
	s_waitcnt lgkmcnt(5)
	v_pk_fma_f32 v[230:231], v[204:205], v[112:113], v[230:231] neg_lo:[1,0,0] neg_hi:[1,0,0]
	v_pk_fma_f32 v[230:231], v[206:207], v[114:115], v[230:231] neg_lo:[1,0,0] neg_hi:[1,0,0]
	ds_read_b128 v[204:207], v8 offset:13312
	s_waitcnt lgkmcnt(5)
	v_pk_fma_f32 v[230:231], v[208:209], v[116:117], v[230:231] neg_lo:[1,0,0] neg_hi:[1,0,0]
	v_pk_fma_f32 v[230:231], v[210:211], v[118:119], v[230:231] neg_lo:[1,0,0] neg_hi:[1,0,0]
	ds_read_b128 v[208:211], v8 offset:13328
	s_waitcnt lgkmcnt(5)
	v_pk_fma_f32 v[230:231], v[212:213], v[120:121], v[230:231] neg_lo:[1,0,0] neg_hi:[1,0,0]
	v_pk_fma_f32 v[230:231], v[214:215], v[122:123], v[230:231] neg_lo:[1,0,0] neg_hi:[1,0,0]
	ds_read_b128 v[212:215], v8 offset:13344
	s_waitcnt lgkmcnt(5)
	v_pk_fma_f32 v[230:231], v[192:193], v[124:125], v[230:231] neg_lo:[1,0,0] neg_hi:[1,0,0]
	v_pk_fma_f32 v[230:231], v[194:195], v[126:127], v[230:231] neg_lo:[1,0,0] neg_hi:[1,0,0]
	ds_read_b128 v[192:195], v8 offset:13360
	s_waitcnt lgkmcnt(5)
	v_pk_fma_f32 v[230:231], v[196:197], v[128:129], v[230:231] neg_lo:[1,0,0] neg_hi:[1,0,0]
	v_pk_fma_f32 v[230:231], v[198:199], v[130:131], v[230:231] neg_lo:[1,0,0] neg_hi:[1,0,0]
	ds_read_b128 v[196:199], v8 offset:13376
	s_waitcnt lgkmcnt(5)
	v_pk_fma_f32 v[230:231], v[200:201], v[132:133], v[230:231] neg_lo:[1,0,0] neg_hi:[1,0,0]
	v_fma_f32 v230, -v202, v134, v230
	ds_read_b128 v[200:203], v8 offset:13392
	v_add_f32_e32 v135, v230, v231
	s_cbranch_vccz .Ls4_u51
	v_cvt_pk_bf16_f32 v233, -v135, v135
	global_store_short v6, v233, s[8:9] offset:768
	s_branch .Ls4_n51

; #define LAS __attribute__((address_space(3)))
; __device__ __forceinline__ float bf2f(unsigned short x) { return __uint_as_float(((unsigned)x) << 16); }
; __device__ __forceinline__ void chunk_prep_phase(const Params& p, int bid, int nblk, LAS unsigned char* lds0) {
;     ...
;             { const float br = betg[52]; ab0 = (f32x2){bf2f(*(const LAS bf16_t*)(lg + P5_VS + 14144 + c * 2)) * br, bf2f(*(const LAS bf16_t*)(lg + P5_KS + 14144 + c * 2)) * br * __expf(decg[52])}; ab1 = (f32x2){0.f, 0.f}; } ab0 -= mq[3][0] * xy[0]; ab1 -= mq[3][1] * xy[1]; ab0 -= mq[3][2] * xy[2]; ab1 -= mq[3][3] * xy[3]; mq[3] = *(const LAS f32x4*)(Mg + 3352);
;             ab0 -= mq[4][0] * xy[4]; ab1 -= mq[4][1] * xy[5]; ab0 -= mq[4][2] * xy[6]; ab1 -= mq[4][3] * xy[7]; mq[4] = *(const LAS f32x4*)(Mg + 3356);
;             ab0 -= mq[5][0] * xy[8]; ab1 -= mq[5][1] * xy[9]; ab0 -= mq[5][2] * xy[10]; ab1 -= mq[5][3] * xy[11]; mq[5] = *(const LAS f32x4*)(Mg + 3360);
;             ab0 -= mq[0][0] * xy[12]; ab1 -= mq[0][1] * xy[13]; ab0 -= mq[0][2] * xy[14]; ab1 -= mq[0][3] * xy[15]; mq[0] = *(const LAS f32x4*)(Mg + 3364);
;             ab0 -= mq[1][0] * xy[16]; ab1 -= mq[1][1] * xy[17]; ab0 -= mq[1][2] * xy[18]; ab1 -= mq[1][3] * xy[19]; mq[1] = *(const LAS f32x4*)(Mg + 3368);
;             ab0 -= mq[2][0] * xy[20]; ab1 -= mq[2][1] * xy[21]; ab0 -= mq[2][2] * xy[22]; ab1 -= mq[2][3] * xy[23]; mq[2] = *(const LAS f32x4*)(Mg + 3372);
;             ab0 -= mq[3][0] * xy[24]; ab1 -= mq[3][1] * xy[25]; ab0 -= mq[3][2] * xy[26]; ab1 -= mq[3][3] * xy[27]; mq[3] = *(const LAS f32x4*)(Mg + 3376);
;             ab0 -= mq[4][0] * xy[28]; ab1 -= mq[4][1] * xy[29]; ab0 -= mq[4][2] * xy[30]; ab1 -= mq[4][3] * xy[31]; mq[4] = *(const LAS f32x4*)(Mg + 3392);
;             ab0 -= mq[5][0] * xy[32]; ab1 -= mq[5][1] * xy[33]; ab0 -= mq[5][2] * xy[34]; ab1 -= mq[5][3] * xy[35]; mq[5] = *(const LAS f32x4*)(Mg + 3396);
;             ab0 -= mq[0][0] * xy[36]; ab1 -= mq[0][1] * xy[37]; ab0 -= mq[0][2] * xy[38]; ab1 -= mq[0][3] * xy[39]; mq[0] = *(const LAS f32x4*)(Mg + 3400);
;             ab0 -= mq[1][0] * xy[40]; ab1 -= mq[1][1] * xy[41]; ab0 -= mq[1][2] * xy[42]; ab1 -= mq[1][3] * xy[43]; mq[1] = *(const LAS f32x4*)(Mg + 3404);
;             ab0 -= mq[2][0] * xy[44]; ab1 -= mq[2][1] * xy[45]; ab0 -= mq[2][2] * xy[46]; ab1 -= mq[2][3] * xy[47]; mq[2] = *(const LAS f32x4*)(Mg + 3408);
.Ls4_n51:
	v_mul_f32_e32 v224, s16, v224
	v_mul_f32_e32 v225, s16, v225
	v_mul_f32_e32 v226, s16, v226
	v_mul_f32_e32 v227, s16, v227
	v_exp_f32_e32 v224, v224
	v_exp_f32_e32 v225, v225
	v_exp_f32_e32 v226, v226
	v_exp_f32_e32 v227, v227
	s_nop 0
	v_lshlrev_b32_e32 v228, 16, v228
	v_mul_f32_e32 v232, v228, v220
	v_mul_f32_e32 v230, v232, v224
	v_mov_b32_e32 v231, 0
	ds_read_u16 v229, v7 offset:14416
	s_waitcnt lgkmcnt(6)
	v_pk_fma_f32 v[230:231], v[204:205], v[84:85], v[230:231] neg_lo:[1,0,0] neg_hi:[1,0,0]
	v_pk_fma_f32 v[230:231], v[206:207], v[86:87], v[230:231] neg_lo:[1,0,0] neg_hi:[1,0,0]
	ds_read_b128 v[204:207], v8 offset:13408
	s_waitcnt lgkmcnt(6)
	v_pk_fma_f32 v[230:231], v[208:209], v[88:89], v[230:231] neg_lo:[1,0,0] neg_hi:[1,0,0]
	v_pk_fma_f32 v[230:231], v[210:211], v[90:91], v[230:231] neg_lo:[1,0,0] neg_hi:[1,0,0]
	ds_read_b128 v[208:211], v8 offset:13424
	s_waitcnt lgkmcnt(6)
	v_pk_fma_f32 v[230:231], v[212:213], v[92:93], v[230:231] neg_lo:[1,0,0] neg_hi:[1,0,0]
	v_pk_fma_f32 v[230:231], v[214:215], v[94:95], v[230:231] neg_lo:[1,0,0] neg_hi:[1,0,0]
	ds_read_b128 v[212:215], v8 offset:13440
	s_waitcnt lgkmcnt(6)
	v_pk_fma_f32 v[230:231], v[192:193], v[96:97], v[230:231] neg_lo:[1,0,0] neg_hi:[1,0,0]
	v_pk_fma_f32 v[230:231], v[194:195], v[98:99], v[230:231] neg_lo:[1,0,0] neg_hi:[1,0,0]
	ds_read_b128 v[192:195], v8 offset:13456
	s_waitcnt lgkmcnt(6)
	v_pk_fma_f32 v[230:231], v[196:197], v[100:101], v[230:231] neg_lo:[1,0,0] neg_hi:[1,0,0]
	v_pk_fma_f32 v[230:231], v[198:199], v[102:103], v[230:231] neg_lo:[1,0,0] neg_hi:[1,0,0]
	ds_read_b128 v[196:199], v8 offset:13472
	s_waitcnt lgkmcnt(6)
	v_pk_fma_f32 v[230:231], v[200:201], v[104:105], v[230:231] neg_lo:[1,0,0] neg_hi:[1,0,0]
	v_pk_fma_f32 v[230:231], v[202:203], v[106:107], v[230:231] neg_lo:[1,0,0] neg_hi:[1,0,0]
	ds_read_b128 v[200:203], v8 offset:13488
	s_waitcnt lgkmcnt(5)
	v_pk_fma_f32 v[230:231], v[204:205], v[108:109], v[230:231] neg_lo:[1,0,0] neg_hi:[1,0,0]
	v_pk_fma_f32 v[230:231], v[206:207], v[110:111], v[230:231] neg_lo:[1,0,0] neg_hi:[1,0,0]
	ds_read_b128 v[204:207], v8 offset:13504
	s_waitcnt lgkmcnt(5)
	v_pk_fma_f32 v[230:231], v[208:209], v[112:113], v[230:231] neg_lo:[1,0,0] neg_hi:[1,0,0]
	v_pk_fma_f32 v[230:231], v[210:211], v[114:115], v[230:231] neg_lo:[1,0,0] neg_hi:[1,0,0]
	ds_read_b128 v[208:211], v8 offset:13568
	s_waitcnt lgkmcnt(5)
	v_pk_fma_f32 v[230:231], v[212:213], v[116:117], v[230:231] neg_lo:[1,0,0] neg_hi:[1,0,0]
	v_pk_fma_f32 v[230:231], v[214:215], v[118:119], v[230:231] neg_lo:[1,0,0] neg_hi:[1,0,0]
	ds_read_b128 v[212:215], v8 offset:13584
	s_waitcnt lgkmcnt(5)
	v_pk_fma_f32 v[230:231], v[192:193], v[120:121], v[230:231] neg_lo:[1,0,0] neg_hi:[1,0,0]
	v_pk_fma_f32 v[230:231], v[194:195], v[122:123], v[230:231] neg_lo:[1,0,0] neg_hi:[1,0,0]
	ds_read_b128 v[192:195], v8 offset:13600
	s_waitcnt lgkmcnt(5)
	v_pk_fma_f32 v[230:231], v[196:197], v[124:125], v[230:231] neg_lo:[1,0,0] neg_hi:[1,0,0]
	v_pk_fma_f32 v[230:231], v[198:199], v[126:127], v[230:231] neg_lo:[1,0,0] neg_hi:[1,0,0]
	ds_read_b128 v[196:199], v8 offset:13616
	s_waitcnt lgkmcnt(5)
	v_pk_fma_f32 v[230:231], v[200:201], v[128:129], v[230:231] neg_lo:[1,0,0] neg_hi:[1,0,0]
	v_pk_fma_f32 v[230:231], v[202:203], v[130:131], v[230:231] neg_lo:[1,0,0] neg_hi:[1,0,0]
	ds_read_b128 v[200:203], v8 offset:13632
	s_waitcnt lgkmcnt(5)
	v_pk_fma_f32 v[230:231], v[204:205], v[132:133], v[230:231] neg_lo:[1,0,0] neg_hi:[1,0,0]
	v_pk_fma_f32 v[230:231], v[206:207], v[134:135], v[230:231] neg_lo:[1,0,0] neg_hi:[1,0,0]
	ds_read_b128 v[204:207], v8 offset:13648
	v_add_f32_e32 v136, v230, v231
	s_cbranch_vccz .Ls4_u52
	v_cvt_pk_bf16_f32 v233, -v136, v136
	global_store_short v6, v233, s[8:9] offset:1024
	s_branch .Ls4_n52

; __device__ __forceinline__ void chunk_prep_phase(const Params& p, int bid, int nblk, LAS unsigned char* lds0) {
;     ...
;             { const float br = betg[53]; ab0 = (f32x2){bf2f(*(const LAS bf16_t*)(lg + P5_VS + 14416 + c * 2)) * br, bf2f(*(const LAS bf16_t*)(lg + P5_KS + 14416 + c * 2)) * br * __expf(decg[53])}; ab1 = (f32x2){0.f, 0.f}; } ab0 -= mq[4][0] * xy[0]; ab1 -= mq[4][1] * xy[1]; ab0 -= mq[4][2] * xy[2]; ab1 -= mq[4][3] * xy[3]; mq[4] = *(const LAS f32x4*)(Mg + 3416);
;             ab0 -= mq[5][0] * xy[4]; ab1 -= mq[5][1] * xy[5]; ab0 -= mq[5][2] * xy[6]; ab1 -= mq[5][3] * xy[7]; mq[5] = *(const LAS f32x4*)(Mg + 3420);
;             ab0 -= mq[0][0] * xy[8]; ab1 -= mq[0][1] * xy[9]; ab0 -= mq[0][2] * xy[10]; ab1 -= mq[0][3] * xy[11]; mq[0] = *(const LAS f32x4*)(Mg + 3424);
;             ab0 -= mq[1][0] * xy[12]; ab1 -= mq[1][1] * xy[13]; ab0 -= mq[1][2] * xy[14]; ab1 -= mq[1][3] * xy[15]; mq[1] = *(const LAS f32x4*)(Mg + 3428);
;             ab0 -= mq[2][0] * xy[16]; ab1 -= mq[2][1] * xy[17]; ab0 -= mq[2][2] * xy[18]; ab1 -= mq[2][3] * xy[19]; mq[2] = *(const LAS f32x4*)(Mg + 3432);
;             ab0 -= mq[3][0] * xy[20]; ab1 -= mq[3][1] * xy[21]; ab0 -= mq[3][2] * xy[22]; ab1 -= mq[3][3] * xy[23]; mq[3] = *(const LAS f32x4*)(Mg + 3436);
;             ab0 -= mq[4][0] * xy[24]; ab1 -= mq[4][1] * xy[25]; ab0 -= mq[4][2] * xy[26]; ab1 -= mq[4][3] * xy[27]; mq[4] = *(const LAS f32x4*)(Mg + 3440);
;             ab0 -= mq[5][0] * xy[28]; ab1 -= mq[5][1] * xy[29]; ab0 -= mq[5][2] * xy[30]; ab1 -= mq[5][3] * xy[31]; mq[5] = *(const LAS f32x4*)(Mg + 3444);
;             ab0 -= mq[0][0] * xy[32]; ab1 -= mq[0][1] * xy[33]; ab0 -= mq[0][2] * xy[34]; ab1 -= mq[0][3] * xy[35]; mq[0] = *(const LAS f32x4*)(Mg + 3456);
;             ab0 -= mq[1][0] * xy[36]; ab1 -= mq[1][1] * xy[37]; ab0 -= mq[1][2] * xy[38]; ab1 -= mq[1][3] * xy[39]; mq[1] = *(const LAS f32x4*)(Mg + 3460);
;             ab0 -= mq[2][0] * xy[40]; ab1 -= mq[2][1] * xy[41]; ab0 -= mq[2][2] * xy[42]; ab1 -= mq[2][3] * xy[43]; mq[2] = *(const LAS f32x4*)(Mg + 3464);
;             ab0 -= mq[3][0] * xy[44]; ab1 -= mq[3][1] * xy[45]; ab0 -= mq[3][2] * xy[46]; ab1 -= mq[3][3] * xy[47]; mq[3] = *(const LAS f32x4*)(Mg + 3468);
;             ab0 -= mq[4][0] * xy[48]; ab1 -= mq[4][1] * xy[49]; ab0 -= mq[4][2] * xy[50]; ab1 -= mq[4][3] * xy[51]; mq[4] = *(const LAS f32x4*)(Mg + 3472);
.Ls4_n52:
	v_lshlrev_b32_e32 v229, 16, v229
	v_mul_f32_e32 v232, v229, v221
	v_mul_f32_e32 v230, v232, v225
	v_mov_b32_e32 v231, 0
	ds_read_u16 v228, v7 offset:14688
	s_waitcnt lgkmcnt(6)
	v_pk_fma_f32 v[230:231], v[208:209], v[84:85], v[230:231] neg_lo:[1,0,0] neg_hi:[1,0,0]
	v_pk_fma_f32 v[230:231], v[210:211], v[86:87], v[230:231] neg_lo:[1,0,0] neg_hi:[1,0,0]
	ds_read_b128 v[208:211], v8 offset:13664
	s_waitcnt lgkmcnt(6)
	v_pk_fma_f32 v[230:231], v[212:213], v[88:89], v[230:231] neg_lo:[1,0,0] neg_hi:[1,0,0]
	v_pk_fma_f32 v[230:231], v[214:215], v[90:91], v[230:231] neg_lo:[1,0,0] neg_hi:[1,0,0]
	ds_read_b128 v[212:215], v8 offset:13680
	s_waitcnt lgkmcnt(6)
	v_pk_fma_f32 v[230:231], v[192:193], v[92:93], v[230:231] neg_lo:[1,0,0] neg_hi:[1,0,0]
	v_pk_fma_f32 v[230:231], v[194:195], v[94:95], v[230:231] neg_lo:[1,0,0] neg_hi:[1,0,0]
	ds_read_b128 v[192:195], v8 offset:13696
	s_waitcnt lgkmcnt(6)
	v_pk_fma_f32 v[230:231], v[196:197], v[96:97], v[230:231] neg_lo:[1,0,0] neg_hi:[1,0,0]
	v_pk_fma_f32 v[230:231], v[198:199], v[98:99], v[230:231] neg_lo:[1,0,0] neg_hi:[1,0,0]
	ds_read_b128 v[196:199], v8 offset:13712
	s_waitcnt lgkmcnt(6)
	v_pk_fma_f32 v[230:231], v[200:201], v[100:101], v[230:231] neg_lo:[1,0,0] neg_hi:[1,0,0]
	v_pk_fma_f32 v[230:231], v[202:203], v[102:103], v[230:231] neg_lo:[1,0,0] neg_hi:[1,0,0]
	ds_read_b128 v[200:203], v8 offset:13728
	s_waitcnt lgkmcnt(6)
	v_pk_fma_f32 v[230:231], v[204:205], v[104:105], v[230:231] neg_lo:[1,0,0] neg_hi:[1,0,0]
	v_pk_fma_f32 v[230:231], v[206:207], v[106:107], v[230:231] neg_lo:[1,0,0] neg_hi:[1,0,0]
	ds_read_b128 v[204:207], v8 offset:13744
	s_waitcnt lgkmcnt(5)
	v_pk_fma_f32 v[230:231], v[208:209], v[108:109], v[230:231] neg_lo:[1,0,0] neg_hi:[1,0,0]
	v_pk_fma_f32 v[230:231], v[210:211], v[110:111], v[230:231] neg_lo:[1,0,0] neg_hi:[1,0,0]
	ds_read_b128 v[208:211], v8 offset:13760
	s_waitcnt lgkmcnt(5)
	v_pk_fma_f32 v[230:231], v[212:213], v[112:113], v[230:231] neg_lo:[1,0,0] neg_hi:[1,0,0]
	v_pk_fma_f32 v[230:231], v[214:215], v[114:115], v[230:231] neg_lo:[1,0,0] neg_hi:[1,0,0]
	ds_read_b128 v[212:215], v8 offset:13776
	s_waitcnt lgkmcnt(5)
	v_pk_fma_f32 v[230:231], v[192:193], v[116:117], v[230:231] neg_lo:[1,0,0] neg_hi:[1,0,0]
	v_pk_fma_f32 v[230:231], v[194:195], v[118:119], v[230:231] neg_lo:[1,0,0] neg_hi:[1,0,0]
	ds_read_b128 v[192:195], v8 offset:13824
	s_waitcnt lgkmcnt(5)
	v_pk_fma_f32 v[230:231], v[196:197], v[120:121], v[230:231] neg_lo:[1,0,0] neg_hi:[1,0,0]
	v_pk_fma_f32 v[230:231], v[198:199], v[122:123], v[230:231] neg_lo:[1,0,0] neg_hi:[1,0,0]
	ds_read_b128 v[196:199], v8 offset:13840
	s_waitcnt lgkmcnt(5)
	v_pk_fma_f32 v[230:231], v[200:201], v[124:125], v[230:231] neg_lo:[1,0,0] neg_hi:[1,0,0]
	v_pk_fma_f32 v[230:231], v[202:203], v[126:127], v[230:231] neg_lo:[1,0,0] neg_hi:[1,0,0]
	ds_read_b128 v[200:203], v8 offset:13856
	s_waitcnt lgkmcnt(5)
	v_pk_fma_f32 v[230:231], v[204:205], v[128:129], v[230:231] neg_lo:[1,0,0] neg_hi:[1,0,0]
	v_pk_fma_f32 v[230:231], v[206:207], v[130:131], v[230:231] neg_lo:[1,0,0] neg_hi:[1,0,0]
	ds_read_b128 v[204:207], v8 offset:13872
	s_waitcnt lgkmcnt(5)
	v_pk_fma_f32 v[230:231], v[208:209], v[132:133], v[230:231] neg_lo:[1,0,0] neg_hi:[1,0,0]
	v_pk_fma_f32 v[230:231], v[210:211], v[134:135], v[230:231] neg_lo:[1,0,0] neg_hi:[1,0,0]
	ds_read_b128 v[208:211], v8 offset:13888
	s_waitcnt lgkmcnt(5)
	v_fma_f32 v230, -v212, v136, v230
	ds_read_b128 v[212:215], v8 offset:13904
	v_add_f32_e32 v137, v230, v231
	s_cbranch_vccz .Ls4_u53
	v_cvt_pk_bf16_f32 v233, -v137, v137
	global_store_short v6, v233, s[8:9] offset:1280
	s_branch .Ls4_n53

; __device__ __forceinline__ void chunk_prep_phase(const Params& p, int bid, int nblk, LAS unsigned char* lds0) {
;     ...
;             { const float br = betg[54]; ab0 = (f32x2){bf2f(*(const LAS bf16_t*)(lg + P5_VS + 14688 + c * 2)) * br, bf2f(*(const LAS bf16_t*)(lg + P5_KS + 14688 + c * 2)) * br * __expf(decg[54])}; ab1 = (f32x2){0.f, 0.f}; } ab0 -= mq[0][0] * xy[0]; ab1 -= mq[0][1] * xy[1]; ab0 -= mq[0][2] * xy[2]; ab1 -= mq[0][3] * xy[3]; mq[0] = *(const LAS f32x4*)(Mg + 3480);
;             ab0 -= mq[1][0] * xy[4]; ab1 -= mq[1][1] * xy[5]; ab0 -= mq[1][2] * xy[6]; ab1 -= mq[1][3] * xy[7]; mq[1] = *(const LAS f32x4*)(Mg + 3484);
;             ab0 -= mq[2][0] * xy[8]; ab1 -= mq[2][1] * xy[9]; ab0 -= mq[2][2] * xy[10]; ab1 -= mq[2][3] * xy[11]; mq[2] = *(const LAS f32x4*)(Mg + 3488);
;             ab0 -= mq[3][0] * xy[12]; ab1 -= mq[3][1] * xy[13]; ab0 -= mq[3][2] * xy[14]; ab1 -= mq[3][3] * xy[15]; mq[3] = *(const LAS f32x4*)(Mg + 3492);
;             ab0 -= mq[4][0] * xy[16]; ab1 -= mq[4][1] * xy[17]; ab0 -= mq[4][2] * xy[18]; ab1 -= mq[4][3] * xy[19]; mq[4] = *(const LAS f32x4*)(Mg + 3496);
;             ab0 -= mq[5][0] * xy[20]; ab1 -= mq[5][1] * xy[21]; ab0 -= mq[5][2] * xy[22]; ab1 -= mq[5][3] * xy[23]; mq[5] = *(const LAS f32x4*)(Mg + 3500);
;             ab0 -= mq[0][0] * xy[24]; ab1 -= mq[0][1] * xy[25]; ab0 -= mq[0][2] * xy[26]; ab1 -= mq[0][3] * xy[27]; mq[0] = *(const LAS f32x4*)(Mg + 3504);
;             ab0 -= mq[1][0] * xy[28]; ab1 -= mq[1][1] * xy[29]; ab0 -= mq[1][2] * xy[30]; ab1 -= mq[1][3] * xy[31]; mq[1] = *(const LAS f32x4*)(Mg + 3508);
;             ab0 -= mq[2][0] * xy[32]; ab1 -= mq[2][1] * xy[33]; ab0 -= mq[2][2] * xy[34]; ab1 -= mq[2][3] * xy[35]; mq[2] = *(const LAS f32x4*)(Mg + 3520);
;             ab0 -= mq[3][0] * xy[36]; ab1 -= mq[3][1] * xy[37]; ab0 -= mq[3][2] * xy[38]; ab1 -= mq[3][3] * xy[39]; mq[3] = *(const LAS f32x4*)(Mg + 3524);
;             ab0 -= mq[4][0] * xy[40]; ab1 -= mq[4][1] * xy[41]; ab0 -= mq[4][2] * xy[42]; ab1 -= mq[4][3] * xy[43]; mq[4] = *(const LAS f32x4*)(Mg + 3528);
;             ab0 -= mq[5][0] * xy[44]; ab1 -= mq[5][1] * xy[45]; ab0 -= mq[5][2] * xy[46]; ab1 -= mq[5][3] * xy[47]; mq[5] = *(const LAS f32x4*)(Mg + 3532);
;             ab0 -= mq[0][0] * xy[48]; ab1 -= mq[0][1] * xy[49]; ab0 -= mq[0][2] * xy[50]; ab1 -= mq[0][3] * xy[51]; mq[0] = *(const LAS f32x4*)(Mg + 3536);
.Ls4_n53:
	v_lshlrev_b32_e32 v228, 16, v228
	v_mul_f32_e32 v232, v228, v222
	v_mul_f32_e32 v230, v232, v226
	v_mov_b32_e32 v231, 0
	ds_read_u16 v229, v7 offset:14960
	s_waitcnt lgkmcnt(6)
	v_pk_fma_f32 v[230:231], v[192:193], v[84:85], v[230:231] neg_lo:[1,0,0] neg_hi:[1,0,0]
	v_pk_fma_f32 v[230:231], v[194:195], v[86:87], v[230:231] neg_lo:[1,0,0] neg_hi:[1,0,0]
	ds_read_b128 v[192:195], v8 offset:13920
	s_waitcnt lgkmcnt(6)
	v_pk_fma_f32 v[230:231], v[196:197], v[88:89], v[230:231] neg_lo:[1,0,0] neg_hi:[1,0,0]
	v_pk_fma_f32 v[230:231], v[198:199], v[90:91], v[230:231] neg_lo:[1,0,0] neg_hi:[1,0,0]
	ds_read_b128 v[196:199], v8 offset:13936
	s_waitcnt lgkmcnt(6)
	v_pk_fma_f32 v[230:231], v[200:201], v[92:93], v[230:231] neg_lo:[1,0,0] neg_hi:[1,0,0]
	v_pk_fma_f32 v[230:231], v[202:203], v[94:95], v[230:231] neg_lo:[1,0,0] neg_hi:[1,0,0]
	ds_read_b128 v[200:203], v8 offset:13952
	s_waitcnt lgkmcnt(6)
	v_pk_fma_f32 v[230:231], v[204:205], v[96:97], v[230:231] neg_lo:[1,0,0] neg_hi:[1,0,0]
	v_pk_fma_f32 v[230:231], v[206:207], v[98:99], v[230:231] neg_lo:[1,0,0] neg_hi:[1,0,0]
	ds_read_b128 v[204:207], v8 offset:13968
	s_waitcnt lgkmcnt(6)
	v_pk_fma_f32 v[230:231], v[208:209], v[100:101], v[230:231] neg_lo:[1,0,0] neg_hi:[1,0,0]
	v_pk_fma_f32 v[230:231], v[210:211], v[102:103], v[230:231] neg_lo:[1,0,0] neg_hi:[1,0,0]
	ds_read_b128 v[208:211], v8 offset:13984
	s_waitcnt lgkmcnt(6)
	v_pk_fma_f32 v[230:231], v[212:213], v[104:105], v[230:231] neg_lo:[1,0,0] neg_hi:[1,0,0]
	v_pk_fma_f32 v[230:231], v[214:215], v[106:107], v[230:231] neg_lo:[1,0,0] neg_hi:[1,0,0]
	ds_read_b128 v[212:215], v8 offset:14000
	s_waitcnt lgkmcnt(5)
	v_pk_fma_f32 v[230:231], v[192:193], v[108:109], v[230:231] neg_lo:[1,0,0] neg_hi:[1,0,0]
	v_pk_fma_f32 v[230:231], v[194:195], v[110:111], v[230:231] neg_lo:[1,0,0] neg_hi:[1,0,0]
	ds_read_b128 v[192:195], v8 offset:14016
	s_waitcnt lgkmcnt(5)
	v_pk_fma_f32 v[230:231], v[196:197], v[112:113], v[230:231] neg_lo:[1,0,0] neg_hi:[1,0,0]
	v_pk_fma_f32 v[230:231], v[198:199], v[114:115], v[230:231] neg_lo:[1,0,0] neg_hi:[1,0,0]
	ds_read_b128 v[196:199], v8 offset:14032
	s_waitcnt lgkmcnt(5)
	v_pk_fma_f32 v[230:231], v[200:201], v[116:117], v[230:231] neg_lo:[1,0,0] neg_hi:[1,0,0]
	v_pk_fma_f32 v[230:231], v[202:203], v[118:119], v[230:231] neg_lo:[1,0,0] neg_hi:[1,0,0]
	ds_read_b128 v[200:203], v8 offset:14080
	s_waitcnt lgkmcnt(5)
	v_pk_fma_f32 v[230:231], v[204:205], v[120:121], v[230:231] neg_lo:[1,0,0] neg_hi:[1,0,0]
	v_pk_fma_f32 v[230:231], v[206:207], v[122:123], v[230:231] neg_lo:[1,0,0] neg_hi:[1,0,0]
	ds_read_b128 v[204:207], v8 offset:14096
	s_waitcnt lgkmcnt(5)
	v_pk_fma_f32 v[230:231], v[208:209], v[124:125], v[230:231] neg_lo:[1,0,0] neg_hi:[1,0,0]
	v_pk_fma_f32 v[230:231], v[210:211], v[126:127], v[230:231] neg_lo:[1,0,0] neg_hi:[1,0,0]
	ds_read_b128 v[208:211], v8 offset:14112
	s_waitcnt lgkmcnt(5)
	v_pk_fma_f32 v[230:231], v[212:213], v[128:129], v[230:231] neg_lo:[1,0,0] neg_hi:[1,0,0]
	v_pk_fma_f32 v[230:231], v[214:215], v[130:131], v[230:231] neg_lo:[1,0,0] neg_hi:[1,0,0]
	ds_read_b128 v[212:215], v8 offset:14128
	s_waitcnt lgkmcnt(5)
	v_pk_fma_f32 v[230:231], v[192:193], v[132:133], v[230:231] neg_lo:[1,0,0] neg_hi:[1,0,0]
	v_pk_fma_f32 v[230:231], v[194:195], v[134:135], v[230:231] neg_lo:[1,0,0] neg_hi:[1,0,0]
	ds_read_b128 v[192:195], v8 offset:14144
	s_waitcnt lgkmcnt(5)
	v_pk_fma_f32 v[230:231], v[196:197], v[136:137], v[230:231] neg_lo:[1,0,0] neg_hi:[1,0,0]
	ds_read_b128 v[196:199], v8 offset:14160
	v_add_f32_e32 v138, v230, v231
	s_cbranch_vccz .Ls4_u54
	v_cvt_pk_bf16_f32 v233, -v138, v138
	global_store_short v6, v233, s[8:9] offset:1536
	s_branch .Ls4_n54

; __device__ __forceinline__ void chunk_prep_phase(const Params& p, int bid, int nblk, LAS unsigned char* lds0) {
;     ...
;             { const float br = betg[55]; ab0 = (f32x2){bf2f(*(const LAS bf16_t*)(lg + P5_VS + 14960 + c * 2)) * br, bf2f(*(const LAS bf16_t*)(lg + P5_KS + 14960 + c * 2)) * br * __expf(decg[55])}; ab1 = (f32x2){0.f, 0.f}; } ab0 -= mq[2][0] * xy[0]; ab1 -= mq[2][1] * xy[1]; ab0 -= mq[2][2] * xy[2]; ab1 -= mq[2][3] * xy[3]; mq[2] = *(const LAS f32x4*)(Mg + 3544);
;             ab0 -= mq[3][0] * xy[4]; ab1 -= mq[3][1] * xy[5]; ab0 -= mq[3][2] * xy[6]; ab1 -= mq[3][3] * xy[7]; mq[3] = *(const LAS f32x4*)(Mg + 3548);
;             ab0 -= mq[4][0] * xy[8]; ab1 -= mq[4][1] * xy[9]; ab0 -= mq[4][2] * xy[10]; ab1 -= mq[4][3] * xy[11]; mq[4] = *(const LAS f32x4*)(Mg + 3552);
;             ab0 -= mq[5][0] * xy[12]; ab1 -= mq[5][1] * xy[13]; ab0 -= mq[5][2] * xy[14]; ab1 -= mq[5][3] * xy[15]; mq[5] = *(const LAS f32x4*)(Mg + 3556);
;             ab0 -= mq[0][0] * xy[16]; ab1 -= mq[0][1] * xy[17]; ab0 -= mq[0][2] * xy[18]; ab1 -= mq[0][3] * xy[19]; mq[0] = *(const LAS f32x4*)(Mg + 3560);
;             ab0 -= mq[1][0] * xy[20]; ab1 -= mq[1][1] * xy[21]; ab0 -= mq[1][2] * xy[22]; ab1 -= mq[1][3] * xy[23]; mq[1] = *(const LAS f32x4*)(Mg + 3564);
;             ab0 -= mq[2][0] * xy[24]; ab1 -= mq[2][1] * xy[25]; ab0 -= mq[2][2] * xy[26]; ab1 -= mq[2][3] * xy[27]; mq[2] = *(const LAS f32x4*)(Mg + 3568);
;             ab0 -= mq[3][0] * xy[28]; ab1 -= mq[3][1] * xy[29]; ab0 -= mq[3][2] * xy[30]; ab1 -= mq[3][3] * xy[31]; mq[3] = *(const LAS f32x4*)(Mg + 3572);
;             ab0 -= mq[4][0] * xy[32]; ab1 -= mq[4][1] * xy[33]; ab0 -= mq[4][2] * xy[34]; ab1 -= mq[4][3] * xy[35]; mq[4] = *(const LAS f32x4*)(Mg + 3584);
;             ab0 -= mq[5][0] * xy[36]; ab1 -= mq[5][1] * xy[37]; ab0 -= mq[5][2] * xy[38]; ab1 -= mq[5][3] * xy[39]; mq[5] = *(const LAS f32x4*)(Mg + 3588);
;             ab0 -= mq[0][0] * xy[40]; ab1 -= mq[0][1] * xy[41]; ab0 -= mq[0][2] * xy[42]; ab1 -= mq[0][3] * xy[43]; mq[0] = *(const LAS f32x4*)(Mg + 3592);
;             ab0 -= mq[1][0] * xy[44]; ab1 -= mq[1][1] * xy[45]; ab0 -= mq[1][2] * xy[46]; ab1 -= mq[1][3] * xy[47]; mq[1] = *(const LAS f32x4*)(Mg + 3596);
;             ab0 -= mq[2][0] * xy[48]; ab1 -= mq[2][1] * xy[49]; ab0 -= mq[2][2] * xy[50]; ab1 -= mq[2][3] * xy[51]; mq[2] = *(const LAS f32x4*)(Mg + 3600);
.Ls4_n54:
	v_lshlrev_b32_e32 v229, 16, v229
	v_mul_f32_e32 v232, v229, v223
	v_mul_f32_e32 v230, v232, v227
	v_mov_b32_e32 v231, 0
	ds_read_u16 v228, v7 offset:15232
	ds_read_b128 v[220:223], v8 offset:16880
	ds_read_b128 v[224:227], v8 offset:16624
	s_waitcnt lgkmcnt(8)
	v_pk_fma_f32 v[230:231], v[200:201], v[84:85], v[230:231] neg_lo:[1,0,0] neg_hi:[1,0,0]
	v_pk_fma_f32 v[230:231], v[202:203], v[86:87], v[230:231] neg_lo:[1,0,0] neg_hi:[1,0,0]
	ds_read_b128 v[200:203], v8 offset:14176
	s_waitcnt lgkmcnt(8)
	v_pk_fma_f32 v[230:231], v[204:205], v[88:89], v[230:231] neg_lo:[1,0,0] neg_hi:[1,0,0]
	v_pk_fma_f32 v[230:231], v[206:207], v[90:91], v[230:231] neg_lo:[1,0,0] neg_hi:[1,0,0]
	ds_read_b128 v[204:207], v8 offset:14192
	s_waitcnt lgkmcnt(8)
	v_pk_fma_f32 v[230:231], v[208:209], v[92:93], v[230:231] neg_lo:[1,0,0] neg_hi:[1,0,0]
	v_pk_fma_f32 v[230:231], v[210:211], v[94:95], v[230:231] neg_lo:[1,0,0] neg_hi:[1,0,0]
	ds_read_b128 v[208:211], v8 offset:14208
	s_waitcnt lgkmcnt(8)
	v_pk_fma_f32 v[230:231], v[212:213], v[96:97], v[230:231] neg_lo:[1,0,0] neg_hi:[1,0,0]
	v_pk_fma_f32 v[230:231], v[214:215], v[98:99], v[230:231] neg_lo:[1,0,0] neg_hi:[1,0,0]
	ds_read_b128 v[212:215], v8 offset:14224
	s_waitcnt lgkmcnt(8)
	v_pk_fma_f32 v[230:231], v[192:193], v[100:101], v[230:231] neg_lo:[1,0,0] neg_hi:[1,0,0]
	v_pk_fma_f32 v[230:231], v[194:195], v[102:103], v[230:231] neg_lo:[1,0,0] neg_hi:[1,0,0]
	ds_read_b128 v[192:195], v8 offset:14240
	s_waitcnt lgkmcnt(8)
	v_pk_fma_f32 v[230:231], v[196:197], v[104:105], v[230:231] neg_lo:[1,0,0] neg_hi:[1,0,0]
	v_pk_fma_f32 v[230:231], v[198:199], v[106:107], v[230:231] neg_lo:[1,0,0] neg_hi:[1,0,0]
	ds_read_b128 v[196:199], v8 offset:14256
	s_waitcnt lgkmcnt(5)
	v_pk_fma_f32 v[230:231], v[200:201], v[108:109], v[230:231] neg_lo:[1,0,0] neg_hi:[1,0,0]
	v_pk_fma_f32 v[230:231], v[202:203], v[110:111], v[230:231] neg_lo:[1,0,0] neg_hi:[1,0,0]
	ds_read_b128 v[200:203], v8 offset:14272
	s_waitcnt lgkmcnt(5)
	v_pk_fma_f32 v[230:231], v[204:205], v[112:113], v[230:231] neg_lo:[1,0,0] neg_hi:[1,0,0]
	v_pk_fma_f32 v[230:231], v[206:207], v[114:115], v[230:231] neg_lo:[1,0,0] neg_hi:[1,0,0]
	ds_read_b128 v[204:207], v8 offset:14288
	s_waitcnt lgkmcnt(5)
	v_pk_fma_f32 v[230:231], v[208:209], v[116:117], v[230:231] neg_lo:[1,0,0] neg_hi:[1,0,0]
	v_pk_fma_f32 v[230:231], v[210:211], v[118:119], v[230:231] neg_lo:[1,0,0] neg_hi:[1,0,0]
	ds_read_b128 v[208:211], v8 offset:14336
	s_waitcnt lgkmcnt(5)
	v_pk_fma_f32 v[230:231], v[212:213], v[120:121], v[230:231] neg_lo:[1,0,0] neg_hi:[1,0,0]
	v_pk_fma_f32 v[230:231], v[214:215], v[122:123], v[230:231] neg_lo:[1,0,0] neg_hi:[1,0,0]
	ds_read_b128 v[212:215], v8 offset:14352
	s_waitcnt lgkmcnt(5)
	v_pk_fma_f32 v[230:231], v[192:193], v[124:125], v[230:231] neg_lo:[1,0,0] neg_hi:[1,0,0]
	v_pk_fma_f32 v[230:231], v[194:195], v[126:127], v[230:231] neg_lo:[1,0,0] neg_hi:[1,0,0]
	ds_read_b128 v[192:195], v8 offset:14368
	s_waitcnt lgkmcnt(5)
	v_pk_fma_f32 v[230:231], v[196:197], v[128:129], v[230:231] neg_lo:[1,0,0] neg_hi:[1,0,0]
	v_pk_fma_f32 v[230:231], v[198:199], v[130:131], v[230:231] neg_lo:[1,0,0] neg_hi:[1,0,0]
	ds_read_b128 v[196:199], v8 offset:14384
	s_waitcnt lgkmcnt(5)
	v_pk_fma_f32 v[230:231], v[200:201], v[132:133], v[230:231] neg_lo:[1,0,0] neg_hi:[1,0,0]
	v_pk_fma_f32 v[230:231], v[202:203], v[134:135], v[230:231] neg_lo:[1,0,0] neg_hi:[1,0,0]
	ds_read_b128 v[200:203], v8 offset:14400
	s_waitcnt lgkmcnt(5)
	v_pk_fma_f32 v[230:231], v[204:205], v[136:137], v[230:231] neg_lo:[1,0,0] neg_hi:[1,0,0]
	v_fma_f32 v230, -v206, v138, v230
	ds_read_b128 v[204:207], v8 offset:14416
	v_add_f32_e32 v139, v230, v231
	s_cbranch_vccz .Ls4_u55
	v_cvt_pk_bf16_f32 v233, -v139, v139
	global_store_short v6, v233, s[8:9] offset:1792
	s_branch .Ls4_n55

; __device__ __forceinline__ void chunk_prep_phase(const Params& p, int bid, int nblk, LAS unsigned char* lds0) {
;     ...
;             { const float br = betg[56]; ab0 = (f32x2){bf2f(*(const LAS bf16_t*)(lg + P5_VS + 15232 + c * 2)) * br, bf2f(*(const LAS bf16_t*)(lg + P5_KS + 15232 + c * 2)) * br * __expf(decg[56])}; ab1 = (f32x2){0.f, 0.f}; } ab0 -= mq[4][0] * xy[0]; ab1 -= mq[4][1] * xy[1]; ab0 -= mq[4][2] * xy[2]; ab1 -= mq[4][3] * xy[3]; mq[4] = *(const LAS f32x4*)(Mg + 3608);
;             ab0 -= mq[5][0] * xy[4]; ab1 -= mq[5][1] * xy[5]; ab0 -= mq[5][2] * xy[6]; ab1 -= mq[5][3] * xy[7]; mq[5] = *(const LAS f32x4*)(Mg + 3612);
;             ab0 -= mq[0][0] * xy[8]; ab1 -= mq[0][1] * xy[9]; ab0 -= mq[0][2] * xy[10]; ab1 -= mq[0][3] * xy[11]; mq[0] = *(const LAS f32x4*)(Mg + 3616);
;             ab0 -= mq[1][0] * xy[12]; ab1 -= mq[1][1] * xy[13]; ab0 -= mq[1][2] * xy[14]; ab1 -= mq[1][3] * xy[15]; mq[1] = *(const LAS f32x4*)(Mg + 3620);
;             ab0 -= mq[2][0] * xy[16]; ab1 -= mq[2][1] * xy[17]; ab0 -= mq[2][2] * xy[18]; ab1 -= mq[2][3] * xy[19]; mq[2] = *(const LAS f32x4*)(Mg + 3624);
;             ab0 -= mq[3][0] * xy[20]; ab1 -= mq[3][1] * xy[21]; ab0 -= mq[3][2] * xy[22]; ab1 -= mq[3][3] * xy[23]; mq[3] = *(const LAS f32x4*)(Mg + 3628);
;             ab0 -= mq[4][0] * xy[24]; ab1 -= mq[4][1] * xy[25]; ab0 -= mq[4][2] * xy[26]; ab1 -= mq[4][3] * xy[27]; mq[4] = *(const LAS f32x4*)(Mg + 3632);
;             ab0 -= mq[5][0] * xy[28]; ab1 -= mq[5][1] * xy[29]; ab0 -= mq[5][2] * xy[30]; ab1 -= mq[5][3] * xy[31]; mq[5] = *(const LAS f32x4*)(Mg + 3636);
;             ab0 -= mq[0][0] * xy[32]; ab1 -= mq[0][1] * xy[33]; ab0 -= mq[0][2] * xy[34]; ab1 -= mq[0][3] * xy[35]; mq[0] = *(const LAS f32x4*)(Mg + 3648);
;             ab0 -= mq[1][0] * xy[36]; ab1 -= mq[1][1] * xy[37]; ab0 -= mq[1][2] * xy[38]; ab1 -= mq[1][3] * xy[39]; mq[1] = *(const LAS f32x4*)(Mg + 3652);
;             ab0 -= mq[2][0] * xy[40]; ab1 -= mq[2][1] * xy[41]; ab0 -= mq[2][2] * xy[42]; ab1 -= mq[2][3] * xy[43]; mq[2] = *(const LAS f32x4*)(Mg + 3656);
;             ab0 -= mq[3][0] * xy[44]; ab1 -= mq[3][1] * xy[45]; ab0 -= mq[3][2] * xy[46]; ab1 -= mq[3][3] * xy[47]; mq[3] = *(const LAS f32x4*)(Mg + 3660);
;             ab0 -= mq[4][0] * xy[48]; ab1 -= mq[4][1] * xy[49]; ab0 -= mq[4][2] * xy[50]; ab1 -= mq[4][3] * xy[51]; mq[4] = *(const LAS f32x4*)(Mg + 3664);
.Ls4_n55:
	v_mul_f32_e32 v0, s16, v0
	v_mul_f32_e32 v1, s16, v1
	v_mul_f32_e32 v2, s16, v2
	v_mul_f32_e32 v3, s16, v3
	v_exp_f32_e32 v0, v0
	v_exp_f32_e32 v1, v1
	v_exp_f32_e32 v2, v2
	v_exp_f32_e32 v3, v3
	s_nop 0
	v_lshlrev_b32_e32 v228, 16, v228
	v_mul_f32_e32 v232, v228, v216
	v_mul_f32_e32 v230, v232, v0
	v_mov_b32_e32 v231, 0
	ds_read_u16 v229, v7 offset:15504
	s_waitcnt lgkmcnt(6)
	v_pk_fma_f32 v[230:231], v[208:209], v[84:85], v[230:231] neg_lo:[1,0,0] neg_hi:[1,0,0]
	v_pk_fma_f32 v[230:231], v[210:211], v[86:87], v[230:231] neg_lo:[1,0,0] neg_hi:[1,0,0]
	ds_read_b128 v[208:211], v8 offset:14432
	s_waitcnt lgkmcnt(6)
	v_pk_fma_f32 v[230:231], v[212:213], v[88:89], v[230:231] neg_lo:[1,0,0] neg_hi:[1,0,0]
	v_pk_fma_f32 v[230:231], v[214:215], v[90:91], v[230:231] neg_lo:[1,0,0] neg_hi:[1,0,0]
	ds_read_b128 v[212:215], v8 offset:14448
	s_waitcnt lgkmcnt(6)
	v_pk_fma_f32 v[230:231], v[192:193], v[92:93], v[230:231] neg_lo:[1,0,0] neg_hi:[1,0,0]
	v_pk_fma_f32 v[230:231], v[194:195], v[94:95], v[230:231] neg_lo:[1,0,0] neg_hi:[1,0,0]
	ds_read_b128 v[192:195], v8 offset:14464
	s_waitcnt lgkmcnt(6)
	v_pk_fma_f32 v[230:231], v[196:197], v[96:97], v[230:231] neg_lo:[1,0,0] neg_hi:[1,0,0]
	v_pk_fma_f32 v[230:231], v[198:199], v[98:99], v[230:231] neg_lo:[1,0,0] neg_hi:[1,0,0]
	ds_read_b128 v[196:199], v8 offset:14480
	s_waitcnt lgkmcnt(6)
	v_pk_fma_f32 v[230:231], v[200:201], v[100:101], v[230:231] neg_lo:[1,0,0] neg_hi:[1,0,0]
	v_pk_fma_f32 v[230:231], v[202:203], v[102:103], v[230:231] neg_lo:[1,0,0] neg_hi:[1,0,0]
	ds_read_b128 v[200:203], v8 offset:14496
	s_waitcnt lgkmcnt(6)
	v_pk_fma_f32 v[230:231], v[204:205], v[104:105], v[230:231] neg_lo:[1,0,0] neg_hi:[1,0,0]
	v_pk_fma_f32 v[230:231], v[206:207], v[106:107], v[230:231] neg_lo:[1,0,0] neg_hi:[1,0,0]
	ds_read_b128 v[204:207], v8 offset:14512
	s_waitcnt lgkmcnt(5)
	v_pk_fma_f32 v[230:231], v[208:209], v[108:109], v[230:231] neg_lo:[1,0,0] neg_hi:[1,0,0]
	v_pk_fma_f32 v[230:231], v[210:211], v[110:111], v[230:231] neg_lo:[1,0,0] neg_hi:[1,0,0]
	ds_read_b128 v[208:211], v8 offset:14528
	s_waitcnt lgkmcnt(5)
	v_pk_fma_f32 v[230:231], v[212:213], v[112:113], v[230:231] neg_lo:[1,0,0] neg_hi:[1,0,0]
	v_pk_fma_f32 v[230:231], v[214:215], v[114:115], v[230:231] neg_lo:[1,0,0] neg_hi:[1,0,0]
	ds_read_b128 v[212:215], v8 offset:14544
	s_waitcnt lgkmcnt(5)
	v_pk_fma_f32 v[230:231], v[192:193], v[116:117], v[230:231] neg_lo:[1,0,0] neg_hi:[1,0,0]
	v_pk_fma_f32 v[230:231], v[194:195], v[118:119], v[230:231] neg_lo:[1,0,0] neg_hi:[1,0,0]
	ds_read_b128 v[192:195], v8 offset:14592
	s_waitcnt lgkmcnt(5)
	v_pk_fma_f32 v[230:231], v[196:197], v[120:121], v[230:231] neg_lo:[1,0,0] neg_hi:[1,0,0]
	v_pk_fma_f32 v[230:231], v[198:199], v[122:123], v[230:231] neg_lo:[1,0,0] neg_hi:[1,0,0]
	ds_read_b128 v[196:199], v8 offset:14608
	s_waitcnt lgkmcnt(5)
	v_pk_fma_f32 v[230:231], v[200:201], v[124:125], v[230:231] neg_lo:[1,0,0] neg_hi:[1,0,0]
	v_pk_fma_f32 v[230:231], v[202:203], v[126:127], v[230:231] neg_lo:[1,0,0] neg_hi:[1,0,0]
	ds_read_b128 v[200:203], v8 offset:14624
	s_waitcnt lgkmcnt(5)
	v_pk_fma_f32 v[230:231], v[204:205], v[128:129], v[230:231] neg_lo:[1,0,0] neg_hi:[1,0,0]
	v_pk_fma_f32 v[230:231], v[206:207], v[130:131], v[230:231] neg_lo:[1,0,0] neg_hi:[1,0,0]
	ds_read_b128 v[204:207], v8 offset:14640
	s_waitcnt lgkmcnt(5)
	v_pk_fma_f32 v[230:231], v[208:209], v[132:133], v[230:231] neg_lo:[1,0,0] neg_hi:[1,0,0]
	v_pk_fma_f32 v[230:231], v[210:211], v[134:135], v[230:231] neg_lo:[1,0,0] neg_hi:[1,0,0]
	ds_read_b128 v[208:211], v8 offset:14656
	s_waitcnt lgkmcnt(5)
	v_pk_fma_f32 v[230:231], v[212:213], v[136:137], v[230:231] neg_lo:[1,0,0] neg_hi:[1,0,0]
	v_pk_fma_f32 v[230:231], v[214:215], v[138:139], v[230:231] neg_lo:[1,0,0] neg_hi:[1,0,0]
	ds_read_b128 v[212:215], v8 offset:14672
	v_add_f32_e32 v140, v230, v231
	s_cbranch_vccz .Ls4_u56
	v_cvt_pk_bf16_f32 v233, -v140, v140
	global_store_short v6, v233, s[8:9] offset:2048
	s_branch .Ls4_n56

; __device__ __forceinline__ void chunk_prep_phase(const Params& p, int bid, int nblk, LAS unsigned char* lds0) {
;     ...
;             { const float br = betg[57]; ab0 = (f32x2){bf2f(*(const LAS bf16_t*)(lg + P5_VS + 15504 + c * 2)) * br, bf2f(*(const LAS bf16_t*)(lg + P5_KS + 15504 + c * 2)) * br * __expf(decg[57])}; ab1 = (f32x2){0.f, 0.f}; } ab0 -= mq[0][0] * xy[0]; ab1 -= mq[0][1] * xy[1]; ab0 -= mq[0][2] * xy[2]; ab1 -= mq[0][3] * xy[3]; mq[0] = *(const LAS f32x4*)(Mg + 3672);
;             ab0 -= mq[1][0] * xy[4]; ab1 -= mq[1][1] * xy[5]; ab0 -= mq[1][2] * xy[6]; ab1 -= mq[1][3] * xy[7]; mq[1] = *(const LAS f32x4*)(Mg + 3676);
;             ab0 -= mq[2][0] * xy[8]; ab1 -= mq[2][1] * xy[9]; ab0 -= mq[2][2] * xy[10]; ab1 -= mq[2][3] * xy[11]; mq[2] = *(const LAS f32x4*)(Mg + 3680);
;             ab0 -= mq[3][0] * xy[12]; ab1 -= mq[3][1] * xy[13]; ab0 -= mq[3][2] * xy[14]; ab1 -= mq[3][3] * xy[15]; mq[3] = *(const LAS f32x4*)(Mg + 3684);
;             ab0 -= mq[4][0] * xy[16]; ab1 -= mq[4][1] * xy[17]; ab0 -= mq[4][2] * xy[18]; ab1 -= mq[4][3] * xy[19]; mq[4] = *(const LAS f32x4*)(Mg + 3688);
;             ab0 -= mq[5][0] * xy[20]; ab1 -= mq[5][1] * xy[21]; ab0 -= mq[5][2] * xy[22]; ab1 -= mq[5][3] * xy[23]; mq[5] = *(const LAS f32x4*)(Mg + 3692);
;             ab0 -= mq[0][0] * xy[24]; ab1 -= mq[0][1] * xy[25]; ab0 -= mq[0][2] * xy[26]; ab1 -= mq[0][3] * xy[27]; mq[0] = *(const LAS f32x4*)(Mg + 3696);
;             ab0 -= mq[1][0] * xy[28]; ab1 -= mq[1][1] * xy[29]; ab0 -= mq[1][2] * xy[30]; ab1 -= mq[1][3] * xy[31]; mq[1] = *(const LAS f32x4*)(Mg + 3700);
;             ab0 -= mq[2][0] * xy[32]; ab1 -= mq[2][1] * xy[33]; ab0 -= mq[2][2] * xy[34]; ab1 -= mq[2][3] * xy[35]; mq[2] = *(const LAS f32x4*)(Mg + 3704);
;             ab0 -= mq[3][0] * xy[36]; ab1 -= mq[3][1] * xy[37]; ab0 -= mq[3][2] * xy[38]; ab1 -= mq[3][3] * xy[39]; mq[3] = *(const LAS f32x4*)(Mg + 3712);
;             ab0 -= mq[4][0] * xy[40]; ab1 -= mq[4][1] * xy[41]; ab0 -= mq[4][2] * xy[42]; ab1 -= mq[4][3] * xy[43]; mq[4] = *(const LAS f32x4*)(Mg + 3716);
;             ab0 -= mq[5][0] * xy[44]; ab1 -= mq[5][1] * xy[45]; ab0 -= mq[5][2] * xy[46]; ab1 -= mq[5][3] * xy[47]; mq[5] = *(const LAS f32x4*)(Mg + 3720);
;             ab0 -= mq[0][0] * xy[48]; ab1 -= mq[0][1] * xy[49]; ab0 -= mq[0][2] * xy[50]; ab1 -= mq[0][3] * xy[51]; mq[0] = *(const LAS f32x4*)(Mg + 3724);
.Ls4_n56:
	v_lshlrev_b32_e32 v229, 16, v229
	v_mul_f32_e32 v232, v229, v217
	v_mul_f32_e32 v230, v232, v1
	v_mov_b32_e32 v231, 0
	ds_read_u16 v228, v7 offset:15776
	s_waitcnt lgkmcnt(6)
	v_pk_fma_f32 v[230:231], v[192:193], v[84:85], v[230:231] neg_lo:[1,0,0] neg_hi:[1,0,0]
	v_pk_fma_f32 v[230:231], v[194:195], v[86:87], v[230:231] neg_lo:[1,0,0] neg_hi:[1,0,0]
	ds_read_b128 v[192:195], v8 offset:14688
	s_waitcnt lgkmcnt(6)
	v_pk_fma_f32 v[230:231], v[196:197], v[88:89], v[230:231] neg_lo:[1,0,0] neg_hi:[1,0,0]
	v_pk_fma_f32 v[230:231], v[198:199], v[90:91], v[230:231] neg_lo:[1,0,0] neg_hi:[1,0,0]
	ds_read_b128 v[196:199], v8 offset:14704
	s_waitcnt lgkmcnt(6)
	v_pk_fma_f32 v[230:231], v[200:201], v[92:93], v[230:231] neg_lo:[1,0,0] neg_hi:[1,0,0]
	v_pk_fma_f32 v[230:231], v[202:203], v[94:95], v[230:231] neg_lo:[1,0,0] neg_hi:[1,0,0]
	ds_read_b128 v[200:203], v8 offset:14720
	s_waitcnt lgkmcnt(6)
	v_pk_fma_f32 v[230:231], v[204:205], v[96:97], v[230:231] neg_lo:[1,0,0] neg_hi:[1,0,0]
	v_pk_fma_f32 v[230:231], v[206:207], v[98:99], v[230:231] neg_lo:[1,0,0] neg_hi:[1,0,0]
	ds_read_b128 v[204:207], v8 offset:14736
	s_waitcnt lgkmcnt(6)
	v_pk_fma_f32 v[230:231], v[208:209], v[100:101], v[230:231] neg_lo:[1,0,0] neg_hi:[1,0,0]
	v_pk_fma_f32 v[230:231], v[210:211], v[102:103], v[230:231] neg_lo:[1,0,0] neg_hi:[1,0,0]
	ds_read_b128 v[208:211], v8 offset:14752
	s_waitcnt lgkmcnt(6)
	v_pk_fma_f32 v[230:231], v[212:213], v[104:105], v[230:231] neg_lo:[1,0,0] neg_hi:[1,0,0]
	v_pk_fma_f32 v[230:231], v[214:215], v[106:107], v[230:231] neg_lo:[1,0,0] neg_hi:[1,0,0]
	ds_read_b128 v[212:215], v8 offset:14768
	s_waitcnt lgkmcnt(5)
	v_pk_fma_f32 v[230:231], v[192:193], v[108:109], v[230:231] neg_lo:[1,0,0] neg_hi:[1,0,0]
	v_pk_fma_f32 v[230:231], v[194:195], v[110:111], v[230:231] neg_lo:[1,0,0] neg_hi:[1,0,0]
	ds_read_b128 v[192:195], v8 offset:14784
	s_waitcnt lgkmcnt(5)
	v_pk_fma_f32 v[230:231], v[196:197], v[112:113], v[230:231] neg_lo:[1,0,0] neg_hi:[1,0,0]
	v_pk_fma_f32 v[230:231], v[198:199], v[114:115], v[230:231] neg_lo:[1,0,0] neg_hi:[1,0,0]
	ds_read_b128 v[196:199], v8 offset:14800
	s_waitcnt lgkmcnt(5)
	v_pk_fma_f32 v[230:231], v[200:201], v[116:117], v[230:231] neg_lo:[1,0,0] neg_hi:[1,0,0]
	v_pk_fma_f32 v[230:231], v[202:203], v[118:119], v[230:231] neg_lo:[1,0,0] neg_hi:[1,0,0]
	ds_read_b128 v[200:203], v8 offset:14816
	s_waitcnt lgkmcnt(5)
	v_pk_fma_f32 v[230:231], v[204:205], v[120:121], v[230:231] neg_lo:[1,0,0] neg_hi:[1,0,0]
	v_pk_fma_f32 v[230:231], v[206:207], v[122:123], v[230:231] neg_lo:[1,0,0] neg_hi:[1,0,0]
	ds_read_b128 v[204:207], v8 offset:14848
	s_waitcnt lgkmcnt(5)
	v_pk_fma_f32 v[230:231], v[208:209], v[124:125], v[230:231] neg_lo:[1,0,0] neg_hi:[1,0,0]
	v_pk_fma_f32 v[230:231], v[210:211], v[126:127], v[230:231] neg_lo:[1,0,0] neg_hi:[1,0,0]
	ds_read_b128 v[208:211], v8 offset:14864
	s_waitcnt lgkmcnt(5)
	v_pk_fma_f32 v[230:231], v[212:213], v[128:129], v[230:231] neg_lo:[1,0,0] neg_hi:[1,0,0]
	v_pk_fma_f32 v[230:231], v[214:215], v[130:131], v[230:231] neg_lo:[1,0,0] neg_hi:[1,0,0]
	ds_read_b128 v[212:215], v8 offset:14880
	s_waitcnt lgkmcnt(5)
	v_pk_fma_f32 v[230:231], v[192:193], v[132:133], v[230:231] neg_lo:[1,0,0] neg_hi:[1,0,0]
	v_pk_fma_f32 v[230:231], v[194:195], v[134:135], v[230:231] neg_lo:[1,0,0] neg_hi:[1,0,0]
	ds_read_b128 v[192:195], v8 offset:14896
	s_waitcnt lgkmcnt(5)
	v_pk_fma_f32 v[230:231], v[196:197], v[136:137], v[230:231] neg_lo:[1,0,0] neg_hi:[1,0,0]
	v_pk_fma_f32 v[230:231], v[198:199], v[138:139], v[230:231] neg_lo:[1,0,0] neg_hi:[1,0,0]
	ds_read_b128 v[196:199], v8 offset:14912
	s_waitcnt lgkmcnt(5)
	v_fma_f32 v230, -v200, v140, v230
	ds_read_b128 v[200:203], v8 offset:14928
	v_add_f32_e32 v141, v230, v231
	s_cbranch_vccz .Ls4_u57
	v_cvt_pk_bf16_f32 v233, -v141, v141
	global_store_short v6, v233, s[8:9] offset:2304
	s_branch .Ls4_n57

; __device__ __forceinline__ void chunk_prep_phase(const Params& p, int bid, int nblk, LAS unsigned char* lds0) {
;     ...
;             { const float br = betg[58]; ab0 = (f32x2){bf2f(*(const LAS bf16_t*)(lg + P5_VS + 15776 + c * 2)) * br, bf2f(*(const LAS bf16_t*)(lg + P5_KS + 15776 + c * 2)) * br * __expf(decg[58])}; ab1 = (f32x2){0.f, 0.f}; } ab0 -= mq[3][0] * xy[0]; ab1 -= mq[3][1] * xy[1]; ab0 -= mq[3][2] * xy[2]; ab1 -= mq[3][3] * xy[3]; mq[3] = *(const LAS f32x4*)(Mg + 3736);
;             ab0 -= mq[4][0] * xy[4]; ab1 -= mq[4][1] * xy[5]; ab0 -= mq[4][2] * xy[6]; ab1 -= mq[4][3] * xy[7]; mq[4] = *(const LAS f32x4*)(Mg + 3740);
;             ab0 -= mq[5][0] * xy[8]; ab1 -= mq[5][1] * xy[9]; ab0 -= mq[5][2] * xy[10]; ab1 -= mq[5][3] * xy[11]; mq[5] = *(const LAS f32x4*)(Mg + 3744);
;             ab0 -= mq[0][0] * xy[12]; ab1 -= mq[0][1] * xy[13]; ab0 -= mq[0][2] * xy[14]; ab1 -= mq[0][3] * xy[15]; mq[0] = *(const LAS f32x4*)(Mg + 3748);
;             ab0 -= mq[1][0] * xy[16]; ab1 -= mq[1][1] * xy[17]; ab0 -= mq[1][2] * xy[18]; ab1 -= mq[1][3] * xy[19]; mq[1] = *(const LAS f32x4*)(Mg + 3752);
;             ab0 -= mq[2][0] * xy[20]; ab1 -= mq[2][1] * xy[21]; ab0 -= mq[2][2] * xy[22]; ab1 -= mq[2][3] * xy[23]; mq[2] = *(const LAS f32x4*)(Mg + 3756);
;             ab0 -= mq[3][0] * xy[24]; ab1 -= mq[3][1] * xy[25]; ab0 -= mq[3][2] * xy[26]; ab1 -= mq[3][3] * xy[27]; mq[3] = *(const LAS f32x4*)(Mg + 3760);
;             ab0 -= mq[4][0] * xy[28]; ab1 -= mq[4][1] * xy[29]; ab0 -= mq[4][2] * xy[30]; ab1 -= mq[4][3] * xy[31]; mq[4] = *(const LAS f32x4*)(Mg + 3764);
;             ab0 -= mq[5][0] * xy[32]; ab1 -= mq[5][1] * xy[33]; ab0 -= mq[5][2] * xy[34]; ab1 -= mq[5][3] * xy[35]; mq[5] = *(const LAS f32x4*)(Mg + 3768);
;             ab0 -= mq[0][0] * xy[36]; ab1 -= mq[0][1] * xy[37]; ab0 -= mq[0][2] * xy[38]; ab1 -= mq[0][3] * xy[39]; mq[0] = *(const LAS f32x4*)(Mg + 3776);
;             ab0 -= mq[1][0] * xy[40]; ab1 -= mq[1][1] * xy[41]; ab0 -= mq[1][2] * xy[42]; ab1 -= mq[1][3] * xy[43]; mq[1] = *(const LAS f32x4*)(Mg + 3780);
;             ab0 -= mq[2][0] * xy[44]; ab1 -= mq[2][1] * xy[45]; ab0 -= mq[2][2] * xy[46]; ab1 -= mq[2][3] * xy[47]; mq[2] = *(const LAS f32x4*)(Mg + 3784);
;             ab0 -= mq[3][0] * xy[48]; ab1 -= mq[3][1] * xy[49]; ab0 -= mq[3][2] * xy[50]; ab1 -= mq[3][3] * xy[51]; mq[3] = *(const LAS f32x4*)(Mg + 3788);
.Ls4_n57:
	v_lshlrev_b32_e32 v228, 16, v228
	v_mul_f32_e32 v232, v228, v218
	v_mul_f32_e32 v230, v232, v2
	v_mov_b32_e32 v231, 0
	ds_read_u16 v229, v7 offset:16048
	s_waitcnt lgkmcnt(6)
	v_pk_fma_f32 v[230:231], v[204:205], v[84:85], v[230:231] neg_lo:[1,0,0] neg_hi:[1,0,0]
	v_pk_fma_f32 v[230:231], v[206:207], v[86:87], v[230:231] neg_lo:[1,0,0] neg_hi:[1,0,0]
	ds_read_b128 v[204:207], v8 offset:14944
	s_waitcnt lgkmcnt(6)
	v_pk_fma_f32 v[230:231], v[208:209], v[88:89], v[230:231] neg_lo:[1,0,0] neg_hi:[1,0,0]
	v_pk_fma_f32 v[230:231], v[210:211], v[90:91], v[230:231] neg_lo:[1,0,0] neg_hi:[1,0,0]
	ds_read_b128 v[208:211], v8 offset:14960
	s_waitcnt lgkmcnt(6)
	v_pk_fma_f32 v[230:231], v[212:213], v[92:93], v[230:231] neg_lo:[1,0,0] neg_hi:[1,0,0]
	v_pk_fma_f32 v[230:231], v[214:215], v[94:95], v[230:231] neg_lo:[1,0,0] neg_hi:[1,0,0]
	ds_read_b128 v[212:215], v8 offset:14976
	s_waitcnt lgkmcnt(6)
	v_pk_fma_f32 v[230:231], v[192:193], v[96:97], v[230:231] neg_lo:[1,0,0] neg_hi:[1,0,0]
	v_pk_fma_f32 v[230:231], v[194:195], v[98:99], v[230:231] neg_lo:[1,0,0] neg_hi:[1,0,0]
	ds_read_b128 v[192:195], v8 offset:14992
	s_waitcnt lgkmcnt(6)
	v_pk_fma_f32 v[230:231], v[196:197], v[100:101], v[230:231] neg_lo:[1,0,0] neg_hi:[1,0,0]
	v_pk_fma_f32 v[230:231], v[198:199], v[102:103], v[230:231] neg_lo:[1,0,0] neg_hi:[1,0,0]
	ds_read_b128 v[196:199], v8 offset:15008
	s_waitcnt lgkmcnt(6)
	v_pk_fma_f32 v[230:231], v[200:201], v[104:105], v[230:231] neg_lo:[1,0,0] neg_hi:[1,0,0]
	v_pk_fma_f32 v[230:231], v[202:203], v[106:107], v[230:231] neg_lo:[1,0,0] neg_hi:[1,0,0]
	ds_read_b128 v[200:203], v8 offset:15024
	s_waitcnt lgkmcnt(5)
	v_pk_fma_f32 v[230:231], v[204:205], v[108:109], v[230:231] neg_lo:[1,0,0] neg_hi:[1,0,0]
	v_pk_fma_f32 v[230:231], v[206:207], v[110:111], v[230:231] neg_lo:[1,0,0] neg_hi:[1,0,0]
	ds_read_b128 v[204:207], v8 offset:15040
	s_waitcnt lgkmcnt(5)
	v_pk_fma_f32 v[230:231], v[208:209], v[112:113], v[230:231] neg_lo:[1,0,0] neg_hi:[1,0,0]
	v_pk_fma_f32 v[230:231], v[210:211], v[114:115], v[230:231] neg_lo:[1,0,0] neg_hi:[1,0,0]
	ds_read_b128 v[208:211], v8 offset:15056
	s_waitcnt lgkmcnt(5)
	v_pk_fma_f32 v[230:231], v[212:213], v[116:117], v[230:231] neg_lo:[1,0,0] neg_hi:[1,0,0]
	v_pk_fma_f32 v[230:231], v[214:215], v[118:119], v[230:231] neg_lo:[1,0,0] neg_hi:[1,0,0]
	ds_read_b128 v[212:215], v8 offset:15072
	s_waitcnt lgkmcnt(5)
	v_pk_fma_f32 v[230:231], v[192:193], v[120:121], v[230:231] neg_lo:[1,0,0] neg_hi:[1,0,0]
	v_pk_fma_f32 v[230:231], v[194:195], v[122:123], v[230:231] neg_lo:[1,0,0] neg_hi:[1,0,0]
	ds_read_b128 v[192:195], v8 offset:15104
	s_waitcnt lgkmcnt(5)
	v_pk_fma_f32 v[230:231], v[196:197], v[124:125], v[230:231] neg_lo:[1,0,0] neg_hi:[1,0,0]
	v_pk_fma_f32 v[230:231], v[198:199], v[126:127], v[230:231] neg_lo:[1,0,0] neg_hi:[1,0,0]
	ds_read_b128 v[196:199], v8 offset:15120
	s_waitcnt lgkmcnt(5)
	v_pk_fma_f32 v[230:231], v[200:201], v[128:129], v[230:231] neg_lo:[1,0,0] neg_hi:[1,0,0]
	v_pk_fma_f32 v[230:231], v[202:203], v[130:131], v[230:231] neg_lo:[1,0,0] neg_hi:[1,0,0]
	ds_read_b128 v[200:203], v8 offset:15136
	s_waitcnt lgkmcnt(5)
	v_pk_fma_f32 v[230:231], v[204:205], v[132:133], v[230:231] neg_lo:[1,0,0] neg_hi:[1,0,0]
	v_pk_fma_f32 v[230:231], v[206:207], v[134:135], v[230:231] neg_lo:[1,0,0] neg_hi:[1,0,0]
	ds_read_b128 v[204:207], v8 offset:15152
	s_waitcnt lgkmcnt(5)
	v_pk_fma_f32 v[230:231], v[208:209], v[136:137], v[230:231] neg_lo:[1,0,0] neg_hi:[1,0,0]
	v_pk_fma_f32 v[230:231], v[210:211], v[138:139], v[230:231] neg_lo:[1,0,0] neg_hi:[1,0,0]
	ds_read_b128 v[208:211], v8 offset:15168
	s_waitcnt lgkmcnt(5)
	v_pk_fma_f32 v[230:231], v[212:213], v[140:141], v[230:231] neg_lo:[1,0,0] neg_hi:[1,0,0]
	ds_read_b128 v[212:215], v8 offset:15184
	v_add_f32_e32 v142, v230, v231
	s_cbranch_vccz .Ls4_u58
	v_cvt_pk_bf16_f32 v233, -v142, v142
	global_store_short v6, v233, s[8:9] offset:2560
	s_branch .Ls4_n58

; __device__ __forceinline__ void chunk_prep_phase(const Params& p, int bid, int nblk, LAS unsigned char* lds0) {
;     ...
;             { const float br = betg[59]; ab0 = (f32x2){bf2f(*(const LAS bf16_t*)(lg + P5_VS + 16048 + c * 2)) * br, bf2f(*(const LAS bf16_t*)(lg + P5_KS + 16048 + c * 2)) * br * __expf(decg[59])}; ab1 = (f32x2){0.f, 0.f}; } ab0 -= mq[0][0] * xy[0]; ab1 -= mq[0][1] * xy[1]; ab0 -= mq[0][2] * xy[2]; ab1 -= mq[0][3] * xy[3]; mq[0] = *(const LAS f32x4*)(Mg + 3800);
;             ab0 -= mq[1][0] * xy[4]; ab1 -= mq[1][1] * xy[5]; ab0 -= mq[1][2] * xy[6]; ab1 -= mq[1][3] * xy[7]; mq[1] = *(const LAS f32x4*)(Mg + 3804);
;             ab0 -= mq[2][0] * xy[8]; ab1 -= mq[2][1] * xy[9]; ab0 -= mq[2][2] * xy[10]; ab1 -= mq[2][3] * xy[11]; mq[2] = *(const LAS f32x4*)(Mg + 3808);
;             ab0 -= mq[3][0] * xy[12]; ab1 -= mq[3][1] * xy[13]; ab0 -= mq[3][2] * xy[14]; ab1 -= mq[3][3] * xy[15]; mq[3] = *(const LAS f32x4*)(Mg + 3812);
;             ab0 -= mq[4][0] * xy[16]; ab1 -= mq[4][1] * xy[17]; ab0 -= mq[4][2] * xy[18]; ab1 -= mq[4][3] * xy[19]; mq[4] = *(const LAS f32x4*)(Mg + 3816);
;             ab0 -= mq[5][0] * xy[20]; ab1 -= mq[5][1] * xy[21]; ab0 -= mq[5][2] * xy[22]; ab1 -= mq[5][3] * xy[23]; mq[5] = *(const LAS f32x4*)(Mg + 3820);
;             ab0 -= mq[0][0] * xy[24]; ab1 -= mq[0][1] * xy[25]; ab0 -= mq[0][2] * xy[26]; ab1 -= mq[0][3] * xy[27]; mq[0] = *(const LAS f32x4*)(Mg + 3824);
;             ab0 -= mq[1][0] * xy[28]; ab1 -= mq[1][1] * xy[29]; ab0 -= mq[1][2] * xy[30]; ab1 -= mq[1][3] * xy[31]; mq[1] = *(const LAS f32x4*)(Mg + 3828);
;             ab0 -= mq[2][0] * xy[32]; ab1 -= mq[2][1] * xy[33]; ab0 -= mq[2][2] * xy[34]; ab1 -= mq[2][3] * xy[35]; mq[2] = *(const LAS f32x4*)(Mg + 3832);
;             ab0 -= mq[3][0] * xy[36]; ab1 -= mq[3][1] * xy[37]; ab0 -= mq[3][2] * xy[38]; ab1 -= mq[3][3] * xy[39]; mq[3] = *(const LAS f32x4*)(Mg + 3840);
;             ab0 -= mq[4][0] * xy[40]; ab1 -= mq[4][1] * xy[41]; ab0 -= mq[4][2] * xy[42]; ab1 -= mq[4][3] * xy[43]; mq[4] = *(const LAS f32x4*)(Mg + 3844);
;             ab0 -= mq[5][0] * xy[44]; ab1 -= mq[5][1] * xy[45]; ab0 -= mq[5][2] * xy[46]; ab1 -= mq[5][3] * xy[47]; mq[5] = *(const LAS f32x4*)(Mg + 3848);
;             ab0 -= mq[0][0] * xy[48]; ab1 -= mq[0][1] * xy[49]; ab0 -= mq[0][2] * xy[50]; ab1 -= mq[0][3] * xy[51]; mq[0] = *(const LAS f32x4*)(Mg + 3852);
.Ls4_n58:
	v_lshlrev_b32_e32 v229, 16, v229
	v_mul_f32_e32 v232, v229, v219
	v_mul_f32_e32 v230, v232, v3
	v_mov_b32_e32 v231, 0
	ds_read_u16 v228, v7 offset:16320
	s_waitcnt lgkmcnt(6)
	v_pk_fma_f32 v[230:231], v[192:193], v[84:85], v[230:231] neg_lo:[1,0,0] neg_hi:[1,0,0]
	v_pk_fma_f32 v[230:231], v[194:195], v[86:87], v[230:231] neg_lo:[1,0,0] neg_hi:[1,0,0]
	ds_read_b128 v[192:195], v8 offset:15200
	s_waitcnt lgkmcnt(6)
	v_pk_fma_f32 v[230:231], v[196:197], v[88:89], v[230:231] neg_lo:[1,0,0] neg_hi:[1,0,0]
	v_pk_fma_f32 v[230:231], v[198:199], v[90:91], v[230:231] neg_lo:[1,0,0] neg_hi:[1,0,0]
	ds_read_b128 v[196:199], v8 offset:15216
	s_waitcnt lgkmcnt(6)
	v_pk_fma_f32 v[230:231], v[200:201], v[92:93], v[230:231] neg_lo:[1,0,0] neg_hi:[1,0,0]
	v_pk_fma_f32 v[230:231], v[202:203], v[94:95], v[230:231] neg_lo:[1,0,0] neg_hi:[1,0,0]
	ds_read_b128 v[200:203], v8 offset:15232
	s_waitcnt lgkmcnt(6)
	v_pk_fma_f32 v[230:231], v[204:205], v[96:97], v[230:231] neg_lo:[1,0,0] neg_hi:[1,0,0]
	v_pk_fma_f32 v[230:231], v[206:207], v[98:99], v[230:231] neg_lo:[1,0,0] neg_hi:[1,0,0]
	ds_read_b128 v[204:207], v8 offset:15248
	s_waitcnt lgkmcnt(6)
	v_pk_fma_f32 v[230:231], v[208:209], v[100:101], v[230:231] neg_lo:[1,0,0] neg_hi:[1,0,0]
	v_pk_fma_f32 v[230:231], v[210:211], v[102:103], v[230:231] neg_lo:[1,0,0] neg_hi:[1,0,0]
	ds_read_b128 v[208:211], v8 offset:15264
	s_waitcnt lgkmcnt(6)
	v_pk_fma_f32 v[230:231], v[212:213], v[104:105], v[230:231] neg_lo:[1,0,0] neg_hi:[1,0,0]
	v_pk_fma_f32 v[230:231], v[214:215], v[106:107], v[230:231] neg_lo:[1,0,0] neg_hi:[1,0,0]
	ds_read_b128 v[212:215], v8 offset:15280
	s_waitcnt lgkmcnt(5)
	v_pk_fma_f32 v[230:231], v[192:193], v[108:109], v[230:231] neg_lo:[1,0,0] neg_hi:[1,0,0]
	v_pk_fma_f32 v[230:231], v[194:195], v[110:111], v[230:231] neg_lo:[1,0,0] neg_hi:[1,0,0]
	ds_read_b128 v[192:195], v8 offset:15296
	s_waitcnt lgkmcnt(5)
	v_pk_fma_f32 v[230:231], v[196:197], v[112:113], v[230:231] neg_lo:[1,0,0] neg_hi:[1,0,0]
	v_pk_fma_f32 v[230:231], v[198:199], v[114:115], v[230:231] neg_lo:[1,0,0] neg_hi:[1,0,0]
	ds_read_b128 v[196:199], v8 offset:15312
	s_waitcnt lgkmcnt(5)
	v_pk_fma_f32 v[230:231], v[200:201], v[116:117], v[230:231] neg_lo:[1,0,0] neg_hi:[1,0,0]
	v_pk_fma_f32 v[230:231], v[202:203], v[118:119], v[230:231] neg_lo:[1,0,0] neg_hi:[1,0,0]
	ds_read_b128 v[200:203], v8 offset:15328
	s_waitcnt lgkmcnt(5)
	v_pk_fma_f32 v[230:231], v[204:205], v[120:121], v[230:231] neg_lo:[1,0,0] neg_hi:[1,0,0]
	v_pk_fma_f32 v[230:231], v[206:207], v[122:123], v[230:231] neg_lo:[1,0,0] neg_hi:[1,0,0]
	ds_read_b128 v[204:207], v8 offset:15360
	s_waitcnt lgkmcnt(5)
	v_pk_fma_f32 v[230:231], v[208:209], v[124:125], v[230:231] neg_lo:[1,0,0] neg_hi:[1,0,0]
	v_pk_fma_f32 v[230:231], v[210:211], v[126:127], v[230:231] neg_lo:[1,0,0] neg_hi:[1,0,0]
	ds_read_b128 v[208:211], v8 offset:15376
	s_waitcnt lgkmcnt(5)
	v_pk_fma_f32 v[230:231], v[212:213], v[128:129], v[230:231] neg_lo:[1,0,0] neg_hi:[1,0,0]
	v_pk_fma_f32 v[230:231], v[214:215], v[130:131], v[230:231] neg_lo:[1,0,0] neg_hi:[1,0,0]
	ds_read_b128 v[212:215], v8 offset:15392
	s_waitcnt lgkmcnt(5)
	v_pk_fma_f32 v[230:231], v[192:193], v[132:133], v[230:231] neg_lo:[1,0,0] neg_hi:[1,0,0]
	v_pk_fma_f32 v[230:231], v[194:195], v[134:135], v[230:231] neg_lo:[1,0,0] neg_hi:[1,0,0]
	ds_read_b128 v[192:195], v8 offset:15408
	s_waitcnt lgkmcnt(5)
	v_pk_fma_f32 v[230:231], v[196:197], v[136:137], v[230:231] neg_lo:[1,0,0] neg_hi:[1,0,0]
	v_pk_fma_f32 v[230:231], v[198:199], v[138:139], v[230:231] neg_lo:[1,0,0] neg_hi:[1,0,0]
	ds_read_b128 v[196:199], v8 offset:15424
	s_waitcnt lgkmcnt(5)
	v_pk_fma_f32 v[230:231], v[200:201], v[140:141], v[230:231] neg_lo:[1,0,0] neg_hi:[1,0,0]
	v_fma_f32 v230, -v202, v142, v230
	ds_read_b128 v[200:203], v8 offset:15440
	v_add_f32_e32 v143, v230, v231
	s_cbranch_vccz .Ls4_u59
	v_cvt_pk_bf16_f32 v233, -v143, v143
	global_store_short v6, v233, s[8:9] offset:2816
	s_branch .Ls4_n59

; __device__ __forceinline__ void chunk_prep_phase(const Params& p, int bid, int nblk, LAS unsigned char* lds0) {
;     ...
;             { const float br = betg[60]; ab0 = (f32x2){bf2f(*(const LAS bf16_t*)(lg + P5_VS + 16320 + c * 2)) * br, bf2f(*(const LAS bf16_t*)(lg + P5_KS + 16320 + c * 2)) * br * __expf(decg[60])}; ab1 = (f32x2){0.f, 0.f}; } ab0 -= mq[3][0] * xy[0]; ab1 -= mq[3][1] * xy[1]; ab0 -= mq[3][2] * xy[2]; ab1 -= mq[3][3] * xy[3]; mq[3] = *(const LAS f32x4*)(Mg + 3864);
;             ab0 -= mq[4][0] * xy[4]; ab1 -= mq[4][1] * xy[5]; ab0 -= mq[4][2] * xy[6]; ab1 -= mq[4][3] * xy[7]; mq[4] = *(const LAS f32x4*)(Mg + 3868);
;             ab0 -= mq[5][0] * xy[8]; ab1 -= mq[5][1] * xy[9]; ab0 -= mq[5][2] * xy[10]; ab1 -= mq[5][3] * xy[11]; mq[5] = *(const LAS f32x4*)(Mg + 3872);
;             ab0 -= mq[0][0] * xy[12]; ab1 -= mq[0][1] * xy[13]; ab0 -= mq[0][2] * xy[14]; ab1 -= mq[0][3] * xy[15]; mq[0] = *(const LAS f32x4*)(Mg + 3876);
;             ab0 -= mq[1][0] * xy[16]; ab1 -= mq[1][1] * xy[17]; ab0 -= mq[1][2] * xy[18]; ab1 -= mq[1][3] * xy[19]; mq[1] = *(const LAS f32x4*)(Mg + 3880);
;             ab0 -= mq[2][0] * xy[20]; ab1 -= mq[2][1] * xy[21]; ab0 -= mq[2][2] * xy[22]; ab1 -= mq[2][3] * xy[23]; mq[2] = *(const LAS f32x4*)(Mg + 3884);
;             ab0 -= mq[3][0] * xy[24]; ab1 -= mq[3][1] * xy[25]; ab0 -= mq[3][2] * xy[26]; ab1 -= mq[3][3] * xy[27]; mq[3] = *(const LAS f32x4*)(Mg + 3888);
;             ab0 -= mq[4][0] * xy[28]; ab1 -= mq[4][1] * xy[29]; ab0 -= mq[4][2] * xy[30]; ab1 -= mq[4][3] * xy[31]; mq[4] = *(const LAS f32x4*)(Mg + 3892);
;             ab0 -= mq[5][0] * xy[32]; ab1 -= mq[5][1] * xy[33]; ab0 -= mq[5][2] * xy[34]; ab1 -= mq[5][3] * xy[35]; mq[5] = *(const LAS f32x4*)(Mg + 3896);
;             ab0 -= mq[0][0] * xy[36]; ab1 -= mq[0][1] * xy[37]; ab0 -= mq[0][2] * xy[38]; ab1 -= mq[0][3] * xy[39]; mq[0] = *(const LAS f32x4*)(Mg + 3904);
;             ab0 -= mq[1][0] * xy[40]; ab1 -= mq[1][1] * xy[41]; ab0 -= mq[1][2] * xy[42]; ab1 -= mq[1][3] * xy[43]; mq[1] = *(const LAS f32x4*)(Mg + 3908);
;             ab0 -= mq[2][0] * xy[44]; ab1 -= mq[2][1] * xy[45]; ab0 -= mq[2][2] * xy[46]; ab1 -= mq[2][3] * xy[47]; mq[2] = *(const LAS f32x4*)(Mg + 3912);
;             ab0 -= mq[3][0] * xy[48]; ab1 -= mq[3][1] * xy[49]; ab0 -= mq[3][2] * xy[50]; ab1 -= mq[3][3] * xy[51]; mq[3] = *(const LAS f32x4*)(Mg + 3916);
.Ls4_n59:
	v_mul_f32_e32 v224, s16, v224
	v_mul_f32_e32 v225, s16, v225
	v_mul_f32_e32 v226, s16, v226
	v_mul_f32_e32 v227, s16, v227
	v_exp_f32_e32 v224, v224
	v_exp_f32_e32 v225, v225
	v_exp_f32_e32 v226, v226
	v_exp_f32_e32 v227, v227
	s_nop 0
	v_lshlrev_b32_e32 v228, 16, v228
	v_mul_f32_e32 v232, v228, v220
	v_mul_f32_e32 v230, v232, v224
	v_mov_b32_e32 v231, 0
	ds_read_u16 v229, v7 offset:16592
	s_waitcnt lgkmcnt(6)
	v_pk_fma_f32 v[230:231], v[204:205], v[84:85], v[230:231] neg_lo:[1,0,0] neg_hi:[1,0,0]
	v_pk_fma_f32 v[230:231], v[206:207], v[86:87], v[230:231] neg_lo:[1,0,0] neg_hi:[1,0,0]
	ds_read_b128 v[204:207], v8 offset:15456
	s_waitcnt lgkmcnt(6)
	v_pk_fma_f32 v[230:231], v[208:209], v[88:89], v[230:231] neg_lo:[1,0,0] neg_hi:[1,0,0]
	v_pk_fma_f32 v[230:231], v[210:211], v[90:91], v[230:231] neg_lo:[1,0,0] neg_hi:[1,0,0]
	ds_read_b128 v[208:211], v8 offset:15472
	s_waitcnt lgkmcnt(6)
	v_pk_fma_f32 v[230:231], v[212:213], v[92:93], v[230:231] neg_lo:[1,0,0] neg_hi:[1,0,0]
	v_pk_fma_f32 v[230:231], v[214:215], v[94:95], v[230:231] neg_lo:[1,0,0] neg_hi:[1,0,0]
	ds_read_b128 v[212:215], v8 offset:15488
	s_waitcnt lgkmcnt(6)
	v_pk_fma_f32 v[230:231], v[192:193], v[96:97], v[230:231] neg_lo:[1,0,0] neg_hi:[1,0,0]
	v_pk_fma_f32 v[230:231], v[194:195], v[98:99], v[230:231] neg_lo:[1,0,0] neg_hi:[1,0,0]
	ds_read_b128 v[192:195], v8 offset:15504
	s_waitcnt lgkmcnt(6)
	v_pk_fma_f32 v[230:231], v[196:197], v[100:101], v[230:231] neg_lo:[1,0,0] neg_hi:[1,0,0]
	v_pk_fma_f32 v[230:231], v[198:199], v[102:103], v[230:231] neg_lo:[1,0,0] neg_hi:[1,0,0]
	ds_read_b128 v[196:199], v8 offset:15520
	s_waitcnt lgkmcnt(6)
	v_pk_fma_f32 v[230:231], v[200:201], v[104:105], v[230:231] neg_lo:[1,0,0] neg_hi:[1,0,0]
	v_pk_fma_f32 v[230:231], v[202:203], v[106:107], v[230:231] neg_lo:[1,0,0] neg_hi:[1,0,0]
	ds_read_b128 v[200:203], v8 offset:15536
	s_waitcnt lgkmcnt(5)
	v_pk_fma_f32 v[230:231], v[204:205], v[108:109], v[230:231] neg_lo:[1,0,0] neg_hi:[1,0,0]
	v_pk_fma_f32 v[230:231], v[206:207], v[110:111], v[230:231] neg_lo:[1,0,0] neg_hi:[1,0,0]
	ds_read_b128 v[204:207], v8 offset:15552
	s_waitcnt lgkmcnt(5)
	v_pk_fma_f32 v[230:231], v[208:209], v[112:113], v[230:231] neg_lo:[1,0,0] neg_hi:[1,0,0]
	v_pk_fma_f32 v[230:231], v[210:211], v[114:115], v[230:231] neg_lo:[1,0,0] neg_hi:[1,0,0]
	ds_read_b128 v[208:211], v8 offset:15568
	s_waitcnt lgkmcnt(5)
	v_pk_fma_f32 v[230:231], v[212:213], v[116:117], v[230:231] neg_lo:[1,0,0] neg_hi:[1,0,0]
	v_pk_fma_f32 v[230:231], v[214:215], v[118:119], v[230:231] neg_lo:[1,0,0] neg_hi:[1,0,0]
	ds_read_b128 v[212:215], v8 offset:15584
	s_waitcnt lgkmcnt(5)
	v_pk_fma_f32 v[230:231], v[192:193], v[120:121], v[230:231] neg_lo:[1,0,0] neg_hi:[1,0,0]
	v_pk_fma_f32 v[230:231], v[194:195], v[122:123], v[230:231] neg_lo:[1,0,0] neg_hi:[1,0,0]
	ds_read_b128 v[192:195], v8 offset:15616
	s_waitcnt lgkmcnt(5)
	v_pk_fma_f32 v[230:231], v[196:197], v[124:125], v[230:231] neg_lo:[1,0,0] neg_hi:[1,0,0]
	v_pk_fma_f32 v[230:231], v[198:199], v[126:127], v[230:231] neg_lo:[1,0,0] neg_hi:[1,0,0]
	ds_read_b128 v[196:199], v8 offset:15632
	s_waitcnt lgkmcnt(5)
	v_pk_fma_f32 v[230:231], v[200:201], v[128:129], v[230:231] neg_lo:[1,0,0] neg_hi:[1,0,0]
	v_pk_fma_f32 v[230:231], v[202:203], v[130:131], v[230:231] neg_lo:[1,0,0] neg_hi:[1,0,0]
	ds_read_b128 v[200:203], v8 offset:15648
	s_waitcnt lgkmcnt(5)
	v_pk_fma_f32 v[230:231], v[204:205], v[132:133], v[230:231] neg_lo:[1,0,0] neg_hi:[1,0,0]
	v_pk_fma_f32 v[230:231], v[206:207], v[134:135], v[230:231] neg_lo:[1,0,0] neg_hi:[1,0,0]
	ds_read_b128 v[204:207], v8 offset:15664
	s_waitcnt lgkmcnt(5)
	v_pk_fma_f32 v[230:231], v[208:209], v[136:137], v[230:231] neg_lo:[1,0,0] neg_hi:[1,0,0]
	v_pk_fma_f32 v[230:231], v[210:211], v[138:139], v[230:231] neg_lo:[1,0,0] neg_hi:[1,0,0]
	ds_read_b128 v[208:211], v8 offset:15680
	s_waitcnt lgkmcnt(5)
	v_pk_fma_f32 v[230:231], v[212:213], v[140:141], v[230:231] neg_lo:[1,0,0] neg_hi:[1,0,0]
	v_pk_fma_f32 v[230:231], v[214:215], v[142:143], v[230:231] neg_lo:[1,0,0] neg_hi:[1,0,0]
	ds_read_b128 v[212:215], v8 offset:15696
	v_add_f32_e32 v144, v230, v231
	s_cbranch_vccz .Ls4_u60
	v_cvt_pk_bf16_f32 v233, -v144, v144
	global_store_short v6, v233, s[8:9] offset:3072
	s_branch .Ls4_n60

; __device__ __forceinline__ void chunk_prep_phase(const Params& p, int bid, int nblk, LAS unsigned char* lds0) {
;     ...
;             { const float br = betg[61]; ab0 = (f32x2){bf2f(*(const LAS bf16_t*)(lg + P5_VS + 16592 + c * 2)) * br, bf2f(*(const LAS bf16_t*)(lg + P5_KS + 16592 + c * 2)) * br * __expf(decg[61])}; ab1 = (f32x2){0.f, 0.f}; } ab0 -= mq[0][0] * xy[0]; ab1 -= mq[0][1] * xy[1]; ab0 -= mq[0][2] * xy[2]; ab1 -= mq[0][3] * xy[3]; mq[0] = *(const LAS f32x4*)(Mg + 3928);
;             ab0 -= mq[1][0] * xy[4]; ab1 -= mq[1][1] * xy[5]; ab0 -= mq[1][2] * xy[6]; ab1 -= mq[1][3] * xy[7]; mq[1] = *(const LAS f32x4*)(Mg + 3932);
;             ab0 -= mq[2][0] * xy[8]; ab1 -= mq[2][1] * xy[9]; ab0 -= mq[2][2] * xy[10]; ab1 -= mq[2][3] * xy[11]; mq[2] = *(const LAS f32x4*)(Mg + 3936);
;             ab0 -= mq[3][0] * xy[12]; ab1 -= mq[3][1] * xy[13]; ab0 -= mq[3][2] * xy[14]; ab1 -= mq[3][3] * xy[15]; mq[3] = *(const LAS f32x4*)(Mg + 3940);
;             ab0 -= mq[4][0] * xy[16]; ab1 -= mq[4][1] * xy[17]; ab0 -= mq[4][2] * xy[18]; ab1 -= mq[4][3] * xy[19]; mq[4] = *(const LAS f32x4*)(Mg + 3944);
;             ab0 -= mq[5][0] * xy[20]; ab1 -= mq[5][1] * xy[21]; ab0 -= mq[5][2] * xy[22]; ab1 -= mq[5][3] * xy[23]; mq[5] = *(const LAS f32x4*)(Mg + 3948);
;             ab0 -= mq[0][0] * xy[24]; ab1 -= mq[0][1] * xy[25]; ab0 -= mq[0][2] * xy[26]; ab1 -= mq[0][3] * xy[27]; mq[0] = *(const LAS f32x4*)(Mg + 3952);
;             ab0 -= mq[1][0] * xy[28]; ab1 -= mq[1][1] * xy[29]; ab0 -= mq[1][2] * xy[30]; ab1 -= mq[1][3] * xy[31]; mq[1] = *(const LAS f32x4*)(Mg + 3956);
;             ab0 -= mq[2][0] * xy[32]; ab1 -= mq[2][1] * xy[33]; ab0 -= mq[2][2] * xy[34]; ab1 -= mq[2][3] * xy[35]; mq[2] = *(const LAS f32x4*)(Mg + 3960);
;             ab0 -= mq[3][0] * xy[36]; ab1 -= mq[3][1] * xy[37]; ab0 -= mq[3][2] * xy[38]; ab1 -= mq[3][3] * xy[39]; mq[3] = *(const LAS f32x4*)(Mg + 3964);
;             ab0 -= mq[4][0] * xy[40]; ab1 -= mq[4][1] * xy[41]; ab0 -= mq[4][2] * xy[42]; ab1 -= mq[4][3] * xy[43]; mq[4] = *(const LAS f32x4*)(Mg + 3968);
;             ab0 -= mq[5][0] * xy[44]; ab1 -= mq[5][1] * xy[45]; ab0 -= mq[5][2] * xy[46]; ab1 -= mq[5][3] * xy[47]; mq[5] = *(const LAS f32x4*)(Mg + 3972);
;             ab0 -= mq[0][0] * xy[48]; ab1 -= mq[0][1] * xy[49]; ab0 -= mq[0][2] * xy[50]; ab1 -= mq[0][3] * xy[51]; mq[0] = *(const LAS f32x4*)(Mg + 3976);
.Ls4_n60:
	v_lshlrev_b32_e32 v229, 16, v229
	v_mul_f32_e32 v232, v229, v221
	v_mul_f32_e32 v230, v232, v225
	v_mov_b32_e32 v231, 0
	ds_read_u16 v228, v7 offset:16864
	s_waitcnt lgkmcnt(6)
	v_pk_fma_f32 v[230:231], v[192:193], v[84:85], v[230:231] neg_lo:[1,0,0] neg_hi:[1,0,0]
	v_pk_fma_f32 v[230:231], v[194:195], v[86:87], v[230:231] neg_lo:[1,0,0] neg_hi:[1,0,0]
	ds_read_b128 v[192:195], v8 offset:15712
	s_waitcnt lgkmcnt(6)
	v_pk_fma_f32 v[230:231], v[196:197], v[88:89], v[230:231] neg_lo:[1,0,0] neg_hi:[1,0,0]
	v_pk_fma_f32 v[230:231], v[198:199], v[90:91], v[230:231] neg_lo:[1,0,0] neg_hi:[1,0,0]
	ds_read_b128 v[196:199], v8 offset:15728
	s_waitcnt lgkmcnt(6)
	v_pk_fma_f32 v[230:231], v[200:201], v[92:93], v[230:231] neg_lo:[1,0,0] neg_hi:[1,0,0]
	v_pk_fma_f32 v[230:231], v[202:203], v[94:95], v[230:231] neg_lo:[1,0,0] neg_hi:[1,0,0]
	ds_read_b128 v[200:203], v8 offset:15744
	s_waitcnt lgkmcnt(6)
	v_pk_fma_f32 v[230:231], v[204:205], v[96:97], v[230:231] neg_lo:[1,0,0] neg_hi:[1,0,0]
	v_pk_fma_f32 v[230:231], v[206:207], v[98:99], v[230:231] neg_lo:[1,0,0] neg_hi:[1,0,0]
	ds_read_b128 v[204:207], v8 offset:15760
	s_waitcnt lgkmcnt(6)
	v_pk_fma_f32 v[230:231], v[208:209], v[100:101], v[230:231] neg_lo:[1,0,0] neg_hi:[1,0,0]
	v_pk_fma_f32 v[230:231], v[210:211], v[102:103], v[230:231] neg_lo:[1,0,0] neg_hi:[1,0,0]
	ds_read_b128 v[208:211], v8 offset:15776
	s_waitcnt lgkmcnt(6)
	v_pk_fma_f32 v[230:231], v[212:213], v[104:105], v[230:231] neg_lo:[1,0,0] neg_hi:[1,0,0]
	v_pk_fma_f32 v[230:231], v[214:215], v[106:107], v[230:231] neg_lo:[1,0,0] neg_hi:[1,0,0]
	ds_read_b128 v[212:215], v8 offset:15792
	s_waitcnt lgkmcnt(5)
	v_pk_fma_f32 v[230:231], v[192:193], v[108:109], v[230:231] neg_lo:[1,0,0] neg_hi:[1,0,0]
	v_pk_fma_f32 v[230:231], v[194:195], v[110:111], v[230:231] neg_lo:[1,0,0] neg_hi:[1,0,0]
	ds_read_b128 v[192:195], v8 offset:15808
	s_waitcnt lgkmcnt(5)
	v_pk_fma_f32 v[230:231], v[196:197], v[112:113], v[230:231] neg_lo:[1,0,0] neg_hi:[1,0,0]
	v_pk_fma_f32 v[230:231], v[198:199], v[114:115], v[230:231] neg_lo:[1,0,0] neg_hi:[1,0,0]
	ds_read_b128 v[196:199], v8 offset:15824
	s_waitcnt lgkmcnt(5)
	v_pk_fma_f32 v[230:231], v[200:201], v[116:117], v[230:231] neg_lo:[1,0,0] neg_hi:[1,0,0]
	v_pk_fma_f32 v[230:231], v[202:203], v[118:119], v[230:231] neg_lo:[1,0,0] neg_hi:[1,0,0]
	ds_read_b128 v[200:203], v8 offset:15840
	s_waitcnt lgkmcnt(5)
	v_pk_fma_f32 v[230:231], v[204:205], v[120:121], v[230:231] neg_lo:[1,0,0] neg_hi:[1,0,0]
	v_pk_fma_f32 v[230:231], v[206:207], v[122:123], v[230:231] neg_lo:[1,0,0] neg_hi:[1,0,0]
	ds_read_b128 v[204:207], v8 offset:15856
	s_waitcnt lgkmcnt(5)
	v_pk_fma_f32 v[230:231], v[208:209], v[124:125], v[230:231] neg_lo:[1,0,0] neg_hi:[1,0,0]
	v_pk_fma_f32 v[230:231], v[210:211], v[126:127], v[230:231] neg_lo:[1,0,0] neg_hi:[1,0,0]
	ds_read_b128 v[208:211], v8 offset:15872
	s_waitcnt lgkmcnt(5)
	v_pk_fma_f32 v[230:231], v[212:213], v[128:129], v[230:231] neg_lo:[1,0,0] neg_hi:[1,0,0]
	v_pk_fma_f32 v[230:231], v[214:215], v[130:131], v[230:231] neg_lo:[1,0,0] neg_hi:[1,0,0]
	ds_read_b128 v[212:215], v8 offset:15888
	s_waitcnt lgkmcnt(5)
	v_pk_fma_f32 v[230:231], v[192:193], v[132:133], v[230:231] neg_lo:[1,0,0] neg_hi:[1,0,0]
	v_pk_fma_f32 v[230:231], v[194:195], v[134:135], v[230:231] neg_lo:[1,0,0] neg_hi:[1,0,0]
	ds_read_b128 v[192:195], v8 offset:15904
	s_waitcnt lgkmcnt(5)
	v_pk_fma_f32 v[230:231], v[196:197], v[136:137], v[230:231] neg_lo:[1,0,0] neg_hi:[1,0,0]
	v_pk_fma_f32 v[230:231], v[198:199], v[138:139], v[230:231] neg_lo:[1,0,0] neg_hi:[1,0,0]
	ds_read_b128 v[196:199], v8 offset:15920
	s_waitcnt lgkmcnt(5)
	v_pk_fma_f32 v[230:231], v[200:201], v[140:141], v[230:231] neg_lo:[1,0,0] neg_hi:[1,0,0]
	v_pk_fma_f32 v[230:231], v[202:203], v[142:143], v[230:231] neg_lo:[1,0,0] neg_hi:[1,0,0]
	ds_read_b128 v[200:203], v8 offset:15936
	s_waitcnt lgkmcnt(5)
	v_fma_f32 v230, -v204, v144, v230
	ds_read_b128 v[204:207], v8 offset:15952
	v_add_f32_e32 v145, v230, v231
	s_cbranch_vccz .Ls4_u61
	v_cvt_pk_bf16_f32 v233, -v145, v145
	global_store_short v6, v233, s[8:9] offset:3328
	s_branch .Ls4_n61

; __device__ __forceinline__ void chunk_prep_phase(const Params& p, int bid, int nblk, LAS unsigned char* lds0) {
;     ...
;             { const float br = betg[62]; ab0 = (f32x2){bf2f(*(const LAS bf16_t*)(lg + P5_VS + 16864 + c * 2)) * br, bf2f(*(const LAS bf16_t*)(lg + P5_KS + 16864 + c * 2)) * br * __expf(decg[62])}; ab1 = (f32x2){0.f, 0.f}; } ab0 -= mq[4][0] * xy[0]; ab1 -= mq[4][1] * xy[1]; ab0 -= mq[4][2] * xy[2]; ab1 -= mq[4][3] * xy[3]; mq[4] = *(const LAS f32x4*)(Mg + 3992);
;             ab0 -= mq[5][0] * xy[4]; ab1 -= mq[5][1] * xy[5]; ab0 -= mq[5][2] * xy[6]; ab1 -= mq[5][3] * xy[7]; mq[5] = *(const LAS f32x4*)(Mg + 3996);
;             ab0 -= mq[0][0] * xy[8]; ab1 -= mq[0][1] * xy[9]; ab0 -= mq[0][2] * xy[10]; ab1 -= mq[0][3] * xy[11]; mq[0] = *(const LAS f32x4*)(Mg + 4000);
;             ab0 -= mq[1][0] * xy[12]; ab1 -= mq[1][1] * xy[13]; ab0 -= mq[1][2] * xy[14]; ab1 -= mq[1][3] * xy[15]; mq[1] = *(const LAS f32x4*)(Mg + 4004);
;             ab0 -= mq[2][0] * xy[16]; ab1 -= mq[2][1] * xy[17]; ab0 -= mq[2][2] * xy[18]; ab1 -= mq[2][3] * xy[19]; mq[2] = *(const LAS f32x4*)(Mg + 4008);
;             ab0 -= mq[3][0] * xy[20]; ab1 -= mq[3][1] * xy[21]; ab0 -= mq[3][2] * xy[22]; ab1 -= mq[3][3] * xy[23]; mq[3] = *(const LAS f32x4*)(Mg + 4012);
;             ab0 -= mq[4][0] * xy[24]; ab1 -= mq[4][1] * xy[25]; ab0 -= mq[4][2] * xy[26]; ab1 -= mq[4][3] * xy[27]; mq[4] = *(const LAS f32x4*)(Mg + 4016);
;             ab0 -= mq[5][0] * xy[28]; ab1 -= mq[5][1] * xy[29]; ab0 -= mq[5][2] * xy[30]; ab1 -= mq[5][3] * xy[31]; mq[5] = *(const LAS f32x4*)(Mg + 4020);
;             ab0 -= mq[0][0] * xy[32]; ab1 -= mq[0][1] * xy[33]; ab0 -= mq[0][2] * xy[34]; ab1 -= mq[0][3] * xy[35]; mq[0] = *(const LAS f32x4*)(Mg + 4024);
;             ab0 -= mq[1][0] * xy[36]; ab1 -= mq[1][1] * xy[37]; ab0 -= mq[1][2] * xy[38]; ab1 -= mq[1][3] * xy[39]; mq[1] = *(const LAS f32x4*)(Mg + 4028);
;             ab0 -= mq[2][0] * xy[40]; ab1 -= mq[2][1] * xy[41]; ab0 -= mq[2][2] * xy[42]; ab1 -= mq[2][3] * xy[43]; mq[2] = *(const LAS f32x4*)(Mg + 4032);
;             ab0 -= mq[3][0] * xy[44]; ab1 -= mq[3][1] * xy[45]; ab0 -= mq[3][2] * xy[46]; ab1 -= mq[3][3] * xy[47]; mq[3] = *(const LAS f32x4*)(Mg + 4036);
;             ab0 -= mq[4][0] * xy[48]; ab1 -= mq[4][1] * xy[49]; ab0 -= mq[4][2] * xy[50]; ab1 -= mq[4][3] * xy[51]; mq[4] = *(const LAS f32x4*)(Mg + 4040);
.Ls4_n61:
	v_lshlrev_b32_e32 v228, 16, v228
	v_mul_f32_e32 v232, v228, v222
	v_mul_f32_e32 v230, v232, v226
	v_mov_b32_e32 v231, 0
	ds_read_u16 v229, v7 offset:17136
	s_waitcnt lgkmcnt(6)
	v_pk_fma_f32 v[230:231], v[208:209], v[84:85], v[230:231] neg_lo:[1,0,0] neg_hi:[1,0,0]
	v_pk_fma_f32 v[230:231], v[210:211], v[86:87], v[230:231] neg_lo:[1,0,0] neg_hi:[1,0,0]
	ds_read_b128 v[208:211], v8 offset:15968
	s_waitcnt lgkmcnt(6)
	v_pk_fma_f32 v[230:231], v[212:213], v[88:89], v[230:231] neg_lo:[1,0,0] neg_hi:[1,0,0]
	v_pk_fma_f32 v[230:231], v[214:215], v[90:91], v[230:231] neg_lo:[1,0,0] neg_hi:[1,0,0]
	ds_read_b128 v[212:215], v8 offset:15984
	s_waitcnt lgkmcnt(6)
	v_pk_fma_f32 v[230:231], v[192:193], v[92:93], v[230:231] neg_lo:[1,0,0] neg_hi:[1,0,0]
	v_pk_fma_f32 v[230:231], v[194:195], v[94:95], v[230:231] neg_lo:[1,0,0] neg_hi:[1,0,0]
	ds_read_b128 v[192:195], v8 offset:16000
	s_waitcnt lgkmcnt(6)
	v_pk_fma_f32 v[230:231], v[196:197], v[96:97], v[230:231] neg_lo:[1,0,0] neg_hi:[1,0,0]
	v_pk_fma_f32 v[230:231], v[198:199], v[98:99], v[230:231] neg_lo:[1,0,0] neg_hi:[1,0,0]
	ds_read_b128 v[196:199], v8 offset:16016
	s_waitcnt lgkmcnt(6)
	v_pk_fma_f32 v[230:231], v[200:201], v[100:101], v[230:231] neg_lo:[1,0,0] neg_hi:[1,0,0]
	v_pk_fma_f32 v[230:231], v[202:203], v[102:103], v[230:231] neg_lo:[1,0,0] neg_hi:[1,0,0]
	ds_read_b128 v[200:203], v8 offset:16032
	s_waitcnt lgkmcnt(6)
	v_pk_fma_f32 v[230:231], v[204:205], v[104:105], v[230:231] neg_lo:[1,0,0] neg_hi:[1,0,0]
	v_pk_fma_f32 v[230:231], v[206:207], v[106:107], v[230:231] neg_lo:[1,0,0] neg_hi:[1,0,0]
	ds_read_b128 v[204:207], v8 offset:16048
	s_waitcnt lgkmcnt(5)
	v_pk_fma_f32 v[230:231], v[208:209], v[108:109], v[230:231] neg_lo:[1,0,0] neg_hi:[1,0,0]
	v_pk_fma_f32 v[230:231], v[210:211], v[110:111], v[230:231] neg_lo:[1,0,0] neg_hi:[1,0,0]
	ds_read_b128 v[208:211], v8 offset:16064
	s_waitcnt lgkmcnt(5)
	v_pk_fma_f32 v[230:231], v[212:213], v[112:113], v[230:231] neg_lo:[1,0,0] neg_hi:[1,0,0]
	v_pk_fma_f32 v[230:231], v[214:215], v[114:115], v[230:231] neg_lo:[1,0,0] neg_hi:[1,0,0]
	ds_read_b128 v[212:215], v8 offset:16080
	s_waitcnt lgkmcnt(5)
	v_pk_fma_f32 v[230:231], v[192:193], v[116:117], v[230:231] neg_lo:[1,0,0] neg_hi:[1,0,0]
	v_pk_fma_f32 v[230:231], v[194:195], v[118:119], v[230:231] neg_lo:[1,0,0] neg_hi:[1,0,0]
	ds_read_b128 v[192:195], v8 offset:16096
	s_waitcnt lgkmcnt(5)
	v_pk_fma_f32 v[230:231], v[196:197], v[120:121], v[230:231] neg_lo:[1,0,0] neg_hi:[1,0,0]
	v_pk_fma_f32 v[230:231], v[198:199], v[122:123], v[230:231] neg_lo:[1,0,0] neg_hi:[1,0,0]
	ds_read_b128 v[196:199], v8 offset:16112
	s_waitcnt lgkmcnt(5)
	v_pk_fma_f32 v[230:231], v[200:201], v[124:125], v[230:231] neg_lo:[1,0,0] neg_hi:[1,0,0]
	v_pk_fma_f32 v[230:231], v[202:203], v[126:127], v[230:231] neg_lo:[1,0,0] neg_hi:[1,0,0]
	ds_read_b128 v[200:203], v8 offset:16128
	s_waitcnt lgkmcnt(5)
	v_pk_fma_f32 v[230:231], v[204:205], v[128:129], v[230:231] neg_lo:[1,0,0] neg_hi:[1,0,0]
	v_pk_fma_f32 v[230:231], v[206:207], v[130:131], v[230:231] neg_lo:[1,0,0] neg_hi:[1,0,0]
	ds_read_b128 v[204:207], v8 offset:16144
	s_waitcnt lgkmcnt(5)
	v_pk_fma_f32 v[230:231], v[208:209], v[132:133], v[230:231] neg_lo:[1,0,0] neg_hi:[1,0,0]
	v_pk_fma_f32 v[230:231], v[210:211], v[134:135], v[230:231] neg_lo:[1,0,0] neg_hi:[1,0,0]
	ds_read_b128 v[208:211], v8 offset:16160
	s_waitcnt lgkmcnt(5)
	v_pk_fma_f32 v[230:231], v[212:213], v[136:137], v[230:231] neg_lo:[1,0,0] neg_hi:[1,0,0]
	v_pk_fma_f32 v[230:231], v[214:215], v[138:139], v[230:231] neg_lo:[1,0,0] neg_hi:[1,0,0]
	ds_read_b128 v[212:215], v8 offset:16176
	s_waitcnt lgkmcnt(5)
	v_pk_fma_f32 v[230:231], v[192:193], v[140:141], v[230:231] neg_lo:[1,0,0] neg_hi:[1,0,0]
	v_pk_fma_f32 v[230:231], v[194:195], v[142:143], v[230:231] neg_lo:[1,0,0] neg_hi:[1,0,0]
	ds_read_b128 v[192:195], v8 offset:16192
	s_waitcnt lgkmcnt(5)
	v_pk_fma_f32 v[230:231], v[196:197], v[144:145], v[230:231] neg_lo:[1,0,0] neg_hi:[1,0,0]
	ds_read_b128 v[196:199], v8 offset:16208
	v_add_f32_e32 v146, v230, v231
	s_cbranch_vccz .Ls4_u62
	v_cvt_pk_bf16_f32 v233, -v146, v146
	global_store_short v6, v233, s[8:9] offset:3584
	s_branch .Ls4_n62

; __device__ __forceinline__ void chunk_prep_phase(const Params& p, int bid, int nblk, LAS unsigned char* lds0) {
;     ...
;             { const float br = betg[63]; ab0 = (f32x2){bf2f(*(const LAS bf16_t*)(lg + P5_VS + 17136 + c * 2)) * br, bf2f(*(const LAS bf16_t*)(lg + P5_KS + 17136 + c * 2)) * br * __expf(decg[63])}; ab1 = (f32x2){0.f, 0.f}; } ab0 -= mq[2][0] * xy[0]; ab1 -= mq[2][1] * xy[1]; ab0 -= mq[2][2] * xy[2]; ab1 -= mq[2][3] * xy[3]; mq[2] = *(const LAS f32x4*)(Mg + 4056);
;             ab0 -= mq[3][0] * xy[4]; ab1 -= mq[3][1] * xy[5]; ab0 -= mq[3][2] * xy[6]; ab1 -= mq[3][3] * xy[7]; mq[3] = *(const LAS f32x4*)(Mg + 4060);
;             ab0 -= mq[4][0] * xy[8]; ab1 -= mq[4][1] * xy[9]; ab0 -= mq[4][2] * xy[10]; ab1 -= mq[4][3] * xy[11]; mq[4] = *(const LAS f32x4*)(Mg + 4064);
;             ab0 -= mq[5][0] * xy[12]; ab1 -= mq[5][1] * xy[13]; ab0 -= mq[5][2] * xy[14]; ab1 -= mq[5][3] * xy[15]; mq[5] = *(const LAS f32x4*)(Mg + 4068);
;             ab0 -= mq[0][0] * xy[16]; ab1 -= mq[0][1] * xy[17]; ab0 -= mq[0][2] * xy[18]; ab1 -= mq[0][3] * xy[19]; mq[0] = *(const LAS f32x4*)(Mg + 4072);
;             ab0 -= mq[1][0] * xy[20]; ab1 -= mq[1][1] * xy[21]; ab0 -= mq[1][2] * xy[22]; ab1 -= mq[1][3] * xy[23]; mq[1] = *(const LAS f32x4*)(Mg + 4076);
;             ab0 -= mq[2][0] * xy[24]; ab1 -= mq[2][1] * xy[25]; ab0 -= mq[2][2] * xy[26]; ab1 -= mq[2][3] * xy[27]; mq[2] = *(const LAS f32x4*)(Mg + 4080);
;             ab0 -= mq[3][0] * xy[28]; ab1 -= mq[3][1] * xy[29]; ab0 -= mq[3][2] * xy[30]; ab1 -= mq[3][3] * xy[31]; mq[3] = *(const LAS f32x4*)(Mg + 4084);
;             ab0 -= mq[4][0] * xy[32]; ab1 -= mq[4][1] * xy[33]; ab0 -= mq[4][2] * xy[34]; ab1 -= mq[4][3] * xy[35]; mq[4] = *(const LAS f32x4*)(Mg + 4088);
;             ab0 -= mq[5][0] * xy[36]; ab1 -= mq[5][1] * xy[37]; ab0 -= mq[5][2] * xy[38]; ab1 -= mq[5][3] * xy[39]; mq[5] = *(const LAS f32x4*)(Mg + 4092);
;             ab0 -= mq[0][0] * xy[40]; ab1 -= mq[0][1] * xy[41]; ab0 -= mq[0][2] * xy[42]; ab1 -= mq[0][3] * xy[43];
;             ab0 -= mq[1][0] * xy[44]; ab1 -= mq[1][1] * xy[45]; ab0 -= mq[1][2] * xy[46]; ab1 -= mq[1][3] * xy[47];
;             ab0 -= mq[2][0] * xy[48]; ab1 -= mq[2][1] * xy[49]; ab0 -= mq[2][2] * xy[50]; ab1 -= mq[2][3] * xy[51];
;             ab0 -= mq[3][0] * xy[52]; ab1 -= mq[3][1] * xy[53]; ab0 -= mq[3][2] * xy[54]; ab1 -= mq[3][3] * xy[55];
.Ls4_n62:
	v_lshlrev_b32_e32 v229, 16, v229
	v_mul_f32_e32 v232, v229, v223
	v_mul_f32_e32 v230, v232, v227
	v_mov_b32_e32 v231, 0
	s_waitcnt lgkmcnt(5)
	v_pk_fma_f32 v[230:231], v[200:201], v[84:85], v[230:231] neg_lo:[1,0,0] neg_hi:[1,0,0]
	v_pk_fma_f32 v[230:231], v[202:203], v[86:87], v[230:231] neg_lo:[1,0,0] neg_hi:[1,0,0]
	ds_read_b128 v[200:203], v8 offset:16224
	s_waitcnt lgkmcnt(5)
	v_pk_fma_f32 v[230:231], v[204:205], v[88:89], v[230:231] neg_lo:[1,0,0] neg_hi:[1,0,0]
	v_pk_fma_f32 v[230:231], v[206:207], v[90:91], v[230:231] neg_lo:[1,0,0] neg_hi:[1,0,0]
	ds_read_b128 v[204:207], v8 offset:16240
	s_waitcnt lgkmcnt(5)
	v_pk_fma_f32 v[230:231], v[208:209], v[92:93], v[230:231] neg_lo:[1,0,0] neg_hi:[1,0,0]
	v_pk_fma_f32 v[230:231], v[210:211], v[94:95], v[230:231] neg_lo:[1,0,0] neg_hi:[1,0,0]
	ds_read_b128 v[208:211], v8 offset:16256
	s_waitcnt lgkmcnt(5)
	v_pk_fma_f32 v[230:231], v[212:213], v[96:97], v[230:231] neg_lo:[1,0,0] neg_hi:[1,0,0]
	v_pk_fma_f32 v[230:231], v[214:215], v[98:99], v[230:231] neg_lo:[1,0,0] neg_hi:[1,0,0]
	ds_read_b128 v[212:215], v8 offset:16272
	s_waitcnt lgkmcnt(5)
	v_pk_fma_f32 v[230:231], v[192:193], v[100:101], v[230:231] neg_lo:[1,0,0] neg_hi:[1,0,0]
	v_pk_fma_f32 v[230:231], v[194:195], v[102:103], v[230:231] neg_lo:[1,0,0] neg_hi:[1,0,0]
	ds_read_b128 v[192:195], v8 offset:16288
	s_waitcnt lgkmcnt(5)
	v_pk_fma_f32 v[230:231], v[196:197], v[104:105], v[230:231] neg_lo:[1,0,0] neg_hi:[1,0,0]
	v_pk_fma_f32 v[230:231], v[198:199], v[106:107], v[230:231] neg_lo:[1,0,0] neg_hi:[1,0,0]
	ds_read_b128 v[196:199], v8 offset:16304
	s_waitcnt lgkmcnt(5)
	v_pk_fma_f32 v[230:231], v[200:201], v[108:109], v[230:231] neg_lo:[1,0,0] neg_hi:[1,0,0]
	v_pk_fma_f32 v[230:231], v[202:203], v[110:111], v[230:231] neg_lo:[1,0,0] neg_hi:[1,0,0]
	ds_read_b128 v[200:203], v8 offset:16320
	s_waitcnt lgkmcnt(5)
	v_pk_fma_f32 v[230:231], v[204:205], v[112:113], v[230:231] neg_lo:[1,0,0] neg_hi:[1,0,0]
	v_pk_fma_f32 v[230:231], v[206:207], v[114:115], v[230:231] neg_lo:[1,0,0] neg_hi:[1,0,0]
	ds_read_b128 v[204:207], v8 offset:16336
	s_waitcnt lgkmcnt(5)
	v_pk_fma_f32 v[230:231], v[208:209], v[116:117], v[230:231] neg_lo:[1,0,0] neg_hi:[1,0,0]
	v_pk_fma_f32 v[230:231], v[210:211], v[118:119], v[230:231] neg_lo:[1,0,0] neg_hi:[1,0,0]
	ds_read_b128 v[208:211], v8 offset:16352
	s_waitcnt lgkmcnt(5)
	v_pk_fma_f32 v[230:231], v[212:213], v[120:121], v[230:231] neg_lo:[1,0,0] neg_hi:[1,0,0]
	v_pk_fma_f32 v[230:231], v[214:215], v[122:123], v[230:231] neg_lo:[1,0,0] neg_hi:[1,0,0]
	ds_read_b128 v[212:215], v8 offset:16368
	s_waitcnt lgkmcnt(5)
	v_pk_fma_f32 v[230:231], v[192:193], v[124:125], v[230:231] neg_lo:[1,0,0] neg_hi:[1,0,0]
	v_pk_fma_f32 v[230:231], v[194:195], v[126:127], v[230:231] neg_lo:[1,0,0] neg_hi:[1,0,0]
	s_waitcnt lgkmcnt(4)
	v_pk_fma_f32 v[230:231], v[196:197], v[128:129], v[230:231] neg_lo:[1,0,0] neg_hi:[1,0,0]
	v_pk_fma_f32 v[230:231], v[198:199], v[130:131], v[230:231] neg_lo:[1,0,0] neg_hi:[1,0,0]
	s_waitcnt lgkmcnt(3)
	v_pk_fma_f32 v[230:231], v[200:201], v[132:133], v[230:231] neg_lo:[1,0,0] neg_hi:[1,0,0]
	v_pk_fma_f32 v[230:231], v[202:203], v[134:135], v[230:231] neg_lo:[1,0,0] neg_hi:[1,0,0]
	s_waitcnt lgkmcnt(2)
	v_pk_fma_f32 v[230:231], v[204:205], v[136:137], v[230:231] neg_lo:[1,0,0] neg_hi:[1,0,0]
	v_pk_fma_f32 v[230:231], v[206:207], v[138:139], v[230:231] neg_lo:[1,0,0] neg_hi:[1,0,0]
	s_waitcnt lgkmcnt(1)
	v_pk_fma_f32 v[230:231], v[208:209], v[140:141], v[230:231] neg_lo:[1,0,0] neg_hi:[1,0,0]
	v_pk_fma_f32 v[230:231], v[210:211], v[142:143], v[230:231] neg_lo:[1,0,0] neg_hi:[1,0,0]
	s_waitcnt lgkmcnt(0)
	v_pk_fma_f32 v[230:231], v[212:213], v[144:145], v[230:231] neg_lo:[1,0,0] neg_hi:[1,0,0]
	v_fma_f32 v230, -v214, v146, v230
	v_add_f32_e32 v147, v230, v231
	s_cbranch_vccz .Ls4_u63
	v_cvt_pk_bf16_f32 v233, -v147, v147
	global_store_short v6, v233, s[8:9] offset:3840
	s_branch .Ls4_n63
